# GEMM core: static s_setprio 1 for second block per CU (blockIdx>=256) during the mainloop, on top of stagger+iso
# baseline (speedup 1.0000x reference)
; DI bfr f2bf(float a) { return (bfr)(pack2(a, 0.f) & 0xffffu); }
; #define GA_LOAD(pr_) do { _Pragma("unroll") for (int i = 0; i < 4; ++i) ra[i] = *(const u32x4*)(Ab + (i * 32) * lda + (pr_) * 64); } while (0)
; #define GB_LOAD(kt_) do { const bfr* bk_ = Bb + (kt_) * NB * 32; \
;     _Pragma("unroll") for (int i = 0; i < 4; ++i) rb[i] = *(const u32x4*)(bk_ + (i * 64) * 32); } while (0)
; #define G_STORE(kt_) do { bfr* as_ = S0 + ((kt_) & 1) * GSTAGE; bfr* bs_ = as_ + 128 * 40; \
;     if (apar == ((kt_) & 1)) { _Pragma("unroll") for (int i = 0; i < 4; ++i) *(u32x4*)(as_ + asoff + i * 32 * 40) = ra[i]; } \
;     _Pragma("unroll") for (int i = 0; i < 4; ++i) *(u32x4*)(bs_ + bsoff + i * 64 * 40) = rb[i]; } while (0)
; template <int lda>
; DI void gemm_mainloop(const bfr* __restrict__ A, const bfr* __restrict__ Bt, int NB, int K, int m0, int n0, char* smem, f32x16 (&acc)[2][4]) {
;     ...
;   u32x4 ra[4], rb[4];
;   const int nk = K >> 5;
;   const int arow = tid >> 3, ac8 = tid & 7, apar = ac8 >> 2;
;   const bfr* Ab = A + (m0 + arow) * lda + ac8 * 8;
;   const int asoff = arow * 40 + (ac8 & 3) * 8;
;   const int brow = tid >> 2, bc4 = tid & 3;
;   const bfr* Bb = Bt + (n0 + brow) * 32 + bc4 * 8;
;   const int bsoff = brow * 40 + bc4 * 8;
;     ...
;   GA_LOAD(0);
;   GB_LOAD(0);
;   G_STORE(0);
;   GB_LOAD(1);
;   __syncthreads();
; DI void phase_gemm_in_even(const Params& p, char* smem) {
;     ...
;       int u = t - NT1, gsel = u >> 6, v = u & 63, mt = v >> 2, nt = v & 3;
;       int isv = gsel >> 1, l = gsel & 1;
;       if (!isv) {
;         float* o = p.out + O_MEMK + (size_t)l * 2097152;
;         bfr* kb = p.KB + (size_t)l * 2097152;
;         gemm_tile<1024>(p.MPB, p.WtXk + (size_t)l * 1048576, 1024, 1024, mt * 128, nt * 256, smem,
;                   [=](int row, int col, float v) {
;                     o[(size_t)row * 1024 + col] = v;
;                     kb[(size_t)row * 1024 + col] = f2bf(v);
;                   });
;       } else {
;         float* o = p.out + O_MEMV + (size_t)l * 2097152;
;         bfr* vt = p.VT + (size_t)l * 2097152;
;         gemm_tile<1024>(p.MPB, p.WtXv + (size_t)l * 1048576, 1024, 1024, mt * 128, nt * 256, smem,
.LBB0_123:
	s_lshl_b32 s1, s56, 15
	s_and_b32 s2, s1, 0x200000
	s_lshl_b32 s1, s56, 5
	s_and_b32 s58, s1, 0x780
	s_lshl_b32 s1, s56, 8
	s_and_b32 s0, s56, 0x7fffff80
	s_and_b32 s57, s1, 0x300
	s_cmpk_lg_i32 s0, 0x700
	s_mov_b64 s[0:1], -1
	s_cbranch_scc0 .LBB0_136
	s_add_u32 s0, s14, s2
	s_addc_u32 s1, s15, 0
	s_mov_b32 s59, 0
	s_mov_b64 s[30:31], 0
	s_lshl_b32 s98, s58, 11
	s_add_u32 s98, s8, s98
	s_addc_u32 s99, s9, 0
	s_lshl_b32 s100, s57, 6
	s_add_u32 s100, s0, s100
	s_addc_u32 s101, s1, 0
	v_writelane_b32 v188, s64, 0
	v_writelane_b32 v188, s65, 1
	v_writelane_b32 v188, s66, 2
	v_writelane_b32 v188, s67, 3
	v_writelane_b32 v188, s68, 4
	v_writelane_b32 v188, s69, 5
	v_writelane_b32 v188, s70, 6
	v_writelane_b32 v188, s71, 7
	v_writelane_b32 v188, s72, 8
	v_writelane_b32 v188, s73, 9
	v_writelane_b32 v188, s74, 10
	v_writelane_b32 v188, s75, 11
	v_writelane_b32 v188, s76, 12
	v_writelane_b32 v188, s77, 13
	v_writelane_b32 v188, s78, 14
	v_writelane_b32 v188, s79, 15
	v_lshrrev_b32_e32 v189, 6, v196
	v_and_b32_e32 v190, 63, v196
	v_readfirstlane_b32 s73, v189
	v_lshrrev_b32_e32 v191, 2, v190
	v_bfe_u32 v192, v190, 4, 2
	v_and_b32_e32 v189, 3, v190
	v_xor_b32_e32 v189, v189, v192
	v_lshlrev_b32_e32 v189, 4, v189
	v_lshl_add_u32 v160, v191, 11, v189
	v_add_u32_e32 v162, 0x8000, v160
	v_lshl_add_u32 v163, v191, 6, v189
	v_and_b32_e32 v191, 31, v190
	v_lshrrev_b32_e32 v192, 5, v190
	v_bfe_u32 v189, v190, 2, 2
	v_xor_b32_e32 v189, v189, v192
	v_lshlrev_b32_e32 v189, 4, v189
	v_lshl_add_u32 v180, v191, 6, v189
	s_lshr_b32 s74, s73, 1
	s_lshl_b32 s74, s74, 12
	s_and_b32 s75, s73, 1
	s_lshl_b32 s75, s75, 13
	v_add_u32_e32 v182, s75, v180
	v_add_u32_e32 v180, s74, v180
	v_xor_b32_e32 v183, 32, v182
	v_xor_b32_e32 v181, 32, v180
	s_lshl_b32 s74, s73, 16
	s_add_u32 s64, s98, s74
	s_addc_u32 s65, s99, 0
	s_lshl_b32 s74, s73, 12
	s_add_u32 s66, s100, s74
	s_addc_u32 s67, s101, 0
	s_lshl_b32 s68, s73, 11
	s_lshl_b32 s69, s73, 12
	s_mov_b32 s70, 0
	s_mov_b32 s71, 0
	s_mov_b32 s72, 0
	s_waitcnt lgkmcnt(0)
	s_barrier
	s_mul_i32 s74, s70, 0x6000
	s_add_u32 s75, s74, s68
	s_mov_b32 m0, s75
	s_add_u32 s76, s74, 0x2000
	s_cmp_eq_u32 s70, 2
	s_cselect_b32 s76, 0x10000, s76
	global_load_lds_dwordx4 v160, s[64:65]
	s_add_u32 m0, s75, 0x400
	s_add_u32 s76, s76, s69
	global_load_lds_dwordx4 v162, s[64:65]
	s_mov_b32 m0, s76
	s_add_u32 s64, s64, 64
	s_addc_u32 s65, s65, 0
	global_load_lds_dwordx4 v163, s[66:67]
	global_load_lds_dwordx4 v163, s[66:67] offset:1024
	global_load_lds_dwordx4 v163, s[66:67] offset:2048
	global_load_lds_dwordx4 v163, s[66:67] offset:3072
	s_add_u32 s66, s66, 0x10000
	s_addc_u32 s67, s67, 0
	s_add_u32 s70, s70, 1
	s_cmp_eq_u32 s70, 3
	s_cselect_b32 s70, 0, s70
	s_mul_i32 s74, s70, 0x6000
	s_add_u32 s75, s74, s68
	s_mov_b32 m0, s75
	s_add_u32 s76, s74, 0x2000
	s_cmp_eq_u32 s70, 2
	s_cselect_b32 s76, 0x10000, s76
	global_load_lds_dwordx4 v160, s[64:65]
	s_add_u32 m0, s75, 0x400
	s_add_u32 s76, s76, s69
	global_load_lds_dwordx4 v162, s[64:65]
	s_mov_b32 m0, s76
	s_add_u32 s64, s64, 64
	s_addc_u32 s65, s65, 0
	global_load_lds_dwordx4 v163, s[66:67]
	global_load_lds_dwordx4 v163, s[66:67] offset:1024
	global_load_lds_dwordx4 v163, s[66:67] offset:2048
	global_load_lds_dwordx4 v163, s[66:67] offset:3072
	s_add_u32 s66, s66, 0x10000
	s_addc_u32 s67, s67, 0
	s_add_u32 s70, s70, 1
	s_cmp_eq_u32 s70, 3
	s_cselect_b32 s70, 0, s70
	s_cmp_lt_u32 s46, 0x100
	s_cbranch_scc1 .Lp1v_nostag
	s_sleep 8
	s_setprio 1

; #define MFMA32(a, b, c) __builtin_amdgcn_mfma_f32_32x32x16_bf16((a), (b), (c), 0, 0, 0)
; #define GA_LOAD(pr_) do { _Pragma("unroll") for (int i = 0; i < 4; ++i) ra[i] = *(const u32x4*)(Ab + (i * 32) * lda + (pr_) * 64); } while (0)
; #define GB_LOAD(kt_) do { const bfr* bk_ = Bb + (kt_) * NB * 32; \
;     _Pragma("unroll") for (int i = 0; i < 4; ++i) rb[i] = *(const u32x4*)(bk_ + (i * 64) * 32); } while (0)
; #define G_STORE(kt_) do { bfr* as_ = S0 + ((kt_) & 1) * GSTAGE; bfr* bs_ = as_ + 128 * 40; \
;     if (apar == ((kt_) & 1)) { _Pragma("unroll") for (int i = 0; i < 4; ++i) *(u32x4*)(as_ + asoff + i * 32 * 40) = ra[i]; } \
;     _Pragma("unroll") for (int i = 0; i < 4; ++i) *(u32x4*)(bs_ + bsoff + i * 64 * 40) = rb[i]; } while (0)
; template <int lda>
; DI void gemm_mainloop(const bfr* __restrict__ A, const bfr* __restrict__ Bt, int NB, int K, int m0, int n0, char* smem, f32x16 (&acc)[2][4]) {
;     ...
;   for (int kt = 0; kt < nk; ++kt) {
;     if (kt + 1 < nk) G_STORE(kt + 1);
;     if (kt + 2 < nk) {
;       GB_LOAD(kt + 2);
;       if ((kt & 1) == 0) GA_LOAD((kt >> 1) + 1);
;     }
;     const bfr* As = S0 + (kt & 1) * GSTAGE;
;     const bfr* Bs = As + 128 * 40;
; #pragma unroll
;     for (int ks = 0; ks < 2; ++ks) {
;       bf16x8 af[2], bfg[4];
; #pragma unroll
;       for (int i = 0; i < 2; ++i) af[i] = *(const bf16x8*)(As + (wr * 64 + i * 32 + r) * 40 + ks * 16 + hl * 8);
; #pragma unroll
;       for (int j = 0; j < 4; ++j) bfg[j] = *(const bf16x8*)(Bs + (wc * 128 + j * 32 + r) * 40 + ks * 16 + hl * 8);
; #pragma unroll
;       for (int i = 0; i < 2; ++i)
; #pragma unroll
;         for (int j = 0; j < 4; ++j) acc[i][j] = MFMA32(af[i], bfg[j], acc[i][j]);
;     }
;     __syncthreads();
;   }
.Lp1v_loop:
	s_waitcnt vmcnt(6)
	s_barrier
	s_mul_i32 s74, s71, 0x6000
	s_add_u32 s75, s74, 0x2000
	s_cmp_eq_u32 s71, 2
	s_cselect_b32 s75, 0x10000, s75
	v_add_u32_e32 v184, s74, v180
	v_add_u32_e32 v186, s75, v182
	v_add_u32_e32 v185, s74, v181
	v_add_u32_e32 v187, s75, v183
	ds_read_b128 v[128:131], v184
	ds_read_b128 v[144:147], v186
	ds_read_b128 v[148:151], v186 offset:2048
	ds_read_b128 v[152:155], v186 offset:4096
	ds_read_b128 v[156:159], v186 offset:6144
	ds_read_b128 v[132:135], v184 offset:2048
	ds_read_b128 v[136:139], v185
	ds_read_b128 v[164:167], v187
	ds_read_b128 v[168:171], v187 offset:2048
	ds_read_b128 v[172:175], v187 offset:4096
	ds_read_b128 v[176:179], v187 offset:6144
	ds_read_b128 v[140:143], v185 offset:2048
	s_add_u32 s71, s71, 1
	s_cmp_eq_u32 s71, 3
	s_cselect_b32 s71, 0, s71
	s_waitcnt lgkmcnt(10)
	v_mfma_f32_32x32x16_bf16 v[112:127], v[128:131], v[144:147], v[112:127]
	s_mul_i32 s74, s70, 0x6000
	s_add_u32 s75, s74, s68
	s_mov_b32 m0, s75
	s_add_u32 s76, s74, 0x2000
	s_cmp_eq_u32 s70, 2
	s_cselect_b32 s76, 0x10000, s76
	global_load_lds_dwordx4 v160, s[64:65]
	s_waitcnt lgkmcnt(9)
	v_mfma_f32_32x32x16_bf16 v[96:111], v[128:131], v[148:151], v[96:111]
	s_add_u32 m0, s75, 0x400
	s_add_u32 s76, s76, s69
	global_load_lds_dwordx4 v162, s[64:65]
	s_waitcnt lgkmcnt(8)
	v_mfma_f32_32x32x16_bf16 v[80:95], v[128:131], v[152:155], v[80:95]
	s_mov_b32 m0, s76
	s_add_u32 s64, s64, 64
	s_addc_u32 s65, s65, 0
	global_load_lds_dwordx4 v163, s[66:67]
	s_waitcnt lgkmcnt(7)
	v_mfma_f32_32x32x16_bf16 v[64:79], v[128:131], v[156:159], v[64:79]
	global_load_lds_dwordx4 v163, s[66:67] offset:1024
	s_waitcnt lgkmcnt(6)
	v_mfma_f32_32x32x16_bf16 v[48:63], v[132:135], v[144:147], v[48:63]
	global_load_lds_dwordx4 v163, s[66:67] offset:2048
	v_mfma_f32_32x32x16_bf16 v[32:47], v[132:135], v[148:151], v[32:47]
	global_load_lds_dwordx4 v163, s[66:67] offset:3072
	s_add_u32 s66, s66, 0x10000
	s_addc_u32 s67, s67, 0
	v_mfma_f32_32x32x16_bf16 v[16:31], v[132:135], v[152:155], v[16:31]
	s_add_u32 s70, s70, 1
	s_cmp_eq_u32 s70, 3
	s_cselect_b32 s70, 0, s70
	v_mfma_f32_32x32x16_bf16 v[0:15], v[132:135], v[156:159], v[0:15]
	s_waitcnt lgkmcnt(4)
	v_mfma_f32_32x32x16_bf16 v[112:127], v[136:139], v[164:167], v[112:127]
	s_waitcnt lgkmcnt(3)
	v_mfma_f32_32x32x16_bf16 v[96:111], v[136:139], v[168:171], v[96:111]
	s_waitcnt lgkmcnt(2)
	v_mfma_f32_32x32x16_bf16 v[80:95], v[136:139], v[172:175], v[80:95]
	s_waitcnt lgkmcnt(1)
	v_mfma_f32_32x32x16_bf16 v[64:79], v[136:139], v[176:179], v[64:79]
	s_waitcnt lgkmcnt(0)
	v_mfma_f32_32x32x16_bf16 v[48:63], v[140:143], v[164:167], v[48:63]
	v_mfma_f32_32x32x16_bf16 v[32:47], v[140:143], v[168:171], v[32:47]
	v_mfma_f32_32x32x16_bf16 v[16:31], v[140:143], v[172:175], v[16:31]
	v_mfma_f32_32x32x16_bf16 v[0:15], v[140:143], v[176:179], v[0:15]
	s_add_u32 s72, s72, 1
	s_cmp_lt_u32 s72, 30
	s_cbranch_scc1 .Lp1v_loop
	s_waitcnt vmcnt(6)
	s_barrier
	s_mul_i32 s74, s71, 0x6000
	s_add_u32 s75, s74, 0x2000
	s_cmp_eq_u32 s71, 2
	s_cselect_b32 s75, 0x10000, s75
	v_add_u32_e32 v184, s74, v180
	v_add_u32_e32 v186, s75, v182
	v_add_u32_e32 v185, s74, v181
	v_add_u32_e32 v187, s75, v183
	ds_read_b128 v[128:131], v184
	ds_read_b128 v[144:147], v186
	ds_read_b128 v[148:151], v186 offset:2048
	ds_read_b128 v[152:155], v186 offset:4096
	ds_read_b128 v[156:159], v186 offset:6144
	ds_read_b128 v[132:135], v184 offset:2048
	ds_read_b128 v[136:139], v185
	ds_read_b128 v[164:167], v187
	ds_read_b128 v[168:171], v187 offset:2048
	ds_read_b128 v[172:175], v187 offset:4096
	ds_read_b128 v[176:179], v187 offset:6144
	ds_read_b128 v[140:143], v185 offset:2048
	s_add_u32 s71, s71, 1
	s_cmp_eq_u32 s71, 3
	s_cselect_b32 s71, 0, s71
	s_waitcnt lgkmcnt(10)
	v_mfma_f32_32x32x16_bf16 v[112:127], v[128:131], v[144:147], v[112:127]
	s_waitcnt lgkmcnt(9)
	v_mfma_f32_32x32x16_bf16 v[96:111], v[128:131], v[148:151], v[96:111]
	s_waitcnt lgkmcnt(8)
	v_mfma_f32_32x32x16_bf16 v[80:95], v[128:131], v[152:155], v[80:95]
	s_waitcnt lgkmcnt(7)
	v_mfma_f32_32x32x16_bf16 v[64:79], v[128:131], v[156:159], v[64:79]
	s_waitcnt lgkmcnt(6)
	v_mfma_f32_32x32x16_bf16 v[48:63], v[132:135], v[144:147], v[48:63]
	v_mfma_f32_32x32x16_bf16 v[32:47], v[132:135], v[148:151], v[32:47]
	v_mfma_f32_32x32x16_bf16 v[16:31], v[132:135], v[152:155], v[16:31]
	v_mfma_f32_32x32x16_bf16 v[0:15], v[132:135], v[156:159], v[0:15]
	s_waitcnt lgkmcnt(4)
	v_mfma_f32_32x32x16_bf16 v[112:127], v[136:139], v[164:167], v[112:127]
	s_waitcnt lgkmcnt(3)
	v_mfma_f32_32x32x16_bf16 v[96:111], v[136:139], v[168:171], v[96:111]
	s_waitcnt lgkmcnt(2)
	v_mfma_f32_32x32x16_bf16 v[80:95], v[136:139], v[172:175], v[80:95]
	s_waitcnt lgkmcnt(1)
	v_mfma_f32_32x32x16_bf16 v[64:79], v[136:139], v[176:179], v[64:79]
	s_waitcnt lgkmcnt(0)
	v_mfma_f32_32x32x16_bf16 v[48:63], v[140:143], v[164:167], v[48:63]
	v_mfma_f32_32x32x16_bf16 v[32:47], v[140:143], v[168:171], v[32:47]
	v_mfma_f32_32x32x16_bf16 v[16:31], v[140:143], v[172:175], v[16:31]
	v_mfma_f32_32x32x16_bf16 v[0:15], v[140:143], v[176:179], v[0:15]
	s_waitcnt vmcnt(0)
	s_barrier
; #define MFMA32(a, b, c) __builtin_amdgcn_mfma_f32_32x32x16_bf16((a), (b), (c), 0, 0, 0)
; DI bfr f2bf(float a) { return (bfr)(pack2(a, 0.f) & 0xffffu); }
; #define GA_LOAD(pr_) do { _Pragma("unroll") for (int i = 0; i < 4; ++i) ra[i] = *(const u32x4*)(Ab + (i * 32) * lda + (pr_) * 64); } while (0)
; #define GB_LOAD(kt_) do { const bfr* bk_ = Bb + (kt_) * NB * 32; \
;     _Pragma("unroll") for (int i = 0; i < 4; ++i) rb[i] = *(const u32x4*)(bk_ + (i * 64) * 32); } while (0)
; template <int lda>
; DI void gemm_mainloop(const bfr* __restrict__ A, const bfr* __restrict__ Bt, int NB, int K, int m0, int n0, char* smem, f32x16 (&acc)[2][4]) {
;     ...
;   for (int kt = 0; kt < nk; ++kt) {
;     if (kt + 1 < nk) G_STORE(kt + 1);
;     if (kt + 2 < nk) {
;       GB_LOAD(kt + 2);
;       if ((kt & 1) == 0) GA_LOAD((kt >> 1) + 1);
;     }
;     const bfr* As = S0 + (kt & 1) * GSTAGE;
;     const bfr* Bs = As + 128 * 40;
; #pragma unroll
;     for (int ks = 0; ks < 2; ++ks) {
;       bf16x8 af[2], bfg[4];
; #pragma unroll
;       for (int i = 0; i < 2; ++i) af[i] = *(const bf16x8*)(As + (wr * 64 + i * 32 + r) * 40 + ks * 16 + hl * 8);
; #pragma unroll
;       for (int j = 0; j < 4; ++j) bfg[j] = *(const bf16x8*)(Bs + (wc * 128 + j * 32 + r) * 40 + ks * 16 + hl * 8);
; #pragma unroll
;       for (int i = 0; i < 2; ++i)
; #pragma unroll
;         for (int j = 0; j < 4; ++j) acc[i][j] = MFMA32(af[i], bfg[j], acc[i][j]);
;     }
;     __syncthreads();
;   }
; DI void phase_gemm_in_even(const Params& p, char* smem) {
;     ...
;         gemm_tile<1024>(p.MPB, p.WtXv + (size_t)l * 1048576, 1024, 1024, mt * 128, nt * 256, smem,
;                   [=](int row, int col, float v) {
;                     o[(size_t)row * 1024 + col] = v;
;                     const int ml = row & 15;
;                     const int rowpart = (row >> 8) * 262144 + ((row & 255) >> 4) * 512 + ((ml >> 2) & 1) * 256 + (((ml >> 3) << 2) | (ml & 3));
;                     const int colpart = (col >> 8) * 65536 + ((col & 255) >> 5) * 8192 + (col & 31) * 8;
;                     vt[rowpart + colpart] = f2bf(v);
;                   });
	s_mul_i32 s74, s71, 0x6000
	s_add_u32 s75, s74, 0x2000
	s_cmp_eq_u32 s71, 2
	s_cselect_b32 s75, 0x10000, s75
	v_add_u32_e32 v184, s74, v180
	v_add_u32_e32 v186, s75, v182
	v_add_u32_e32 v185, s74, v181
	v_add_u32_e32 v187, s75, v183
	ds_read_b128 v[128:131], v184
	ds_read_b128 v[144:147], v186
	ds_read_b128 v[148:151], v186 offset:2048
	ds_read_b128 v[152:155], v186 offset:4096
	ds_read_b128 v[156:159], v186 offset:6144
	ds_read_b128 v[132:135], v184 offset:2048
	ds_read_b128 v[136:139], v185
	ds_read_b128 v[164:167], v187
	ds_read_b128 v[168:171], v187 offset:2048
	ds_read_b128 v[172:175], v187 offset:4096
	ds_read_b128 v[176:179], v187 offset:6144
	ds_read_b128 v[140:143], v185 offset:2048
	s_add_u32 s71, s71, 1
	s_cmp_eq_u32 s71, 3
	s_cselect_b32 s71, 0, s71
	s_waitcnt lgkmcnt(10)
	v_mfma_f32_32x32x16_bf16 v[112:127], v[128:131], v[144:147], v[112:127]
	s_waitcnt lgkmcnt(9)
	v_mfma_f32_32x32x16_bf16 v[96:111], v[128:131], v[148:151], v[96:111]
	s_waitcnt lgkmcnt(8)
	v_mfma_f32_32x32x16_bf16 v[80:95], v[128:131], v[152:155], v[80:95]
	s_waitcnt lgkmcnt(7)
	v_mfma_f32_32x32x16_bf16 v[64:79], v[128:131], v[156:159], v[64:79]
	s_waitcnt lgkmcnt(6)
	v_mfma_f32_32x32x16_bf16 v[48:63], v[132:135], v[144:147], v[48:63]
	v_mfma_f32_32x32x16_bf16 v[32:47], v[132:135], v[148:151], v[32:47]
	v_mfma_f32_32x32x16_bf16 v[16:31], v[132:135], v[152:155], v[16:31]
	v_mfma_f32_32x32x16_bf16 v[0:15], v[132:135], v[156:159], v[0:15]
	s_waitcnt lgkmcnt(4)
	v_mfma_f32_32x32x16_bf16 v[112:127], v[136:139], v[164:167], v[112:127]
	s_waitcnt lgkmcnt(3)
	v_mfma_f32_32x32x16_bf16 v[96:111], v[136:139], v[168:171], v[96:111]
	s_waitcnt lgkmcnt(2)
	v_mfma_f32_32x32x16_bf16 v[80:95], v[136:139], v[172:175], v[80:95]
	s_waitcnt lgkmcnt(1)
	v_mfma_f32_32x32x16_bf16 v[64:79], v[136:139], v[176:179], v[64:79]
	s_waitcnt lgkmcnt(0)
	v_mfma_f32_32x32x16_bf16 v[48:63], v[140:143], v[164:167], v[48:63]
	v_mfma_f32_32x32x16_bf16 v[32:47], v[140:143], v[168:171], v[32:47]
	v_mfma_f32_32x32x16_bf16 v[16:31], v[140:143], v[172:175], v[16:31]
	v_mfma_f32_32x32x16_bf16 v[0:15], v[140:143], v[176:179], v[0:15]
	s_setprio 0
	s_nop 7
	v_readlane_b32 s64, v188, 0
	v_readlane_b32 s65, v188, 1
	v_readlane_b32 s66, v188, 2
	v_readlane_b32 s67, v188, 3
	v_readlane_b32 s68, v188, 4
	v_readlane_b32 s69, v188, 5
	v_readlane_b32 s70, v188, 6
	v_readlane_b32 s71, v188, 7
	v_readlane_b32 s72, v188, 8
	v_readlane_b32 s73, v188, 9
	v_readlane_b32 s74, v188, 10
	v_readlane_b32 s75, v188, 11
	v_readlane_b32 s76, v188, 12
	v_readlane_b32 s77, v188, 13
	v_readlane_b32 s78, v188, 14
	v_readlane_b32 s79, v188, 15
	s_nop 7
	s_waitcnt vmcnt(1)
	s_nop 0
	s_nop 0
	s_nop 0
	s_waitcnt vmcnt(0)
	s_nop 0
	v_add_u32_e32 v140, v171, v173
	s_nop 0
	v_add_u32_e32 v160, v171, v172
	s_nop 0
	s_nop 0
	s_nop 0
	s_nop 0
	s_nop 0
	s_nop 0
	s_nop 0
	s_nop 0
	s_nop 0
	s_nop 0
	s_nop 0
	s_waitcnt lgkmcnt(0)
	s_nop 0
	s_nop 0
	s_lshl_b32 s0, s2, 2
	s_add_u32 s30, s33, s0
	s_addc_u32 s31, s38, 0
	s_lshl_b32 s0, s2, 1
	s_add_u32 s0, s6, s0
	s_nop 0
	s_addc_u32 s1, s7, 0
	s_nop 0
	s_nop 0
	s_nop 0
	s_nop 0
	s_nop 0
	s_nop 0
	s_nop 0
	s_nop 0
	s_nop 0
	s_waitcnt lgkmcnt(3)
	s_nop 0
	s_nop 0
	v_mov_b32_e32 v152, v196
	s_nop 0
	s_nop 0
	s_nop 0
	s_nop 0
	s_nop 0
	s_nop 0
	s_nop 0
	s_waitcnt lgkmcnt(0)
	s_nop 0
	s_nop 0
	v_ashrrev_i32_e32 v153, 1, v152
	v_and_b32_e32 v153, 0xffffffc0, v153
	v_and_b32_e32 v155, 31, v152
	v_add_u32_e32 v173, s58, v153
	v_lshrrev_b32_e32 v153, 3, v152
	v_lshlrev_b32_e32 v152, 1, v152
	v_and_b32_e32 v152, 0x80, v152
	v_or_b32_e32 v170, s57, v152
	v_or_b32_e32 v152, v170, v155
	v_lshlrev_b32_e32 v175, 8, v170
	s_nop 0
	v_lshlrev_b32_e32 v170, 10, v173
	v_and_b32_e32 v174, 4, v153
	v_and_b32_e32 v172, 0xfffc0000, v170
	v_lshlrev_b32_e32 v170, 5, v173
	v_lshlrev_b32_e32 v160, 2, v152
	v_lshlrev_b32_e32 v197, 3, v155
	v_and_b32_e32 v170, 0x1800, v170
	v_lshlrev_b32_e32 v228, 6, v174
	v_lshl_add_u64 v[152:153], s[30:31], 0, v[160:161]
	v_or_b32_e32 v160, v175, v197
	s_nop 0
	v_or3_b32 v229, v228, v170, v172
	v_or_b32_e32 v231, 10, v174
	v_or_b32_e32 v156, v229, v160
	v_ashrrev_i32_e32 v157, 31, v156
	v_or_b32_e32 v230, 1, v174
	v_or_b32_e32 v154, v173, v174
	v_lshl_add_u64 v[226:227], v[156:157], 1, s[0:1]
	s_nop 0
	v_or_b32_e32 v188, 2, v174
	v_or_b32_e32 v191, 9, v174
	v_or_b32_e32 v158, v173, v188
	v_or_b32_e32 v189, 3, v174
	v_ashrrev_i32_e32 v159, 31, v158
	v_or_b32_e32 v162, v173, v189
	v_or_b32_e32 v190, 8, v174
	s_nop 0
	v_or_b32_e32 v178, 11, v174
	v_or_b32_e32 v170, v173, v178
	v_ashrrev_i32_e32 v171, 31, v170
	v_or_b32_e32 v156, v173, v230
	v_lshlrev_b64 v[158:159], 12, v[158:159]
	v_ashrrev_i32_e32 v163, 31, v162
	v_or_b32_e32 v164, v173, v190
	s_nop 0
	v_lshlrev_b64 v[170:171], 12, v[170:171]
	v_ashrrev_i32_e32 v155, 31, v154
	v_ashrrev_i32_e32 v157, 31, v156
	v_lshl_add_u64 v[158:159], v[152:153], 0, v[158:159]
	v_lshlrev_b64 v[162:163], 12, v[162:163]
	v_ashrrev_i32_e32 v165, 31, v164
	v_lshl_add_u64 v[170:171], v[152:153], 0, v[170:171]
	s_nop 0
	v_or_b32_e32 v179, 16, v174
	v_lshlrev_b64 v[154:155], 12, v[154:155]
	v_lshlrev_b64 v[156:157], 12, v[156:157]
	global_store_dword v[158:159], v114, off
	v_lshl_add_u64 v[162:163], v[152:153], 0, v[162:163]
	v_lshlrev_b64 v[164:165], 12, v[164:165]
	global_store_dword v[170:171], v119, off
	s_nop 0
	v_or_b32_e32 v166, v173, v191
	v_or_b32_e32 v168, v173, v231
	v_ashrrev_i32_e32 v167, 31, v166
	v_ashrrev_i32_e32 v169, 31, v168
	v_lshlrev_b64 v[166:167], 12, v[166:167]
	v_lshlrev_b64 v[168:169], 12, v[168:169]
	v_lshl_add_u64 v[166:167], v[152:153], 0, v[166:167]
	v_lshl_add_u64 v[168:169], v[152:153], 0, v[168:169]
	global_store_dword v[166:167], v117, off
; DI bfr f2bf(float a) { return (bfr)(pack2(a, 0.f) & 0xffffu); }
; DI void phase_gemm_in_even(const Params& p, char* smem) {
;     ...
;         gemm_tile<1024>(p.MPB, p.WtXv + (size_t)l * 1048576, 1024, 1024, mt * 128, nt * 256, smem,
;                   [=](int row, int col, float v) {
;                     o[(size_t)row * 1024 + col] = v;
;                     const int ml = row & 15;
;                     const int rowpart = (row >> 8) * 262144 + ((row & 255) >> 4) * 512 + ((ml >> 2) & 1) * 256 + (((ml >> 3) << 2) | (ml & 3));
;                     const int colpart = (col >> 8) * 65536 + ((col & 255) >> 5) * 8192 + (col & 31) * 8;
;                     vt[rowpart + colpart] = f2bf(v);
;                   });
	global_store_dword v[168:169], v118, off
	v_cvt_pk_bf16_f32 v119, v118, v119
	v_cvt_pk_bf16_f32 v118, v116, v117
	v_cvt_pk_bf16_f32 v117, v114, v115
	v_or_b32_e32 v114, v173, v179
	v_lshl_add_u64 v[154:155], v[152:153], 0, v[154:155]
	v_lshl_add_u64 v[156:157], v[152:153], 0, v[156:157]
	global_store_dword v[162:163], v115, off
	v_lshl_add_u64 v[164:165], v[152:153], 0, v[164:165]
	v_ashrrev_i32_e32 v115, 31, v114
	global_store_dword v[154:155], v112, off
	global_store_dword v[156:157], v113, off
	global_store_dword v[164:165], v116, off
	v_cvt_pk_bf16_f32 v116, v112, v113
	v_lshlrev_b64 v[112:113], 12, v[114:115]
	v_lshlrev_b32_e32 v114, 5, v114
	v_or_b32_e32 v172, v172, v228
	s_nop 0
	v_and_or_b32 v180, v114, s49, v172
	v_or_b32_e32 v114, v180, v160
	v_ashrrev_i32_e32 v115, 31, v114
	global_store_dwordx4 v[226:227], v[116:119], off
	v_lshl_add_u64 v[114:115], v[114:115], 1, s[0:1]
	v_or_b32_e32 v181, 17, v174
	v_cvt_pk_bf16_f32 v116, v120, s0
	global_store_short v[114:115], v116, off
	v_or_b32_e32 v116, v173, v181
	v_ashrrev_i32_e32 v117, 31, v116
	v_lshlrev_b64 v[114:115], 12, v[116:117]
	v_lshlrev_b32_e32 v116, 5, v116
	v_and_or_b32 v182, v116, s49, v172
	v_or_b32_e32 v116, v182, v160
	v_ashrrev_i32_e32 v117, 31, v116
	v_cvt_pk_bf16_f32 v118, v121, s0
	v_lshl_add_u64 v[116:117], v[116:117], 1, s[0:1]
	v_or_b32_e32 v183, 18, v174
	global_store_short v[116:117], v118, off offset:2
	v_or_b32_e32 v118, v173, v183
	v_ashrrev_i32_e32 v119, 31, v118
	v_lshlrev_b64 v[116:117], 12, v[118:119]
	v_lshlrev_b32_e32 v118, 5, v118
	s_nop 0
	v_and_or_b32 v184, v118, s49, v172
	v_or_b32_e32 v118, v184, v160
	v_lshl_add_u64 v[112:113], v[152:153], 0, v[112:113]
	v_ashrrev_i32_e32 v119, 31, v118
	global_store_dword v[112:113], v120, off
	v_cvt_pk_bf16_f32 v120, v122, s0
	v_lshl_add_u64 v[118:119], v[118:119], 1, s[0:1]
	v_or_b32_e32 v185, 19, v174
	v_lshl_add_u64 v[114:115], v[152:153], 0, v[114:115]
	global_store_short v[118:119], v120, off offset:4
	v_or_b32_e32 v120, v173, v185
	global_store_dword v[114:115], v121, off
	v_ashrrev_i32_e32 v121, 31, v120
	v_lshlrev_b64 v[118:119], 12, v[120:121]
	v_lshlrev_b32_e32 v120, 5, v120
	v_and_or_b32 v186, v120, s49, v172
	v_or_b32_e32 v120, v186, v160
	v_lshl_add_u64 v[116:117], v[152:153], 0, v[116:117]
	v_ashrrev_i32_e32 v121, 31, v120
	global_store_dword v[116:117], v122, off
	v_cvt_pk_bf16_f32 v122, v123, s0
	v_lshl_add_u64 v[120:121], v[120:121], 1, s[0:1]
	v_or_b32_e32 v187, 24, v174
	v_lshl_add_u64 v[118:119], v[152:153], 0, v[118:119]
	global_store_short v[120:121], v122, off offset:6
	v_or_b32_e32 v122, v173, v187
	s_nop 0
	global_store_dword v[118:119], v123, off
	v_ashrrev_i32_e32 v123, 31, v122
	v_lshlrev_b64 v[120:121], 12, v[122:123]
	v_lshlrev_b32_e32 v122, 5, v122
	v_lshl_add_u64 v[120:121], v[152:153], 0, v[120:121]
	global_store_dword v[120:121], v124, off
	v_cvt_pk_bf16_f32 v124, v124, s0
	s_nop 0
	s_nop 0
	s_nop 0
	v_and_or_b32 v192, v122, s49, v172
	v_or_b32_e32 v122, v192, v160
	v_ashrrev_i32_e32 v123, 31, v122
	v_or_b32_e32 v193, 25, v174
	v_lshl_add_u64 v[122:123], v[122:123], 1, s[0:1]
	v_or_b32_e32 v176, v173, v193
	global_store_short v[122:123], v124, off offset:8
	s_nop 0
	v_ashrrev_i32_e32 v177, 31, v176
	v_lshlrev_b32_e32 v124, 5, v176
	v_lshlrev_b64 v[122:123], 12, v[176:177]
	v_and_or_b32 v177, v124, s49, v172
	v_lshl_add_u64 v[122:123], v[152:153], 0, v[122:123]
	v_or_b32_e32 v124, v177, v160
	global_store_dword v[122:123], v125, off
	s_nop 0
	v_cvt_pk_bf16_f32 v176, v125, s0
	v_ashrrev_i32_e32 v125, 31, v124
	v_lshl_add_u64 v[124:125], v[124:125], 1, s[0:1]
	global_store_short v[124:125], v176, off offset:10
	s_nop 0
	s_nop 6
	global_store_dword v[154:155], v96, off offset:128
	s_nop 0
	v_or_b32_e32 v146, 26, v174
	v_or_b32_e32 v144, v173, v146
	v_ashrrev_i32_e32 v145, 31, v144
	v_lshlrev_b64 v[124:125], 12, v[144:145]
	v_lshl_add_u64 v[124:125], v[152:153], 0, v[124:125]
	v_or_b32_e32 v145, 27, v174
	global_store_dword v[124:125], v126, off
	s_nop 0
	v_lshlrev_b32_e32 v136, 5, v144
	v_and_or_b32 v144, v136, s49, v172
	v_or_b32_e32 v136, v144, v160
	v_ashrrev_i32_e32 v137, 31, v136
	v_cvt_pk_bf16_f32 v126, v126, s0
	v_lshl_add_u64 v[136:137], v[136:137], 1, s[0:1]
	v_or_b32_e32 v138, v173, v145
	s_nop 0
	global_store_short v[136:137], v126, off offset:12
	v_ashrrev_i32_e32 v139, 31, v138
	v_lshlrev_b32_e32 v126, 5, v138
	v_lshlrev_b64 v[136:137], 12, v[138:139]
	v_and_or_b32 v139, v126, s49, v172
	v_lshl_add_u64 v[136:137], v[152:153], 0, v[136:137]
	v_or_b32_e32 v126, v139, v160
	s_nop 0
	global_store_dword v[136:137], v127, off
	v_cvt_pk_bf16_f32 v138, v127, s0
	v_ashrrev_i32_e32 v127, 31, v126
	v_lshl_add_u64 v[126:127], v[126:127], 1, s[0:1]
	global_store_short v[126:127], v138, off offset:14
	v_or_b32_e32 v126, 0x2000, v175
	v_and_or_b32 v126, v126, s50, v197
	s_nop 0
	global_store_dword v[156:157], v97, off offset:128
	global_store_dword v[158:159], v98, off offset:128
	global_store_dword v[162:163], v99, off offset:128
	global_store_dword v[164:165], v100, off offset:128
	global_store_dword v[166:167], v101, off offset:128
	global_store_dword v[168:169], v102, off offset:128
	global_store_dword v[170:171], v103, off offset:128
	v_cvt_pk_bf16_f32 v103, v102, v103
	v_cvt_pk_bf16_f32 v102, v100, v101
	v_cvt_pk_bf16_f32 v100, v96, v97
	v_or_b32_e32 v96, v126, v180
	v_ashrrev_i32_e32 v97, 31, v96
	v_cvt_pk_bf16_f32 v101, v98, v99
	s_nop 0
	v_cvt_pk_bf16_f32 v98, v104, s0
	v_lshl_add_u64 v[96:97], v[96:97], 1, s[0:1]
	s_nop 0
	s_nop 0
	v_or_b32_e32 v128, v126, v229
	v_ashrrev_i32_e32 v129, 31, v128
	v_lshl_add_u64 v[128:129], v[128:129], 1, s[0:1]
; DI bfr f2bf(float a) { return (bfr)(pack2(a, 0.f) & 0xffffu); }
; DI void phase_gemm_in_even(const Params& p, char* smem) {
;     ...
;         gemm_tile<1024>(p.MPB, p.WtXv + (size_t)l * 1048576, 1024, 1024, mt * 128, nt * 256, smem,
;                   [=](int row, int col, float v) {
;                     o[(size_t)row * 1024 + col] = v;
;                     const int ml = row & 15;
;                     const int rowpart = (row >> 8) * 262144 + ((row & 255) >> 4) * 512 + ((ml >> 2) & 1) * 256 + (((ml >> 3) << 2) | (ml & 3));
;                     const int colpart = (col >> 8) * 65536 + ((col & 255) >> 5) * 8192 + (col & 31) * 8;
;                     vt[rowpart + colpart] = f2bf(v);
;                   });
	global_store_dwordx4 v[128:129], v[100:103], off
	global_store_dword v[112:113], v104, off offset:128
	global_store_short v[96:97], v98, off
	global_store_dword v[114:115], v105, off offset:128
	v_or_b32_e32 v96, v126, v182
	v_ashrrev_i32_e32 v97, 31, v96
	v_cvt_pk_bf16_f32 v98, v105, s0
	v_lshl_add_u64 v[96:97], v[96:97], 1, s[0:1]
	global_store_short v[96:97], v98, off offset:2
	global_store_dword v[116:117], v106, off offset:128
	v_or_b32_e32 v96, v126, v184
	v_ashrrev_i32_e32 v97, 31, v96
	v_cvt_pk_bf16_f32 v98, v106, s0
	v_lshl_add_u64 v[96:97], v[96:97], 1, s[0:1]
	global_store_short v[96:97], v98, off offset:4
	global_store_dword v[118:119], v107, off offset:128
	v_or_b32_e32 v96, v126, v186
	v_ashrrev_i32_e32 v97, 31, v96
	v_cvt_pk_bf16_f32 v98, v107, s0
	v_lshl_add_u64 v[96:97], v[96:97], 1, s[0:1]
	global_store_short v[96:97], v98, off offset:6
	global_store_dword v[120:121], v108, off offset:128
	v_or_b32_e32 v96, v126, v192
	v_ashrrev_i32_e32 v97, 31, v96
	v_cvt_pk_bf16_f32 v98, v108, s0
	v_lshl_add_u64 v[96:97], v[96:97], 1, s[0:1]
	global_store_short v[96:97], v98, off offset:8
	global_store_dword v[122:123], v109, off offset:128
	v_or_b32_e32 v96, v126, v177
	v_ashrrev_i32_e32 v97, 31, v96
	v_cvt_pk_bf16_f32 v98, v109, s0
	v_lshl_add_u64 v[96:97], v[96:97], 1, s[0:1]
	global_store_short v[96:97], v98, off offset:10
	global_store_dword v[124:125], v110, off offset:128
	v_or_b32_e32 v96, v126, v144
	v_ashrrev_i32_e32 v97, 31, v96
	v_cvt_pk_bf16_f32 v98, v110, s0
	v_lshl_add_u64 v[96:97], v[96:97], 1, s[0:1]
	global_store_short v[96:97], v98, off offset:12
	global_store_dword v[136:137], v111, off offset:128
	v_or_b32_e32 v96, v126, v139
	v_ashrrev_i32_e32 v97, 31, v96
	v_cvt_pk_bf16_f32 v98, v111, s0
	v_lshl_add_u64 v[96:97], v[96:97], 1, s[0:1]
	global_store_short v[96:97], v98, off offset:14
	v_or_b32_e32 v96, 0x4000, v175
	v_and_or_b32 v96, v96, s51, v197
	global_store_dword v[154:155], v80, off offset:256
	v_or_b32_e32 v98, v96, v229
	global_store_dword v[156:157], v81, off offset:256
	global_store_dword v[158:159], v82, off offset:256
	global_store_dword v[162:163], v83, off offset:256
	global_store_dword v[164:165], v84, off offset:256
	global_store_dword v[166:167], v85, off offset:256
	global_store_dword v[168:169], v86, off offset:256
	global_store_dword v[170:171], v87, off offset:256
	v_cvt_pk_bf16_f32 v87, v86, v87
	v_cvt_pk_bf16_f32 v86, v84, v85
	v_cvt_pk_bf16_f32 v84, v80, v81
	v_or_b32_e32 v80, v96, v180
	v_ashrrev_i32_e32 v99, 31, v98
	v_ashrrev_i32_e32 v81, 31, v80
	v_lshl_add_u64 v[98:99], v[98:99], 1, s[0:1]
	v_cvt_pk_bf16_f32 v85, v82, v83
	v_cvt_pk_bf16_f32 v82, v88, s0
	v_lshl_add_u64 v[80:81], v[80:81], 1, s[0:1]
	global_store_dwordx4 v[98:99], v[84:87], off
	global_store_dword v[112:113], v88, off offset:256
	global_store_short v[80:81], v82, off
	global_store_dword v[114:115], v89, off offset:256
	v_or_b32_e32 v80, v96, v182
	v_ashrrev_i32_e32 v81, 31, v80
	v_cvt_pk_bf16_f32 v82, v89, s0
	v_lshl_add_u64 v[80:81], v[80:81], 1, s[0:1]
	global_store_short v[80:81], v82, off offset:2
	global_store_dword v[116:117], v90, off offset:256
	v_or_b32_e32 v80, v96, v184
	v_ashrrev_i32_e32 v81, 31, v80
	v_cvt_pk_bf16_f32 v82, v90, s0
	v_lshl_add_u64 v[80:81], v[80:81], 1, s[0:1]
	global_store_short v[80:81], v82, off offset:4
	global_store_dword v[118:119], v91, off offset:256
	v_or_b32_e32 v80, v96, v186
	v_ashrrev_i32_e32 v81, 31, v80
	v_cvt_pk_bf16_f32 v82, v91, s0
	v_lshl_add_u64 v[80:81], v[80:81], 1, s[0:1]
	global_store_short v[80:81], v82, off offset:6
	global_store_dword v[120:121], v92, off offset:256
	v_or_b32_e32 v80, v96, v192
	v_ashrrev_i32_e32 v81, 31, v80
	v_cvt_pk_bf16_f32 v82, v92, s0
	v_lshl_add_u64 v[80:81], v[80:81], 1, s[0:1]
	global_store_short v[80:81], v82, off offset:8
	global_store_dword v[122:123], v93, off offset:256
	v_or_b32_e32 v80, v96, v177
	v_ashrrev_i32_e32 v81, 31, v80
	v_cvt_pk_bf16_f32 v82, v93, s0
	v_lshl_add_u64 v[80:81], v[80:81], 1, s[0:1]
	global_store_short v[80:81], v82, off offset:10
	global_store_dword v[124:125], v94, off offset:256
	v_or_b32_e32 v80, v96, v144
	v_ashrrev_i32_e32 v81, 31, v80
	v_cvt_pk_bf16_f32 v82, v94, s0
	v_lshl_add_u64 v[80:81], v[80:81], 1, s[0:1]
	global_store_short v[80:81], v82, off offset:12
	global_store_dword v[136:137], v95, off offset:256
	v_or_b32_e32 v80, v96, v139
	v_ashrrev_i32_e32 v81, 31, v80
	v_cvt_pk_bf16_f32 v82, v95, s0
	v_lshl_add_u64 v[80:81], v[80:81], 1, s[0:1]
	global_store_short v[80:81], v82, off offset:14
	v_or_b32_e32 v80, 0x6000, v175
	v_and_or_b32 v82, v80, s52, v197
	global_store_dword v[154:155], v64, off offset:384
	v_or_b32_e32 v80, v82, v229
	global_store_dword v[156:157], v65, off offset:384
	global_store_dword v[158:159], v66, off offset:384
	global_store_dword v[162:163], v67, off offset:384
	global_store_dword v[164:165], v68, off offset:384
	global_store_dword v[166:167], v69, off offset:384
	global_store_dword v[168:169], v70, off offset:384
	global_store_dword v[170:171], v71, off offset:384
	v_cvt_pk_bf16_f32 v71, v70, v71
	v_cvt_pk_bf16_f32 v70, v68, v69
	v_cvt_pk_bf16_f32 v68, v64, v65
	v_or_b32_e32 v64, v82, v180
	v_ashrrev_i32_e32 v81, 31, v80
	v_ashrrev_i32_e32 v65, 31, v64
	v_lshl_add_u64 v[80:81], v[80:81], 1, s[0:1]
	v_cvt_pk_bf16_f32 v69, v66, v67
	v_cvt_pk_bf16_f32 v66, v72, s0
	v_lshl_add_u64 v[64:65], v[64:65], 1, s[0:1]
	global_store_dwordx4 v[80:81], v[68:71], off
	global_store_dword v[112:113], v72, off offset:384
	global_store_short v[64:65], v66, off
	global_store_dword v[114:115], v73, off offset:384
	v_or_b32_e32 v64, v82, v182
	v_ashrrev_i32_e32 v65, 31, v64
	v_cvt_pk_bf16_f32 v66, v73, s0
; DI bfr f2bf(float a) { return (bfr)(pack2(a, 0.f) & 0xffffu); }
; DI void phase_gemm_in_even(const Params& p, char* smem) {
;     ...
;         gemm_tile<1024>(p.MPB, p.WtXv + (size_t)l * 1048576, 1024, 1024, mt * 128, nt * 256, smem,
;                   [=](int row, int col, float v) {
;                     o[(size_t)row * 1024 + col] = v;
;                     const int ml = row & 15;
;                     const int rowpart = (row >> 8) * 262144 + ((row & 255) >> 4) * 512 + ((ml >> 2) & 1) * 256 + (((ml >> 3) << 2) | (ml & 3));
;                     const int colpart = (col >> 8) * 65536 + ((col & 255) >> 5) * 8192 + (col & 31) * 8;
;                     vt[rowpart + colpart] = f2bf(v);
;                   });
	v_lshl_add_u64 v[64:65], v[64:65], 1, s[0:1]
	global_store_short v[64:65], v66, off offset:2
	global_store_dword v[116:117], v74, off offset:384
	v_or_b32_e32 v64, v82, v184
	v_ashrrev_i32_e32 v65, 31, v64
	v_cvt_pk_bf16_f32 v66, v74, s0
	v_lshl_add_u64 v[64:65], v[64:65], 1, s[0:1]
	global_store_short v[64:65], v66, off offset:4
	global_store_dword v[118:119], v75, off offset:384
	v_or_b32_e32 v64, v82, v186
	v_ashrrev_i32_e32 v65, 31, v64
	v_cvt_pk_bf16_f32 v66, v75, s0
	v_lshl_add_u64 v[64:65], v[64:65], 1, s[0:1]
	global_store_short v[64:65], v66, off offset:6
	global_store_dword v[120:121], v76, off offset:384
	v_or_b32_e32 v64, v82, v192
	v_ashrrev_i32_e32 v65, 31, v64
	v_cvt_pk_bf16_f32 v66, v76, s0
	v_lshl_add_u64 v[64:65], v[64:65], 1, s[0:1]
	global_store_short v[64:65], v66, off offset:8
	global_store_dword v[122:123], v77, off offset:384
	v_or_b32_e32 v64, v82, v177
	v_ashrrev_i32_e32 v65, 31, v64
	v_cvt_pk_bf16_f32 v66, v77, s0
	v_lshl_add_u64 v[64:65], v[64:65], 1, s[0:1]
	global_store_short v[64:65], v66, off offset:10
	global_store_dword v[124:125], v78, off offset:384
	v_or_b32_e32 v64, v82, v144
	v_ashrrev_i32_e32 v65, 31, v64
	v_cvt_pk_bf16_f32 v66, v78, s0
	v_lshl_add_u64 v[64:65], v[64:65], 1, s[0:1]
	global_store_short v[64:65], v66, off offset:12
	global_store_dword v[136:137], v79, off offset:384
	v_or_b32_e32 v64, v82, v139
	v_ashrrev_i32_e32 v65, 31, v64
	v_cvt_pk_bf16_f32 v66, v79, s0
	v_lshl_add_u64 v[64:65], v[64:65], 1, s[0:1]
	v_or_b32_e32 v83, 32, v173
	global_store_short v[64:65], v66, off offset:14
	v_lshlrev_b32_e32 v66, 5, v83
	v_and_or_b32 v86, v66, s53, v172
	v_or_b32_e32 v66, v86, v160
	v_or_b32_e32 v68, v83, v188
	v_or_b32_e32 v74, v83, v191
	v_or_b32_e32 v76, v83, v231
	v_or_b32_e32 v78, v83, v178
	v_ashrrev_i32_e32 v67, 31, v66
	v_ashrrev_i32_e32 v69, 31, v68
	v_or_b32_e32 v70, v83, v189
	v_ashrrev_i32_e32 v75, 31, v74
	v_ashrrev_i32_e32 v77, 31, v76
	v_ashrrev_i32_e32 v79, 31, v78
	v_or_b32_e32 v64, v83, v174
	v_lshl_add_u64 v[80:81], v[66:67], 1, s[0:1]
	v_or_b32_e32 v66, v83, v230
	v_lshlrev_b64 v[68:69], 12, v[68:69]
	v_ashrrev_i32_e32 v71, 31, v70
	v_or_b32_e32 v72, v83, v190
	v_lshlrev_b64 v[74:75], 12, v[74:75]
	v_lshlrev_b64 v[76:77], 12, v[76:77]
	v_lshlrev_b64 v[78:79], 12, v[78:79]
	v_ashrrev_i32_e32 v65, 31, v64
	v_ashrrev_i32_e32 v67, 31, v66
	v_lshl_add_u64 v[68:69], v[152:153], 0, v[68:69]
	v_lshlrev_b64 v[70:71], 12, v[70:71]
	v_ashrrev_i32_e32 v73, 31, v72
	v_lshl_add_u64 v[74:75], v[152:153], 0, v[74:75]
	v_lshl_add_u64 v[76:77], v[152:153], 0, v[76:77]
	v_lshl_add_u64 v[78:79], v[152:153], 0, v[78:79]
	v_lshlrev_b64 v[64:65], 12, v[64:65]
	v_lshlrev_b64 v[66:67], 12, v[66:67]
	global_store_dword v[68:69], v50, off
	v_lshl_add_u64 v[70:71], v[152:153], 0, v[70:71]
	v_lshlrev_b64 v[72:73], 12, v[72:73]
	global_store_dword v[74:75], v53, off
	global_store_dword v[76:77], v54, off
	global_store_dword v[78:79], v55, off
	v_cvt_pk_bf16_f32 v55, v54, v55
	v_cvt_pk_bf16_f32 v54, v52, v53
	v_cvt_pk_bf16_f32 v53, v50, v51
	v_or_b32_e32 v50, v83, v179
	v_lshl_add_u64 v[64:65], v[152:153], 0, v[64:65]
	v_lshl_add_u64 v[66:67], v[152:153], 0, v[66:67]
	global_store_dword v[70:71], v51, off
	v_lshl_add_u64 v[72:73], v[152:153], 0, v[72:73]
	v_ashrrev_i32_e32 v51, 31, v50
	global_store_dword v[64:65], v48, off
	global_store_dword v[66:67], v49, off
	global_store_dword v[72:73], v52, off
	v_cvt_pk_bf16_f32 v52, v48, v49
	v_lshlrev_b64 v[48:49], 12, v[50:51]
	v_lshlrev_b32_e32 v50, 5, v50
	v_and_or_b32 v87, v50, s54, v172
	v_or_b32_e32 v50, v87, v160
	v_ashrrev_i32_e32 v51, 31, v50
	global_store_dwordx4 v[80:81], v[52:55], off
	v_lshl_add_u64 v[50:51], v[50:51], 1, s[0:1]
	v_lshl_add_u64 v[48:49], v[152:153], 0, v[48:49]
	v_cvt_pk_bf16_f32 v52, v56, s0
	global_store_short v[50:51], v52, off
	v_or_b32_e32 v52, v83, v181
	v_ashrrev_i32_e32 v53, 31, v52
	v_lshlrev_b64 v[50:51], 12, v[52:53]
	v_lshlrev_b32_e32 v52, 5, v52
	v_and_or_b32 v88, v52, s54, v172
	v_or_b32_e32 v52, v88, v160
	v_ashrrev_i32_e32 v53, 31, v52
	v_cvt_pk_bf16_f32 v54, v57, s0
	v_lshl_add_u64 v[52:53], v[52:53], 1, s[0:1]
	global_store_short v[52:53], v54, off offset:2
	v_or_b32_e32 v54, v83, v183
	v_ashrrev_i32_e32 v55, 31, v54
	v_lshlrev_b64 v[52:53], 12, v[54:55]
	v_lshlrev_b32_e32 v54, 5, v54
	v_and_or_b32 v89, v54, s54, v172
	v_or_b32_e32 v54, v89, v160
	v_ashrrev_i32_e32 v55, 31, v54
	global_store_dword v[48:49], v56, off
	v_cvt_pk_bf16_f32 v56, v58, s0
	v_lshl_add_u64 v[54:55], v[54:55], 1, s[0:1]
	v_lshl_add_u64 v[50:51], v[152:153], 0, v[50:51]
	global_store_short v[54:55], v56, off offset:4
	v_or_b32_e32 v56, v83, v185
	global_store_dword v[50:51], v57, off
	v_ashrrev_i32_e32 v57, 31, v56
	v_lshlrev_b64 v[54:55], 12, v[56:57]
	v_lshlrev_b32_e32 v56, 5, v56
	v_and_or_b32 v90, v56, s54, v172
	v_or_b32_e32 v56, v90, v160
	v_lshl_add_u64 v[52:53], v[152:153], 0, v[52:53]
	v_ashrrev_i32_e32 v57, 31, v56
	global_store_dword v[52:53], v58, off
	v_cvt_pk_bf16_f32 v58, v59, s0
	v_lshl_add_u64 v[56:57], v[56:57], 1, s[0:1]
	v_lshl_add_u64 v[54:55], v[152:153], 0, v[54:55]
	global_store_short v[56:57], v58, off offset:6
	v_or_b32_e32 v58, v83, v187
	global_store_dword v[54:55], v59, off
	v_ashrrev_i32_e32 v59, 31, v58
	v_lshlrev_b64 v[56:57], 12, v[58:59]
	v_lshlrev_b32_e32 v58, 5, v58
	v_and_or_b32 v91, v58, s54, v172
	v_or_b32_e32 v58, v91, v160
	v_lshl_add_u64 v[56:57], v[152:153], 0, v[56:57]
	v_ashrrev_i32_e32 v59, 31, v58
	global_store_dword v[56:57], v60, off
	v_cvt_pk_bf16_f32 v60, v60, s0
	v_lshl_add_u64 v[58:59], v[58:59], 1, s[0:1]
	v_or_b32_e32 v80, v83, v193
	global_store_short v[58:59], v60, off offset:8
; DI bfr f2bf(float a) { return (bfr)(pack2(a, 0.f) & 0xffffu); }
; DI void phase_gemm_in_even(const Params& p, char* smem) {
;     ...
;         gemm_tile<1024>(p.MPB, p.WtXv + (size_t)l * 1048576, 1024, 1024, mt * 128, nt * 256, smem,
;                   [=](int row, int col, float v) {
;                     o[(size_t)row * 1024 + col] = v;
;                     const int ml = row & 15;
;                     const int rowpart = (row >> 8) * 262144 + ((row & 255) >> 4) * 512 + ((ml >> 2) & 1) * 256 + (((ml >> 3) << 2) | (ml & 3));
;                     const int colpart = (col >> 8) * 65536 + ((col & 255) >> 5) * 8192 + (col & 31) * 8;
;                     vt[rowpart + colpart] = f2bf(v);
;                   });
	v_ashrrev_i32_e32 v81, 31, v80
	v_lshlrev_b32_e32 v60, 5, v80
	v_lshlrev_b64 v[58:59], 12, v[80:81]
	v_and_or_b32 v92, v60, s54, v172
	v_lshl_add_u64 v[58:59], v[152:153], 0, v[58:59]
	v_or_b32_e32 v60, v92, v160
	global_store_dword v[58:59], v61, off
	v_cvt_pk_bf16_f32 v80, v61, s0
	v_ashrrev_i32_e32 v61, 31, v60
	v_lshl_add_u64 v[60:61], v[60:61], 1, s[0:1]
	global_store_short v[60:61], v80, off offset:10
	v_or_b32_e32 v80, v83, v146
	v_ashrrev_i32_e32 v81, 31, v80
	v_lshlrev_b64 v[60:61], 12, v[80:81]
	v_lshlrev_b32_e32 v80, 5, v80
	v_and_or_b32 v93, v80, s54, v172
	v_or_b32_e32 v80, v93, v160
	v_lshl_add_u64 v[60:61], v[152:153], 0, v[60:61]
	v_ashrrev_i32_e32 v81, 31, v80
	global_store_dword v[60:61], v62, off
	v_cvt_pk_bf16_f32 v62, v62, s0
	v_lshl_add_u64 v[80:81], v[80:81], 1, s[0:1]
	v_or_b32_e32 v84, v83, v145
	global_store_short v[80:81], v62, off offset:12
	v_ashrrev_i32_e32 v85, 31, v84
	v_lshlrev_b32_e32 v62, 5, v84
	v_lshlrev_b64 v[80:81], 12, v[84:85]
	v_and_or_b32 v84, v62, s54, v172
	v_lshl_add_u64 v[80:81], v[152:153], 0, v[80:81]
	v_or_b32_e32 v62, v84, v160
	global_store_dword v[80:81], v63, off
	v_cvt_pk_bf16_f32 v83, v63, s0
	v_ashrrev_i32_e32 v63, 31, v62
	v_lshl_add_u64 v[62:63], v[62:63], 1, s[0:1]
	global_store_short v[62:63], v83, off offset:14
	global_store_dword v[64:65], v32, off offset:128
	v_or_b32_e32 v62, v126, v86
	global_store_dword v[66:67], v33, off offset:128
	global_store_dword v[68:69], v34, off offset:128
	global_store_dword v[70:71], v35, off offset:128
	global_store_dword v[72:73], v36, off offset:128
	global_store_dword v[74:75], v37, off offset:128
	global_store_dword v[76:77], v38, off offset:128
	global_store_dword v[78:79], v39, off offset:128
	v_cvt_pk_bf16_f32 v39, v38, v39
	v_cvt_pk_bf16_f32 v38, v36, v37
	v_cvt_pk_bf16_f32 v36, v32, v33
	v_or_b32_e32 v32, v87, v126
	v_ashrrev_i32_e32 v63, 31, v62
	v_ashrrev_i32_e32 v33, 31, v32
	v_lshl_add_u64 v[62:63], v[62:63], 1, s[0:1]
	v_cvt_pk_bf16_f32 v37, v34, v35
	v_cvt_pk_bf16_f32 v34, v40, s0
	v_lshl_add_u64 v[32:33], v[32:33], 1, s[0:1]
	global_store_dwordx4 v[62:63], v[36:39], off
	global_store_dword v[48:49], v40, off offset:128
	global_store_short v[32:33], v34, off
	global_store_dword v[50:51], v41, off offset:128
	v_or_b32_e32 v32, v88, v126
	v_ashrrev_i32_e32 v33, 31, v32
	v_cvt_pk_bf16_f32 v34, v41, s0
	v_lshl_add_u64 v[32:33], v[32:33], 1, s[0:1]
	global_store_short v[32:33], v34, off offset:2
	global_store_dword v[52:53], v42, off offset:128
	v_or_b32_e32 v32, v89, v126
	v_ashrrev_i32_e32 v33, 31, v32
	v_cvt_pk_bf16_f32 v34, v42, s0
	v_lshl_add_u64 v[32:33], v[32:33], 1, s[0:1]
	global_store_short v[32:33], v34, off offset:4
	global_store_dword v[54:55], v43, off offset:128
	v_or_b32_e32 v32, v90, v126
	v_ashrrev_i32_e32 v33, 31, v32
	v_cvt_pk_bf16_f32 v34, v43, s0
	v_lshl_add_u64 v[32:33], v[32:33], 1, s[0:1]
	global_store_short v[32:33], v34, off offset:6
	global_store_dword v[56:57], v44, off offset:128
	v_or_b32_e32 v32, v91, v126
	v_ashrrev_i32_e32 v33, 31, v32
	v_cvt_pk_bf16_f32 v34, v44, s0
	v_lshl_add_u64 v[32:33], v[32:33], 1, s[0:1]
	global_store_short v[32:33], v34, off offset:8
	global_store_dword v[58:59], v45, off offset:128
	v_or_b32_e32 v32, v92, v126
	v_ashrrev_i32_e32 v33, 31, v32
	v_cvt_pk_bf16_f32 v34, v45, s0
	v_lshl_add_u64 v[32:33], v[32:33], 1, s[0:1]
	global_store_short v[32:33], v34, off offset:10
	global_store_dword v[60:61], v46, off offset:128
	v_or_b32_e32 v32, v93, v126
	v_ashrrev_i32_e32 v33, 31, v32
	v_cvt_pk_bf16_f32 v34, v46, s0
	v_lshl_add_u64 v[32:33], v[32:33], 1, s[0:1]
	global_store_short v[32:33], v34, off offset:12
	global_store_dword v[80:81], v47, off offset:128
	v_or_b32_e32 v32, v84, v126
	v_ashrrev_i32_e32 v33, 31, v32
	v_cvt_pk_bf16_f32 v34, v47, s0
	v_lshl_add_u64 v[32:33], v[32:33], 1, s[0:1]
	global_store_short v[32:33], v34, off offset:14
	global_store_dword v[64:65], v16, off offset:256
	v_or_b32_e32 v32, v96, v86
	global_store_dword v[66:67], v17, off offset:256
	global_store_dword v[68:69], v18, off offset:256
	global_store_dword v[70:71], v19, off offset:256
	global_store_dword v[72:73], v20, off offset:256
	global_store_dword v[74:75], v21, off offset:256
	global_store_dword v[76:77], v22, off offset:256
	global_store_dword v[78:79], v23, off offset:256
	v_cvt_pk_bf16_f32 v23, v22, v23
	v_cvt_pk_bf16_f32 v22, v20, v21
	v_cvt_pk_bf16_f32 v20, v16, v17
	v_or_b32_e32 v16, v87, v96
	v_ashrrev_i32_e32 v33, 31, v32
	v_ashrrev_i32_e32 v17, 31, v16
	v_lshl_add_u64 v[32:33], v[32:33], 1, s[0:1]
	v_cvt_pk_bf16_f32 v21, v18, v19
	v_cvt_pk_bf16_f32 v18, v24, s0
	v_lshl_add_u64 v[16:17], v[16:17], 1, s[0:1]
	global_store_dwordx4 v[32:33], v[20:23], off
	global_store_dword v[48:49], v24, off offset:256
	global_store_short v[16:17], v18, off
	global_store_dword v[50:51], v25, off offset:256
	v_or_b32_e32 v16, v88, v96
	v_ashrrev_i32_e32 v17, 31, v16
	v_cvt_pk_bf16_f32 v18, v25, s0
	v_lshl_add_u64 v[16:17], v[16:17], 1, s[0:1]
	global_store_short v[16:17], v18, off offset:2
	global_store_dword v[52:53], v26, off offset:256
	v_or_b32_e32 v16, v89, v96
	v_ashrrev_i32_e32 v17, 31, v16
	v_cvt_pk_bf16_f32 v18, v26, s0
	v_lshl_add_u64 v[16:17], v[16:17], 1, s[0:1]
	global_store_short v[16:17], v18, off offset:4
	global_store_dword v[54:55], v27, off offset:256
	v_or_b32_e32 v16, v90, v96
	v_ashrrev_i32_e32 v17, 31, v16
	v_cvt_pk_bf16_f32 v18, v27, s0
	v_lshl_add_u64 v[16:17], v[16:17], 1, s[0:1]
	global_store_short v[16:17], v18, off offset:6
	global_store_dword v[56:57], v28, off offset:256
	v_or_b32_e32 v16, v91, v96
	v_ashrrev_i32_e32 v17, 31, v16
	v_cvt_pk_bf16_f32 v18, v28, s0
; DI bfr f2bf(float a) { return (bfr)(pack2(a, 0.f) & 0xffffu); }
; #define GA_LOAD(pr_) do { _Pragma("unroll") for (int i = 0; i < 4; ++i) ra[i] = *(const u32x4*)(Ab + (i * 32) * lda + (pr_) * 64); } while (0)
; #define GB_LOAD(kt_) do { const bfr* bk_ = Bb + (kt_) * NB * 32; \
;     _Pragma("unroll") for (int i = 0; i < 4; ++i) rb[i] = *(const u32x4*)(bk_ + (i * 64) * 32); } while (0)
; #define G_STORE(kt_) do { bfr* as_ = S0 + ((kt_) & 1) * GSTAGE; bfr* bs_ = as_ + 128 * 40; \
;     if (apar == ((kt_) & 1)) { _Pragma("unroll") for (int i = 0; i < 4; ++i) *(u32x4*)(as_ + asoff + i * 32 * 40) = ra[i]; } \
;     _Pragma("unroll") for (int i = 0; i < 4; ++i) *(u32x4*)(bs_ + bsoff + i * 64 * 40) = rb[i]; } while (0)
; template <int lda>
; DI void gemm_mainloop(const bfr* __restrict__ A, const bfr* __restrict__ Bt, int NB, int K, int m0, int n0, char* smem, f32x16 (&acc)[2][4]) {
;     ...
;   u32x4 ra[4], rb[4];
;   const int nk = K >> 5;
;   const int arow = tid >> 3, ac8 = tid & 7, apar = ac8 >> 2;
;   const bfr* Ab = A + (m0 + arow) * lda + ac8 * 8;
;   const int asoff = arow * 40 + (ac8 & 3) * 8;
;   const int brow = tid >> 2, bc4 = tid & 3;
;   const bfr* Bb = Bt + (n0 + brow) * 32 + bc4 * 8;
;   const int bsoff = brow * 40 + bc4 * 8;
;     ...
;   GA_LOAD(0);
;   GB_LOAD(0);
;   G_STORE(0);
;   GB_LOAD(1);
;   __syncthreads();
; DI void phase_gemm_in_even(const Params& p, char* smem) {
;     ...
;         gemm_tile<1024>(p.MPB, p.WtXv + (size_t)l * 1048576, 1024, 1024, mt * 128, nt * 256, smem,
;                   [=](int row, int col, float v) {
;                     o[(size_t)row * 1024 + col] = v;
;                     const int ml = row & 15;
;                     const int rowpart = (row >> 8) * 262144 + ((row & 255) >> 4) * 512 + ((ml >> 2) & 1) * 256 + (((ml >> 3) << 2) | (ml & 3));
;                     const int colpart = (col >> 8) * 65536 + ((col & 255) >> 5) * 8192 + (col & 31) * 8;
;                     vt[rowpart + colpart] = f2bf(v);
;                   });
	v_lshl_add_u64 v[16:17], v[16:17], 1, s[0:1]
	global_store_short v[16:17], v18, off offset:8
	global_store_dword v[58:59], v29, off offset:256
	v_or_b32_e32 v16, v92, v96
	v_ashrrev_i32_e32 v17, 31, v16
	v_cvt_pk_bf16_f32 v18, v29, s0
	v_lshl_add_u64 v[16:17], v[16:17], 1, s[0:1]
	global_store_short v[16:17], v18, off offset:10
	global_store_dword v[60:61], v30, off offset:256
	v_or_b32_e32 v16, v93, v96
	v_ashrrev_i32_e32 v17, 31, v16
	v_cvt_pk_bf16_f32 v18, v30, s0
	v_lshl_add_u64 v[16:17], v[16:17], 1, s[0:1]
	global_store_short v[16:17], v18, off offset:12
	global_store_dword v[80:81], v31, off offset:256
	v_or_b32_e32 v16, v84, v96
	v_ashrrev_i32_e32 v17, 31, v16
	v_cvt_pk_bf16_f32 v18, v31, s0
	v_lshl_add_u64 v[16:17], v[16:17], 1, s[0:1]
	global_store_short v[16:17], v18, off offset:14
	global_store_dword v[64:65], v0, off offset:384
	v_or_b32_e32 v16, v82, v86
	global_store_dword v[66:67], v1, off offset:384
	global_store_dword v[68:69], v2, off offset:384
	global_store_dword v[70:71], v3, off offset:384
	global_store_dword v[72:73], v4, off offset:384
	global_store_dword v[74:75], v5, off offset:384
	global_store_dword v[76:77], v6, off offset:384
	global_store_dword v[78:79], v7, off offset:384
	v_cvt_pk_bf16_f32 v7, v6, v7
	v_cvt_pk_bf16_f32 v6, v4, v5
	v_cvt_pk_bf16_f32 v4, v0, v1
	v_or_b32_e32 v0, v87, v82
	v_ashrrev_i32_e32 v17, 31, v16
	v_ashrrev_i32_e32 v1, 31, v0
	v_lshl_add_u64 v[16:17], v[16:17], 1, s[0:1]
	v_cvt_pk_bf16_f32 v5, v2, v3
	v_cvt_pk_bf16_f32 v2, v8, s0
	v_lshl_add_u64 v[0:1], v[0:1], 1, s[0:1]
	global_store_dwordx4 v[16:17], v[4:7], off
	global_store_dword v[48:49], v8, off offset:384
	global_store_short v[0:1], v2, off
	global_store_dword v[50:51], v9, off offset:384
	v_or_b32_e32 v0, v88, v82
	v_ashrrev_i32_e32 v1, 31, v0
	v_cvt_pk_bf16_f32 v2, v9, s0
	v_lshl_add_u64 v[0:1], v[0:1], 1, s[0:1]
	global_store_short v[0:1], v2, off offset:2
	global_store_dword v[52:53], v10, off offset:384
	v_or_b32_e32 v0, v89, v82
	v_ashrrev_i32_e32 v1, 31, v0
	v_cvt_pk_bf16_f32 v2, v10, s0
	v_lshl_add_u64 v[0:1], v[0:1], 1, s[0:1]
	global_store_short v[0:1], v2, off offset:4
	global_store_dword v[54:55], v11, off offset:384
	v_or_b32_e32 v0, v90, v82
	v_ashrrev_i32_e32 v1, 31, v0
	v_cvt_pk_bf16_f32 v2, v11, s0
	v_lshl_add_u64 v[0:1], v[0:1], 1, s[0:1]
	global_store_short v[0:1], v2, off offset:6
	global_store_dword v[56:57], v12, off offset:384
	v_or_b32_e32 v0, v91, v82
	v_ashrrev_i32_e32 v1, 31, v0
	v_cvt_pk_bf16_f32 v2, v12, s0
	v_lshl_add_u64 v[0:1], v[0:1], 1, s[0:1]
	global_store_short v[0:1], v2, off offset:8
	global_store_dword v[58:59], v13, off offset:384
	v_or_b32_e32 v0, v92, v82
	v_ashrrev_i32_e32 v1, 31, v0
	v_cvt_pk_bf16_f32 v2, v13, s0
	v_lshl_add_u64 v[0:1], v[0:1], 1, s[0:1]
	global_store_short v[0:1], v2, off offset:10
	global_store_dword v[60:61], v14, off offset:384
	v_or_b32_e32 v0, v93, v82
	v_ashrrev_i32_e32 v1, 31, v0
	v_cvt_pk_bf16_f32 v2, v14, s0
	v_lshl_add_u64 v[0:1], v[0:1], 1, s[0:1]
	global_store_short v[0:1], v2, off offset:12
	global_store_dword v[80:81], v15, off offset:384
	v_or_b32_e32 v0, v84, v82
	v_ashrrev_i32_e32 v1, 31, v0
	v_cvt_pk_bf16_f32 v2, v15, s0
	v_lshl_add_u64 v[0:1], v[0:1], 1, s[0:1]
	global_store_short v[0:1], v2, off offset:14
	s_mov_b64 s[0:1], 0
.LBB0_136:
	s_and_b64 vcc, exec, s[0:1]
	s_cbranch_vccz .LBB0_146
	s_add_u32 s0, s12, s2
	s_addc_u32 s1, s13, 0
	s_mov_b32 s59, 0
	s_mov_b64 s[30:31], 0
	s_lshl_b32 s98, s58, 11
	s_add_u32 s98, s8, s98
	s_addc_u32 s99, s9, 0
	s_lshl_b32 s100, s57, 6
	s_add_u32 s100, s0, s100
	s_addc_u32 s101, s1, 0
	v_writelane_b32 v188, s64, 0
	v_writelane_b32 v188, s65, 1
	v_writelane_b32 v188, s66, 2
	v_writelane_b32 v188, s67, 3
	v_writelane_b32 v188, s68, 4
	v_writelane_b32 v188, s69, 5
	v_writelane_b32 v188, s70, 6
	v_writelane_b32 v188, s71, 7
	v_writelane_b32 v188, s72, 8
	v_writelane_b32 v188, s73, 9
	v_writelane_b32 v188, s74, 10
	v_writelane_b32 v188, s75, 11
	v_writelane_b32 v188, s76, 12
	v_writelane_b32 v188, s77, 13
	v_writelane_b32 v188, s78, 14
	v_writelane_b32 v188, s79, 15
	v_lshrrev_b32_e32 v189, 6, v196
	v_and_b32_e32 v190, 63, v196
	v_readfirstlane_b32 s73, v189
	v_lshrrev_b32_e32 v191, 2, v190
	v_bfe_u32 v192, v190, 4, 2
	v_and_b32_e32 v189, 3, v190
	v_xor_b32_e32 v189, v189, v192
	v_lshlrev_b32_e32 v189, 4, v189
	v_lshl_add_u32 v160, v191, 11, v189
	v_add_u32_e32 v162, 0x8000, v160
	v_lshl_add_u32 v163, v191, 6, v189
	v_and_b32_e32 v191, 31, v190
	v_lshrrev_b32_e32 v192, 5, v190
	v_bfe_u32 v189, v190, 2, 2
	v_xor_b32_e32 v189, v189, v192
	v_lshlrev_b32_e32 v189, 4, v189
	v_lshl_add_u32 v180, v191, 6, v189
	s_lshr_b32 s74, s73, 1
	s_lshl_b32 s74, s74, 12
	s_and_b32 s75, s73, 1
	s_lshl_b32 s75, s75, 13
	v_add_u32_e32 v182, s75, v180
	v_add_u32_e32 v180, s74, v180
	v_xor_b32_e32 v183, 32, v182
	v_xor_b32_e32 v181, 32, v180
	s_lshl_b32 s74, s73, 16
	s_add_u32 s64, s98, s74
	s_addc_u32 s65, s99, 0
	s_lshl_b32 s74, s73, 12
	s_add_u32 s66, s100, s74
	s_addc_u32 s67, s101, 0
	s_lshl_b32 s68, s73, 11
	s_lshl_b32 s69, s73, 12
	s_mov_b32 s70, 0
	s_mov_b32 s71, 0
	s_mov_b32 s72, 0
	s_waitcnt lgkmcnt(0)
	s_barrier
	s_mul_i32 s74, s70, 0x6000
	s_add_u32 s75, s74, s68
	s_mov_b32 m0, s75
	s_add_u32 s76, s74, 0x2000
	s_cmp_eq_u32 s70, 2
	s_cselect_b32 s76, 0x10000, s76
	global_load_lds_dwordx4 v160, s[64:65]
	s_add_u32 m0, s75, 0x400
	s_add_u32 s76, s76, s69
	global_load_lds_dwordx4 v162, s[64:65]
	s_mov_b32 m0, s76
	s_add_u32 s64, s64, 64
	s_addc_u32 s65, s65, 0
	global_load_lds_dwordx4 v163, s[66:67]
	global_load_lds_dwordx4 v163, s[66:67] offset:1024
	global_load_lds_dwordx4 v163, s[66:67] offset:2048
	global_load_lds_dwordx4 v163, s[66:67] offset:3072
	s_add_u32 s66, s66, 0x10000
	s_addc_u32 s67, s67, 0
	s_add_u32 s70, s70, 1
	s_cmp_eq_u32 s70, 3
	s_cselect_b32 s70, 0, s70
	s_mul_i32 s74, s70, 0x6000
	s_add_u32 s75, s74, s68
	s_mov_b32 m0, s75
	s_add_u32 s76, s74, 0x2000
	s_cmp_eq_u32 s70, 2
	s_cselect_b32 s76, 0x10000, s76
	global_load_lds_dwordx4 v160, s[64:65]
	s_add_u32 m0, s75, 0x400
	s_add_u32 s76, s76, s69
	global_load_lds_dwordx4 v162, s[64:65]
	s_mov_b32 m0, s76
	s_add_u32 s64, s64, 64
	s_addc_u32 s65, s65, 0
	global_load_lds_dwordx4 v163, s[66:67]
	global_load_lds_dwordx4 v163, s[66:67] offset:1024
	global_load_lds_dwordx4 v163, s[66:67] offset:2048
	global_load_lds_dwordx4 v163, s[66:67] offset:3072
	s_add_u32 s66, s66, 0x10000
	s_addc_u32 s67, s67, 0
	s_add_u32 s70, s70, 1
	s_cmp_eq_u32 s70, 3
	s_cselect_b32 s70, 0, s70
	s_cmp_lt_u32 s46, 0x100
	s_cbranch_scc1 .Lp1k_nostag
	s_sleep 8
	s_setprio 1

; #define MFMA32(a, b, c) __builtin_amdgcn_mfma_f32_32x32x16_bf16((a), (b), (c), 0, 0, 0)
; #define GA_LOAD(pr_) do { _Pragma("unroll") for (int i = 0; i < 4; ++i) ra[i] = *(const u32x4*)(Ab + (i * 32) * lda + (pr_) * 64); } while (0)
; #define GB_LOAD(kt_) do { const bfr* bk_ = Bb + (kt_) * NB * 32; \
;     _Pragma("unroll") for (int i = 0; i < 4; ++i) rb[i] = *(const u32x4*)(bk_ + (i * 64) * 32); } while (0)
; #define G_STORE(kt_) do { bfr* as_ = S0 + ((kt_) & 1) * GSTAGE; bfr* bs_ = as_ + 128 * 40; \
;     if (apar == ((kt_) & 1)) { _Pragma("unroll") for (int i = 0; i < 4; ++i) *(u32x4*)(as_ + asoff + i * 32 * 40) = ra[i]; } \
;     _Pragma("unroll") for (int i = 0; i < 4; ++i) *(u32x4*)(bs_ + bsoff + i * 64 * 40) = rb[i]; } while (0)
; template <int lda>
; DI void gemm_mainloop(const bfr* __restrict__ A, const bfr* __restrict__ Bt, int NB, int K, int m0, int n0, char* smem, f32x16 (&acc)[2][4]) {
;     ...
;   for (int kt = 0; kt < nk; ++kt) {
;     if (kt + 1 < nk) G_STORE(kt + 1);
;     if (kt + 2 < nk) {
;       GB_LOAD(kt + 2);
;       if ((kt & 1) == 0) GA_LOAD((kt >> 1) + 1);
;     }
;     const bfr* As = S0 + (kt & 1) * GSTAGE;
;     const bfr* Bs = As + 128 * 40;
; #pragma unroll
;     for (int ks = 0; ks < 2; ++ks) {
;       bf16x8 af[2], bfg[4];
; #pragma unroll
;       for (int i = 0; i < 2; ++i) af[i] = *(const bf16x8*)(As + (wr * 64 + i * 32 + r) * 40 + ks * 16 + hl * 8);
; #pragma unroll
;       for (int j = 0; j < 4; ++j) bfg[j] = *(const bf16x8*)(Bs + (wc * 128 + j * 32 + r) * 40 + ks * 16 + hl * 8);
; #pragma unroll
;       for (int i = 0; i < 2; ++i)
; #pragma unroll
;         for (int j = 0; j < 4; ++j) acc[i][j] = MFMA32(af[i], bfg[j], acc[i][j]);
;     }
;     __syncthreads();
;   }
.Lp1k_loop:
	s_waitcnt vmcnt(6)
	s_barrier
	s_mul_i32 s74, s71, 0x6000
	s_add_u32 s75, s74, 0x2000
	s_cmp_eq_u32 s71, 2
	s_cselect_b32 s75, 0x10000, s75
	v_add_u32_e32 v184, s74, v180
	v_add_u32_e32 v186, s75, v182
	v_add_u32_e32 v185, s74, v181
	v_add_u32_e32 v187, s75, v183
	ds_read_b128 v[128:131], v184
	ds_read_b128 v[144:147], v186
	ds_read_b128 v[148:151], v186 offset:2048
	ds_read_b128 v[152:155], v186 offset:4096
	ds_read_b128 v[156:159], v186 offset:6144
	ds_read_b128 v[132:135], v184 offset:2048
	ds_read_b128 v[136:139], v185
	ds_read_b128 v[164:167], v187
	ds_read_b128 v[168:171], v187 offset:2048
	ds_read_b128 v[172:175], v187 offset:4096
	ds_read_b128 v[176:179], v187 offset:6144
	ds_read_b128 v[140:143], v185 offset:2048
	s_add_u32 s71, s71, 1
	s_cmp_eq_u32 s71, 3
	s_cselect_b32 s71, 0, s71
	s_waitcnt lgkmcnt(10)
	v_mfma_f32_32x32x16_bf16 v[112:127], v[128:131], v[144:147], v[112:127]
	s_mul_i32 s74, s70, 0x6000
	s_add_u32 s75, s74, s68
	s_mov_b32 m0, s75
	s_add_u32 s76, s74, 0x2000
	s_cmp_eq_u32 s70, 2
	s_cselect_b32 s76, 0x10000, s76
	global_load_lds_dwordx4 v160, s[64:65]
	s_waitcnt lgkmcnt(9)
	v_mfma_f32_32x32x16_bf16 v[96:111], v[128:131], v[148:151], v[96:111]
	s_add_u32 m0, s75, 0x400
	s_add_u32 s76, s76, s69
	global_load_lds_dwordx4 v162, s[64:65]
	s_waitcnt lgkmcnt(8)
	v_mfma_f32_32x32x16_bf16 v[80:95], v[128:131], v[152:155], v[80:95]
	s_mov_b32 m0, s76
	s_add_u32 s64, s64, 64
	s_addc_u32 s65, s65, 0
	global_load_lds_dwordx4 v163, s[66:67]
	s_waitcnt lgkmcnt(7)
	v_mfma_f32_32x32x16_bf16 v[64:79], v[128:131], v[156:159], v[64:79]
	global_load_lds_dwordx4 v163, s[66:67] offset:1024
	s_waitcnt lgkmcnt(6)
	v_mfma_f32_32x32x16_bf16 v[48:63], v[132:135], v[144:147], v[48:63]
	global_load_lds_dwordx4 v163, s[66:67] offset:2048
	v_mfma_f32_32x32x16_bf16 v[32:47], v[132:135], v[148:151], v[32:47]
	global_load_lds_dwordx4 v163, s[66:67] offset:3072
	s_add_u32 s66, s66, 0x10000
	s_addc_u32 s67, s67, 0
	v_mfma_f32_32x32x16_bf16 v[16:31], v[132:135], v[152:155], v[16:31]
	s_add_u32 s70, s70, 1
	s_cmp_eq_u32 s70, 3
	s_cselect_b32 s70, 0, s70
	v_mfma_f32_32x32x16_bf16 v[0:15], v[132:135], v[156:159], v[0:15]
	s_waitcnt lgkmcnt(4)
	v_mfma_f32_32x32x16_bf16 v[112:127], v[136:139], v[164:167], v[112:127]
	s_waitcnt lgkmcnt(3)
	v_mfma_f32_32x32x16_bf16 v[96:111], v[136:139], v[168:171], v[96:111]
	s_waitcnt lgkmcnt(2)
	v_mfma_f32_32x32x16_bf16 v[80:95], v[136:139], v[172:175], v[80:95]
	s_waitcnt lgkmcnt(1)
	v_mfma_f32_32x32x16_bf16 v[64:79], v[136:139], v[176:179], v[64:79]
	s_waitcnt lgkmcnt(0)
	v_mfma_f32_32x32x16_bf16 v[48:63], v[140:143], v[164:167], v[48:63]
	v_mfma_f32_32x32x16_bf16 v[32:47], v[140:143], v[168:171], v[32:47]
	v_mfma_f32_32x32x16_bf16 v[16:31], v[140:143], v[172:175], v[16:31]
	v_mfma_f32_32x32x16_bf16 v[0:15], v[140:143], v[176:179], v[0:15]
	s_add_u32 s72, s72, 1
	s_cmp_lt_u32 s72, 30
	s_cbranch_scc1 .Lp1k_loop
	s_waitcnt vmcnt(6)
	s_barrier
; #define MFMA32(a, b, c) __builtin_amdgcn_mfma_f32_32x32x16_bf16((a), (b), (c), 0, 0, 0)
; #define GA_LOAD(pr_) do { _Pragma("unroll") for (int i = 0; i < 4; ++i) ra[i] = *(const u32x4*)(Ab + (i * 32) * lda + (pr_) * 64); } while (0)
; #define GB_LOAD(kt_) do { const bfr* bk_ = Bb + (kt_) * NB * 32; \
;     _Pragma("unroll") for (int i = 0; i < 4; ++i) rb[i] = *(const u32x4*)(bk_ + (i * 64) * 32); } while (0)
; #define G_STORE(kt_) do { bfr* as_ = S0 + ((kt_) & 1) * GSTAGE; bfr* bs_ = as_ + 128 * 40; \
;     if (apar == ((kt_) & 1)) { _Pragma("unroll") for (int i = 0; i < 4; ++i) *(u32x4*)(as_ + asoff + i * 32 * 40) = ra[i]; } \
;     _Pragma("unroll") for (int i = 0; i < 4; ++i) *(u32x4*)(bs_ + bsoff + i * 64 * 40) = rb[i]; } while (0)
; template <int lda>
; DI void gemm_mainloop(const bfr* __restrict__ A, const bfr* __restrict__ Bt, int NB, int K, int m0, int n0, char* smem, f32x16 (&acc)[2][4]) {
;     ...
;   for (int kt = 0; kt < nk; ++kt) {
;     if (kt + 1 < nk) G_STORE(kt + 1);
;     if (kt + 2 < nk) {
;       GB_LOAD(kt + 2);
;       if ((kt & 1) == 0) GA_LOAD((kt >> 1) + 1);
;     }
;     const bfr* As = S0 + (kt & 1) * GSTAGE;
;     const bfr* Bs = As + 128 * 40;
; #pragma unroll
;     for (int ks = 0; ks < 2; ++ks) {
;       bf16x8 af[2], bfg[4];
; #pragma unroll
;       for (int i = 0; i < 2; ++i) af[i] = *(const bf16x8*)(As + (wr * 64 + i * 32 + r) * 40 + ks * 16 + hl * 8);
; #pragma unroll
;       for (int j = 0; j < 4; ++j) bfg[j] = *(const bf16x8*)(Bs + (wc * 128 + j * 32 + r) * 40 + ks * 16 + hl * 8);
; #pragma unroll
;       for (int i = 0; i < 2; ++i)
; #pragma unroll
;         for (int j = 0; j < 4; ++j) acc[i][j] = MFMA32(af[i], bfg[j], acc[i][j]);
;     }
;     __syncthreads();
;   }
	s_mul_i32 s74, s71, 0x6000
	s_add_u32 s75, s74, 0x2000
	s_cmp_eq_u32 s71, 2
	s_cselect_b32 s75, 0x10000, s75
	v_add_u32_e32 v184, s74, v180
	v_add_u32_e32 v186, s75, v182
	v_add_u32_e32 v185, s74, v181
	v_add_u32_e32 v187, s75, v183
	ds_read_b128 v[128:131], v184
	ds_read_b128 v[144:147], v186
	ds_read_b128 v[148:151], v186 offset:2048
	ds_read_b128 v[152:155], v186 offset:4096
	ds_read_b128 v[156:159], v186 offset:6144
	ds_read_b128 v[132:135], v184 offset:2048
	ds_read_b128 v[136:139], v185
	ds_read_b128 v[164:167], v187
	ds_read_b128 v[168:171], v187 offset:2048
	ds_read_b128 v[172:175], v187 offset:4096
	ds_read_b128 v[176:179], v187 offset:6144
	ds_read_b128 v[140:143], v185 offset:2048
	s_add_u32 s71, s71, 1
	s_cmp_eq_u32 s71, 3
	s_cselect_b32 s71, 0, s71
	s_waitcnt lgkmcnt(10)
	v_mfma_f32_32x32x16_bf16 v[112:127], v[128:131], v[144:147], v[112:127]
	s_waitcnt lgkmcnt(9)
	v_mfma_f32_32x32x16_bf16 v[96:111], v[128:131], v[148:151], v[96:111]
	s_waitcnt lgkmcnt(8)
	v_mfma_f32_32x32x16_bf16 v[80:95], v[128:131], v[152:155], v[80:95]
	s_waitcnt lgkmcnt(7)
	v_mfma_f32_32x32x16_bf16 v[64:79], v[128:131], v[156:159], v[64:79]
	s_waitcnt lgkmcnt(6)
	v_mfma_f32_32x32x16_bf16 v[48:63], v[132:135], v[144:147], v[48:63]
	v_mfma_f32_32x32x16_bf16 v[32:47], v[132:135], v[148:151], v[32:47]
	v_mfma_f32_32x32x16_bf16 v[16:31], v[132:135], v[152:155], v[16:31]
	v_mfma_f32_32x32x16_bf16 v[0:15], v[132:135], v[156:159], v[0:15]
	s_waitcnt lgkmcnt(4)
	v_mfma_f32_32x32x16_bf16 v[112:127], v[136:139], v[164:167], v[112:127]
	s_waitcnt lgkmcnt(3)
	v_mfma_f32_32x32x16_bf16 v[96:111], v[136:139], v[168:171], v[96:111]
	s_waitcnt lgkmcnt(2)
	v_mfma_f32_32x32x16_bf16 v[80:95], v[136:139], v[172:175], v[80:95]
	s_waitcnt lgkmcnt(1)
	v_mfma_f32_32x32x16_bf16 v[64:79], v[136:139], v[176:179], v[64:79]
	s_waitcnt lgkmcnt(0)
	v_mfma_f32_32x32x16_bf16 v[48:63], v[140:143], v[164:167], v[48:63]
	v_mfma_f32_32x32x16_bf16 v[32:47], v[140:143], v[168:171], v[32:47]
	v_mfma_f32_32x32x16_bf16 v[16:31], v[140:143], v[172:175], v[16:31]
	v_mfma_f32_32x32x16_bf16 v[0:15], v[140:143], v[176:179], v[0:15]
	s_waitcnt vmcnt(0)
	s_barrier
	s_mul_i32 s74, s71, 0x6000
	s_add_u32 s75, s74, 0x2000
	s_cmp_eq_u32 s71, 2
	s_cselect_b32 s75, 0x10000, s75
	v_add_u32_e32 v184, s74, v180
	v_add_u32_e32 v186, s75, v182
	v_add_u32_e32 v185, s74, v181
	v_add_u32_e32 v187, s75, v183
	ds_read_b128 v[128:131], v184
	ds_read_b128 v[144:147], v186
	ds_read_b128 v[148:151], v186 offset:2048
	ds_read_b128 v[152:155], v186 offset:4096
	ds_read_b128 v[156:159], v186 offset:6144
	ds_read_b128 v[132:135], v184 offset:2048
	ds_read_b128 v[136:139], v185
	ds_read_b128 v[164:167], v187
	ds_read_b128 v[168:171], v187 offset:2048
	ds_read_b128 v[172:175], v187 offset:4096
	ds_read_b128 v[176:179], v187 offset:6144
	ds_read_b128 v[140:143], v185 offset:2048
	s_add_u32 s71, s71, 1
	s_cmp_eq_u32 s71, 3
	s_cselect_b32 s71, 0, s71
	s_waitcnt lgkmcnt(10)
	v_mfma_f32_32x32x16_bf16 v[112:127], v[128:131], v[144:147], v[112:127]
	s_waitcnt lgkmcnt(9)
	v_mfma_f32_32x32x16_bf16 v[96:111], v[128:131], v[148:151], v[96:111]
	s_waitcnt lgkmcnt(8)
	v_mfma_f32_32x32x16_bf16 v[80:95], v[128:131], v[152:155], v[80:95]
	s_waitcnt lgkmcnt(7)
	v_mfma_f32_32x32x16_bf16 v[64:79], v[128:131], v[156:159], v[64:79]
	s_waitcnt lgkmcnt(6)
	v_mfma_f32_32x32x16_bf16 v[48:63], v[132:135], v[144:147], v[48:63]
	v_mfma_f32_32x32x16_bf16 v[32:47], v[132:135], v[148:151], v[32:47]
	v_mfma_f32_32x32x16_bf16 v[16:31], v[132:135], v[152:155], v[16:31]
	v_mfma_f32_32x32x16_bf16 v[0:15], v[132:135], v[156:159], v[0:15]
	s_waitcnt lgkmcnt(4)
	v_mfma_f32_32x32x16_bf16 v[112:127], v[136:139], v[164:167], v[112:127]
	s_waitcnt lgkmcnt(3)
	v_mfma_f32_32x32x16_bf16 v[96:111], v[136:139], v[168:171], v[96:111]
	s_waitcnt lgkmcnt(2)
	v_mfma_f32_32x32x16_bf16 v[80:95], v[136:139], v[172:175], v[80:95]
	s_waitcnt lgkmcnt(1)
	v_mfma_f32_32x32x16_bf16 v[64:79], v[136:139], v[176:179], v[64:79]
	s_waitcnt lgkmcnt(0)
	v_mfma_f32_32x32x16_bf16 v[48:63], v[140:143], v[164:167], v[48:63]
	v_mfma_f32_32x32x16_bf16 v[32:47], v[140:143], v[168:171], v[32:47]
	v_mfma_f32_32x32x16_bf16 v[16:31], v[140:143], v[172:175], v[16:31]
	v_mfma_f32_32x32x16_bf16 v[0:15], v[140:143], v[176:179], v[0:15]
	s_setprio 0
	s_nop 7
	v_readlane_b32 s64, v188, 0
	v_readlane_b32 s65, v188, 1
	v_readlane_b32 s66, v188, 2
	v_readlane_b32 s67, v188, 3
	v_readlane_b32 s68, v188, 4
	v_readlane_b32 s69, v188, 5
	v_readlane_b32 s70, v188, 6
	v_readlane_b32 s71, v188, 7
	v_readlane_b32 s72, v188, 8
	v_readlane_b32 s73, v188, 9
	v_readlane_b32 s74, v188, 10
	v_readlane_b32 s75, v188, 11
	v_readlane_b32 s76, v188, 12
	v_readlane_b32 s77, v188, 13
	v_readlane_b32 s78, v188, 14
	v_readlane_b32 s79, v188, 15
	s_nop 7
	s_branch .Lp1k_tail

; #define GA_LOAD(pr_) do { _Pragma("unroll") for (int i = 0; i < 4; ++i) ra[i] = *(const u32x4*)(Ab + (i * 32) * lda + (pr_) * 64); } while (0)
; #define GB_LOAD(kt_) do { const bfr* bk_ = Bb + (kt_) * NB * 32; \
;     _Pragma("unroll") for (int i = 0; i < 4; ++i) rb[i] = *(const u32x4*)(bk_ + (i * 64) * 32); } while (0)
; #define G_STORE(kt_) do { bfr* as_ = S0 + ((kt_) & 1) * GSTAGE; bfr* bs_ = as_ + 128 * 40; \
;     if (apar == ((kt_) & 1)) { _Pragma("unroll") for (int i = 0; i < 4; ++i) *(u32x4*)(as_ + asoff + i * 32 * 40) = ra[i]; } \
;     _Pragma("unroll") for (int i = 0; i < 4; ++i) *(u32x4*)(bs_ + bsoff + i * 64 * 40) = rb[i]; } while (0)
; template <int lda>
; DI void gemm_mainloop(const bfr* __restrict__ A, const bfr* __restrict__ Bt, int NB, int K, int m0, int n0, char* smem, f32x16 (&acc)[2][4]) {
;     ...
;   u32x4 ra[4], rb[4];
;   const int nk = K >> 5;
;   const int arow = tid >> 3, ac8 = tid & 7, apar = ac8 >> 2;
;   const bfr* Ab = A + (m0 + arow) * lda + ac8 * 8;
;   const int asoff = arow * 40 + (ac8 & 3) * 8;
;   const int brow = tid >> 2, bc4 = tid & 3;
;   const bfr* Bb = Bt + (n0 + brow) * 32 + bc4 * 8;
;   const int bsoff = brow * 40 + bc4 * 8;
;     ...
;   GA_LOAD(0);
;   GB_LOAD(0);
;   G_STORE(0);
;   GB_LOAD(1);
;   __syncthreads();
; DI void phase_gemm_in_even(const Params& p, char* smem) {
;     ...
;   for (int t0 = blockIdx.x; t0 < NT1 + NT2; t0 += gridDim.x) {
;     const int t = (t0 < NT1 && (gridDim.x & 7) == 0) ? xcd_tile(t0, 14) : t0;
;     if (t < NT1) {
;       int mt = t / 14, nt = t % 14;
;       bfr* PB = p.PB;
;       gemm_tile<1024>(p.H, p.WtInE, 3712, 1024, mt * 128, nt * 256, smem,
.LBB0_151:
	s_andn2_b64 vcc, exec, s[0:1]
	s_cbranch_vccnz .LBB0_119
	s_mul_hi_i32 s0, s56, 0x92492493
	s_add_i32 s0, s0, s56
	s_lshr_b32 s1, s0, 31
	s_ashr_i32 s0, s0, 3
	s_add_i32 s0, s0, s1
	s_mul_i32 s1, s0, 14
	s_sub_i32 s1, s56, s1
	s_lshl_b32 s56, s0, 7
	s_lshl_b32 s2, s1, 8
	s_mov_b32 s57, 0
	s_mov_b64 s[30:31], 0
	s_lshl_b32 s98, s56, 11
	s_add_u32 s98, s16, s98
	s_addc_u32 s99, s17, 0
	s_lshl_b32 s100, s2, 6
	s_add_u32 s100, s10, s100
	s_addc_u32 s101, s11, 0
	v_writelane_b32 v188, s64, 0
	v_writelane_b32 v188, s65, 1
	v_writelane_b32 v188, s66, 2
	v_writelane_b32 v188, s67, 3
	v_writelane_b32 v188, s68, 4
	v_writelane_b32 v188, s69, 5
	v_writelane_b32 v188, s70, 6
	v_writelane_b32 v188, s71, 7
	v_writelane_b32 v188, s72, 8
	v_writelane_b32 v188, s73, 9
	v_writelane_b32 v188, s74, 10
	v_writelane_b32 v188, s75, 11
	v_writelane_b32 v188, s76, 12
	v_writelane_b32 v188, s77, 13
	v_writelane_b32 v188, s78, 14
	v_writelane_b32 v188, s79, 15
	v_lshrrev_b32_e32 v189, 6, v196
	v_and_b32_e32 v190, 63, v196
	v_readfirstlane_b32 s73, v189
	v_lshrrev_b32_e32 v191, 2, v190
	v_bfe_u32 v192, v190, 4, 2
	v_and_b32_e32 v189, 3, v190
	v_xor_b32_e32 v189, v189, v192
	v_lshlrev_b32_e32 v189, 4, v189
	v_lshl_add_u32 v160, v191, 11, v189
	v_add_u32_e32 v162, 0x8000, v160
	v_lshl_add_u32 v163, v191, 6, v189
	v_and_b32_e32 v191, 31, v190
	v_lshrrev_b32_e32 v192, 5, v190
	v_bfe_u32 v189, v190, 2, 2
	v_xor_b32_e32 v189, v189, v192
	v_lshlrev_b32_e32 v189, 4, v189
	v_lshl_add_u32 v180, v191, 6, v189
	s_lshr_b32 s74, s73, 1
	s_lshl_b32 s74, s74, 12
	s_and_b32 s75, s73, 1
	s_lshl_b32 s75, s75, 13
	v_add_u32_e32 v182, s75, v180
	v_add_u32_e32 v180, s74, v180
	v_xor_b32_e32 v183, 32, v182
	v_xor_b32_e32 v181, 32, v180
	s_lshl_b32 s74, s73, 16
	s_add_u32 s64, s98, s74
	s_addc_u32 s65, s99, 0
	s_lshl_b32 s74, s73, 12
	s_add_u32 s66, s100, s74
	s_addc_u32 s67, s101, 0
	s_lshl_b32 s68, s73, 11
	s_lshl_b32 s69, s73, 12
	s_mov_b32 s70, 0
	s_mov_b32 s71, 0
	s_mov_b32 s72, 0
	s_waitcnt lgkmcnt(0)
	s_barrier
	s_mul_i32 s74, s70, 0x6000
	s_add_u32 s75, s74, s68
	s_mov_b32 m0, s75
	s_add_u32 s76, s74, 0x2000
	s_cmp_eq_u32 s70, 2
	s_cselect_b32 s76, 0x10000, s76
	global_load_lds_dwordx4 v160, s[64:65]
	s_add_u32 m0, s75, 0x400
	s_add_u32 s76, s76, s69
	global_load_lds_dwordx4 v162, s[64:65]
	s_mov_b32 m0, s76
	s_add_u32 s64, s64, 64
	s_addc_u32 s65, s65, 0
	global_load_lds_dwordx4 v163, s[66:67]
	global_load_lds_dwordx4 v163, s[66:67] offset:1024
	global_load_lds_dwordx4 v163, s[66:67] offset:2048
	global_load_lds_dwordx4 v163, s[66:67] offset:3072
	s_add_u32 s66, s66, 0x3a000
	s_addc_u32 s67, s67, 0
	s_add_u32 s70, s70, 1
	s_cmp_eq_u32 s70, 3
	s_cselect_b32 s70, 0, s70
	s_mul_i32 s74, s70, 0x6000
	s_add_u32 s75, s74, s68
	s_mov_b32 m0, s75
	s_add_u32 s76, s74, 0x2000
	s_cmp_eq_u32 s70, 2
	s_cselect_b32 s76, 0x10000, s76
	global_load_lds_dwordx4 v160, s[64:65]
	s_add_u32 m0, s75, 0x400
	s_add_u32 s76, s76, s69
	global_load_lds_dwordx4 v162, s[64:65]
	s_mov_b32 m0, s76
	s_add_u32 s64, s64, 64
	s_addc_u32 s65, s65, 0
	global_load_lds_dwordx4 v163, s[66:67]
	global_load_lds_dwordx4 v163, s[66:67] offset:1024
	global_load_lds_dwordx4 v163, s[66:67] offset:2048
	global_load_lds_dwordx4 v163, s[66:67] offset:3072
	s_add_u32 s66, s66, 0x3a000
	s_addc_u32 s67, s67, 0
	s_add_u32 s70, s70, 1
	s_cmp_eq_u32 s70, 3
	s_cselect_b32 s70, 0, s70
	s_cmp_lt_u32 s46, 0x100
	s_cbranch_scc1 .Lp1e_nostag
	s_sleep 8
	s_setprio 1

; #define MFMA32(a, b, c) __builtin_amdgcn_mfma_f32_32x32x16_bf16((a), (b), (c), 0, 0, 0)
; #define GA_LOAD(pr_) do { _Pragma("unroll") for (int i = 0; i < 4; ++i) ra[i] = *(const u32x4*)(Ab + (i * 32) * lda + (pr_) * 64); } while (0)
; #define GB_LOAD(kt_) do { const bfr* bk_ = Bb + (kt_) * NB * 32; \
;     _Pragma("unroll") for (int i = 0; i < 4; ++i) rb[i] = *(const u32x4*)(bk_ + (i * 64) * 32); } while (0)
; #define G_STORE(kt_) do { bfr* as_ = S0 + ((kt_) & 1) * GSTAGE; bfr* bs_ = as_ + 128 * 40; \
;     if (apar == ((kt_) & 1)) { _Pragma("unroll") for (int i = 0; i < 4; ++i) *(u32x4*)(as_ + asoff + i * 32 * 40) = ra[i]; } \
;     _Pragma("unroll") for (int i = 0; i < 4; ++i) *(u32x4*)(bs_ + bsoff + i * 64 * 40) = rb[i]; } while (0)
; template <int lda>
; DI void gemm_mainloop(const bfr* __restrict__ A, const bfr* __restrict__ Bt, int NB, int K, int m0, int n0, char* smem, f32x16 (&acc)[2][4]) {
;     ...
;   for (int kt = 0; kt < nk; ++kt) {
;     if (kt + 1 < nk) G_STORE(kt + 1);
;     if (kt + 2 < nk) {
;       GB_LOAD(kt + 2);
;       if ((kt & 1) == 0) GA_LOAD((kt >> 1) + 1);
;     }
;     const bfr* As = S0 + (kt & 1) * GSTAGE;
;     const bfr* Bs = As + 128 * 40;
; #pragma unroll
;     for (int ks = 0; ks < 2; ++ks) {
;       bf16x8 af[2], bfg[4];
; #pragma unroll
;       for (int i = 0; i < 2; ++i) af[i] = *(const bf16x8*)(As + (wr * 64 + i * 32 + r) * 40 + ks * 16 + hl * 8);
; #pragma unroll
;       for (int j = 0; j < 4; ++j) bfg[j] = *(const bf16x8*)(Bs + (wc * 128 + j * 32 + r) * 40 + ks * 16 + hl * 8);
; #pragma unroll
;       for (int i = 0; i < 2; ++i)
; #pragma unroll
;         for (int j = 0; j < 4; ++j) acc[i][j] = MFMA32(af[i], bfg[j], acc[i][j]);
;     }
;     __syncthreads();
;   }
.Lp1e_loop:
	s_waitcnt vmcnt(6)
	s_barrier
	s_mul_i32 s74, s71, 0x6000
	s_add_u32 s75, s74, 0x2000
	s_cmp_eq_u32 s71, 2
	s_cselect_b32 s75, 0x10000, s75
	v_add_u32_e32 v184, s74, v180
	v_add_u32_e32 v186, s75, v182
	v_add_u32_e32 v185, s74, v181
	v_add_u32_e32 v187, s75, v183
	ds_read_b128 v[128:131], v184
	ds_read_b128 v[144:147], v186
	ds_read_b128 v[148:151], v186 offset:2048
	ds_read_b128 v[152:155], v186 offset:4096
	ds_read_b128 v[156:159], v186 offset:6144
	ds_read_b128 v[132:135], v184 offset:2048
	ds_read_b128 v[136:139], v185
	ds_read_b128 v[164:167], v187
	ds_read_b128 v[168:171], v187 offset:2048
	ds_read_b128 v[172:175], v187 offset:4096
	ds_read_b128 v[176:179], v187 offset:6144
	ds_read_b128 v[140:143], v185 offset:2048
	s_add_u32 s71, s71, 1
	s_cmp_eq_u32 s71, 3
	s_cselect_b32 s71, 0, s71
	s_waitcnt lgkmcnt(10)
	v_mfma_f32_32x32x16_bf16 v[112:127], v[128:131], v[144:147], v[112:127]
	s_mul_i32 s74, s70, 0x6000
	s_add_u32 s75, s74, s68
	s_mov_b32 m0, s75
	s_add_u32 s76, s74, 0x2000
	s_cmp_eq_u32 s70, 2
	s_cselect_b32 s76, 0x10000, s76
	global_load_lds_dwordx4 v160, s[64:65]
	s_waitcnt lgkmcnt(9)
	v_mfma_f32_32x32x16_bf16 v[96:111], v[128:131], v[148:151], v[96:111]
	s_add_u32 m0, s75, 0x400
	s_add_u32 s76, s76, s69
	global_load_lds_dwordx4 v162, s[64:65]
	s_waitcnt lgkmcnt(8)
	v_mfma_f32_32x32x16_bf16 v[80:95], v[128:131], v[152:155], v[80:95]
	s_mov_b32 m0, s76
	s_add_u32 s64, s64, 64
	s_addc_u32 s65, s65, 0
	global_load_lds_dwordx4 v163, s[66:67]
	s_waitcnt lgkmcnt(7)
	v_mfma_f32_32x32x16_bf16 v[64:79], v[128:131], v[156:159], v[64:79]
	global_load_lds_dwordx4 v163, s[66:67] offset:1024
	s_waitcnt lgkmcnt(6)
	v_mfma_f32_32x32x16_bf16 v[48:63], v[132:135], v[144:147], v[48:63]
	global_load_lds_dwordx4 v163, s[66:67] offset:2048
	v_mfma_f32_32x32x16_bf16 v[32:47], v[132:135], v[148:151], v[32:47]
	global_load_lds_dwordx4 v163, s[66:67] offset:3072
	s_add_u32 s66, s66, 0x3a000
	s_addc_u32 s67, s67, 0
	v_mfma_f32_32x32x16_bf16 v[16:31], v[132:135], v[152:155], v[16:31]
	s_add_u32 s70, s70, 1
	s_cmp_eq_u32 s70, 3
	s_cselect_b32 s70, 0, s70
	v_mfma_f32_32x32x16_bf16 v[0:15], v[132:135], v[156:159], v[0:15]
	s_waitcnt lgkmcnt(4)
	v_mfma_f32_32x32x16_bf16 v[112:127], v[136:139], v[164:167], v[112:127]
	s_waitcnt lgkmcnt(3)
	v_mfma_f32_32x32x16_bf16 v[96:111], v[136:139], v[168:171], v[96:111]
	s_waitcnt lgkmcnt(2)
	v_mfma_f32_32x32x16_bf16 v[80:95], v[136:139], v[172:175], v[80:95]
	s_waitcnt lgkmcnt(1)
	v_mfma_f32_32x32x16_bf16 v[64:79], v[136:139], v[176:179], v[64:79]
	s_waitcnt lgkmcnt(0)
	v_mfma_f32_32x32x16_bf16 v[48:63], v[140:143], v[164:167], v[48:63]
	v_mfma_f32_32x32x16_bf16 v[32:47], v[140:143], v[168:171], v[32:47]
	v_mfma_f32_32x32x16_bf16 v[16:31], v[140:143], v[172:175], v[16:31]
	v_mfma_f32_32x32x16_bf16 v[0:15], v[140:143], v[176:179], v[0:15]
	s_add_u32 s72, s72, 1
	s_cmp_lt_u32 s72, 30
	s_cbranch_scc1 .Lp1e_loop
	s_waitcnt vmcnt(6)
	s_barrier
; #define MFMA32(a, b, c) __builtin_amdgcn_mfma_f32_32x32x16_bf16((a), (b), (c), 0, 0, 0)
; #define GA_LOAD(pr_) do { _Pragma("unroll") for (int i = 0; i < 4; ++i) ra[i] = *(const u32x4*)(Ab + (i * 32) * lda + (pr_) * 64); } while (0)
; #define GB_LOAD(kt_) do { const bfr* bk_ = Bb + (kt_) * NB * 32; \
;     _Pragma("unroll") for (int i = 0; i < 4; ++i) rb[i] = *(const u32x4*)(bk_ + (i * 64) * 32); } while (0)
; #define G_STORE(kt_) do { bfr* as_ = S0 + ((kt_) & 1) * GSTAGE; bfr* bs_ = as_ + 128 * 40; \
;     if (apar == ((kt_) & 1)) { _Pragma("unroll") for (int i = 0; i < 4; ++i) *(u32x4*)(as_ + asoff + i * 32 * 40) = ra[i]; } \
;     _Pragma("unroll") for (int i = 0; i < 4; ++i) *(u32x4*)(bs_ + bsoff + i * 64 * 40) = rb[i]; } while (0)
; template <int lda>
; DI void gemm_mainloop(const bfr* __restrict__ A, const bfr* __restrict__ Bt, int NB, int K, int m0, int n0, char* smem, f32x16 (&acc)[2][4]) {
;     ...
;   for (int kt = 0; kt < nk; ++kt) {
;     if (kt + 1 < nk) G_STORE(kt + 1);
;     if (kt + 2 < nk) {
;       GB_LOAD(kt + 2);
;       if ((kt & 1) == 0) GA_LOAD((kt >> 1) + 1);
;     }
;     const bfr* As = S0 + (kt & 1) * GSTAGE;
;     const bfr* Bs = As + 128 * 40;
; #pragma unroll
;     for (int ks = 0; ks < 2; ++ks) {
;       bf16x8 af[2], bfg[4];
; #pragma unroll
;       for (int i = 0; i < 2; ++i) af[i] = *(const bf16x8*)(As + (wr * 64 + i * 32 + r) * 40 + ks * 16 + hl * 8);
; #pragma unroll
;       for (int j = 0; j < 4; ++j) bfg[j] = *(const bf16x8*)(Bs + (wc * 128 + j * 32 + r) * 40 + ks * 16 + hl * 8);
; #pragma unroll
;       for (int i = 0; i < 2; ++i)
; #pragma unroll
;         for (int j = 0; j < 4; ++j) acc[i][j] = MFMA32(af[i], bfg[j], acc[i][j]);
;     }
;     __syncthreads();
;   }
	s_mul_i32 s74, s71, 0x6000
	s_add_u32 s75, s74, 0x2000
	s_cmp_eq_u32 s71, 2
	s_cselect_b32 s75, 0x10000, s75
	v_add_u32_e32 v184, s74, v180
	v_add_u32_e32 v186, s75, v182
	v_add_u32_e32 v185, s74, v181
	v_add_u32_e32 v187, s75, v183
	ds_read_b128 v[128:131], v184
	ds_read_b128 v[144:147], v186
	ds_read_b128 v[148:151], v186 offset:2048
	ds_read_b128 v[152:155], v186 offset:4096
	ds_read_b128 v[156:159], v186 offset:6144
	ds_read_b128 v[132:135], v184 offset:2048
	ds_read_b128 v[136:139], v185
	ds_read_b128 v[164:167], v187
	ds_read_b128 v[168:171], v187 offset:2048
	ds_read_b128 v[172:175], v187 offset:4096
	ds_read_b128 v[176:179], v187 offset:6144
	ds_read_b128 v[140:143], v185 offset:2048
	s_add_u32 s71, s71, 1
	s_cmp_eq_u32 s71, 3
	s_cselect_b32 s71, 0, s71
	s_waitcnt lgkmcnt(10)
	v_mfma_f32_32x32x16_bf16 v[112:127], v[128:131], v[144:147], v[112:127]
	s_waitcnt lgkmcnt(9)
	v_mfma_f32_32x32x16_bf16 v[96:111], v[128:131], v[148:151], v[96:111]
	s_waitcnt lgkmcnt(8)
	v_mfma_f32_32x32x16_bf16 v[80:95], v[128:131], v[152:155], v[80:95]
	s_waitcnt lgkmcnt(7)
	v_mfma_f32_32x32x16_bf16 v[64:79], v[128:131], v[156:159], v[64:79]
	s_waitcnt lgkmcnt(6)
	v_mfma_f32_32x32x16_bf16 v[48:63], v[132:135], v[144:147], v[48:63]
	v_mfma_f32_32x32x16_bf16 v[32:47], v[132:135], v[148:151], v[32:47]
	v_mfma_f32_32x32x16_bf16 v[16:31], v[132:135], v[152:155], v[16:31]
	v_mfma_f32_32x32x16_bf16 v[0:15], v[132:135], v[156:159], v[0:15]
	s_waitcnt lgkmcnt(4)
	v_mfma_f32_32x32x16_bf16 v[112:127], v[136:139], v[164:167], v[112:127]
	s_waitcnt lgkmcnt(3)
	v_mfma_f32_32x32x16_bf16 v[96:111], v[136:139], v[168:171], v[96:111]
	s_waitcnt lgkmcnt(2)
	v_mfma_f32_32x32x16_bf16 v[80:95], v[136:139], v[172:175], v[80:95]
	s_waitcnt lgkmcnt(1)
	v_mfma_f32_32x32x16_bf16 v[64:79], v[136:139], v[176:179], v[64:79]
	s_waitcnt lgkmcnt(0)
	v_mfma_f32_32x32x16_bf16 v[48:63], v[140:143], v[164:167], v[48:63]
	v_mfma_f32_32x32x16_bf16 v[32:47], v[140:143], v[168:171], v[32:47]
	v_mfma_f32_32x32x16_bf16 v[16:31], v[140:143], v[172:175], v[16:31]
	v_mfma_f32_32x32x16_bf16 v[0:15], v[140:143], v[176:179], v[0:15]
	s_waitcnt vmcnt(0)
	s_barrier
	s_mul_i32 s74, s71, 0x6000
	s_add_u32 s75, s74, 0x2000
	s_cmp_eq_u32 s71, 2
	s_cselect_b32 s75, 0x10000, s75
	v_add_u32_e32 v184, s74, v180
	v_add_u32_e32 v186, s75, v182
	v_add_u32_e32 v185, s74, v181
	v_add_u32_e32 v187, s75, v183
	ds_read_b128 v[128:131], v184
	ds_read_b128 v[144:147], v186
	ds_read_b128 v[148:151], v186 offset:2048
	ds_read_b128 v[152:155], v186 offset:4096
	ds_read_b128 v[156:159], v186 offset:6144
	ds_read_b128 v[132:135], v184 offset:2048
	ds_read_b128 v[136:139], v185
	ds_read_b128 v[164:167], v187
	ds_read_b128 v[168:171], v187 offset:2048
	ds_read_b128 v[172:175], v187 offset:4096
	ds_read_b128 v[176:179], v187 offset:6144
	ds_read_b128 v[140:143], v185 offset:2048
	s_add_u32 s71, s71, 1
	s_cmp_eq_u32 s71, 3
	s_cselect_b32 s71, 0, s71
	s_waitcnt lgkmcnt(10)
	v_mfma_f32_32x32x16_bf16 v[112:127], v[128:131], v[144:147], v[112:127]
	s_waitcnt lgkmcnt(9)
	v_mfma_f32_32x32x16_bf16 v[96:111], v[128:131], v[148:151], v[96:111]
	s_waitcnt lgkmcnt(8)
	v_mfma_f32_32x32x16_bf16 v[80:95], v[128:131], v[152:155], v[80:95]
	s_waitcnt lgkmcnt(7)
	v_mfma_f32_32x32x16_bf16 v[64:79], v[128:131], v[156:159], v[64:79]
	s_waitcnt lgkmcnt(6)
	v_mfma_f32_32x32x16_bf16 v[48:63], v[132:135], v[144:147], v[48:63]
	v_mfma_f32_32x32x16_bf16 v[32:47], v[132:135], v[148:151], v[32:47]
	v_mfma_f32_32x32x16_bf16 v[16:31], v[132:135], v[152:155], v[16:31]
	v_mfma_f32_32x32x16_bf16 v[0:15], v[132:135], v[156:159], v[0:15]
	s_waitcnt lgkmcnt(4)
	v_mfma_f32_32x32x16_bf16 v[112:127], v[136:139], v[164:167], v[112:127]
	s_waitcnt lgkmcnt(3)
	v_mfma_f32_32x32x16_bf16 v[96:111], v[136:139], v[168:171], v[96:111]
	s_waitcnt lgkmcnt(2)
	v_mfma_f32_32x32x16_bf16 v[80:95], v[136:139], v[172:175], v[80:95]
	s_waitcnt lgkmcnt(1)
	v_mfma_f32_32x32x16_bf16 v[64:79], v[136:139], v[176:179], v[64:79]
	s_waitcnt lgkmcnt(0)
	v_mfma_f32_32x32x16_bf16 v[48:63], v[140:143], v[164:167], v[48:63]
	v_mfma_f32_32x32x16_bf16 v[32:47], v[140:143], v[168:171], v[32:47]
	v_mfma_f32_32x32x16_bf16 v[16:31], v[140:143], v[172:175], v[16:31]
	v_mfma_f32_32x32x16_bf16 v[0:15], v[140:143], v[176:179], v[0:15]
	s_setprio 0
	s_nop 7
	v_readlane_b32 s64, v188, 0
	v_readlane_b32 s65, v188, 1
	v_readlane_b32 s66, v188, 2
	v_readlane_b32 s67, v188, 3
	v_readlane_b32 s68, v188, 4
	v_readlane_b32 s69, v188, 5
	v_readlane_b32 s70, v188, 6
	v_readlane_b32 s71, v188, 7
	v_readlane_b32 s72, v188, 8
	v_readlane_b32 s73, v188, 9
	v_readlane_b32 s74, v188, 10
	v_readlane_b32 s75, v188, 11
	v_readlane_b32 s76, v188, 12
	v_readlane_b32 s77, v188, 13
	v_readlane_b32 s78, v188, 14
	v_readlane_b32 s79, v188, 15
	s_nop 7
	s_branch .LBB0_118

; #define GA_LOAD(pr_) do { _Pragma("unroll") for (int i = 0; i < 4; ++i) ra[i] = *(const u32x4*)(Ab + (i * 32) * lda + (pr_) * 64); } while (0)
; #define GB_LOAD(kt_) do { const bfr* bk_ = Bb + (kt_) * NB * 32; \
;     _Pragma("unroll") for (int i = 0; i < 4; ++i) rb[i] = *(const u32x4*)(bk_ + (i * 64) * 32); } while (0)
; #define G_STORE(kt_) do { bfr* as_ = S0 + ((kt_) & 1) * GSTAGE; bfr* bs_ = as_ + 128 * 40; \
;     if (apar == ((kt_) & 1)) { _Pragma("unroll") for (int i = 0; i < 4; ++i) *(u32x4*)(as_ + asoff + i * 32 * 40) = ra[i]; } \
;     _Pragma("unroll") for (int i = 0; i < 4; ++i) *(u32x4*)(bs_ + bsoff + i * 64 * 40) = rb[i]; } while (0)
; template <int lda>
; DI void gemm_mainloop(const bfr* __restrict__ A, const bfr* __restrict__ Bt, int NB, int K, int m0, int n0, char* smem, f32x16 (&acc)[2][4]) {
;     ...
;   u32x4 ra[4], rb[4];
;   const int nk = K >> 5;
;   const int arow = tid >> 3, ac8 = tid & 7, apar = ac8 >> 2;
;   const bfr* Ab = A + (m0 + arow) * lda + ac8 * 8;
;   const int asoff = arow * 40 + (ac8 & 3) * 8;
;   const int brow = tid >> 2, bc4 = tid & 3;
;   const bfr* Bb = Bt + (n0 + brow) * 32 + bc4 * 8;
;   const int bsoff = brow * 40 + bc4 * 8;
;     ...
;   GA_LOAD(0);
;   GB_LOAD(0);
;   G_STORE(0);
;   GB_LOAD(1);
;   __syncthreads();
; template <bool FIRST, bool HAS_H>
; DI void phase_gemm_resid(const Params& p, const bfr* A, const bfr* Wt, const float* gnext, float* ss, char* smem) {
;     ...
;   for (int t0 = blockIdx.x; t0 < 128 * 4; t0 += gridDim.x) {
;     const int t = ((gridDim.x & 7) == 0) ? xcd_tile(t0, 4) : t0;
;     const int mt = t >> 2, nt = t & 3, m0 = mt * 128, n0 = nt * 256;
;     f32x16 acc[2][4];
;     gemm_mainloop<1024>(A, Wt, 1024, 1024, m0, n0, smem, acc);
.LBB0_843:
	s_lshl_b32 s5, s4, 5
	s_and_b32 s40, s5, 0xffffff80
	s_lshl_b32 s4, s4, 8
	s_and_b32 s39, s4, 0x300
	s_mov_b32 s41, 0
	s_mov_b64 s[24:25], 0
	s_lshl_b32 s98, s40, 11
	s_add_u32 s98, s12, s98
	s_addc_u32 s99, s13, 0
	s_lshl_b32 s100, s39, 6
	s_add_u32 s100, s6, s100
	s_addc_u32 s101, s7, 0
	v_writelane_b32 v187, s64, 0
	v_writelane_b32 v187, s65, 1
	v_writelane_b32 v187, s66, 2
	v_writelane_b32 v187, s67, 3
	v_writelane_b32 v187, s68, 4
	v_writelane_b32 v187, s69, 5
	v_writelane_b32 v187, s70, 6
	v_writelane_b32 v187, s71, 7
	v_writelane_b32 v187, s72, 8
	v_writelane_b32 v187, s73, 9
	v_writelane_b32 v187, s74, 10
	v_writelane_b32 v187, s75, 11
	v_writelane_b32 v187, s76, 12
	v_writelane_b32 v187, s77, 13
	v_writelane_b32 v187, s78, 14
	v_writelane_b32 v187, s79, 15
	v_lshrrev_b32_e32 v188, 6, v196
	v_and_b32_e32 v190, 63, v196
	v_readfirstlane_b32 s73, v188
	v_lshrrev_b32_e32 v191, 2, v190
	v_bfe_u32 v192, v190, 4, 2
	v_and_b32_e32 v188, 3, v190
	v_xor_b32_e32 v188, v188, v192
	v_lshlrev_b32_e32 v188, 4, v188
	v_lshl_add_u32 v176, v191, 11, v188
	v_add_u32_e32 v177, 0x8000, v176
	v_lshl_add_u32 v178, v191, 6, v188
	v_and_b32_e32 v191, 31, v190
	v_lshrrev_b32_e32 v192, 5, v190
	v_bfe_u32 v188, v190, 2, 2
	v_xor_b32_e32 v188, v188, v192
	v_lshlrev_b32_e32 v188, 4, v188
	v_lshl_add_u32 v179, v191, 6, v188
	s_lshr_b32 s74, s73, 1
	s_lshl_b32 s74, s74, 12
	s_and_b32 s75, s73, 1
	s_lshl_b32 s75, s75, 13
	v_add_u32_e32 v181, s75, v179
	v_add_u32_e32 v179, s74, v179
	v_xor_b32_e32 v182, 32, v181
	v_xor_b32_e32 v180, 32, v179
	s_lshl_b32 s74, s73, 16
	s_add_u32 s64, s98, s74
	s_addc_u32 s65, s99, 0
	s_lshl_b32 s74, s73, 12
	s_add_u32 s66, s100, s74
	s_addc_u32 s67, s101, 0
	s_lshl_b32 s68, s73, 11
	s_lshl_b32 s69, s73, 12
	s_mov_b32 s70, 0
	s_mov_b32 s71, 0
	s_mov_b32 s72, 0
	s_waitcnt lgkmcnt(0)
	s_barrier
	s_mul_i32 s74, s70, 0x6000
	s_add_u32 s75, s74, s68
	s_mov_b32 m0, s75
	s_add_u32 s76, s74, 0x2000
	s_cmp_eq_u32 s70, 2
	s_cselect_b32 s76, 0x10000, s76
	global_load_lds_dwordx4 v176, s[64:65]
	s_add_u32 m0, s75, 0x400
	s_add_u32 s76, s76, s69
	global_load_lds_dwordx4 v177, s[64:65]
	s_mov_b32 m0, s76
	s_add_u32 s64, s64, 64
	s_addc_u32 s65, s65, 0
	global_load_lds_dwordx4 v178, s[66:67]
	global_load_lds_dwordx4 v178, s[66:67] offset:1024
	global_load_lds_dwordx4 v178, s[66:67] offset:2048
	global_load_lds_dwordx4 v178, s[66:67] offset:3072
	s_add_u32 s66, s66, 0x10000
	s_addc_u32 s67, s67, 0
	s_add_u32 s70, s70, 1
	s_cmp_eq_u32 s70, 3
	s_cselect_b32 s70, 0, s70
	s_mul_i32 s74, s70, 0x6000
	s_add_u32 s75, s74, s68
	s_mov_b32 m0, s75
	s_add_u32 s76, s74, 0x2000
	s_cmp_eq_u32 s70, 2
	s_cselect_b32 s76, 0x10000, s76
	global_load_lds_dwordx4 v176, s[64:65]
	s_add_u32 m0, s75, 0x400
	s_add_u32 s76, s76, s69
	global_load_lds_dwordx4 v177, s[64:65]
	s_mov_b32 m0, s76
	s_add_u32 s64, s64, 64
	s_addc_u32 s65, s65, 0
	global_load_lds_dwordx4 v178, s[66:67]
	global_load_lds_dwordx4 v178, s[66:67] offset:1024
	global_load_lds_dwordx4 v178, s[66:67] offset:2048
	global_load_lds_dwordx4 v178, s[66:67] offset:3072
	s_add_u32 s66, s66, 0x10000
	s_addc_u32 s67, s67, 0
	s_add_u32 s70, s70, 1
	s_cmp_eq_u32 s70, 3
	s_cselect_b32 s70, 0, s70
	s_cmp_lt_u32 s46, 0x100
	s_cbranch_scc1 .Lp6_nostag
	s_sleep 8
	s_setprio 1

; #define MFMA32(a, b, c) __builtin_amdgcn_mfma_f32_32x32x16_bf16((a), (b), (c), 0, 0, 0)
; #define GA_LOAD(pr_) do { _Pragma("unroll") for (int i = 0; i < 4; ++i) ra[i] = *(const u32x4*)(Ab + (i * 32) * lda + (pr_) * 64); } while (0)
; #define GB_LOAD(kt_) do { const bfr* bk_ = Bb + (kt_) * NB * 32; \
;     _Pragma("unroll") for (int i = 0; i < 4; ++i) rb[i] = *(const u32x4*)(bk_ + (i * 64) * 32); } while (0)
; #define G_STORE(kt_) do { bfr* as_ = S0 + ((kt_) & 1) * GSTAGE; bfr* bs_ = as_ + 128 * 40; \
;     if (apar == ((kt_) & 1)) { _Pragma("unroll") for (int i = 0; i < 4; ++i) *(u32x4*)(as_ + asoff + i * 32 * 40) = ra[i]; } \
;     _Pragma("unroll") for (int i = 0; i < 4; ++i) *(u32x4*)(bs_ + bsoff + i * 64 * 40) = rb[i]; } while (0)
; template <int lda>
; DI void gemm_mainloop(const bfr* __restrict__ A, const bfr* __restrict__ Bt, int NB, int K, int m0, int n0, char* smem, f32x16 (&acc)[2][4]) {
;     ...
;   for (int kt = 0; kt < nk; ++kt) {
;     if (kt + 1 < nk) G_STORE(kt + 1);
;     if (kt + 2 < nk) {
;       GB_LOAD(kt + 2);
;       if ((kt & 1) == 0) GA_LOAD((kt >> 1) + 1);
;     }
;     const bfr* As = S0 + (kt & 1) * GSTAGE;
;     const bfr* Bs = As + 128 * 40;
; #pragma unroll
;     for (int ks = 0; ks < 2; ++ks) {
;       bf16x8 af[2], bfg[4];
; #pragma unroll
;       for (int i = 0; i < 2; ++i) af[i] = *(const bf16x8*)(As + (wr * 64 + i * 32 + r) * 40 + ks * 16 + hl * 8);
; #pragma unroll
;       for (int j = 0; j < 4; ++j) bfg[j] = *(const bf16x8*)(Bs + (wc * 128 + j * 32 + r) * 40 + ks * 16 + hl * 8);
; #pragma unroll
;       for (int i = 0; i < 2; ++i)
; #pragma unroll
;         for (int j = 0; j < 4; ++j) acc[i][j] = MFMA32(af[i], bfg[j], acc[i][j]);
;     }
;     __syncthreads();
;   }
.Lp6_loop:
	s_waitcnt vmcnt(6)
	s_barrier
	s_mul_i32 s74, s71, 0x6000
	s_add_u32 s75, s74, 0x2000
	s_cmp_eq_u32 s71, 2
	s_cselect_b32 s75, 0x10000, s75
	v_add_u32_e32 v183, s74, v179
	v_add_u32_e32 v185, s75, v181
	v_add_u32_e32 v184, s74, v180
	v_add_u32_e32 v186, s75, v182
	ds_read_b128 v[128:131], v183
	ds_read_b128 v[144:147], v185
	ds_read_b128 v[148:151], v185 offset:2048
	ds_read_b128 v[152:155], v185 offset:4096
	ds_read_b128 v[156:159], v185 offset:6144
	ds_read_b128 v[132:135], v183 offset:2048
	ds_read_b128 v[136:139], v184
	ds_read_b128 v[160:163], v186
	ds_read_b128 v[164:167], v186 offset:2048
	ds_read_b128 v[168:171], v186 offset:4096
	ds_read_b128 v[172:175], v186 offset:6144
	ds_read_b128 v[140:143], v184 offset:2048
	s_add_u32 s71, s71, 1
	s_cmp_eq_u32 s71, 3
	s_cselect_b32 s71, 0, s71
	s_waitcnt lgkmcnt(10)
	v_mfma_f32_32x32x16_bf16 v[112:127], v[128:131], v[144:147], v[112:127]
	s_mul_i32 s74, s70, 0x6000
	s_add_u32 s75, s74, s68
	s_mov_b32 m0, s75
	s_add_u32 s76, s74, 0x2000
	s_cmp_eq_u32 s70, 2
	s_cselect_b32 s76, 0x10000, s76
	global_load_lds_dwordx4 v176, s[64:65]
	s_waitcnt lgkmcnt(9)
	v_mfma_f32_32x32x16_bf16 v[96:111], v[128:131], v[148:151], v[96:111]
	s_add_u32 m0, s75, 0x400
	s_add_u32 s76, s76, s69
	global_load_lds_dwordx4 v177, s[64:65]
	s_waitcnt lgkmcnt(8)
	v_mfma_f32_32x32x16_bf16 v[80:95], v[128:131], v[152:155], v[80:95]
	s_mov_b32 m0, s76
	s_add_u32 s64, s64, 64
	s_addc_u32 s65, s65, 0
	global_load_lds_dwordx4 v178, s[66:67]
	s_waitcnt lgkmcnt(7)
	v_mfma_f32_32x32x16_bf16 v[64:79], v[128:131], v[156:159], v[64:79]
	global_load_lds_dwordx4 v178, s[66:67] offset:1024
	s_waitcnt lgkmcnt(6)
	v_mfma_f32_32x32x16_bf16 v[48:63], v[132:135], v[144:147], v[48:63]
	global_load_lds_dwordx4 v178, s[66:67] offset:2048
	v_mfma_f32_32x32x16_bf16 v[32:47], v[132:135], v[148:151], v[32:47]
	global_load_lds_dwordx4 v178, s[66:67] offset:3072
	s_add_u32 s66, s66, 0x10000
	s_addc_u32 s67, s67, 0
	v_mfma_f32_32x32x16_bf16 v[16:31], v[132:135], v[152:155], v[16:31]
	s_add_u32 s70, s70, 1
	s_cmp_eq_u32 s70, 3
	s_cselect_b32 s70, 0, s70
	v_mfma_f32_32x32x16_bf16 v[0:15], v[132:135], v[156:159], v[0:15]
	s_waitcnt lgkmcnt(4)
	v_mfma_f32_32x32x16_bf16 v[112:127], v[136:139], v[160:163], v[112:127]
	s_waitcnt lgkmcnt(3)
	v_mfma_f32_32x32x16_bf16 v[96:111], v[136:139], v[164:167], v[96:111]
	s_waitcnt lgkmcnt(2)
	v_mfma_f32_32x32x16_bf16 v[80:95], v[136:139], v[168:171], v[80:95]
	s_waitcnt lgkmcnt(1)
	v_mfma_f32_32x32x16_bf16 v[64:79], v[136:139], v[172:175], v[64:79]
	s_waitcnt lgkmcnt(0)
	v_mfma_f32_32x32x16_bf16 v[48:63], v[140:143], v[160:163], v[48:63]
	v_mfma_f32_32x32x16_bf16 v[32:47], v[140:143], v[164:167], v[32:47]
	v_mfma_f32_32x32x16_bf16 v[16:31], v[140:143], v[168:171], v[16:31]
	v_mfma_f32_32x32x16_bf16 v[0:15], v[140:143], v[172:175], v[0:15]
	s_add_u32 s72, s72, 1
	s_cmp_lt_u32 s72, 30
	s_cbranch_scc1 .Lp6_loop
	s_waitcnt vmcnt(6)
	s_barrier
	s_mul_i32 s74, s71, 0x6000
	s_add_u32 s75, s74, 0x2000
	s_cmp_eq_u32 s71, 2
	s_cselect_b32 s75, 0x10000, s75
	v_add_u32_e32 v183, s74, v179
	v_add_u32_e32 v185, s75, v181
	v_add_u32_e32 v184, s74, v180
	v_add_u32_e32 v186, s75, v182
	ds_read_b128 v[128:131], v183
	ds_read_b128 v[144:147], v185
	ds_read_b128 v[148:151], v185 offset:2048
	ds_read_b128 v[152:155], v185 offset:4096
	ds_read_b128 v[156:159], v185 offset:6144
	ds_read_b128 v[132:135], v183 offset:2048
	ds_read_b128 v[136:139], v184
	ds_read_b128 v[160:163], v186
	ds_read_b128 v[164:167], v186 offset:2048
	ds_read_b128 v[168:171], v186 offset:4096
	ds_read_b128 v[172:175], v186 offset:6144
	ds_read_b128 v[140:143], v184 offset:2048
	s_add_u32 s71, s71, 1
	s_cmp_eq_u32 s71, 3
	s_cselect_b32 s71, 0, s71
	s_waitcnt lgkmcnt(10)
	v_mfma_f32_32x32x16_bf16 v[112:127], v[128:131], v[144:147], v[112:127]
	s_waitcnt lgkmcnt(9)
	v_mfma_f32_32x32x16_bf16 v[96:111], v[128:131], v[148:151], v[96:111]
	s_waitcnt lgkmcnt(8)
	v_mfma_f32_32x32x16_bf16 v[80:95], v[128:131], v[152:155], v[80:95]
	s_waitcnt lgkmcnt(7)
	v_mfma_f32_32x32x16_bf16 v[64:79], v[128:131], v[156:159], v[64:79]
	s_waitcnt lgkmcnt(6)
	v_mfma_f32_32x32x16_bf16 v[48:63], v[132:135], v[144:147], v[48:63]
	v_mfma_f32_32x32x16_bf16 v[32:47], v[132:135], v[148:151], v[32:47]
	v_mfma_f32_32x32x16_bf16 v[16:31], v[132:135], v[152:155], v[16:31]
	v_mfma_f32_32x32x16_bf16 v[0:15], v[132:135], v[156:159], v[0:15]
	s_waitcnt lgkmcnt(4)
	v_mfma_f32_32x32x16_bf16 v[112:127], v[136:139], v[160:163], v[112:127]
	s_waitcnt lgkmcnt(3)
	v_mfma_f32_32x32x16_bf16 v[96:111], v[136:139], v[164:167], v[96:111]
	s_waitcnt lgkmcnt(2)
	v_mfma_f32_32x32x16_bf16 v[80:95], v[136:139], v[168:171], v[80:95]
	s_waitcnt lgkmcnt(1)
	v_mfma_f32_32x32x16_bf16 v[64:79], v[136:139], v[172:175], v[64:79]
	s_waitcnt lgkmcnt(0)
	v_mfma_f32_32x32x16_bf16 v[48:63], v[140:143], v[160:163], v[48:63]
	v_mfma_f32_32x32x16_bf16 v[32:47], v[140:143], v[164:167], v[32:47]
	v_mfma_f32_32x32x16_bf16 v[16:31], v[140:143], v[168:171], v[16:31]
	v_mfma_f32_32x32x16_bf16 v[0:15], v[140:143], v[172:175], v[0:15]
	s_waitcnt vmcnt(0)
	s_barrier
; #define MFMA32(a, b, c) __builtin_amdgcn_mfma_f32_32x32x16_bf16((a), (b), (c), 0, 0, 0)
; template <int lda>
; DI void gemm_mainloop(const bfr* __restrict__ A, const bfr* __restrict__ Bt, int NB, int K, int m0, int n0, char* smem, f32x16 (&acc)[2][4]) {
;     ...
;     const bfr* As = S0 + (kt & 1) * GSTAGE;
;     const bfr* Bs = As + 128 * 40;
; #pragma unroll
;     for (int ks = 0; ks < 2; ++ks) {
;       bf16x8 af[2], bfg[4];
; #pragma unroll
;       for (int i = 0; i < 2; ++i) af[i] = *(const bf16x8*)(As + (wr * 64 + i * 32 + r) * 40 + ks * 16 + hl * 8);
; #pragma unroll
;       for (int j = 0; j < 4; ++j) bfg[j] = *(const bf16x8*)(Bs + (wc * 128 + j * 32 + r) * 40 + ks * 16 + hl * 8);
; #pragma unroll
;       for (int i = 0; i < 2; ++i)
; #pragma unroll
;         for (int j = 0; j < 4; ++j) acc[i][j] = MFMA32(af[i], bfg[j], acc[i][j]);
;     }
;     __syncthreads();
; template <bool FIRST, bool HAS_H>
; DI void phase_gemm_resid(const Params& p, const bfr* A, const bfr* Wt, const float* gnext, float* ss, char* smem) {
;     ...
;     int tid2 = threadIdx.x;
;     asm volatile("" : "+v"(tid2));
;     const int lane = tid2 & 63, wid = tid2 >> 6, wr = wid >> 1, wc = wid & 1, r = lane & 31, hl = lane >> 5;
;     const float* xsrc = FIRST ? p.x_prompt : X;
;     const int rbase = m0 + wr * 64 + 4 * hl, cbase = n0 + wc * 128 + r;
; #pragma unroll
;     for (int i = 0; i < 2; ++i) {
; #pragma unroll
;       for (int qh = 0; qh < 2; ++qh) {
;         float rs[8];
; #pragma unroll
;         for (int q = 0; q < 8; ++q) rs[q] = 0.f;
; #pragma unroll
;         for (int jh = 0; jh < 2; ++jh) {
;           float xo[2][8];
; #pragma unroll
;           for (int jj = 0; jj < 2; ++jj)
; #pragma unroll
;             for (int q = 0; q < 8; ++q)
;               xo[jj][q] = xsrc[(rbase + i * 32 + crow(qh * 8 + q, 0)) * 1024 + cbase + (jh * 2 + jj) * 32];
; #pragma unroll
;           for (int q = 0; q < 8; ++q) {
;             const int o = (rbase + i * 32 + crow(qh * 8 + q, 0)) * 1024 + cbase;
; #pragma unroll
;             for (int jj = 0; jj < 2; ++jj) {
;               const int j = jh * 2 + jj;
;               const float xn = xo[jj][q] + acc[i][j][qh * 8 + q];
;               X[o + j * 32] = xn;
;               if (HAS_H) Hn[o + j * 32] = f2bf(xn * gnext[cbase + j * 32]);
;               rs[q] += xn * xn;
;             }
;           }
;         }
	s_mul_i32 s74, s71, 0x6000
	s_add_u32 s75, s74, 0x2000
	s_cmp_eq_u32 s71, 2
	s_cselect_b32 s75, 0x10000, s75
	v_add_u32_e32 v183, s74, v179
	v_add_u32_e32 v185, s75, v181
	v_add_u32_e32 v184, s74, v180
	v_add_u32_e32 v186, s75, v182
	ds_read_b128 v[128:131], v183
	ds_read_b128 v[144:147], v185
	ds_read_b128 v[148:151], v185 offset:2048
	ds_read_b128 v[152:155], v185 offset:4096
	ds_read_b128 v[156:159], v185 offset:6144
	ds_read_b128 v[132:135], v183 offset:2048
	ds_read_b128 v[136:139], v184
	ds_read_b128 v[160:163], v186
	ds_read_b128 v[164:167], v186 offset:2048
	ds_read_b128 v[168:171], v186 offset:4096
	ds_read_b128 v[172:175], v186 offset:6144
	ds_read_b128 v[140:143], v184 offset:2048
	s_add_u32 s71, s71, 1
	s_cmp_eq_u32 s71, 3
	s_cselect_b32 s71, 0, s71
	s_waitcnt lgkmcnt(10)
	v_mfma_f32_32x32x16_bf16 v[112:127], v[128:131], v[144:147], v[112:127]
	s_waitcnt lgkmcnt(9)
	v_mfma_f32_32x32x16_bf16 v[96:111], v[128:131], v[148:151], v[96:111]
	s_waitcnt lgkmcnt(8)
	v_mfma_f32_32x32x16_bf16 v[80:95], v[128:131], v[152:155], v[80:95]
	s_waitcnt lgkmcnt(7)
	v_mfma_f32_32x32x16_bf16 v[64:79], v[128:131], v[156:159], v[64:79]
	s_waitcnt lgkmcnt(6)
	v_mfma_f32_32x32x16_bf16 v[48:63], v[132:135], v[144:147], v[48:63]
	v_mfma_f32_32x32x16_bf16 v[32:47], v[132:135], v[148:151], v[32:47]
	v_mfma_f32_32x32x16_bf16 v[16:31], v[132:135], v[152:155], v[16:31]
	v_mfma_f32_32x32x16_bf16 v[0:15], v[132:135], v[156:159], v[0:15]
	s_waitcnt lgkmcnt(4)
	v_mfma_f32_32x32x16_bf16 v[112:127], v[136:139], v[160:163], v[112:127]
	s_waitcnt lgkmcnt(3)
	v_mfma_f32_32x32x16_bf16 v[96:111], v[136:139], v[164:167], v[96:111]
	s_waitcnt lgkmcnt(2)
	v_mfma_f32_32x32x16_bf16 v[80:95], v[136:139], v[168:171], v[80:95]
	s_waitcnt lgkmcnt(1)
	v_mfma_f32_32x32x16_bf16 v[64:79], v[136:139], v[172:175], v[64:79]
	s_waitcnt lgkmcnt(0)
	v_mfma_f32_32x32x16_bf16 v[48:63], v[140:143], v[160:163], v[48:63]
	v_mfma_f32_32x32x16_bf16 v[32:47], v[140:143], v[164:167], v[32:47]
	v_mfma_f32_32x32x16_bf16 v[16:31], v[140:143], v[168:171], v[16:31]
	v_mfma_f32_32x32x16_bf16 v[0:15], v[140:143], v[172:175], v[0:15]
	s_setprio 0
	s_nop 7
	v_readlane_b32 s64, v187, 0
	v_readlane_b32 s65, v187, 1
	v_readlane_b32 s66, v187, 2
	v_readlane_b32 s67, v187, 3
	v_readlane_b32 s68, v187, 4
	v_readlane_b32 s69, v187, 5
	v_readlane_b32 s70, v187, 6
	v_readlane_b32 s71, v187, 7
	v_readlane_b32 s72, v187, 8
	v_readlane_b32 s73, v187, 9
	v_readlane_b32 s74, v187, 10
	v_readlane_b32 s75, v187, 11
	v_readlane_b32 s76, v187, 12
	v_readlane_b32 s77, v187, 13
	v_readlane_b32 s78, v187, 14
	v_readlane_b32 s79, v187, 15
	s_nop 7
	s_waitcnt vmcnt(1)
	s_nop 0
	s_nop 0
	s_nop 0
	s_waitcnt vmcnt(0)
	s_nop 0
	v_add_u32_e32 v136, v169, v171
	s_nop 0
	v_add_u32_e32 v188, v169, v170
	s_nop 0
	s_nop 0
	s_nop 0
	s_nop 0
	s_nop 0
	s_nop 0
	s_nop 0
	s_nop 0
	s_nop 0
	s_nop 0
	s_nop 0
	s_waitcnt lgkmcnt(0)
	s_nop 0
	s_nop 0
	s_nop 0
	s_nop 0
	s_nop 0
	s_nop 0
	s_nop 0
	s_nop 0
	s_nop 0
	s_nop 0
	s_nop 0
	s_nop 0
	s_nop 0
	s_nop 0
	s_nop 0
	s_nop 0
	s_nop 0
	s_nop 0
	v_mov_b32_e32 v188, v196
	s_waitcnt lgkmcnt(0)
	s_nop 0
	s_nop 0
	v_ashrrev_i32_e32 v190, 1, v188
	v_and_b32_e32 v190, 0xffffffc0, v190
	v_and_b32_e32 v225, 31, v188
	v_add_u32_e32 v190, s40, v190
	v_lshrrev_b32_e32 v191, 3, v188
	v_lshlrev_b32_e32 v188, 1, v188
	v_and_or_b32 v224, v191, 4, v190
	v_and_b32_e32 v188, 0x80, v188
	v_or3_b32 v197, s39, v188, v225
	v_lshlrev_b32_e32 v199, 10, v224
	v_or_b32_e32 v190, v199, v197
	v_ashrrev_i32_e32 v191, 31, v190
	v_lshlrev_b64 v[192:193], 2, v[190:191]
	s_nop 0
	v_lshl_add_u64 v[194:195], s[18:19], 0, v[192:193]
	global_load_dword v188, v[194:195], off
	v_or_b32_e32 v198, 32, v197
	v_or_b32_e32 v226, 0x2400, v199
	v_or_b32_e32 v228, 0x2800, v199
	v_or_b32_e32 v229, 0x2c00, v199
	v_lshl_add_u64 v[192:193], s[16:17], 0, v[192:193]
	s_nop 0
	v_or_b32_e32 v216, 0x400, v199
	v_or_b32_e32 v194, v216, v197
	v_ashrrev_i32_e32 v195, 31, v194
	v_or_b32_e32 v217, 0x800, v199
	v_lshl_add_u64 v[212:213], v[194:195], 2, s[18:19]
	v_or_b32_e32 v214, v217, v197
	v_ashrrev_i32_e32 v195, 31, v199
	v_mov_b32_e32 v194, v190
	v_ashrrev_i32_e32 v215, 31, v214
	v_lshl_add_u64 v[194:195], v[194:195], 2, s[18:19]
	global_load_dword v218, v[194:195], off offset:128
	v_lshl_add_u64 v[214:215], v[214:215], 2, s[18:19]
	global_load_dword v219, v[212:213], off
	global_load_dword v220, v[214:215], off
	v_or_b32_e32 v212, v216, v198
	v_ashrrev_i32_e32 v213, 31, v212
	v_lshl_add_u64 v[212:213], v[212:213], 2, s[18:19]
	global_load_dword v222, v[212:213], off
	s_nop 0
	v_or_b32_e32 v221, 0xc00, v199
	v_or_b32_e32 v223, 0x2000, v199
	v_or_b32_e32 v214, v223, v197
	v_ashrrev_i32_e32 v215, 31, v214
	v_lshl_add_u64 v[214:215], v[214:215], 2, s[18:19]
	v_cmp_eq_u32_e32 vcc, 31, v225
	v_ashrrev_i32_e32 v225, 31, v224
	s_nop 0
	s_nop 0
	s_nop 0
	v_or_b32_e32 v200, v217, v198
	v_ashrrev_i32_e32 v201, 31, v200
	v_lshl_add_u64 v[200:201], v[200:201], 2, s[18:19]
	global_load_dword v227, v[200:201], off
	v_or_b32_e32 v212, v221, v197
	v_or_b32_e32 v200, v226, v197
	v_or_b32_e32 v202, v228, v197
	s_nop 0
	v_ashrrev_i32_e32 v213, 31, v212
	v_ashrrev_i32_e32 v201, 31, v200
	v_ashrrev_i32_e32 v203, 31, v202
	v_lshl_add_u64 v[212:213], v[212:213], 2, s[18:19]
	v_lshl_add_u64 v[200:201], v[200:201], 2, s[18:19]
	v_lshl_add_u64 v[202:203], v[202:203], 2, s[18:19]
	s_nop 0
	s_nop 0
	s_nop 0
	s_nop 0
	v_or_b32_e32 v204, v229, v197
	v_ashrrev_i32_e32 v205, 31, v204
	v_lshl_add_u64 v[204:205], v[204:205], 2, s[18:19]
	v_or_b32_e32 v206, v228, v198
	v_ashrrev_i32_e32 v207, 31, v206
	v_lshl_add_u64 v[206:207], v[206:207], 2, s[18:19]
	s_waitcnt vmcnt(0)
; DI bfr f2bf(float a) { return (bfr)(pack2(a, 0.f) & 0xffffu); }
; DI int crow(int reg, int h) { return (reg & 3) + 8 * (reg >> 2) + 4 * h; }
; template <bool FIRST, bool HAS_H>
; DI void phase_gemm_resid(const Params& p, const bfr* A, const bfr* Wt, const float* gnext, float* ss, char* smem) {
;     ...
;     int tid2 = threadIdx.x;
;     asm volatile("" : "+v"(tid2));
;     const int lane = tid2 & 63, wid = tid2 >> 6, wr = wid >> 1, wc = wid & 1, r = lane & 31, hl = lane >> 5;
;     const float* xsrc = FIRST ? p.x_prompt : X;
;     const int rbase = m0 + wr * 64 + 4 * hl, cbase = n0 + wc * 128 + r;
; #pragma unroll
;     for (int i = 0; i < 2; ++i) {
; #pragma unroll
;       for (int qh = 0; qh < 2; ++qh) {
;         float rs[8];
; #pragma unroll
;         for (int q = 0; q < 8; ++q) rs[q] = 0.f;
; #pragma unroll
;         for (int jh = 0; jh < 2; ++jh) {
;           float xo[2][8];
; #pragma unroll
;           for (int jj = 0; jj < 2; ++jj)
; #pragma unroll
;             for (int q = 0; q < 8; ++q)
;               xo[jj][q] = xsrc[(rbase + i * 32 + crow(qh * 8 + q, 0)) * 1024 + cbase + (jh * 2 + jj) * 32];
; #pragma unroll
;           for (int q = 0; q < 8; ++q) {
;             const int o = (rbase + i * 32 + crow(qh * 8 + q, 0)) * 1024 + cbase;
; #pragma unroll
;             for (int jj = 0; jj < 2; ++jj) {
;               const int j = jh * 2 + jj;
;               const float xn = xo[jj][q] + acc[i][j][qh * 8 + q];
;               X[o + j * 32] = xn;
;               if (HAS_H) Hn[o + j * 32] = f2bf(xn * gnext[cbase + j * 32]);
;               rs[q] += xn * xn;
;             }
;           }
;         }
	s_nop 3
	v_add_f32_e32 v98, v98, v227
	s_nop 0
	global_load_dword v210, v[212:213], off
	global_load_dword v211, v[214:215], off
	s_nop 0
	global_load_dword v212, v[200:201], off
	global_load_dword v213, v[202:203], off
	global_load_dword v214, v[204:205], off
	v_or_b32_e32 v200, v221, v198
	v_or_b32_e32 v202, v223, v198
	v_or_b32_e32 v204, v226, v198
	v_ashrrev_i32_e32 v201, 31, v200
	v_ashrrev_i32_e32 v203, 31, v202
	v_ashrrev_i32_e32 v205, 31, v204
	v_or_b32_e32 v208, v229, v198
	v_lshl_add_u64 v[200:201], v[200:201], 2, s[18:19]
	v_lshl_add_u64 v[202:203], v[202:203], 2, s[18:19]
	v_lshl_add_u64 v[204:205], v[204:205], 2, s[18:19]
	v_ashrrev_i32_e32 v209, 31, v208
	v_lshl_add_u64 v[208:209], v[208:209], 2, s[18:19]
	global_load_dword v200, v[200:201], off
	s_nop 0
	global_load_dword v201, v[202:203], off
	s_nop 0
	global_load_dword v202, v[204:205], off
	global_load_dword v203, v[206:207], off
	s_nop 0
	global_load_dword v204, v[208:209], off
	v_add_f32_e32 v205, v112, v188
	v_or_b32_e32 v112, 0x400, v190
	global_store_dword v[192:193], v205, off
	v_lshlrev_b32_e32 v188, 2, v197
	v_add_f32_e32 v207, v96, v218
	v_add_f32_e32 v209, v113, v219
	v_ashrrev_i32_e32 v113, 31, v112
	v_or_b32_e32 v96, 0x420, v190
	global_load_dword v206, v188, s[14:15]
	s_nop 0
	global_store_dword v[192:193], v207, off offset:128
	v_lshl_add_u64 v[112:113], v[112:113], 2, s[16:17]
	v_add_f32_e32 v185, v97, v222
	v_ashrrev_i32_e32 v97, 31, v96
	global_load_dword v208, v188, s[14:15] offset:128
	v_lshl_add_u64 v[96:97], v[96:97], 2, s[16:17]
	global_store_dword v[112:113], v209, off
	s_nop 0
	v_or_b32_e32 v172, 0x800, v190
	v_ashrrev_i32_e32 v173, 31, v172
	global_load_dword v184, v188, s[14:15]
	v_add_f32_e32 v177, v114, v220
	global_store_dword v[96:97], v185, off
	v_lshl_add_u64 v[96:97], v[172:173], 2, s[16:17]
	v_or_b32_e32 v174, 0x820, v190
	global_load_dword v176, v188, s[14:15] offset:128
	v_ashrrev_i32_e32 v175, 31, v174
	global_store_dword v[96:97], v177, off
	global_load_dword v178, v188, s[14:15]
	v_lshl_add_u64 v[96:97], v[174:175], 2, s[16:17]
	global_store_dword v[96:97], v98, off
	global_load_dword v179, v188, s[14:15] offset:128
	s_nop 0
	v_lshl_add_u64 v[158:159], v[172:173], 1, s[10:11]
	v_lshl_add_u64 v[96:97], v[224:225], 2, s[8:9]
	s_waitcnt vmcnt(21)
	v_add_f32_e32 v115, v115, v210
	s_nop 0
	s_waitcnt vmcnt(10)
	v_mul_f32_e32 v112, v205, v206
	s_nop 0
	v_cvt_pk_bf16_f32 v114, v112, s0
	v_lshl_add_u64 v[112:113], v[190:191], 1, s[10:11]
	global_store_short v[112:113], v114, off
	s_waitcnt vmcnt(9)
	v_mul_f32_e32 v114, v207, v208
	v_cvt_pk_bf16_f32 v114, v114, s0
	global_store_short v[112:113], v114, off offset:64
	s_nop 0
	v_or_b32_e32 v154, 0xc00, v190
	v_ashrrev_i32_e32 v155, 31, v154
	v_mul_f32_e32 v152, v98, v98
	s_waitcnt vmcnt(8)
	v_mul_f32_e32 v156, v209, v184
	v_cvt_pk_bf16_f32 v156, v156, s0
	global_store_short v[112:113], v156, off offset:2048
	v_mul_f32_e32 v114, v207, v207
	s_nop 0
	v_add_f32_e32 v169, v119, v214
	v_add_f32_e32 v171, v103, v204
	s_waitcnt vmcnt(5)
	v_mul_f32_e32 v157, v177, v178
	v_cvt_pk_bf16_f32 v157, v157, s0
	global_store_short v[158:159], v157, off
	s_waitcnt vmcnt(4)
	v_mul_f32_e32 v157, v98, v179
	v_cvt_pk_bf16_f32 v157, v157, s0
	v_lshl_add_u64 v[158:159], v[174:175], 1, s[10:11]
	s_nop 0
	global_store_short v[158:159], v157, off
	v_lshl_add_u64 v[158:159], v[154:155], 2, s[16:17]
	global_store_dword v[158:159], v115, off
	global_load_dword v153, v188, s[14:15]
	v_or_b32_e32 v158, 0xc20, v190
	v_ashrrev_i32_e32 v159, 31, v158
	v_add_f32_e32 v157, v99, v200
	v_lshl_add_u64 v[98:99], v[158:159], 2, s[16:17]
	global_store_dword v[98:99], v157, off
	s_nop 0
	global_load_dword v160, v188, s[14:15] offset:128
	v_add_f32_e32 v161, v100, v201
	v_add_f32_e32 v163, v117, v212
	v_add_f32_e32 v165, v118, v213
	v_add_f32_e32 v167, v102, v203
	v_mul_f32_e32 v156, v185, v176
	v_cvt_pk_bf16_f32 v156, v156, s0
	s_nop 0
	v_or_b32_e32 v148, 0x2000, v190
	v_ashrrev_i32_e32 v149, 31, v148
	v_add_f32_e32 v150, v116, v211
	v_lshl_add_u64 v[98:99], v[148:149], 2, s[16:17]
	global_store_dword v[98:99], v150, off
	global_load_dword v151, v188, s[14:15]
	v_or_b32_e32 v116, 0x2400, v190
	s_nop 0
	v_or_b32_e32 v140, 0x2020, v190
	v_ashrrev_i32_e32 v141, 31, v140
	v_lshl_add_u64 v[98:99], v[140:141], 2, s[16:17]
	global_store_dword v[98:99], v161, off
	global_load_dword v162, v188, s[14:15] offset:128
	v_ashrrev_i32_e32 v117, 31, v116
	v_lshl_add_u64 v[98:99], v[116:117], 2, s[16:17]
	v_or_b32_e32 v142, 0x2420, v190
	global_store_dword v[98:99], v163, off
	v_ashrrev_i32_e32 v143, 31, v142
	s_nop 0
	global_load_dword v146, v188, s[14:15]
	v_add_f32_e32 v147, v101, v202
	v_lshl_add_u64 v[98:99], v[142:143], 2, s[16:17]
	global_store_dword v[98:99], v147, off
	global_load_dword v164, v188, s[14:15] offset:128
	v_lshl_add_u64 v[116:117], v[116:117], 1, s[10:11]
	global_store_short v[112:113], v156, off offset:2112
	s_nop 0
	v_or_b32_e32 v136, 0x2800, v190
	v_ashrrev_i32_e32 v137, 31, v136
	v_lshl_add_u64 v[98:99], v[136:137], 2, s[16:17]
	global_store_dword v[98:99], v165, off
	global_load_dword v166, v188, s[14:15]
	v_mul_f32_e32 v156, v185, v185
	v_fmac_f32_e32 v114, v205, v205
	s_nop 0
	v_or_b32_e32 v128, 0x2820, v190
	v_ashrrev_i32_e32 v129, 31, v128
	v_lshl_add_u64 v[98:99], v[128:129], 2, s[16:17]
	global_store_dword v[98:99], v167, off
	global_load_dword v168, v188, s[14:15] offset:128
	v_or_b32_e32 v98, 0x2c00, v190
	v_ashrrev_i32_e32 v99, 31, v98
	v_lshl_add_u64 v[100:101], v[98:99], 2, s[16:17]
	global_store_dword v[100:101], v169, off
	global_load_dword v170, v188, s[14:15]
	v_or_b32_e32 v100, 0x2c20, v190
	v_ashrrev_i32_e32 v101, 31, v100
	v_lshl_add_u64 v[102:103], v[100:101], 2, s[16:17]
	global_store_dword v[102:103], v171, off
	v_or_b32_e32 v102, 64, v197
	v_or_b32_e32 v118, v216, v102
	v_or_b32_e32 v130, v217, v102
	v_or_b32_e32 v132, v221, v102
	v_or_b32_e32 v134, v223, v102
	v_ashrrev_i32_e32 v119, 31, v118
	v_ashrrev_i32_e32 v131, 31, v130
	v_ashrrev_i32_e32 v133, 31, v132
	v_ashrrev_i32_e32 v135, 31, v134
	v_or_b32_e32 v138, v226, v102
	v_or_b32_e32 v144, v228, v102
	v_lshl_add_u64 v[118:119], v[118:119], 2, s[18:19]
	v_lshl_add_u64 v[130:131], v[130:131], 2, s[18:19]
	v_lshl_add_u64 v[132:133], v[132:133], 2, s[18:19]
	v_lshl_add_u64 v[134:135], v[134:135], 2, s[18:19]
	v_ashrrev_i32_e32 v139, 31, v138
	v_ashrrev_i32_e32 v145, 31, v144
	s_waitcnt vmcnt(18)
; DI bfr f2bf(float a) { return (bfr)(pack2(a, 0.f) & 0xffffu); }
; DI int crow(int reg, int h) { return (reg & 3) + 8 * (reg >> 2) + 4 * h; }
; template <bool FIRST, bool HAS_H>
; DI void phase_gemm_resid(const Params& p, const bfr* A, const bfr* Wt, const float* gnext, float* ss, char* smem) {
;     ...
;     int tid2 = threadIdx.x;
;     asm volatile("" : "+v"(tid2));
;     const int lane = tid2 & 63, wid = tid2 >> 6, wr = wid >> 1, wc = wid & 1, r = lane & 31, hl = lane >> 5;
;     const float* xsrc = FIRST ? p.x_prompt : X;
;     const int rbase = m0 + wr * 64 + 4 * hl, cbase = n0 + wc * 128 + r;
; #pragma unroll
;     for (int i = 0; i < 2; ++i) {
; #pragma unroll
;       for (int qh = 0; qh < 2; ++qh) {
;         float rs[8];
; #pragma unroll
;         for (int q = 0; q < 8; ++q) rs[q] = 0.f;
; #pragma unroll
;         for (int jh = 0; jh < 2; ++jh) {
;           float xo[2][8];
; #pragma unroll
;           for (int jj = 0; jj < 2; ++jj)
; #pragma unroll
;             for (int q = 0; q < 8; ++q)
;               xo[jj][q] = xsrc[(rbase + i * 32 + crow(qh * 8 + q, 0)) * 1024 + cbase + (jh * 2 + jj) * 32];
; #pragma unroll
;           for (int q = 0; q < 8; ++q) {
;             const int o = (rbase + i * 32 + crow(qh * 8 + q, 0)) * 1024 + cbase;
; #pragma unroll
;             for (int jj = 0; jj < 2; ++jj) {
;               const int j = jh * 2 + jj;
;               const float xn = xo[jj][q] + acc[i][j][qh * 8 + q];
;               X[o + j * 32] = xn;
;               if (HAS_H) Hn[o + j * 32] = f2bf(xn * gnext[cbase + j * 32]);
;               rs[q] += xn * xn;
;             }
;           }
;         }
	v_mul_f32_e32 v103, v115, v153
	v_lshl_add_u64 v[138:139], v[138:139], 2, s[18:19]
	v_lshl_add_u64 v[144:145], v[144:145], 2, s[18:19]
	global_load_dword v172, v[194:195], off offset:256
	global_load_dword v173, v[118:119], off
	s_nop 0
	global_load_dword v130, v[130:131], off
	s_nop 0
	global_load_dword v131, v[132:133], off
	s_nop 0
	global_load_dword v132, v[134:135], off
	global_load_dword v133, v[138:139], off
	s_nop 0
	global_load_dword v134, v[144:145], off
	global_load_dword v135, v[194:195], off offset:384
	v_cvt_pk_bf16_f32 v103, v103, s0
	v_lshl_add_u64 v[118:119], v[154:155], 1, s[10:11]
	global_store_short v[118:119], v103, off
	v_or_b32_e32 v103, 0x60, v197
	v_or_b32_e32 v118, v216, v103
	v_ashrrev_i32_e32 v119, 31, v118
	v_lshl_add_u64 v[118:119], v[118:119], 2, s[18:19]
	global_load_dword v138, v[118:119], off
	s_waitcnt vmcnt(26)
	v_mul_f32_e32 v118, v157, v160
	v_cvt_pk_bf16_f32 v139, v118, s0
	v_lshl_add_u64 v[118:119], v[158:159], 1, s[10:11]
	global_store_short v[118:119], v139, off
	v_or_b32_e32 v118, v217, v103
	v_mul_f32_e32 v139, v157, v157
	v_ashrrev_i32_e32 v119, 31, v118
	v_fmac_f32_e32 v139, v115, v115
	s_waitcnt vmcnt(25)
	v_mul_f32_e32 v115, v150, v151
	v_lshl_add_u64 v[118:119], v[118:119], 2, s[18:19]
	v_cvt_pk_bf16_f32 v115, v115, s0
	global_load_dword v144, v[118:119], off
	v_lshl_add_u64 v[118:119], v[148:149], 1, s[10:11]
	global_store_short v[118:119], v115, off
	s_waitcnt vmcnt(25)
	v_mul_f32_e32 v115, v161, v162
	v_cvt_pk_bf16_f32 v115, v115, s0
	v_lshl_add_u64 v[118:119], v[140:141], 1, s[10:11]
	global_store_short v[118:119], v115, off
	v_or_b32_e32 v118, v221, v103
	v_ashrrev_i32_e32 v119, 31, v118
	v_lshl_add_u64 v[118:119], v[118:119], 2, s[18:19]
	global_load_dword v140, v[118:119], off
	s_waitcnt vmcnt(25)
	v_mul_f32_e32 v118, v163, v146
	v_cvt_pk_bf16_f32 v118, v118, s0
	global_store_short v[116:117], v118, off
	s_waitcnt vmcnt(24)
	v_mul_f32_e32 v116, v147, v164
	v_cvt_pk_bf16_f32 v118, v116, s0
	v_lshl_add_u64 v[116:117], v[142:143], 1, s[10:11]
	global_store_short v[116:117], v118, off
	v_or_b32_e32 v116, v223, v103
	v_ashrrev_i32_e32 v117, 31, v116
	v_lshl_add_u64 v[116:117], v[116:117], 2, s[18:19]
	global_load_dword v141, v[116:117], off
	s_waitcnt vmcnt(23)
	v_mul_f32_e32 v116, v165, v166
	v_cvt_pk_bf16_f32 v118, v116, s0
	v_lshl_add_u64 v[116:117], v[136:137], 1, s[10:11]
	global_store_short v[116:117], v118, off
	v_mul_f32_e32 v142, v147, v147
	global_load_dword v145, v188, s[14:15] offset:128
	v_mul_f32_e32 v115, v161, v161
	v_fmac_f32_e32 v115, v150, v150
	s_waitcnt vmcnt(23)
	v_mul_f32_e32 v116, v167, v168
	v_cvt_pk_bf16_f32 v118, v116, s0
	v_or_b32_e32 v116, v226, v103
	v_ashrrev_i32_e32 v117, 31, v116
	v_lshl_add_u64 v[116:117], v[116:117], 2, s[18:19]
	global_load_dword v136, v[116:117], off
	v_lshl_add_u64 v[116:117], v[128:129], 1, s[10:11]
	global_store_short v[116:117], v118, off
	v_or_b32_e32 v118, v228, v103
	s_waitcnt vmcnt(23)
	v_mul_f32_e32 v116, v169, v170
	v_ashrrev_i32_e32 v119, 31, v118
	v_cvt_pk_bf16_f32 v143, v116, s0
	v_or_b32_e32 v116, v229, v102
	v_lshl_add_u64 v[118:119], v[118:119], 2, s[18:19]
	global_load_dword v146, v[118:119], off
	v_ashrrev_i32_e32 v117, 31, v116
	v_or_b32_e32 v118, v229, v103
	v_lshl_add_u64 v[116:117], v[116:117], 2, s[18:19]
	v_ashrrev_i32_e32 v119, 31, v118
	v_lshl_add_u64 v[118:119], v[118:119], 2, s[18:19]
	global_load_dword v147, v[116:117], off
	global_load_dword v148, v[118:119], off
	v_fmac_f32_e32 v142, v163, v163
	v_mul_f32_e32 v137, v167, v167
	s_waitcnt vmcnt(24)
	v_add_f32_e32 v149, v80, v172
	global_store_dword v[192:193], v149, off offset:256
	v_or_b32_e32 v80, 0x440, v190
	global_load_dword v150, v188, s[14:15] offset:256
	s_waitcnt vmcnt(25)
	v_add_f32_e32 v153, v81, v173
	v_ashrrev_i32_e32 v81, 31, v80
	v_lshl_add_u64 v[80:81], v[80:81], 2, s[16:17]
	s_waitcnt vmcnt(19)
	v_add_f32_e32 v135, v64, v135
	v_or_b32_e32 v64, 0x460, v190
	global_store_dword v[192:193], v135, off offset:384
	global_load_dword v151, v188, s[14:15] offset:384
	v_add_f32_e32 v157, v82, v130
	global_store_dword v[80:81], v153, off
	global_load_dword v154, v188, s[14:15] offset:256
	v_or_b32_e32 v82, 0xc40, v190
	s_waitcnt vmcnt(21)
	v_add_f32_e32 v138, v65, v138
	v_ashrrev_i32_e32 v65, 31, v64
	v_lshl_add_u64 v[64:65], v[64:65], 2, s[16:17]
	global_store_dword v[64:65], v138, off
	v_or_b32_e32 v64, 0x840, v190
	v_ashrrev_i32_e32 v65, 31, v64
	v_lshl_add_u64 v[80:81], v[64:65], 2, s[16:17]
	global_load_dword v155, v188, s[14:15] offset:384
	v_add_f32_e32 v160, v83, v131
	global_store_dword v[80:81], v157, off
	v_or_b32_e32 v80, 0x860, v190
	v_ashrrev_i32_e32 v81, 31, v80
	global_load_dword v158, v188, s[14:15] offset:256
	s_waitcnt vmcnt(23)
	v_add_f32_e32 v144, v66, v144
	v_lshl_add_u64 v[116:117], v[80:81], 2, s[16:17]
	v_ashrrev_i32_e32 v83, 31, v82
	v_or_b32_e32 v66, 0xc60, v190
	global_store_dword v[116:117], v144, off
	v_lshl_add_u64 v[116:117], v[82:83], 2, s[16:17]
	global_load_dword v159, v188, s[14:15] offset:384
	v_add_f32_e32 v163, v84, v132
	global_store_dword v[116:117], v160, off
	s_waitcnt vmcnt(23)
	v_add_f32_e32 v140, v67, v140
	v_ashrrev_i32_e32 v67, 31, v66
	v_lshl_add_u64 v[116:117], v[66:67], 2, s[16:17]
	global_load_dword v161, v188, s[14:15] offset:256
	v_or_b32_e32 v84, 0x2440, v190
	global_store_dword v[116:117], v140, off
	v_or_b32_e32 v116, 0x2040, v190
	v_ashrrev_i32_e32 v117, 31, v116
	v_lshl_add_u64 v[118:119], v[116:117], 2, s[16:17]
	global_load_dword v162, v188, s[14:15] offset:384
	v_add_f32_e32 v166, v85, v133
	global_store_dword v[118:119], v163, off
	v_or_b32_e32 v118, 0x2060, v190
	v_ashrrev_i32_e32 v119, 31, v118
	global_load_dword v164, v188, s[14:15] offset:256
	s_waitcnt vmcnt(25)
; DI bfr f2bf(float a) { return (bfr)(pack2(a, 0.f) & 0xffffu); }
; DI int crow(int reg, int h) { return (reg & 3) + 8 * (reg >> 2) + 4 * h; }
; template <bool FIRST, bool HAS_H>
; DI void phase_gemm_resid(const Params& p, const bfr* A, const bfr* Wt, const float* gnext, float* ss, char* smem) {
;     ...
;     int tid2 = threadIdx.x;
;     asm volatile("" : "+v"(tid2));
;     const int lane = tid2 & 63, wid = tid2 >> 6, wr = wid >> 1, wc = wid & 1, r = lane & 31, hl = lane >> 5;
;     const float* xsrc = FIRST ? p.x_prompt : X;
;     const int rbase = m0 + wr * 64 + 4 * hl, cbase = n0 + wc * 128 + r;
; #pragma unroll
;     for (int i = 0; i < 2; ++i) {
; #pragma unroll
;       for (int qh = 0; qh < 2; ++qh) {
;         float rs[8];
; #pragma unroll
;         for (int q = 0; q < 8; ++q) rs[q] = 0.f;
; #pragma unroll
;         for (int jh = 0; jh < 2; ++jh) {
;           float xo[2][8];
; #pragma unroll
;           for (int jj = 0; jj < 2; ++jj)
; #pragma unroll
;             for (int q = 0; q < 8; ++q)
;               xo[jj][q] = xsrc[(rbase + i * 32 + crow(qh * 8 + q, 0)) * 1024 + cbase + (jh * 2 + jj) * 32];
; #pragma unroll
;           for (int q = 0; q < 8; ++q) {
;             const int o = (rbase + i * 32 + crow(qh * 8 + q, 0)) * 1024 + cbase;
; #pragma unroll
;             for (int jj = 0; jj < 2; ++jj) {
;               const int j = jh * 2 + jj;
;               const float xn = xo[jj][q] + acc[i][j][qh * 8 + q];
;               X[o + j * 32] = xn;
;               if (HAS_H) Hn[o + j * 32] = f2bf(xn * gnext[cbase + j * 32]);
;               rs[q] += xn * xn;
;             }
;           }
;         }
	v_add_f32_e32 v141, v68, v141
	v_lshl_add_u64 v[128:129], v[118:119], 2, s[16:17]
	v_ashrrev_i32_e32 v85, 31, v84
	v_or_b32_e32 v68, 0x2460, v190
	global_store_dword v[128:129], v141, off
	v_lshl_add_u64 v[128:129], v[84:85], 2, s[16:17]
	v_fmac_f32_e32 v137, v165, v165
	global_load_dword v165, v188, s[14:15] offset:384
	v_add_f32_e32 v134, v86, v134
	global_store_dword v[128:129], v166, off
	s_waitcnt vmcnt(25)
	v_add_f32_e32 v136, v69, v136
	v_ashrrev_i32_e32 v69, 31, v68
	v_lshl_add_u64 v[128:129], v[68:69], 2, s[16:17]
	global_load_dword v167, v188, s[14:15] offset:256
	v_or_b32_e32 v86, 0x2c40, v190
	global_store_dword v[128:129], v136, off
	v_or_b32_e32 v128, 0x2840, v190
	v_ashrrev_i32_e32 v129, 31, v128
	v_lshl_add_u64 v[130:131], v[128:129], 2, s[16:17]
	global_load_dword v168, v188, s[14:15] offset:384
	s_waitcnt vmcnt(26)
	v_add_f32_e32 v146, v70, v146
	global_store_dword v[130:131], v134, off
	v_or_b32_e32 v130, 0x2860, v190
	v_ashrrev_i32_e32 v131, 31, v130
	global_load_dword v170, v188, s[14:15] offset:256
	v_lshl_add_u64 v[132:133], v[130:131], 2, s[16:17]
	global_store_dword v[132:133], v146, off
	s_waitcnt vmcnt(28)
	v_add_f32_e32 v147, v87, v147
	v_ashrrev_i32_e32 v87, 31, v86
	global_load_dword v172, v188, s[14:15] offset:384
	v_lshl_add_u64 v[132:133], v[86:87], 2, s[16:17]
	v_or_b32_e32 v70, 0x2c60, v190
	global_store_dword v[132:133], v147, off
	s_waitcnt vmcnt(29)
	v_add_f32_e32 v148, v71, v148
	v_ashrrev_i32_e32 v71, 31, v70
	global_load_dword v173, v188, s[14:15] offset:256
	v_lshl_add_u64 v[132:133], v[70:71], 2, s[16:17]
	global_store_dword v[132:133], v148, off
	global_load_dword v132, v188, s[14:15] offset:384
	v_lshl_add_u64 v[98:99], v[98:99], 1, s[10:11]
	global_store_short v[98:99], v143, off
	v_mul_f32_e32 v98, v171, v145
	v_cvt_pk_bf16_f32 v133, v98, s0
	v_lshl_add_u64 v[98:99], v[100:101], 1, s[10:11]
	global_store_short v[98:99], v133, off
	s_waitcnt vmcnt(32)
	v_mul_f32_e32 v99, v149, v150
	v_cvt_pk_bf16_f32 v99, v99, s0
	global_store_short v[112:113], v99, off offset:128
	s_waitcnt vmcnt(31)
	v_mul_f32_e32 v99, v135, v151
	v_cvt_pk_bf16_f32 v99, v99, s0
	global_store_short v[112:113], v99, off offset:192
	s_waitcnt vmcnt(30)
	v_mul_f32_e32 v99, v153, v154
	v_cvt_pk_bf16_f32 v99, v99, s0
	global_store_short v[112:113], v99, off offset:2176
	s_waitcnt vmcnt(29)
	v_mul_f32_e32 v99, v138, v155
	v_cvt_pk_bf16_f32 v99, v99, s0
	global_store_short v[112:113], v99, off offset:2240
	s_waitcnt vmcnt(28)
	v_mul_f32_e32 v99, v157, v158
	v_cvt_pk_bf16_f32 v99, v99, s0
	v_lshl_add_u64 v[64:65], v[64:65], 1, s[10:11]
	global_store_short v[64:65], v99, off
	v_mul_f32_e32 v98, v171, v171
	s_waitcnt vmcnt(27)
	v_mul_f32_e32 v64, v144, v159
	v_cvt_pk_bf16_f32 v99, v64, s0
	v_lshl_add_u64 v[64:65], v[80:81], 1, s[10:11]
	global_store_short v[64:65], v99, off
	v_fmac_f32_e32 v156, v209, v209
	v_fmac_f32_e32 v152, v177, v177
	s_waitcnt vmcnt(26)
	v_mul_f32_e32 v64, v160, v161
	v_cvt_pk_bf16_f32 v80, v64, s0
	v_lshl_add_u64 v[64:65], v[82:83], 1, s[10:11]
	global_store_short v[64:65], v80, off
	v_fmac_f32_e32 v98, v169, v169
	v_fmac_f32_e32 v114, v149, v149
	s_waitcnt vmcnt(25)
	v_mul_f32_e32 v64, v140, v162
	v_cvt_pk_bf16_f32 v80, v64, s0
	v_lshl_add_u64 v[64:65], v[66:67], 1, s[10:11]
	global_store_short v[64:65], v80, off
	v_fmac_f32_e32 v156, v153, v153
	s_waitcnt vmcnt(24)
	v_mul_f32_e32 v64, v163, v164
	v_cvt_pk_bf16_f32 v66, v64, s0
	v_lshl_add_u64 v[64:65], v[116:117], 1, s[10:11]
	global_store_short v[64:65], v66, off
	v_fmac_f32_e32 v152, v157, v157
	v_fmac_f32_e32 v139, v160, v160
	v_fmac_f32_e32 v115, v163, v163
	v_fmac_f32_e32 v142, v166, v166
	s_waitcnt vmcnt(23)
	v_mul_f32_e32 v64, v141, v165
	v_cvt_pk_bf16_f32 v66, v64, s0
	v_lshl_add_u64 v[64:65], v[118:119], 1, s[10:11]
	global_store_short v[64:65], v66, off
	v_fmac_f32_e32 v137, v134, v134
	v_fmac_f32_e32 v98, v147, v147
	s_waitcnt vmcnt(22)
	v_mul_f32_e32 v64, v166, v167
	v_cvt_pk_bf16_f32 v66, v64, s0
	v_lshl_add_u64 v[64:65], v[84:85], 1, s[10:11]
	global_store_short v[64:65], v66, off
	v_fmac_f32_e32 v114, v135, v135
	v_fmac_f32_e32 v156, v138, v138
	s_waitcnt vmcnt(21)
	v_mul_f32_e32 v64, v136, v168
	v_cvt_pk_bf16_f32 v66, v64, s0
	v_lshl_add_u64 v[64:65], v[68:69], 1, s[10:11]
	global_store_short v[64:65], v66, off
	v_fmac_f32_e32 v152, v144, v144
	s_waitcnt vmcnt(20)
	v_mul_f32_e32 v64, v134, v170
	v_cvt_pk_bf16_f32 v66, v64, s0
	v_lshl_add_u64 v[64:65], v[128:129], 1, s[10:11]
	global_store_short v[64:65], v66, off
	v_fmac_f32_e32 v139, v140, v140
	s_waitcnt vmcnt(19)
; DI bfr f2bf(float a) { return (bfr)(pack2(a, 0.f) & 0xffffu); }
; #define DPPF(v, ctrl, rmask) __builtin_bit_cast(float, __builtin_amdgcn_update_dpp(0, __builtin_bit_cast(int, (v)), (ctrl), (rmask), 0xf, false))
; DI int crow(int reg, int h) { return (reg & 3) + 8 * (reg >> 2) + 4 * h; }
; DI float row16_sum(float v) {
;   v += DPPF(v, 0xB1, 0xf);
;   v += DPPF(v, 0x4E, 0xf);
;   v += DPPF(v, 0x141, 0xf);
;   v += DPPF(v, 0x140, 0xf);
;   return v;
; }
; DI float half32_sum_hi(float v) {
;   v = row16_sum(v);
;   v += DPPF(v, 0x142, 0xa);
;   return v;
; template <bool FIRST, bool HAS_H>
; DI void phase_gemm_resid(const Params& p, const bfr* A, const bfr* Wt, const float* gnext, float* ss, char* smem) {
;     ...
;           for (int q = 0; q < 8; ++q) {
;             const int o = (rbase + i * 32 + crow(qh * 8 + q, 0)) * 1024 + cbase;
; #pragma unroll
;             for (int jj = 0; jj < 2; ++jj) {
;               const int j = jh * 2 + jj;
;               const float xn = xo[jj][q] + acc[i][j][qh * 8 + q];
;               X[o + j * 32] = xn;
;               if (HAS_H) Hn[o + j * 32] = f2bf(xn * gnext[cbase + j * 32]);
;               rs[q] += xn * xn;
;             }
;           }
;         }
; #pragma unroll
;         for (int q = 0; q < 8; ++q) rs[q] = half32_sum_hi(rs[q]);
;         if (r == 31) {
; #pragma unroll
;           for (int q = 0; q < 8; ++q) unsafeAtomicAdd(ss + rbase + i * 32 + crow(qh * 8 + q, 0), rs[q]);
	v_mul_f32_e32 v64, v146, v172
	v_cvt_pk_bf16_f32 v66, v64, s0
	v_lshl_add_u64 v[64:65], v[130:131], 1, s[10:11]
	global_store_short v[64:65], v66, off
	v_fmac_f32_e32 v115, v141, v141
	v_fmac_f32_e32 v142, v136, v136
	s_waitcnt vmcnt(18)
	v_mul_f32_e32 v64, v147, v173
	v_cvt_pk_bf16_f32 v66, v64, s0
	v_lshl_add_u64 v[64:65], v[86:87], 1, s[10:11]
	global_store_short v[64:65], v66, off
	s_waitcnt vmcnt(17)
	v_mul_f32_e32 v64, v148, v132
	v_fmac_f32_e32 v137, v146, v146
	v_cvt_pk_bf16_f32 v66, v64, s0
	v_lshl_add_u64 v[64:65], v[70:71], 1, s[10:11]
	v_fmac_f32_e32 v98, v148, v148
	global_store_short v[64:65], v66, off
	v_add_f32_dpp v64, v114, v114 quad_perm:[1,0,3,2] row_mask:0xf bank_mask:0xf bound_ctrl:1
	v_add_f32_dpp v66, v156, v156 quad_perm:[1,0,3,2] row_mask:0xf bank_mask:0xf bound_ctrl:1
	v_add_f32_dpp v68, v152, v152 quad_perm:[1,0,3,2] row_mask:0xf bank_mask:0xf bound_ctrl:1
	v_add_f32_dpp v70, v139, v139 quad_perm:[1,0,3,2] row_mask:0xf bank_mask:0xf bound_ctrl:1
	v_add_f32_dpp v80, v115, v115 quad_perm:[1,0,3,2] row_mask:0xf bank_mask:0xf bound_ctrl:1
	v_add_f32_dpp v82, v142, v142 quad_perm:[1,0,3,2] row_mask:0xf bank_mask:0xf bound_ctrl:1
	v_add_f32_dpp v84, v137, v137 quad_perm:[1,0,3,2] row_mask:0xf bank_mask:0xf bound_ctrl:1
	v_add_f32_dpp v86, v98, v98 quad_perm:[1,0,3,2] row_mask:0xf bank_mask:0xf bound_ctrl:1
	v_add_f32_dpp v64, v64, v64 quad_perm:[2,3,0,1] row_mask:0xf bank_mask:0xf bound_ctrl:1
	v_add_f32_dpp v66, v66, v66 quad_perm:[2,3,0,1] row_mask:0xf bank_mask:0xf bound_ctrl:1
	v_add_f32_dpp v68, v68, v68 quad_perm:[2,3,0,1] row_mask:0xf bank_mask:0xf bound_ctrl:1
	v_add_f32_dpp v70, v70, v70 quad_perm:[2,3,0,1] row_mask:0xf bank_mask:0xf bound_ctrl:1
	v_add_f32_dpp v80, v80, v80 quad_perm:[2,3,0,1] row_mask:0xf bank_mask:0xf bound_ctrl:1
	v_add_f32_dpp v82, v82, v82 quad_perm:[2,3,0,1] row_mask:0xf bank_mask:0xf bound_ctrl:1
	v_add_f32_dpp v84, v84, v84 quad_perm:[2,3,0,1] row_mask:0xf bank_mask:0xf bound_ctrl:1
	v_add_f32_dpp v86, v86, v86 quad_perm:[2,3,0,1] row_mask:0xf bank_mask:0xf bound_ctrl:1
	v_add_f32_dpp v64, v64, v64 row_half_mirror row_mask:0xf bank_mask:0xf bound_ctrl:1
	v_add_f32_dpp v66, v66, v66 row_half_mirror row_mask:0xf bank_mask:0xf bound_ctrl:1
	v_add_f32_dpp v68, v68, v68 row_half_mirror row_mask:0xf bank_mask:0xf bound_ctrl:1
	v_add_f32_dpp v70, v70, v70 row_half_mirror row_mask:0xf bank_mask:0xf bound_ctrl:1
	v_add_f32_dpp v80, v80, v80 row_half_mirror row_mask:0xf bank_mask:0xf bound_ctrl:1
	v_add_f32_dpp v82, v82, v82 row_half_mirror row_mask:0xf bank_mask:0xf bound_ctrl:1
	v_add_f32_dpp v84, v84, v84 row_half_mirror row_mask:0xf bank_mask:0xf bound_ctrl:1
	v_add_f32_dpp v86, v86, v86 row_half_mirror row_mask:0xf bank_mask:0xf bound_ctrl:1
	v_add_f32_dpp v64, v64, v64 row_mirror row_mask:0xf bank_mask:0xf bound_ctrl:1
	v_mov_b32_e32 v65, 0
	v_add_f32_dpp v66, v66, v66 row_mirror row_mask:0xf bank_mask:0xf bound_ctrl:1
	v_mov_b32_e32 v67, 0
	v_add_f32_dpp v68, v68, v68 row_mirror row_mask:0xf bank_mask:0xf bound_ctrl:1
	v_mov_b32_e32 v69, 0
	v_add_f32_dpp v70, v70, v70 row_mirror row_mask:0xf bank_mask:0xf bound_ctrl:1
	v_mov_b32_e32 v71, 0
	v_add_f32_dpp v80, v80, v80 row_mirror row_mask:0xf bank_mask:0xf bound_ctrl:1
	v_mov_b32_e32 v81, 0
	v_add_f32_dpp v82, v82, v82 row_mirror row_mask:0xf bank_mask:0xf bound_ctrl:1
	v_mov_b32_e32 v83, 0
	v_add_f32_dpp v84, v84, v84 row_mirror row_mask:0xf bank_mask:0xf bound_ctrl:1
	v_mov_b32_e32 v85, 0
	v_add_f32_dpp v86, v86, v86 row_mirror row_mask:0xf bank_mask:0xf bound_ctrl:1
	v_mov_b32_e32 v87, 0
	v_mov_b32_dpp v65, v64 row_bcast:15 row_mask:0xa bank_mask:0xf
	v_mov_b32_dpp v67, v66 row_bcast:15 row_mask:0xa bank_mask:0xf
	v_mov_b32_dpp v69, v68 row_bcast:15 row_mask:0xa bank_mask:0xf
	v_mov_b32_dpp v71, v70 row_bcast:15 row_mask:0xa bank_mask:0xf
	v_mov_b32_dpp v81, v80 row_bcast:15 row_mask:0xa bank_mask:0xf
	v_mov_b32_dpp v83, v82 row_bcast:15 row_mask:0xa bank_mask:0xf
	v_mov_b32_dpp v85, v84 row_bcast:15 row_mask:0xa bank_mask:0xf
	v_mov_b32_dpp v87, v86 row_bcast:15 row_mask:0xa bank_mask:0xf
	s_and_saveexec_b64 s[4:5], vcc
	s_cbranch_execz .LBB0_856
	v_add_f32_e32 v64, v64, v65
	v_add_f32_e32 v86, v86, v87
	v_add_f32_e32 v84, v84, v85
	v_add_f32_e32 v82, v82, v83
	v_add_f32_e32 v80, v80, v81
	v_add_f32_e32 v70, v70, v71
	v_add_f32_e32 v68, v68, v69
	v_add_f32_e32 v66, v66, v67
	global_atomic_add_f32 v[96:97], v64, off
	global_atomic_add_f32 v[96:97], v66, off offset:4
	global_atomic_add_f32 v[96:97], v68, off offset:8
	global_atomic_add_f32 v[96:97], v70, off offset:12
	global_atomic_add_f32 v[96:97], v80, off offset:32
	global_atomic_add_f32 v[96:97], v82, off offset:36
	global_atomic_add_f32 v[96:97], v84, off offset:40
	global_atomic_add_f32 v[96:97], v86, off offset:44

; #define GA_LOAD(pr_) do { _Pragma("unroll") for (int i = 0; i < 4; ++i) ra[i] = *(const u32x4*)(Ab + (i * 32) * lda + (pr_) * 64); } while (0)
; #define GB_LOAD(kt_) do { const bfr* bk_ = Bb + (kt_) * NB * 32; \
;     _Pragma("unroll") for (int i = 0; i < 4; ++i) rb[i] = *(const u32x4*)(bk_ + (i * 64) * 32); } while (0)
; #define G_STORE(kt_) do { bfr* as_ = S0 + ((kt_) & 1) * GSTAGE; bfr* bs_ = as_ + 128 * 40; \
;     if (apar == ((kt_) & 1)) { _Pragma("unroll") for (int i = 0; i < 4; ++i) *(u32x4*)(as_ + asoff + i * 32 * 40) = ra[i]; } \
;     _Pragma("unroll") for (int i = 0; i < 4; ++i) *(u32x4*)(bs_ + bsoff + i * 64 * 40) = rb[i]; } while (0)
; template <int lda>
; DI void gemm_mainloop(const bfr* __restrict__ A, const bfr* __restrict__ Bt, int NB, int K, int m0, int n0, char* smem, f32x16 (&acc)[2][4]) {
;   bfr* S0 = (bfr*)smem;
;   int tid = threadIdx.x;
;   asm volatile("" : "+v"(tid));
;   const int lane = tid & 63, wid = tid >> 6, wr = wid >> 1, wc = wid & 1;
;   const int r = lane & 31, hl = lane >> 5;
; #pragma unroll
;   for (int i = 0; i < 2; ++i)
; #pragma unroll
;     for (int j = 0; j < 4; ++j)
; #pragma unroll
;       for (int q = 0; q < 16; ++q) acc[i][j][q] = 0.f;
;   u32x4 ra[4], rb[4];
;   const int nk = K >> 5;
;   const int arow = tid >> 3, ac8 = tid & 7, apar = ac8 >> 2;
;   const bfr* Ab = A + (m0 + arow) * lda + ac8 * 8;
;   const int asoff = arow * 40 + (ac8 & 3) * 8;
;   const int brow = tid >> 2, bc4 = tid & 3;
;   const bfr* Bb = Bt + (n0 + brow) * 32 + bc4 * 8;
;   const int bsoff = brow * 40 + bc4 * 8;
;     ...
;   GA_LOAD(0);
;   GB_LOAD(0);
;   G_STORE(0);
;   GB_LOAD(1);
;   __syncthreads();
; DI void phase_gemm_bf16out(const Params& p, const bfr* A, const bfr* Wt, bfr* C, int N, const float* ss, char* smem) {
;     ...
;   for (int t0 = blockIdx.x; t0 < 128 * ntn; t0 += gridDim.x) {
;     const int t = ((gridDim.x & 7) == 0) ? xcd_tile(t0, ntn) : t0;
;     int mt = t / ntn, nt = t % ntn;
;     gemm_tile<1024>(A, Wt, N, 1024, mt * 128, nt * 256, smem,
.LBB0_925:
	s_ashr_i32 s5, s4, 31
	s_lshr_b32 s5, s5, 30
	s_add_i32 s5, s4, s5
	s_and_b32 s6, s5, 0xfffffc
	s_lshl_b32 s5, s5, 5
	s_and_b32 s30, s5, 0xffffff80
	s_sub_i32 s4, s4, s6
	s_lshl_b32 s29, s4, 8
	s_mov_b32 s31, 0
	s_mov_b64 s[6:7], 0
	s_lshl_b32 s98, s30, 11
	s_add_u32 s98, s10, s98
	s_addc_u32 s99, s11, 0
	s_lshl_b32 s100, s29, 6
	s_add_u32 s100, s12, s100
	s_addc_u32 s101, s13, 0
	v_writelane_b32 v187, s64, 0
	v_writelane_b32 v187, s65, 1
	v_writelane_b32 v187, s66, 2
	v_writelane_b32 v187, s67, 3
	v_writelane_b32 v187, s68, 4
	v_writelane_b32 v187, s69, 5
	v_writelane_b32 v187, s70, 6
	v_writelane_b32 v187, s71, 7
	v_writelane_b32 v187, s72, 8
	v_writelane_b32 v187, s73, 9
	v_writelane_b32 v187, s74, 10
	v_writelane_b32 v187, s75, 11
	v_writelane_b32 v187, s76, 12
	v_writelane_b32 v187, s77, 13
	v_writelane_b32 v187, s78, 14
	v_writelane_b32 v187, s79, 15
	v_lshrrev_b32_e32 v188, 6, v196
	v_and_b32_e32 v189, 63, v196
	v_readfirstlane_b32 s73, v188
	v_lshrrev_b32_e32 v190, 2, v189
	v_bfe_u32 v191, v189, 4, 2
	v_and_b32_e32 v188, 3, v189
	v_xor_b32_e32 v188, v188, v191
	v_lshlrev_b32_e32 v188, 4, v188
	v_lshl_add_u32 v176, v190, 11, v188
	v_add_u32_e32 v177, 0x8000, v176
	v_lshl_add_u32 v178, v190, 6, v188
	v_and_b32_e32 v190, 31, v189
	v_lshrrev_b32_e32 v191, 5, v189
	v_bfe_u32 v188, v189, 2, 2
	v_xor_b32_e32 v188, v188, v191
	v_lshlrev_b32_e32 v188, 4, v188
	v_lshl_add_u32 v179, v190, 6, v188
	s_lshr_b32 s74, s73, 1
	s_lshl_b32 s74, s74, 12
	s_and_b32 s75, s73, 1
	s_lshl_b32 s75, s75, 13
	v_add_u32_e32 v181, s75, v179
	v_add_u32_e32 v179, s74, v179
	v_xor_b32_e32 v182, 32, v181
	v_xor_b32_e32 v180, 32, v179
	s_lshl_b32 s74, s73, 16
	s_add_u32 s64, s98, s74
	s_addc_u32 s65, s99, 0
	s_lshl_b32 s74, s73, 12
	s_add_u32 s66, s100, s74
	s_addc_u32 s67, s101, 0
	s_lshl_b32 s68, s73, 11
	s_lshl_b32 s69, s73, 12
	s_mov_b32 s70, 0
	s_mov_b32 s71, 0
	s_mov_b32 s72, 0
	s_waitcnt lgkmcnt(0)
	s_barrier
	s_mul_i32 s74, s70, 0x6000
	s_add_u32 s75, s74, s68
	s_mov_b32 m0, s75
	s_add_u32 s76, s74, 0x2000
	s_cmp_eq_u32 s70, 2
	s_cselect_b32 s76, 0x10000, s76
	global_load_lds_dwordx4 v176, s[64:65]
	s_add_u32 m0, s75, 0x400
	s_add_u32 s76, s76, s69
	global_load_lds_dwordx4 v177, s[64:65]
	s_mov_b32 m0, s76
	s_add_u32 s64, s64, 64
	s_addc_u32 s65, s65, 0
	global_load_lds_dwordx4 v178, s[66:67]
	global_load_lds_dwordx4 v178, s[66:67] offset:1024
	global_load_lds_dwordx4 v178, s[66:67] offset:2048
	global_load_lds_dwordx4 v178, s[66:67] offset:3072
	s_add_u32 s66, s66, 0x10000
	s_addc_u32 s67, s67, 0
	s_add_u32 s70, s70, 1
	s_cmp_eq_u32 s70, 3
	s_cselect_b32 s70, 0, s70
	s_mul_i32 s74, s70, 0x6000
	s_add_u32 s75, s74, s68
	s_mov_b32 m0, s75
	s_add_u32 s76, s74, 0x2000
	s_cmp_eq_u32 s70, 2
	s_cselect_b32 s76, 0x10000, s76
	global_load_lds_dwordx4 v176, s[64:65]
	s_add_u32 m0, s75, 0x400
	s_add_u32 s76, s76, s69
	global_load_lds_dwordx4 v177, s[64:65]
	s_mov_b32 m0, s76
	s_add_u32 s64, s64, 64
	s_addc_u32 s65, s65, 0
	global_load_lds_dwordx4 v178, s[66:67]
	global_load_lds_dwordx4 v178, s[66:67] offset:1024
	global_load_lds_dwordx4 v178, s[66:67] offset:2048
	global_load_lds_dwordx4 v178, s[66:67] offset:3072
	s_add_u32 s66, s66, 0x10000
	s_addc_u32 s67, s67, 0
	s_add_u32 s70, s70, 1
	s_cmp_eq_u32 s70, 3
	s_cselect_b32 s70, 0, s70
	s_cmp_lt_u32 s46, 0x100
	s_cbranch_scc1 .Lp8_nostag
	s_sleep 8
	s_setprio 1

; #define MFMA32(a, b, c) __builtin_amdgcn_mfma_f32_32x32x16_bf16((a), (b), (c), 0, 0, 0)
; #define GA_LOAD(pr_) do { _Pragma("unroll") for (int i = 0; i < 4; ++i) ra[i] = *(const u32x4*)(Ab + (i * 32) * lda + (pr_) * 64); } while (0)
; #define GB_LOAD(kt_) do { const bfr* bk_ = Bb + (kt_) * NB * 32; \
;     _Pragma("unroll") for (int i = 0; i < 4; ++i) rb[i] = *(const u32x4*)(bk_ + (i * 64) * 32); } while (0)
; #define G_STORE(kt_) do { bfr* as_ = S0 + ((kt_) & 1) * GSTAGE; bfr* bs_ = as_ + 128 * 40; \
;     if (apar == ((kt_) & 1)) { _Pragma("unroll") for (int i = 0; i < 4; ++i) *(u32x4*)(as_ + asoff + i * 32 * 40) = ra[i]; } \
;     _Pragma("unroll") for (int i = 0; i < 4; ++i) *(u32x4*)(bs_ + bsoff + i * 64 * 40) = rb[i]; } while (0)
; template <int lda>
; DI void gemm_mainloop(const bfr* __restrict__ A, const bfr* __restrict__ Bt, int NB, int K, int m0, int n0, char* smem, f32x16 (&acc)[2][4]) {
;     ...
;   for (int kt = 0; kt < nk; ++kt) {
;     if (kt + 1 < nk) G_STORE(kt + 1);
;     if (kt + 2 < nk) {
;       GB_LOAD(kt + 2);
;       if ((kt & 1) == 0) GA_LOAD((kt >> 1) + 1);
;     }
;     const bfr* As = S0 + (kt & 1) * GSTAGE;
;     const bfr* Bs = As + 128 * 40;
; #pragma unroll
;     for (int ks = 0; ks < 2; ++ks) {
;       bf16x8 af[2], bfg[4];
; #pragma unroll
;       for (int i = 0; i < 2; ++i) af[i] = *(const bf16x8*)(As + (wr * 64 + i * 32 + r) * 40 + ks * 16 + hl * 8);
; #pragma unroll
;       for (int j = 0; j < 4; ++j) bfg[j] = *(const bf16x8*)(Bs + (wc * 128 + j * 32 + r) * 40 + ks * 16 + hl * 8);
; #pragma unroll
;       for (int i = 0; i < 2; ++i)
; #pragma unroll
;         for (int j = 0; j < 4; ++j) acc[i][j] = MFMA32(af[i], bfg[j], acc[i][j]);
;     }
;     __syncthreads();
.Lp8_loop:
	s_waitcnt vmcnt(6)
	s_barrier
	s_mul_i32 s74, s71, 0x6000
	s_add_u32 s75, s74, 0x2000
	s_cmp_eq_u32 s71, 2
	s_cselect_b32 s75, 0x10000, s75
	v_add_u32_e32 v183, s74, v179
	v_add_u32_e32 v185, s75, v181
	v_add_u32_e32 v184, s74, v180
	v_add_u32_e32 v186, s75, v182
	ds_read_b128 v[128:131], v183
	ds_read_b128 v[144:147], v185
	ds_read_b128 v[148:151], v185 offset:2048
	ds_read_b128 v[152:155], v185 offset:4096
	ds_read_b128 v[156:159], v185 offset:6144
	ds_read_b128 v[132:135], v183 offset:2048
	ds_read_b128 v[136:139], v184
	ds_read_b128 v[160:163], v186
	ds_read_b128 v[164:167], v186 offset:2048
	ds_read_b128 v[168:171], v186 offset:4096
	ds_read_b128 v[172:175], v186 offset:6144
	ds_read_b128 v[140:143], v184 offset:2048
	s_add_u32 s71, s71, 1
	s_cmp_eq_u32 s71, 3
	s_cselect_b32 s71, 0, s71
	s_waitcnt lgkmcnt(10)
	v_mfma_f32_32x32x16_bf16 v[112:127], v[128:131], v[144:147], v[112:127]
	s_mul_i32 s74, s70, 0x6000
	s_add_u32 s75, s74, s68
	s_mov_b32 m0, s75
	s_add_u32 s76, s74, 0x2000
	s_cmp_eq_u32 s70, 2
	s_cselect_b32 s76, 0x10000, s76
	global_load_lds_dwordx4 v176, s[64:65]
	s_waitcnt lgkmcnt(9)
	v_mfma_f32_32x32x16_bf16 v[96:111], v[128:131], v[148:151], v[96:111]
	s_add_u32 m0, s75, 0x400
	s_add_u32 s76, s76, s69
	global_load_lds_dwordx4 v177, s[64:65]
	s_waitcnt lgkmcnt(8)
	v_mfma_f32_32x32x16_bf16 v[80:95], v[128:131], v[152:155], v[80:95]
	s_mov_b32 m0, s76
	s_add_u32 s64, s64, 64
	s_addc_u32 s65, s65, 0
	global_load_lds_dwordx4 v178, s[66:67]
	s_waitcnt lgkmcnt(7)
	v_mfma_f32_32x32x16_bf16 v[64:79], v[128:131], v[156:159], v[64:79]
	global_load_lds_dwordx4 v178, s[66:67] offset:1024
	s_waitcnt lgkmcnt(6)
	v_mfma_f32_32x32x16_bf16 v[48:63], v[132:135], v[144:147], v[48:63]
	global_load_lds_dwordx4 v178, s[66:67] offset:2048
	v_mfma_f32_32x32x16_bf16 v[32:47], v[132:135], v[148:151], v[32:47]
	global_load_lds_dwordx4 v178, s[66:67] offset:3072
	s_add_u32 s66, s66, 0x10000
	s_addc_u32 s67, s67, 0
	v_mfma_f32_32x32x16_bf16 v[16:31], v[132:135], v[152:155], v[16:31]
	s_add_u32 s70, s70, 1
	s_cmp_eq_u32 s70, 3
	s_cselect_b32 s70, 0, s70
	v_mfma_f32_32x32x16_bf16 v[0:15], v[132:135], v[156:159], v[0:15]
	s_waitcnt lgkmcnt(4)
	v_mfma_f32_32x32x16_bf16 v[112:127], v[136:139], v[160:163], v[112:127]
	s_waitcnt lgkmcnt(3)
	v_mfma_f32_32x32x16_bf16 v[96:111], v[136:139], v[164:167], v[96:111]
	s_waitcnt lgkmcnt(2)
	v_mfma_f32_32x32x16_bf16 v[80:95], v[136:139], v[168:171], v[80:95]
	s_waitcnt lgkmcnt(1)
	v_mfma_f32_32x32x16_bf16 v[64:79], v[136:139], v[172:175], v[64:79]
	s_waitcnt lgkmcnt(0)
	v_mfma_f32_32x32x16_bf16 v[48:63], v[140:143], v[160:163], v[48:63]
	v_mfma_f32_32x32x16_bf16 v[32:47], v[140:143], v[164:167], v[32:47]
	v_mfma_f32_32x32x16_bf16 v[16:31], v[140:143], v[168:171], v[16:31]
	v_mfma_f32_32x32x16_bf16 v[0:15], v[140:143], v[172:175], v[0:15]
	s_add_u32 s72, s72, 1
	s_cmp_lt_u32 s72, 30
	s_cbranch_scc1 .Lp8_loop
	s_waitcnt vmcnt(6)
	s_barrier
; #define MFMA32(a, b, c) __builtin_amdgcn_mfma_f32_32x32x16_bf16((a), (b), (c), 0, 0, 0)
; #define GA_LOAD(pr_) do { _Pragma("unroll") for (int i = 0; i < 4; ++i) ra[i] = *(const u32x4*)(Ab + (i * 32) * lda + (pr_) * 64); } while (0)
; #define GB_LOAD(kt_) do { const bfr* bk_ = Bb + (kt_) * NB * 32; \
;     _Pragma("unroll") for (int i = 0; i < 4; ++i) rb[i] = *(const u32x4*)(bk_ + (i * 64) * 32); } while (0)
; #define G_STORE(kt_) do { bfr* as_ = S0 + ((kt_) & 1) * GSTAGE; bfr* bs_ = as_ + 128 * 40; \
;     if (apar == ((kt_) & 1)) { _Pragma("unroll") for (int i = 0; i < 4; ++i) *(u32x4*)(as_ + asoff + i * 32 * 40) = ra[i]; } \
;     _Pragma("unroll") for (int i = 0; i < 4; ++i) *(u32x4*)(bs_ + bsoff + i * 64 * 40) = rb[i]; } while (0)
; template <int lda>
; DI void gemm_mainloop(const bfr* __restrict__ A, const bfr* __restrict__ Bt, int NB, int K, int m0, int n0, char* smem, f32x16 (&acc)[2][4]) {
;     ...
;   for (int kt = 0; kt < nk; ++kt) {
;     if (kt + 1 < nk) G_STORE(kt + 1);
;     if (kt + 2 < nk) {
;       GB_LOAD(kt + 2);
;       if ((kt & 1) == 0) GA_LOAD((kt >> 1) + 1);
;     }
;     const bfr* As = S0 + (kt & 1) * GSTAGE;
;     const bfr* Bs = As + 128 * 40;
; #pragma unroll
;     for (int ks = 0; ks < 2; ++ks) {
;       bf16x8 af[2], bfg[4];
; #pragma unroll
;       for (int i = 0; i < 2; ++i) af[i] = *(const bf16x8*)(As + (wr * 64 + i * 32 + r) * 40 + ks * 16 + hl * 8);
; #pragma unroll
;       for (int j = 0; j < 4; ++j) bfg[j] = *(const bf16x8*)(Bs + (wc * 128 + j * 32 + r) * 40 + ks * 16 + hl * 8);
; #pragma unroll
;       for (int i = 0; i < 2; ++i)
; #pragma unroll
;         for (int j = 0; j < 4; ++j) acc[i][j] = MFMA32(af[i], bfg[j], acc[i][j]);
;     }
;     __syncthreads();
	s_mul_i32 s74, s71, 0x6000
	s_add_u32 s75, s74, 0x2000
	s_cmp_eq_u32 s71, 2
	s_cselect_b32 s75, 0x10000, s75
	v_add_u32_e32 v183, s74, v179
	v_add_u32_e32 v185, s75, v181
	v_add_u32_e32 v184, s74, v180
	v_add_u32_e32 v186, s75, v182
	ds_read_b128 v[128:131], v183
	ds_read_b128 v[144:147], v185
	ds_read_b128 v[148:151], v185 offset:2048
	ds_read_b128 v[152:155], v185 offset:4096
	ds_read_b128 v[156:159], v185 offset:6144
	ds_read_b128 v[132:135], v183 offset:2048
	ds_read_b128 v[136:139], v184
	ds_read_b128 v[160:163], v186
	ds_read_b128 v[164:167], v186 offset:2048
	ds_read_b128 v[168:171], v186 offset:4096
	ds_read_b128 v[172:175], v186 offset:6144
	ds_read_b128 v[140:143], v184 offset:2048
	s_add_u32 s71, s71, 1
	s_cmp_eq_u32 s71, 3
	s_cselect_b32 s71, 0, s71
	s_waitcnt lgkmcnt(10)
	v_mfma_f32_32x32x16_bf16 v[112:127], v[128:131], v[144:147], v[112:127]
	s_waitcnt lgkmcnt(9)
	v_mfma_f32_32x32x16_bf16 v[96:111], v[128:131], v[148:151], v[96:111]
	s_waitcnt lgkmcnt(8)
	v_mfma_f32_32x32x16_bf16 v[80:95], v[128:131], v[152:155], v[80:95]
	s_waitcnt lgkmcnt(7)
	v_mfma_f32_32x32x16_bf16 v[64:79], v[128:131], v[156:159], v[64:79]
	s_waitcnt lgkmcnt(6)
	v_mfma_f32_32x32x16_bf16 v[48:63], v[132:135], v[144:147], v[48:63]
	v_mfma_f32_32x32x16_bf16 v[32:47], v[132:135], v[148:151], v[32:47]
	v_mfma_f32_32x32x16_bf16 v[16:31], v[132:135], v[152:155], v[16:31]
	v_mfma_f32_32x32x16_bf16 v[0:15], v[132:135], v[156:159], v[0:15]
	s_waitcnt lgkmcnt(4)
	v_mfma_f32_32x32x16_bf16 v[112:127], v[136:139], v[160:163], v[112:127]
	s_waitcnt lgkmcnt(3)
	v_mfma_f32_32x32x16_bf16 v[96:111], v[136:139], v[164:167], v[96:111]
	s_waitcnt lgkmcnt(2)
	v_mfma_f32_32x32x16_bf16 v[80:95], v[136:139], v[168:171], v[80:95]
	s_waitcnt lgkmcnt(1)
	v_mfma_f32_32x32x16_bf16 v[64:79], v[136:139], v[172:175], v[64:79]
	s_waitcnt lgkmcnt(0)
	v_mfma_f32_32x32x16_bf16 v[48:63], v[140:143], v[160:163], v[48:63]
	v_mfma_f32_32x32x16_bf16 v[32:47], v[140:143], v[164:167], v[32:47]
	v_mfma_f32_32x32x16_bf16 v[16:31], v[140:143], v[168:171], v[16:31]
	v_mfma_f32_32x32x16_bf16 v[0:15], v[140:143], v[172:175], v[0:15]
	s_waitcnt vmcnt(0)
	s_barrier
	s_mul_i32 s74, s71, 0x6000
	s_add_u32 s75, s74, 0x2000
	s_cmp_eq_u32 s71, 2
	s_cselect_b32 s75, 0x10000, s75
	v_add_u32_e32 v183, s74, v179
	v_add_u32_e32 v185, s75, v181
	v_add_u32_e32 v184, s74, v180
	v_add_u32_e32 v186, s75, v182
	ds_read_b128 v[128:131], v183
	ds_read_b128 v[144:147], v185
	ds_read_b128 v[148:151], v185 offset:2048
	ds_read_b128 v[152:155], v185 offset:4096
	ds_read_b128 v[156:159], v185 offset:6144
	ds_read_b128 v[132:135], v183 offset:2048
	ds_read_b128 v[136:139], v184
	ds_read_b128 v[160:163], v186
	ds_read_b128 v[164:167], v186 offset:2048
	ds_read_b128 v[168:171], v186 offset:4096
	ds_read_b128 v[172:175], v186 offset:6144
	ds_read_b128 v[140:143], v184 offset:2048
	s_add_u32 s71, s71, 1
	s_cmp_eq_u32 s71, 3
	s_cselect_b32 s71, 0, s71
	s_waitcnt lgkmcnt(10)
	v_mfma_f32_32x32x16_bf16 v[112:127], v[128:131], v[144:147], v[112:127]
	s_waitcnt lgkmcnt(9)
	v_mfma_f32_32x32x16_bf16 v[96:111], v[128:131], v[148:151], v[96:111]
	s_waitcnt lgkmcnt(8)
	v_mfma_f32_32x32x16_bf16 v[80:95], v[128:131], v[152:155], v[80:95]
	s_waitcnt lgkmcnt(7)
	v_mfma_f32_32x32x16_bf16 v[64:79], v[128:131], v[156:159], v[64:79]
	s_waitcnt lgkmcnt(6)
	v_mfma_f32_32x32x16_bf16 v[48:63], v[132:135], v[144:147], v[48:63]
	v_mfma_f32_32x32x16_bf16 v[32:47], v[132:135], v[148:151], v[32:47]
	v_mfma_f32_32x32x16_bf16 v[16:31], v[132:135], v[152:155], v[16:31]
	v_mfma_f32_32x32x16_bf16 v[0:15], v[132:135], v[156:159], v[0:15]
	s_waitcnt lgkmcnt(4)
	v_mfma_f32_32x32x16_bf16 v[112:127], v[136:139], v[160:163], v[112:127]
	s_waitcnt lgkmcnt(3)
	v_mfma_f32_32x32x16_bf16 v[96:111], v[136:139], v[164:167], v[96:111]
	s_waitcnt lgkmcnt(2)
	v_mfma_f32_32x32x16_bf16 v[80:95], v[136:139], v[168:171], v[80:95]
	s_waitcnt lgkmcnt(1)
	v_mfma_f32_32x32x16_bf16 v[64:79], v[136:139], v[172:175], v[64:79]
	s_waitcnt lgkmcnt(0)
	v_mfma_f32_32x32x16_bf16 v[48:63], v[140:143], v[160:163], v[48:63]
	v_mfma_f32_32x32x16_bf16 v[32:47], v[140:143], v[164:167], v[32:47]
	v_mfma_f32_32x32x16_bf16 v[16:31], v[140:143], v[168:171], v[16:31]
	v_mfma_f32_32x32x16_bf16 v[0:15], v[140:143], v[172:175], v[0:15]
	s_setprio 0
	s_nop 7
	v_readlane_b32 s64, v187, 0
	v_readlane_b32 s65, v187, 1
	v_readlane_b32 s66, v187, 2
	v_readlane_b32 s67, v187, 3
	v_readlane_b32 s68, v187, 4
	v_readlane_b32 s69, v187, 5
	v_readlane_b32 s70, v187, 6
	v_readlane_b32 s71, v187, 7
	v_readlane_b32 s72, v187, 8
	v_readlane_b32 s73, v187, 9
	v_readlane_b32 s74, v187, 10
	v_readlane_b32 s75, v187, 11
	v_readlane_b32 s76, v187, 12
	v_readlane_b32 s77, v187, 13
	v_readlane_b32 s78, v187, 14
	v_readlane_b32 s79, v187, 15
	s_nop 7
	s_branch .LBB0_922

; #define GA_LOAD(pr_) do { _Pragma("unroll") for (int i = 0; i < 4; ++i) ra[i] = *(const u32x4*)(Ab + (i * 32) * lda + (pr_) * 64); } while (0)
; #define GB_LOAD(kt_) do { const bfr* bk_ = Bb + (kt_) * NB * 32; \
;     _Pragma("unroll") for (int i = 0; i < 4; ++i) rb[i] = *(const u32x4*)(bk_ + (i * 64) * 32); } while (0)
; #define G_STORE(kt_) do { bfr* as_ = S0 + ((kt_) & 1) * GSTAGE; bfr* bs_ = as_ + 128 * 40; \
;     if (apar == ((kt_) & 1)) { _Pragma("unroll") for (int i = 0; i < 4; ++i) *(u32x4*)(as_ + asoff + i * 32 * 40) = ra[i]; } \
;     _Pragma("unroll") for (int i = 0; i < 4; ++i) *(u32x4*)(bs_ + bsoff + i * 64 * 40) = rb[i]; } while (0)
; template <int lda>
; DI void gemm_mainloop(const bfr* __restrict__ A, const bfr* __restrict__ Bt, int NB, int K, int m0, int n0, char* smem, f32x16 (&acc)[2][4]) {
;   bfr* S0 = (bfr*)smem;
;   int tid = threadIdx.x;
;   asm volatile("" : "+v"(tid));
;   const int lane = tid & 63, wid = tid >> 6, wr = wid >> 1, wc = wid & 1;
;   const int r = lane & 31, hl = lane >> 5;
; #pragma unroll
;   for (int i = 0; i < 2; ++i)
; #pragma unroll
;     for (int j = 0; j < 4; ++j)
; #pragma unroll
;       for (int q = 0; q < 16; ++q) acc[i][j][q] = 0.f;
;   u32x4 ra[4], rb[4];
;   const int nk = K >> 5;
;   const int arow = tid >> 3, ac8 = tid & 7, apar = ac8 >> 2;
;   const bfr* Ab = A + (m0 + arow) * lda + ac8 * 8;
;   const int asoff = arow * 40 + (ac8 & 3) * 8;
;   const int brow = tid >> 2, bc4 = tid & 3;
;   const bfr* Bb = Bt + (n0 + brow) * 32 + bc4 * 8;
;   const int bsoff = brow * 40 + bc4 * 8;
;     ...
;   GA_LOAD(0);
;   GB_LOAD(0);
;   G_STORE(0);
;   GB_LOAD(1);
;   __syncthreads();
; template <bool FIRST, bool HAS_H>
; DI void phase_gemm_resid(const Params& p, const bfr* A, const bfr* Wt, const float* gnext, float* ss, char* smem) {
;     ...
;   for (int t0 = blockIdx.x; t0 < 128 * 4; t0 += gridDim.x) {
;     const int t = ((gridDim.x & 7) == 0) ? xcd_tile(t0, 4) : t0;
;     const int mt = t >> 2, nt = t & 3, m0 = mt * 128, n0 = nt * 256;
;     f32x16 acc[2][4];
;     gemm_mainloop<1024>(A, Wt, 1024, 1024, m0, n0, smem, acc);
.LBB0_1099:
	s_lshl_b32 s5, s4, 5
	s_and_b32 s36, s5, 0xffffff80
	s_lshl_b32 s4, s4, 8
	s_and_b32 s33, s4, 0x300
	s_mov_b32 s37, 0
	s_mov_b64 s[20:21], 0
	s_lshl_b32 s98, s36, 11
	s_add_u32 s98, s2, s98
	s_addc_u32 s99, s3, 0
	s_lshl_b32 s100, s33, 6
	s_add_u32 s100, s8, s100
	s_addc_u32 s101, s9, 0
	v_writelane_b32 v187, s64, 0
	v_writelane_b32 v187, s65, 1
	v_writelane_b32 v187, s66, 2
	v_writelane_b32 v187, s67, 3
	v_writelane_b32 v187, s68, 4
	v_writelane_b32 v187, s69, 5
	v_writelane_b32 v187, s70, 6
	v_writelane_b32 v187, s71, 7
	v_writelane_b32 v187, s72, 8
	v_writelane_b32 v187, s73, 9
	v_writelane_b32 v187, s74, 10
	v_writelane_b32 v187, s75, 11
	v_writelane_b32 v187, s76, 12
	v_writelane_b32 v187, s77, 13
	v_writelane_b32 v187, s78, 14
	v_writelane_b32 v187, s79, 15
	v_lshrrev_b32_e32 v188, 6, v196
	v_and_b32_e32 v189, 63, v196
	v_readfirstlane_b32 s73, v188
	v_lshrrev_b32_e32 v190, 2, v189
	v_bfe_u32 v191, v189, 4, 2
	v_and_b32_e32 v188, 3, v189
	v_xor_b32_e32 v188, v188, v191
	v_lshlrev_b32_e32 v188, 4, v188
	v_lshl_add_u32 v176, v190, 11, v188
	v_add_u32_e32 v177, 0x8000, v176
	v_lshl_add_u32 v178, v190, 6, v188
	v_and_b32_e32 v190, 31, v189
	v_lshrrev_b32_e32 v191, 5, v189
	v_bfe_u32 v188, v189, 2, 2
	v_xor_b32_e32 v188, v188, v191
	v_lshlrev_b32_e32 v188, 4, v188
	v_lshl_add_u32 v179, v190, 6, v188
	s_lshr_b32 s74, s73, 1
	s_lshl_b32 s74, s74, 12
	s_and_b32 s75, s73, 1
	s_lshl_b32 s75, s75, 13
	v_add_u32_e32 v181, s75, v179
	v_add_u32_e32 v179, s74, v179
	v_xor_b32_e32 v182, 32, v181
	v_xor_b32_e32 v180, 32, v179
	s_lshl_b32 s74, s73, 16
	s_add_u32 s64, s98, s74
	s_addc_u32 s65, s99, 0
	s_lshl_b32 s74, s73, 12
	s_add_u32 s66, s100, s74
	s_addc_u32 s67, s101, 0
	s_lshl_b32 s68, s73, 11
	s_lshl_b32 s69, s73, 12
	s_mov_b32 s70, 0
	s_mov_b32 s71, 0
	s_mov_b32 s72, 0
	s_waitcnt lgkmcnt(0)
	s_barrier
	s_mul_i32 s74, s70, 0x6000
	s_add_u32 s75, s74, s68
	s_mov_b32 m0, s75
	s_add_u32 s76, s74, 0x2000
	s_cmp_eq_u32 s70, 2
	s_cselect_b32 s76, 0x10000, s76
	global_load_lds_dwordx4 v176, s[64:65]
	s_add_u32 m0, s75, 0x400
	s_add_u32 s76, s76, s69
	global_load_lds_dwordx4 v177, s[64:65]
	s_mov_b32 m0, s76
	s_add_u32 s64, s64, 64
	s_addc_u32 s65, s65, 0
	global_load_lds_dwordx4 v178, s[66:67]
	global_load_lds_dwordx4 v178, s[66:67] offset:1024
	global_load_lds_dwordx4 v178, s[66:67] offset:2048
	global_load_lds_dwordx4 v178, s[66:67] offset:3072
	s_add_u32 s66, s66, 0x10000
	s_addc_u32 s67, s67, 0
	s_add_u32 s70, s70, 1
	s_cmp_eq_u32 s70, 3
	s_cselect_b32 s70, 0, s70
	s_mul_i32 s74, s70, 0x6000
	s_add_u32 s75, s74, s68
	s_mov_b32 m0, s75
	s_add_u32 s76, s74, 0x2000
	s_cmp_eq_u32 s70, 2
	s_cselect_b32 s76, 0x10000, s76
	global_load_lds_dwordx4 v176, s[64:65]
	s_add_u32 m0, s75, 0x400
	s_add_u32 s76, s76, s69
	global_load_lds_dwordx4 v177, s[64:65]
	s_mov_b32 m0, s76
	s_add_u32 s64, s64, 64
	s_addc_u32 s65, s65, 0
	global_load_lds_dwordx4 v178, s[66:67]
	global_load_lds_dwordx4 v178, s[66:67] offset:1024
	global_load_lds_dwordx4 v178, s[66:67] offset:2048
	global_load_lds_dwordx4 v178, s[66:67] offset:3072
	s_add_u32 s66, s66, 0x10000
	s_addc_u32 s67, s67, 0
	s_add_u32 s70, s70, 1
	s_cmp_eq_u32 s70, 3
	s_cselect_b32 s70, 0, s70
	s_cmp_lt_u32 s46, 0x100
	s_cbranch_scc1 .Lp10_nostag
	s_sleep 8
	s_setprio 1

; #define MFMA32(a, b, c) __builtin_amdgcn_mfma_f32_32x32x16_bf16((a), (b), (c), 0, 0, 0)
; #define GA_LOAD(pr_) do { _Pragma("unroll") for (int i = 0; i < 4; ++i) ra[i] = *(const u32x4*)(Ab + (i * 32) * lda + (pr_) * 64); } while (0)
; #define GB_LOAD(kt_) do { const bfr* bk_ = Bb + (kt_) * NB * 32; \
;     _Pragma("unroll") for (int i = 0; i < 4; ++i) rb[i] = *(const u32x4*)(bk_ + (i * 64) * 32); } while (0)
; #define G_STORE(kt_) do { bfr* as_ = S0 + ((kt_) & 1) * GSTAGE; bfr* bs_ = as_ + 128 * 40; \
;     if (apar == ((kt_) & 1)) { _Pragma("unroll") for (int i = 0; i < 4; ++i) *(u32x4*)(as_ + asoff + i * 32 * 40) = ra[i]; } \
;     _Pragma("unroll") for (int i = 0; i < 4; ++i) *(u32x4*)(bs_ + bsoff + i * 64 * 40) = rb[i]; } while (0)
; template <int lda>
; DI void gemm_mainloop(const bfr* __restrict__ A, const bfr* __restrict__ Bt, int NB, int K, int m0, int n0, char* smem, f32x16 (&acc)[2][4]) {
;     ...
;   for (int kt = 0; kt < nk; ++kt) {
;     if (kt + 1 < nk) G_STORE(kt + 1);
;     if (kt + 2 < nk) {
;       GB_LOAD(kt + 2);
;       if ((kt & 1) == 0) GA_LOAD((kt >> 1) + 1);
;     }
;     const bfr* As = S0 + (kt & 1) * GSTAGE;
;     const bfr* Bs = As + 128 * 40;
; #pragma unroll
;     for (int ks = 0; ks < 2; ++ks) {
;       bf16x8 af[2], bfg[4];
; #pragma unroll
;       for (int i = 0; i < 2; ++i) af[i] = *(const bf16x8*)(As + (wr * 64 + i * 32 + r) * 40 + ks * 16 + hl * 8);
; #pragma unroll
;       for (int j = 0; j < 4; ++j) bfg[j] = *(const bf16x8*)(Bs + (wc * 128 + j * 32 + r) * 40 + ks * 16 + hl * 8);
; #pragma unroll
;       for (int i = 0; i < 2; ++i)
; #pragma unroll
;         for (int j = 0; j < 4; ++j) acc[i][j] = MFMA32(af[i], bfg[j], acc[i][j]);
;     }
;     __syncthreads();
.Lp10_loop:
	s_waitcnt vmcnt(6)
	s_barrier
	s_mul_i32 s74, s71, 0x6000
	s_add_u32 s75, s74, 0x2000
	s_cmp_eq_u32 s71, 2
	s_cselect_b32 s75, 0x10000, s75
	v_add_u32_e32 v183, s74, v179
	v_add_u32_e32 v185, s75, v181
	v_add_u32_e32 v184, s74, v180
	v_add_u32_e32 v186, s75, v182
	ds_read_b128 v[128:131], v183
	ds_read_b128 v[144:147], v185
	ds_read_b128 v[148:151], v185 offset:2048
	ds_read_b128 v[152:155], v185 offset:4096
	ds_read_b128 v[156:159], v185 offset:6144
	ds_read_b128 v[132:135], v183 offset:2048
	ds_read_b128 v[136:139], v184
	ds_read_b128 v[160:163], v186
	ds_read_b128 v[164:167], v186 offset:2048
	ds_read_b128 v[168:171], v186 offset:4096
	ds_read_b128 v[172:175], v186 offset:6144
	ds_read_b128 v[140:143], v184 offset:2048
	s_add_u32 s71, s71, 1
	s_cmp_eq_u32 s71, 3
	s_cselect_b32 s71, 0, s71
	s_waitcnt lgkmcnt(10)
	v_mfma_f32_32x32x16_bf16 v[112:127], v[128:131], v[144:147], v[112:127]
	s_mul_i32 s74, s70, 0x6000
	s_add_u32 s75, s74, s68
	s_mov_b32 m0, s75
	s_add_u32 s76, s74, 0x2000
	s_cmp_eq_u32 s70, 2
	s_cselect_b32 s76, 0x10000, s76
	global_load_lds_dwordx4 v176, s[64:65]
	s_waitcnt lgkmcnt(9)
	v_mfma_f32_32x32x16_bf16 v[96:111], v[128:131], v[148:151], v[96:111]
	s_add_u32 m0, s75, 0x400
	s_add_u32 s76, s76, s69
	global_load_lds_dwordx4 v177, s[64:65]
	s_waitcnt lgkmcnt(8)
	v_mfma_f32_32x32x16_bf16 v[80:95], v[128:131], v[152:155], v[80:95]
	s_mov_b32 m0, s76
	s_add_u32 s64, s64, 64
	s_addc_u32 s65, s65, 0
	global_load_lds_dwordx4 v178, s[66:67]
	s_waitcnt lgkmcnt(7)
	v_mfma_f32_32x32x16_bf16 v[64:79], v[128:131], v[156:159], v[64:79]
	global_load_lds_dwordx4 v178, s[66:67] offset:1024
	s_waitcnt lgkmcnt(6)
	v_mfma_f32_32x32x16_bf16 v[48:63], v[132:135], v[144:147], v[48:63]
	global_load_lds_dwordx4 v178, s[66:67] offset:2048
	v_mfma_f32_32x32x16_bf16 v[32:47], v[132:135], v[148:151], v[32:47]
	global_load_lds_dwordx4 v178, s[66:67] offset:3072
	s_add_u32 s66, s66, 0x10000
	s_addc_u32 s67, s67, 0
	v_mfma_f32_32x32x16_bf16 v[16:31], v[132:135], v[152:155], v[16:31]
	s_add_u32 s70, s70, 1
	s_cmp_eq_u32 s70, 3
	s_cselect_b32 s70, 0, s70
	v_mfma_f32_32x32x16_bf16 v[0:15], v[132:135], v[156:159], v[0:15]
	s_waitcnt lgkmcnt(4)
	v_mfma_f32_32x32x16_bf16 v[112:127], v[136:139], v[160:163], v[112:127]
	s_waitcnt lgkmcnt(3)
	v_mfma_f32_32x32x16_bf16 v[96:111], v[136:139], v[164:167], v[96:111]
	s_waitcnt lgkmcnt(2)
	v_mfma_f32_32x32x16_bf16 v[80:95], v[136:139], v[168:171], v[80:95]
	s_waitcnt lgkmcnt(1)
	v_mfma_f32_32x32x16_bf16 v[64:79], v[136:139], v[172:175], v[64:79]
	s_waitcnt lgkmcnt(0)
	v_mfma_f32_32x32x16_bf16 v[48:63], v[140:143], v[160:163], v[48:63]
	v_mfma_f32_32x32x16_bf16 v[32:47], v[140:143], v[164:167], v[32:47]
	v_mfma_f32_32x32x16_bf16 v[16:31], v[140:143], v[168:171], v[16:31]
	v_mfma_f32_32x32x16_bf16 v[0:15], v[140:143], v[172:175], v[0:15]
	s_add_u32 s72, s72, 1
	s_cmp_lt_u32 s72, 30
	s_cbranch_scc1 .Lp10_loop
	s_waitcnt vmcnt(6)
	s_barrier
	s_mul_i32 s74, s71, 0x6000
	s_add_u32 s75, s74, 0x2000
	s_cmp_eq_u32 s71, 2
	s_cselect_b32 s75, 0x10000, s75
	v_add_u32_e32 v183, s74, v179
	v_add_u32_e32 v185, s75, v181
	v_add_u32_e32 v184, s74, v180
	v_add_u32_e32 v186, s75, v182
	ds_read_b128 v[128:131], v183
	ds_read_b128 v[144:147], v185
	ds_read_b128 v[148:151], v185 offset:2048
	ds_read_b128 v[152:155], v185 offset:4096
	ds_read_b128 v[156:159], v185 offset:6144
	ds_read_b128 v[132:135], v183 offset:2048
	ds_read_b128 v[136:139], v184
	ds_read_b128 v[160:163], v186
	ds_read_b128 v[164:167], v186 offset:2048
	ds_read_b128 v[168:171], v186 offset:4096
	ds_read_b128 v[172:175], v186 offset:6144
	ds_read_b128 v[140:143], v184 offset:2048
	s_add_u32 s71, s71, 1
	s_cmp_eq_u32 s71, 3
	s_cselect_b32 s71, 0, s71
	s_waitcnt lgkmcnt(10)
	v_mfma_f32_32x32x16_bf16 v[112:127], v[128:131], v[144:147], v[112:127]
	s_waitcnt lgkmcnt(9)
	v_mfma_f32_32x32x16_bf16 v[96:111], v[128:131], v[148:151], v[96:111]
	s_waitcnt lgkmcnt(8)
	v_mfma_f32_32x32x16_bf16 v[80:95], v[128:131], v[152:155], v[80:95]
	s_waitcnt lgkmcnt(7)
	v_mfma_f32_32x32x16_bf16 v[64:79], v[128:131], v[156:159], v[64:79]
	s_waitcnt lgkmcnt(6)
	v_mfma_f32_32x32x16_bf16 v[48:63], v[132:135], v[144:147], v[48:63]
	v_mfma_f32_32x32x16_bf16 v[32:47], v[132:135], v[148:151], v[32:47]
	v_mfma_f32_32x32x16_bf16 v[16:31], v[132:135], v[152:155], v[16:31]
	v_mfma_f32_32x32x16_bf16 v[0:15], v[132:135], v[156:159], v[0:15]
	s_waitcnt lgkmcnt(4)
	v_mfma_f32_32x32x16_bf16 v[112:127], v[136:139], v[160:163], v[112:127]
	s_waitcnt lgkmcnt(3)
	v_mfma_f32_32x32x16_bf16 v[96:111], v[136:139], v[164:167], v[96:111]
	s_waitcnt lgkmcnt(2)
	v_mfma_f32_32x32x16_bf16 v[80:95], v[136:139], v[168:171], v[80:95]
	s_waitcnt lgkmcnt(1)
	v_mfma_f32_32x32x16_bf16 v[64:79], v[136:139], v[172:175], v[64:79]
	s_waitcnt lgkmcnt(0)
	v_mfma_f32_32x32x16_bf16 v[48:63], v[140:143], v[160:163], v[48:63]
	v_mfma_f32_32x32x16_bf16 v[32:47], v[140:143], v[164:167], v[32:47]
	v_mfma_f32_32x32x16_bf16 v[16:31], v[140:143], v[168:171], v[16:31]
	v_mfma_f32_32x32x16_bf16 v[0:15], v[140:143], v[172:175], v[0:15]
	s_waitcnt vmcnt(0)
	s_barrier
; #define MFMA32(a, b, c) __builtin_amdgcn_mfma_f32_32x32x16_bf16((a), (b), (c), 0, 0, 0)
; template <int lda>
; DI void gemm_mainloop(const bfr* __restrict__ A, const bfr* __restrict__ Bt, int NB, int K, int m0, int n0, char* smem, f32x16 (&acc)[2][4]) {
;     ...
;     const bfr* As = S0 + (kt & 1) * GSTAGE;
;     const bfr* Bs = As + 128 * 40;
; #pragma unroll
;     for (int ks = 0; ks < 2; ++ks) {
;       bf16x8 af[2], bfg[4];
; #pragma unroll
;       for (int i = 0; i < 2; ++i) af[i] = *(const bf16x8*)(As + (wr * 64 + i * 32 + r) * 40 + ks * 16 + hl * 8);
; #pragma unroll
;       for (int j = 0; j < 4; ++j) bfg[j] = *(const bf16x8*)(Bs + (wc * 128 + j * 32 + r) * 40 + ks * 16 + hl * 8);
; #pragma unroll
;       for (int i = 0; i < 2; ++i)
; #pragma unroll
;         for (int j = 0; j < 4; ++j) acc[i][j] = MFMA32(af[i], bfg[j], acc[i][j]);
;     }
;     __syncthreads();
; template <bool FIRST, bool HAS_H>
; DI void phase_gemm_resid(const Params& p, const bfr* A, const bfr* Wt, const float* gnext, float* ss, char* smem) {
;     ...
;     int tid2 = threadIdx.x;
;     asm volatile("" : "+v"(tid2));
;     const int lane = tid2 & 63, wid = tid2 >> 6, wr = wid >> 1, wc = wid & 1, r = lane & 31, hl = lane >> 5;
;     const float* xsrc = FIRST ? p.x_prompt : X;
;     const int rbase = m0 + wr * 64 + 4 * hl, cbase = n0 + wc * 128 + r;
; #pragma unroll
;     for (int i = 0; i < 2; ++i) {
; #pragma unroll
;       for (int qh = 0; qh < 2; ++qh) {
;         float rs[8];
; #pragma unroll
;         for (int q = 0; q < 8; ++q) rs[q] = 0.f;
; #pragma unroll
;         for (int jh = 0; jh < 2; ++jh) {
;           float xo[2][8];
; #pragma unroll
;           for (int jj = 0; jj < 2; ++jj)
; #pragma unroll
;             for (int q = 0; q < 8; ++q)
;               xo[jj][q] = xsrc[(rbase + i * 32 + crow(qh * 8 + q, 0)) * 1024 + cbase + (jh * 2 + jj) * 32];
; #pragma unroll
;           for (int q = 0; q < 8; ++q) {
;             const int o = (rbase + i * 32 + crow(qh * 8 + q, 0)) * 1024 + cbase;
; #pragma unroll
;             for (int jj = 0; jj < 2; ++jj) {
;               const int j = jh * 2 + jj;
;               const float xn = xo[jj][q] + acc[i][j][qh * 8 + q];
;               X[o + j * 32] = xn;
;               if (HAS_H) Hn[o + j * 32] = f2bf(xn * gnext[cbase + j * 32]);
;               rs[q] += xn * xn;
;             }
;           }
;         }
	s_mul_i32 s74, s71, 0x6000
	s_add_u32 s75, s74, 0x2000
	s_cmp_eq_u32 s71, 2
	s_cselect_b32 s75, 0x10000, s75
	v_add_u32_e32 v183, s74, v179
	v_add_u32_e32 v185, s75, v181
	v_add_u32_e32 v184, s74, v180
	v_add_u32_e32 v186, s75, v182
	ds_read_b128 v[128:131], v183
	ds_read_b128 v[144:147], v185
	ds_read_b128 v[148:151], v185 offset:2048
	ds_read_b128 v[152:155], v185 offset:4096
	ds_read_b128 v[156:159], v185 offset:6144
	ds_read_b128 v[132:135], v183 offset:2048
	ds_read_b128 v[136:139], v184
	ds_read_b128 v[160:163], v186
	ds_read_b128 v[164:167], v186 offset:2048
	ds_read_b128 v[168:171], v186 offset:4096
	ds_read_b128 v[172:175], v186 offset:6144
	ds_read_b128 v[140:143], v184 offset:2048
	s_add_u32 s71, s71, 1
	s_cmp_eq_u32 s71, 3
	s_cselect_b32 s71, 0, s71
	s_waitcnt lgkmcnt(10)
	v_mfma_f32_32x32x16_bf16 v[112:127], v[128:131], v[144:147], v[112:127]
	s_waitcnt lgkmcnt(9)
	v_mfma_f32_32x32x16_bf16 v[96:111], v[128:131], v[148:151], v[96:111]
	s_waitcnt lgkmcnt(8)
	v_mfma_f32_32x32x16_bf16 v[80:95], v[128:131], v[152:155], v[80:95]
	s_waitcnt lgkmcnt(7)
	v_mfma_f32_32x32x16_bf16 v[64:79], v[128:131], v[156:159], v[64:79]
	s_waitcnt lgkmcnt(6)
	v_mfma_f32_32x32x16_bf16 v[48:63], v[132:135], v[144:147], v[48:63]
	v_mfma_f32_32x32x16_bf16 v[32:47], v[132:135], v[148:151], v[32:47]
	v_mfma_f32_32x32x16_bf16 v[16:31], v[132:135], v[152:155], v[16:31]
	v_mfma_f32_32x32x16_bf16 v[0:15], v[132:135], v[156:159], v[0:15]
	s_waitcnt lgkmcnt(4)
	v_mfma_f32_32x32x16_bf16 v[112:127], v[136:139], v[160:163], v[112:127]
	s_waitcnt lgkmcnt(3)
	v_mfma_f32_32x32x16_bf16 v[96:111], v[136:139], v[164:167], v[96:111]
	s_waitcnt lgkmcnt(2)
	v_mfma_f32_32x32x16_bf16 v[80:95], v[136:139], v[168:171], v[80:95]
	s_waitcnt lgkmcnt(1)
	v_mfma_f32_32x32x16_bf16 v[64:79], v[136:139], v[172:175], v[64:79]
	s_waitcnt lgkmcnt(0)
	v_mfma_f32_32x32x16_bf16 v[48:63], v[140:143], v[160:163], v[48:63]
	v_mfma_f32_32x32x16_bf16 v[32:47], v[140:143], v[164:167], v[32:47]
	v_mfma_f32_32x32x16_bf16 v[16:31], v[140:143], v[168:171], v[16:31]
	v_mfma_f32_32x32x16_bf16 v[0:15], v[140:143], v[172:175], v[0:15]
	s_setprio 0
	s_nop 7
	v_readlane_b32 s64, v187, 0
	v_readlane_b32 s65, v187, 1
	v_readlane_b32 s66, v187, 2
	v_readlane_b32 s67, v187, 3
	v_readlane_b32 s68, v187, 4
	v_readlane_b32 s69, v187, 5
	v_readlane_b32 s70, v187, 6
	v_readlane_b32 s71, v187, 7
	v_readlane_b32 s72, v187, 8
	v_readlane_b32 s73, v187, 9
	v_readlane_b32 s74, v187, 10
	v_readlane_b32 s75, v187, 11
	v_readlane_b32 s76, v187, 12
	v_readlane_b32 s77, v187, 13
	v_readlane_b32 s78, v187, 14
	v_readlane_b32 s79, v187, 15
	s_nop 7
	s_waitcnt vmcnt(1)
	s_nop 0
	s_nop 0
	s_nop 0
	s_waitcnt vmcnt(0)
	s_nop 0
	v_add_u32_e32 v132, v169, v171
	s_nop 0
	v_add_u32_e32 v133, v169, v170
	s_nop 0
	s_nop 0
	s_nop 0
	s_nop 0
	s_nop 0
	s_nop 0
	s_nop 0
	s_nop 0
	s_nop 0
	s_nop 0
	s_nop 0
	v_mov_b32_e32 v192, v196
	s_waitcnt lgkmcnt(0)
	s_nop 0
	s_nop 0
	s_nop 0
	s_nop 0
	s_nop 0
	s_nop 0
	s_nop 0
	s_nop 0
	s_nop 0
	s_nop 0
	s_nop 0
	s_nop 0
	s_nop 0
	s_nop 0
	s_nop 0
	s_nop 0
	s_nop 0
	s_waitcnt lgkmcnt(0)
	s_nop 0
	s_nop 0
	v_ashrrev_i32_e32 v194, 1, v192
	v_and_b32_e32 v194, 0xffffffc0, v194
	v_add_u32_e32 v194, s36, v194
	v_lshrrev_b32_e32 v195, 3, v192
	v_and_b32_e32 v229, 31, v192
	v_and_or_b32 v228, v195, 4, v194
	v_lshlrev_b32_e32 v192, 1, v192
	s_nop 0
	v_and_b32_e32 v192, 0x80, v192
	v_lshlrev_b32_e32 v204, 10, v228
	v_or3_b32 v202, s33, v192, v229
	v_or_b32_e32 v194, v204, v202
	v_ashrrev_i32_e32 v195, 31, v194
	v_or_b32_e32 v203, 32, v202
	v_or_b32_e32 v230, 0x2c00, v204
	s_nop 0
	v_or_b32_e32 v218, 0x400, v204
	v_or_b32_e32 v216, v218, v202
	v_ashrrev_i32_e32 v217, 31, v216
	v_lshl_add_u64 v[216:217], v[216:217], 2, s[10:11]
	global_load_dword v219, v[216:217], off
	v_or_b32_e32 v216, v218, v203
	v_ashrrev_i32_e32 v217, 31, v216
	s_nop 0
	v_ashrrev_i32_e32 v201, 31, v204
	v_mov_b32_e32 v200, v194
	v_lshl_add_u64 v[198:199], v[194:195], 2, s[10:11]
	v_lshl_add_u64 v[200:201], v[200:201], 2, s[10:11]
	global_load_dword v192, v[198:199], off
	global_load_dword v205, v[200:201], off offset:128
	v_lshl_add_u64 v[216:217], v[216:217], 2, s[10:11]
	s_nop 0
	v_or_b32_e32 v221, 0x800, v204
	global_load_dword v220, v[216:217], off
	v_or_b32_e32 v216, v221, v202
	v_ashrrev_i32_e32 v217, 31, v216
	v_lshl_add_u64 v[216:217], v[216:217], 2, s[10:11]
	global_load_dword v222, v[216:217], off
	v_or_b32_e32 v216, v221, v203
	v_ashrrev_i32_e32 v217, 31, v216
	v_lshl_add_u64 v[216:217], v[216:217], 2, s[10:11]
	global_load_dword v223, v[216:217], off
	s_nop 0
	v_or_b32_e32 v224, 0xc00, v204
	v_or_b32_e32 v225, 0x2000, v204
	v_or_b32_e32 v226, 0x2400, v204
	v_or_b32_e32 v227, 0x2800, v204
	v_or_b32_e32 v216, v224, v202
	v_ashrrev_i32_e32 v217, 31, v216
	v_lshl_add_u64 v[216:217], v[216:217], 2, s[10:11]
	s_nop 0
	v_cmp_eq_u32_e32 vcc, 31, v229
	v_ashrrev_i32_e32 v229, 31, v228
	s_nop 0
	s_nop 0
	s_nop 0
	s_nop 0
	s_nop 0
	s_waitcnt vmcnt(3)
; DI bfr f2bf(float a) { return (bfr)(pack2(a, 0.f) & 0xffffu); }
; DI int crow(int reg, int h) { return (reg & 3) + 8 * (reg >> 2) + 4 * h; }
; template <bool FIRST, bool HAS_H>
; DI void phase_gemm_resid(const Params& p, const bfr* A, const bfr* Wt, const float* gnext, float* ss, char* smem) {
;     ...
;     int tid2 = threadIdx.x;
;     asm volatile("" : "+v"(tid2));
;     const int lane = tid2 & 63, wid = tid2 >> 6, wr = wid >> 1, wc = wid & 1, r = lane & 31, hl = lane >> 5;
;     const float* xsrc = FIRST ? p.x_prompt : X;
;     const int rbase = m0 + wr * 64 + 4 * hl, cbase = n0 + wc * 128 + r;
; #pragma unroll
;     for (int i = 0; i < 2; ++i) {
; #pragma unroll
;       for (int qh = 0; qh < 2; ++qh) {
;         float rs[8];
; #pragma unroll
;         for (int q = 0; q < 8; ++q) rs[q] = 0.f;
; #pragma unroll
;         for (int jh = 0; jh < 2; ++jh) {
;           float xo[2][8];
; #pragma unroll
;           for (int jj = 0; jj < 2; ++jj)
; #pragma unroll
;             for (int q = 0; q < 8; ++q)
;               xo[jj][q] = xsrc[(rbase + i * 32 + crow(qh * 8 + q, 0)) * 1024 + cbase + (jh * 2 + jj) * 32];
; #pragma unroll
;           for (int q = 0; q < 8; ++q) {
;             const int o = (rbase + i * 32 + crow(qh * 8 + q, 0)) * 1024 + cbase;
; #pragma unroll
;             for (int jj = 0; jj < 2; ++jj) {
;               const int j = jh * 2 + jj;
;               const float xn = xo[jj][q] + acc[i][j][qh * 8 + q];
;               X[o + j * 32] = xn;
;               if (HAS_H) Hn[o + j * 32] = f2bf(xn * gnext[cbase + j * 32]);
;               rs[q] += xn * xn;
;             }
;           }
;         }
	s_nop 9
	v_add_f32_e32 v205, v96, v205
	s_nop 0
	v_or_b32_e32 v206, v225, v202
	v_or_b32_e32 v208, v226, v202
	v_ashrrev_i32_e32 v207, 31, v206
	v_ashrrev_i32_e32 v209, 31, v208
	v_lshl_add_u64 v[206:207], v[206:207], 2, s[10:11]
	v_lshl_add_u64 v[208:209], v[208:209], 2, s[10:11]
	v_or_b32_e32 v96, 0x420, v194
	s_nop 0
	v_or_b32_e32 v210, v227, v202
	v_ashrrev_i32_e32 v211, 31, v210
	v_or_b32_e32 v212, v230, v202
	v_lshl_add_u64 v[210:211], v[210:211], 2, s[10:11]
	v_ashrrev_i32_e32 v213, 31, v212
	v_lshl_add_u64 v[212:213], v[212:213], 2, s[10:11]
	global_load_dword v231, v[216:217], off
	global_load_dword v232, v[206:207], off
	global_load_dword v233, v[208:209], off
	global_load_dword v234, v[210:211], off
	global_load_dword v235, v[212:213], off
	v_or_b32_e32 v206, v224, v203
	v_or_b32_e32 v208, v225, v203
	v_or_b32_e32 v210, v226, v203
	v_ashrrev_i32_e32 v207, 31, v206
	v_ashrrev_i32_e32 v209, 31, v208
	v_ashrrev_i32_e32 v211, 31, v210
	v_or_b32_e32 v212, v227, v203
	v_or_b32_e32 v216, v230, v203
	v_lshl_add_u64 v[206:207], v[206:207], 2, s[10:11]
	v_lshl_add_u64 v[208:209], v[208:209], 2, s[10:11]
	v_lshl_add_u64 v[210:211], v[210:211], 2, s[10:11]
	v_ashrrev_i32_e32 v213, 31, v212
	v_ashrrev_i32_e32 v217, 31, v216
	v_lshl_add_u64 v[212:213], v[212:213], 2, s[10:11]
	v_lshl_add_u64 v[216:217], v[216:217], 2, s[10:11]
	global_load_dword v206, v[206:207], off
	s_nop 0
	global_load_dword v207, v[208:209], off
	s_nop 0
	global_load_dword v208, v[210:211], off
	global_load_dword v209, v[212:213], off
	s_nop 0
	global_load_dword v210, v[216:217], off
	v_add_f32_e32 v211, v112, v192
	v_or_b32_e32 v112, 0x400, v194
	global_store_dword v[198:199], v211, off
	v_lshlrev_b32_e32 v192, 2, v202
	s_nop 0
	v_add_f32_e32 v189, v113, v219
	v_ashrrev_i32_e32 v113, 31, v112
	global_load_dword v212, v192, s[12:13]
	v_lshl_add_u64 v[112:113], v[112:113], 2, s[10:11]
	global_store_dword v[198:199], v205, off offset:128
	global_load_dword v188, v192, s[12:13] offset:128
	s_waitcnt vmcnt(14)
	v_add_f32_e32 v98, v98, v223
	s_nop 0
	v_add_f32_e32 v185, v97, v220
	v_ashrrev_i32_e32 v97, 31, v96
	global_store_dword v[112:113], v189, off
	v_lshl_add_u64 v[96:97], v[96:97], 2, s[10:11]
	global_load_dword v184, v192, s[12:13]
	s_waitcnt vmcnt(15)
	v_add_f32_e32 v115, v115, v231
	s_nop 0
	v_or_b32_e32 v172, 0x800, v194
	v_ashrrev_i32_e32 v173, 31, v172
	global_store_dword v[96:97], v185, off
	v_add_f32_e32 v176, v114, v222
	v_lshl_add_u64 v[96:97], v[172:173], 2, s[10:11]
	v_or_b32_e32 v174, 0x820, v194
	global_load_dword v186, v192, s[12:13] offset:128
	v_ashrrev_i32_e32 v175, 31, v174
	global_store_dword v[96:97], v176, off
	global_load_dword v177, v192, s[12:13]
	v_lshl_add_u64 v[96:97], v[174:175], 2, s[10:11]
	global_store_dword v[96:97], v98, off
	global_load_dword v178, v192, s[12:13] offset:128
	s_nop 0
	v_lshl_add_u64 v[162:163], v[172:173], 1, s[6:7]
	v_lshl_add_u64 v[96:97], v[228:229], 2, s[14:15]
	s_waitcnt vmcnt(10)
	v_mul_f32_e32 v112, v211, v212
	s_nop 0
	v_cvt_pk_bf16_f32 v114, v112, s0
	v_lshl_add_u64 v[112:113], v[194:195], 1, s[6:7]
	global_store_short v[112:113], v114, off
	s_waitcnt vmcnt(9)
	v_mul_f32_e32 v114, v205, v188
	v_cvt_pk_bf16_f32 v114, v114, s0
	global_store_short v[112:113], v114, off offset:64
	v_mul_f32_e32 v114, v205, v205
	s_nop 0
	s_waitcnt vmcnt(8)
	v_mul_f32_e32 v160, v189, v184
	v_cvt_pk_bf16_f32 v160, v160, s0
	global_store_short v[112:113], v160, off offset:2048
	v_fmac_f32_e32 v114, v211, v211
	s_waitcnt vmcnt(7)
	v_mul_f32_e32 v160, v185, v186
	s_nop 0
	v_or_b32_e32 v152, 0xc00, v194
	v_ashrrev_i32_e32 v153, 31, v152
	v_lshl_add_u64 v[154:155], v[152:153], 2, s[10:11]
	global_store_dword v[154:155], v115, off
	s_waitcnt vmcnt(6)
	v_mul_f32_e32 v161, v176, v177
	v_cvt_pk_bf16_f32 v161, v161, s0
	global_store_short v[162:163], v161, off
	s_nop 0
	s_waitcnt vmcnt(5)
	v_mul_f32_e32 v161, v98, v178
	v_or_b32_e32 v154, 0xc20, v194
	v_cvt_pk_bf16_f32 v161, v161, s0
	v_lshl_add_u64 v[162:163], v[174:175], 1, s[6:7]
	v_ashrrev_i32_e32 v155, 31, v154
	global_store_short v[162:163], v161, off
	v_mul_f32_e32 v161, v98, v98
	s_nop 0
	global_load_dword v158, v192, s[12:13]
	v_add_f32_e32 v159, v99, v206
	v_lshl_add_u64 v[98:99], v[154:155], 2, s[10:11]
	global_store_dword v[98:99], v159, off
	global_load_dword v162, v192, s[12:13] offset:128
	v_or_b32_e32 v156, 0x2000, v194
	v_ashrrev_i32_e32 v157, 31, v156
	s_nop 0
	v_add_f32_e32 v163, v116, v232
	v_lshl_add_u64 v[98:99], v[156:157], 2, s[10:11]
	global_store_dword v[98:99], v163, off
	v_or_b32_e32 v116, 0x2400, v194
	v_add_f32_e32 v165, v117, v233
	v_ashrrev_i32_e32 v117, 31, v116
	v_add_f32_e32 v167, v102, v209
	s_nop 0
	v_or_b32_e32 v148, 0x2020, v194
	v_ashrrev_i32_e32 v149, 31, v148
	global_load_dword v150, v192, s[12:13]
	v_add_f32_e32 v151, v100, v207
	v_lshl_add_u64 v[98:99], v[148:149], 2, s[10:11]
	global_store_dword v[98:99], v151, off
	global_load_dword v164, v192, s[12:13] offset:128
	s_nop 0
	v_lshl_add_u64 v[98:99], v[116:117], 2, s[10:11]
	v_or_b32_e32 v140, 0x2420, v194
	global_store_dword v[98:99], v165, off
	v_ashrrev_i32_e32 v141, 31, v140
	v_lshl_add_u64 v[98:99], v[140:141], 2, s[10:11]
	v_add_f32_e32 v169, v119, v235
	v_add_f32_e32 v171, v103, v210
	s_nop 0
	global_load_dword v144, v192, s[12:13]
	v_add_f32_e32 v145, v101, v208
	global_store_dword v[98:99], v145, off
	global_load_dword v146, v192, s[12:13] offset:128
	v_add_f32_e32 v147, v118, v234
	v_cvt_pk_bf16_f32 v160, v160, s0
	global_store_short v[112:113], v160, off offset:2112
	s_nop 0
	v_or_b32_e32 v136, 0x2800, v194
	v_ashrrev_i32_e32 v137, 31, v136
	v_lshl_add_u64 v[98:99], v[136:137], 2, s[10:11]
; DI bfr f2bf(float a) { return (bfr)(pack2(a, 0.f) & 0xffffu); }
; DI int crow(int reg, int h) { return (reg & 3) + 8 * (reg >> 2) + 4 * h; }
; template <bool FIRST, bool HAS_H>
; DI void phase_gemm_resid(const Params& p, const bfr* A, const bfr* Wt, const float* gnext, float* ss, char* smem) {
;     ...
;     int tid2 = threadIdx.x;
;     asm volatile("" : "+v"(tid2));
;     const int lane = tid2 & 63, wid = tid2 >> 6, wr = wid >> 1, wc = wid & 1, r = lane & 31, hl = lane >> 5;
;     const float* xsrc = FIRST ? p.x_prompt : X;
;     const int rbase = m0 + wr * 64 + 4 * hl, cbase = n0 + wc * 128 + r;
; #pragma unroll
;     for (int i = 0; i < 2; ++i) {
; #pragma unroll
;       for (int qh = 0; qh < 2; ++qh) {
;         float rs[8];
; #pragma unroll
;         for (int q = 0; q < 8; ++q) rs[q] = 0.f;
; #pragma unroll
;         for (int jh = 0; jh < 2; ++jh) {
;           float xo[2][8];
; #pragma unroll
;           for (int jj = 0; jj < 2; ++jj)
; #pragma unroll
;             for (int q = 0; q < 8; ++q)
;               xo[jj][q] = xsrc[(rbase + i * 32 + crow(qh * 8 + q, 0)) * 1024 + cbase + (jh * 2 + jj) * 32];
; #pragma unroll
;           for (int q = 0; q < 8; ++q) {
;             const int o = (rbase + i * 32 + crow(qh * 8 + q, 0)) * 1024 + cbase;
; #pragma unroll
;             for (int jj = 0; jj < 2; ++jj) {
;               const int j = jh * 2 + jj;
;               const float xn = xo[jj][q] + acc[i][j][qh * 8 + q];
;               X[o + j * 32] = xn;
;               if (HAS_H) Hn[o + j * 32] = f2bf(xn * gnext[cbase + j * 32]);
;               rs[q] += xn * xn;
;             }
;           }
;         }
	global_store_dword v[98:99], v147, off
	global_load_dword v166, v192, s[12:13]
	v_lshl_add_u64 v[116:117], v[116:117], 1, s[6:7]
	v_mul_f32_e32 v160, v185, v185
	s_nop 0
	v_or_b32_e32 v128, 0x2820, v194
	v_ashrrev_i32_e32 v129, 31, v128
	v_lshl_add_u64 v[98:99], v[128:129], 2, s[10:11]
	global_store_dword v[98:99], v167, off
	global_load_dword v168, v192, s[12:13] offset:128
	v_or_b32_e32 v98, 0x2c00, v194
	v_ashrrev_i32_e32 v99, 31, v98
	v_lshl_add_u64 v[100:101], v[98:99], 2, s[10:11]
	global_store_dword v[100:101], v169, off
	global_load_dword v170, v192, s[12:13]
	v_or_b32_e32 v100, 0x2c20, v194
	v_ashrrev_i32_e32 v101, 31, v100
	v_lshl_add_u64 v[102:103], v[100:101], 2, s[10:11]
	global_store_dword v[102:103], v171, off
	v_or_b32_e32 v102, 64, v202
	v_or_b32_e32 v118, v218, v102
	v_or_b32_e32 v130, v221, v102
	v_or_b32_e32 v132, v224, v102
	v_or_b32_e32 v134, v225, v102
	v_ashrrev_i32_e32 v119, 31, v118
	v_ashrrev_i32_e32 v131, 31, v130
	v_ashrrev_i32_e32 v133, 31, v132
	v_ashrrev_i32_e32 v135, 31, v134
	v_or_b32_e32 v138, v226, v102
	v_or_b32_e32 v142, v227, v102
	v_lshl_add_u64 v[118:119], v[118:119], 2, s[10:11]
	v_lshl_add_u64 v[130:131], v[130:131], 2, s[10:11]
	v_lshl_add_u64 v[132:133], v[132:133], 2, s[10:11]
	v_lshl_add_u64 v[134:135], v[134:135], 2, s[10:11]
	v_ashrrev_i32_e32 v139, 31, v138
	v_ashrrev_i32_e32 v143, 31, v142
	v_lshl_add_u64 v[138:139], v[138:139], 2, s[10:11]
	s_waitcnt vmcnt(18)
	v_mul_f32_e32 v103, v115, v158
	v_lshl_add_u64 v[142:143], v[142:143], 2, s[10:11]
	global_load_dword v172, v[200:201], off offset:256
	global_load_dword v173, v[118:119], off
	s_nop 0
	global_load_dword v130, v[130:131], off
	s_nop 0
	global_load_dword v131, v[132:133], off
	s_nop 0
	global_load_dword v132, v[134:135], off
	global_load_dword v133, v[138:139], off
	s_nop 0
	global_load_dword v134, v[142:143], off
	global_load_dword v135, v[200:201], off offset:384
	v_cvt_pk_bf16_f32 v103, v103, s0
	v_lshl_add_u64 v[118:119], v[152:153], 1, s[6:7]
	global_store_short v[118:119], v103, off
	v_or_b32_e32 v103, 0x60, v202
	v_or_b32_e32 v118, v218, v103
	v_ashrrev_i32_e32 v119, 31, v118
	v_lshl_add_u64 v[118:119], v[118:119], 2, s[10:11]
	global_load_dword v138, v[118:119], off
	s_waitcnt vmcnt(26)
	v_mul_f32_e32 v118, v159, v162
	v_cvt_pk_bf16_f32 v139, v118, s0
	v_lshl_add_u64 v[118:119], v[154:155], 1, s[6:7]
	global_store_short v[118:119], v139, off
	v_or_b32_e32 v118, v221, v103
	v_mul_f32_e32 v139, v159, v159
	v_ashrrev_i32_e32 v119, 31, v118
	v_fmac_f32_e32 v139, v115, v115
	s_waitcnt vmcnt(25)
	v_mul_f32_e32 v115, v163, v150
	v_lshl_add_u64 v[118:119], v[118:119], 2, s[10:11]
	v_cvt_pk_bf16_f32 v115, v115, s0
	global_load_dword v142, v[118:119], off
	v_lshl_add_u64 v[118:119], v[156:157], 1, s[6:7]
	global_store_short v[118:119], v115, off
	s_waitcnt vmcnt(25)
	v_mul_f32_e32 v115, v151, v164
	v_cvt_pk_bf16_f32 v115, v115, s0
	v_lshl_add_u64 v[118:119], v[148:149], 1, s[6:7]
	global_store_short v[118:119], v115, off
	v_or_b32_e32 v118, v224, v103
	v_ashrrev_i32_e32 v119, 31, v118
	v_lshl_add_u64 v[118:119], v[118:119], 2, s[10:11]
	global_load_dword v143, v[118:119], off
	s_waitcnt vmcnt(25)
	v_mul_f32_e32 v118, v165, v144
	v_cvt_pk_bf16_f32 v118, v118, s0
	global_store_short v[116:117], v118, off
	s_waitcnt vmcnt(24)
	v_mul_f32_e32 v116, v145, v146
	v_cvt_pk_bf16_f32 v118, v116, s0
	v_lshl_add_u64 v[116:117], v[140:141], 1, s[6:7]
	global_store_short v[116:117], v118, off
	v_or_b32_e32 v116, v225, v103
	v_ashrrev_i32_e32 v117, 31, v116
	v_lshl_add_u64 v[116:117], v[116:117], 2, s[10:11]
	global_load_dword v140, v[116:117], off
	s_waitcnt vmcnt(23)
	v_mul_f32_e32 v116, v147, v166
	v_cvt_pk_bf16_f32 v118, v116, s0
	v_lshl_add_u64 v[116:117], v[136:137], 1, s[6:7]
	global_store_short v[116:117], v118, off
	v_mul_f32_e32 v137, v167, v167
	v_mul_f32_e32 v141, v145, v145
	v_fmac_f32_e32 v137, v147, v147
	global_load_dword v145, v192, s[12:13] offset:128
	s_waitcnt vmcnt(23)
	v_mul_f32_e32 v116, v167, v168
	v_cvt_pk_bf16_f32 v118, v116, s0
	v_or_b32_e32 v116, v226, v103
	v_ashrrev_i32_e32 v117, 31, v116
	v_lshl_add_u64 v[116:117], v[116:117], 2, s[10:11]
	global_load_dword v136, v[116:117], off
	v_lshl_add_u64 v[116:117], v[128:129], 1, s[6:7]
	global_store_short v[116:117], v118, off
	v_or_b32_e32 v118, v227, v103
	s_waitcnt vmcnt(23)
	v_mul_f32_e32 v116, v169, v170
	v_ashrrev_i32_e32 v119, 31, v118
	v_cvt_pk_bf16_f32 v144, v116, s0
	v_or_b32_e32 v116, v230, v102
	v_lshl_add_u64 v[118:119], v[118:119], 2, s[10:11]
	global_load_dword v146, v[118:119], off
	v_ashrrev_i32_e32 v117, 31, v116
	v_or_b32_e32 v118, v230, v103
	v_lshl_add_u64 v[116:117], v[116:117], 2, s[10:11]
	v_ashrrev_i32_e32 v119, 31, v118
	v_lshl_add_u64 v[118:119], v[118:119], 2, s[10:11]
	global_load_dword v147, v[116:117], off
	global_load_dword v148, v[118:119], off
	v_mul_f32_e32 v115, v151, v151
	v_fmac_f32_e32 v115, v163, v163
	s_waitcnt vmcnt(24)
	v_add_f32_e32 v149, v80, v172
	global_store_dword v[198:199], v149, off offset:256
	v_or_b32_e32 v80, 0x440, v194
	global_load_dword v150, v192, s[12:13] offset:256
	s_waitcnt vmcnt(25)
	v_add_f32_e32 v152, v81, v173
	v_ashrrev_i32_e32 v81, 31, v80
	v_lshl_add_u64 v[80:81], v[80:81], 2, s[10:11]
	s_waitcnt vmcnt(19)
	v_add_f32_e32 v135, v64, v135
	v_or_b32_e32 v64, 0x460, v194
	global_store_dword v[198:199], v135, off offset:384
	global_load_dword v151, v192, s[12:13] offset:384
	v_add_f32_e32 v155, v82, v130
	global_store_dword v[80:81], v152, off
	global_load_dword v153, v192, s[12:13] offset:256
	v_or_b32_e32 v82, 0xc40, v194
	s_waitcnt vmcnt(21)
; DI bfr f2bf(float a) { return (bfr)(pack2(a, 0.f) & 0xffffu); }
; DI int crow(int reg, int h) { return (reg & 3) + 8 * (reg >> 2) + 4 * h; }
; template <bool FIRST, bool HAS_H>
; DI void phase_gemm_resid(const Params& p, const bfr* A, const bfr* Wt, const float* gnext, float* ss, char* smem) {
;     ...
;     int tid2 = threadIdx.x;
;     asm volatile("" : "+v"(tid2));
;     const int lane = tid2 & 63, wid = tid2 >> 6, wr = wid >> 1, wc = wid & 1, r = lane & 31, hl = lane >> 5;
;     const float* xsrc = FIRST ? p.x_prompt : X;
;     const int rbase = m0 + wr * 64 + 4 * hl, cbase = n0 + wc * 128 + r;
; #pragma unroll
;     for (int i = 0; i < 2; ++i) {
; #pragma unroll
;       for (int qh = 0; qh < 2; ++qh) {
;         float rs[8];
; #pragma unroll
;         for (int q = 0; q < 8; ++q) rs[q] = 0.f;
; #pragma unroll
;         for (int jh = 0; jh < 2; ++jh) {
;           float xo[2][8];
; #pragma unroll
;           for (int jj = 0; jj < 2; ++jj)
; #pragma unroll
;             for (int q = 0; q < 8; ++q)
;               xo[jj][q] = xsrc[(rbase + i * 32 + crow(qh * 8 + q, 0)) * 1024 + cbase + (jh * 2 + jj) * 32];
; #pragma unroll
;           for (int q = 0; q < 8; ++q) {
;             const int o = (rbase + i * 32 + crow(qh * 8 + q, 0)) * 1024 + cbase;
; #pragma unroll
;             for (int jj = 0; jj < 2; ++jj) {
;               const int j = jh * 2 + jj;
;               const float xn = xo[jj][q] + acc[i][j][qh * 8 + q];
;               X[o + j * 32] = xn;
;               if (HAS_H) Hn[o + j * 32] = f2bf(xn * gnext[cbase + j * 32]);
;               rs[q] += xn * xn;
;             }
;           }
;         }
	v_add_f32_e32 v138, v65, v138
	v_ashrrev_i32_e32 v65, 31, v64
	v_lshl_add_u64 v[64:65], v[64:65], 2, s[10:11]
	global_store_dword v[64:65], v138, off
	v_or_b32_e32 v64, 0x840, v194
	v_ashrrev_i32_e32 v65, 31, v64
	v_lshl_add_u64 v[80:81], v[64:65], 2, s[10:11]
	global_load_dword v154, v192, s[12:13] offset:384
	v_add_f32_e32 v158, v83, v131
	global_store_dword v[80:81], v155, off
	v_or_b32_e32 v80, 0x860, v194
	v_ashrrev_i32_e32 v81, 31, v80
	global_load_dword v156, v192, s[12:13] offset:256
	s_waitcnt vmcnt(23)
	v_add_f32_e32 v142, v66, v142
	v_lshl_add_u64 v[116:117], v[80:81], 2, s[10:11]
	v_ashrrev_i32_e32 v83, 31, v82
	v_or_b32_e32 v66, 0xc60, v194
	global_store_dword v[116:117], v142, off
	v_lshl_add_u64 v[116:117], v[82:83], 2, s[10:11]
	global_load_dword v157, v192, s[12:13] offset:384
	v_add_f32_e32 v163, v84, v132
	global_store_dword v[116:117], v158, off
	s_waitcnt vmcnt(23)
	v_add_f32_e32 v143, v67, v143
	v_ashrrev_i32_e32 v67, 31, v66
	v_lshl_add_u64 v[116:117], v[66:67], 2, s[10:11]
	global_load_dword v159, v192, s[12:13] offset:256
	v_or_b32_e32 v84, 0x2440, v194
	global_store_dword v[116:117], v143, off
	v_or_b32_e32 v116, 0x2040, v194
	v_ashrrev_i32_e32 v117, 31, v116
	v_lshl_add_u64 v[118:119], v[116:117], 2, s[10:11]
	global_load_dword v162, v192, s[12:13] offset:384
	v_add_f32_e32 v166, v85, v133
	global_store_dword v[118:119], v163, off
	v_or_b32_e32 v118, 0x2060, v194
	v_ashrrev_i32_e32 v119, 31, v118
	global_load_dword v164, v192, s[12:13] offset:256
	s_waitcnt vmcnt(25)
	v_add_f32_e32 v140, v68, v140
	v_lshl_add_u64 v[128:129], v[118:119], 2, s[10:11]
	v_ashrrev_i32_e32 v85, 31, v84
	v_or_b32_e32 v68, 0x2460, v194
	global_store_dword v[128:129], v140, off
	v_lshl_add_u64 v[128:129], v[84:85], 2, s[10:11]
	v_fmac_f32_e32 v141, v165, v165
	global_load_dword v165, v192, s[12:13] offset:384
	v_add_f32_e32 v134, v86, v134
	global_store_dword v[128:129], v166, off
	s_waitcnt vmcnt(25)
	v_add_f32_e32 v136, v69, v136
	v_ashrrev_i32_e32 v69, 31, v68
	v_lshl_add_u64 v[128:129], v[68:69], 2, s[10:11]
	global_load_dword v167, v192, s[12:13] offset:256
	v_or_b32_e32 v86, 0x2c40, v194
	global_store_dword v[128:129], v136, off
	v_or_b32_e32 v128, 0x2840, v194
	v_ashrrev_i32_e32 v129, 31, v128
	v_lshl_add_u64 v[130:131], v[128:129], 2, s[10:11]
	global_load_dword v168, v192, s[12:13] offset:384
	s_waitcnt vmcnt(26)
	v_add_f32_e32 v146, v70, v146
	global_store_dword v[130:131], v134, off
	v_or_b32_e32 v130, 0x2860, v194
	v_ashrrev_i32_e32 v131, 31, v130
	global_load_dword v170, v192, s[12:13] offset:256
	v_lshl_add_u64 v[132:133], v[130:131], 2, s[10:11]
	global_store_dword v[132:133], v146, off
	s_waitcnt vmcnt(28)
	v_add_f32_e32 v147, v87, v147
	v_ashrrev_i32_e32 v87, 31, v86
	global_load_dword v172, v192, s[12:13] offset:384
	v_lshl_add_u64 v[132:133], v[86:87], 2, s[10:11]
	v_or_b32_e32 v70, 0x2c60, v194
	global_store_dword v[132:133], v147, off
	s_waitcnt vmcnt(29)
	v_add_f32_e32 v148, v71, v148
	v_ashrrev_i32_e32 v71, 31, v70
	global_load_dword v173, v192, s[12:13] offset:256
	v_lshl_add_u64 v[132:133], v[70:71], 2, s[10:11]
	global_store_dword v[132:133], v148, off
	global_load_dword v132, v192, s[12:13] offset:384
	v_lshl_add_u64 v[98:99], v[98:99], 1, s[6:7]
	global_store_short v[98:99], v144, off
	v_mul_f32_e32 v98, v171, v145
	v_cvt_pk_bf16_f32 v133, v98, s0
	v_lshl_add_u64 v[98:99], v[100:101], 1, s[6:7]
	global_store_short v[98:99], v133, off
	s_waitcnt vmcnt(32)
	v_mul_f32_e32 v99, v149, v150
	v_cvt_pk_bf16_f32 v99, v99, s0
	global_store_short v[112:113], v99, off offset:128
	s_waitcnt vmcnt(31)
	v_mul_f32_e32 v99, v135, v151
	v_cvt_pk_bf16_f32 v99, v99, s0
	global_store_short v[112:113], v99, off offset:192
	s_waitcnt vmcnt(30)
	v_mul_f32_e32 v99, v152, v153
	v_cvt_pk_bf16_f32 v99, v99, s0
	global_store_short v[112:113], v99, off offset:2176
	s_waitcnt vmcnt(29)
	v_mul_f32_e32 v99, v138, v154
	v_cvt_pk_bf16_f32 v99, v99, s0
	global_store_short v[112:113], v99, off offset:2240
	s_waitcnt vmcnt(28)
	v_mul_f32_e32 v99, v155, v156
	v_cvt_pk_bf16_f32 v99, v99, s0
	v_lshl_add_u64 v[64:65], v[64:65], 1, s[6:7]
	global_store_short v[64:65], v99, off
	v_mul_f32_e32 v98, v171, v171
	s_waitcnt vmcnt(27)
	v_mul_f32_e32 v64, v142, v157
	v_cvt_pk_bf16_f32 v99, v64, s0
	v_lshl_add_u64 v[64:65], v[80:81], 1, s[6:7]
	global_store_short v[64:65], v99, off
	v_fmac_f32_e32 v160, v189, v189
	v_fmac_f32_e32 v161, v176, v176
	s_waitcnt vmcnt(26)
	v_mul_f32_e32 v64, v158, v159
	v_cvt_pk_bf16_f32 v80, v64, s0
	v_lshl_add_u64 v[64:65], v[82:83], 1, s[6:7]
	global_store_short v[64:65], v80, off
	v_fmac_f32_e32 v98, v169, v169
	v_fmac_f32_e32 v114, v149, v149
	s_waitcnt vmcnt(25)
	v_mul_f32_e32 v64, v143, v162
	v_cvt_pk_bf16_f32 v80, v64, s0
	v_lshl_add_u64 v[64:65], v[66:67], 1, s[6:7]
	global_store_short v[64:65], v80, off
	v_fmac_f32_e32 v160, v152, v152
	s_waitcnt vmcnt(24)
	v_mul_f32_e32 v64, v163, v164
	v_cvt_pk_bf16_f32 v66, v64, s0
	v_lshl_add_u64 v[64:65], v[116:117], 1, s[6:7]
	global_store_short v[64:65], v66, off
	v_fmac_f32_e32 v161, v155, v155
	v_fmac_f32_e32 v139, v158, v158
	v_fmac_f32_e32 v115, v163, v163
	v_fmac_f32_e32 v141, v166, v166
	s_waitcnt vmcnt(23)
	v_mul_f32_e32 v64, v140, v165
	v_cvt_pk_bf16_f32 v66, v64, s0
	v_lshl_add_u64 v[64:65], v[118:119], 1, s[6:7]
	global_store_short v[64:65], v66, off
	v_fmac_f32_e32 v137, v134, v134
	v_fmac_f32_e32 v98, v147, v147
	s_waitcnt vmcnt(22)
; DI bfr f2bf(float a) { return (bfr)(pack2(a, 0.f) & 0xffffu); }
; #define DPPF(v, ctrl, rmask) __builtin_bit_cast(float, __builtin_amdgcn_update_dpp(0, __builtin_bit_cast(int, (v)), (ctrl), (rmask), 0xf, false))
; DI int crow(int reg, int h) { return (reg & 3) + 8 * (reg >> 2) + 4 * h; }
; DI float row16_sum(float v) {
;   v += DPPF(v, 0xB1, 0xf);
;   v += DPPF(v, 0x4E, 0xf);
;   v += DPPF(v, 0x141, 0xf);
;   v += DPPF(v, 0x140, 0xf);
;   return v;
; }
; DI float half32_sum_hi(float v) {
;   v = row16_sum(v);
;   v += DPPF(v, 0x142, 0xa);
;   return v;
; template <bool FIRST, bool HAS_H>
; DI void phase_gemm_resid(const Params& p, const bfr* A, const bfr* Wt, const float* gnext, float* ss, char* smem) {
;     ...
;           for (int q = 0; q < 8; ++q) {
;             const int o = (rbase + i * 32 + crow(qh * 8 + q, 0)) * 1024 + cbase;
; #pragma unroll
;             for (int jj = 0; jj < 2; ++jj) {
;               const int j = jh * 2 + jj;
;               const float xn = xo[jj][q] + acc[i][j][qh * 8 + q];
;               X[o + j * 32] = xn;
;               if (HAS_H) Hn[o + j * 32] = f2bf(xn * gnext[cbase + j * 32]);
;               rs[q] += xn * xn;
;             }
;           }
;         }
; #pragma unroll
;         for (int q = 0; q < 8; ++q) rs[q] = half32_sum_hi(rs[q]);
;         if (r == 31) {
; #pragma unroll
;           for (int q = 0; q < 8; ++q) unsafeAtomicAdd(ss + rbase + i * 32 + crow(qh * 8 + q, 0), rs[q]);
	v_mul_f32_e32 v64, v166, v167
	v_cvt_pk_bf16_f32 v66, v64, s0
	v_lshl_add_u64 v[64:65], v[84:85], 1, s[6:7]
	global_store_short v[64:65], v66, off
	v_fmac_f32_e32 v114, v135, v135
	v_fmac_f32_e32 v160, v138, v138
	s_waitcnt vmcnt(21)
	v_mul_f32_e32 v64, v136, v168
	v_cvt_pk_bf16_f32 v66, v64, s0
	v_lshl_add_u64 v[64:65], v[68:69], 1, s[6:7]
	global_store_short v[64:65], v66, off
	v_fmac_f32_e32 v161, v142, v142
	s_waitcnt vmcnt(20)
	v_mul_f32_e32 v64, v134, v170
	v_cvt_pk_bf16_f32 v66, v64, s0
	v_lshl_add_u64 v[64:65], v[128:129], 1, s[6:7]
	global_store_short v[64:65], v66, off
	v_fmac_f32_e32 v139, v143, v143
	s_waitcnt vmcnt(19)
	v_mul_f32_e32 v64, v146, v172
	v_cvt_pk_bf16_f32 v66, v64, s0
	v_lshl_add_u64 v[64:65], v[130:131], 1, s[6:7]
	global_store_short v[64:65], v66, off
	v_fmac_f32_e32 v115, v140, v140
	v_fmac_f32_e32 v141, v136, v136
	s_waitcnt vmcnt(18)
	v_mul_f32_e32 v64, v147, v173
	v_cvt_pk_bf16_f32 v66, v64, s0
	v_lshl_add_u64 v[64:65], v[86:87], 1, s[6:7]
	global_store_short v[64:65], v66, off
	s_waitcnt vmcnt(17)
	v_mul_f32_e32 v64, v148, v132
	v_fmac_f32_e32 v137, v146, v146
	v_cvt_pk_bf16_f32 v66, v64, s0
	v_lshl_add_u64 v[64:65], v[70:71], 1, s[6:7]
	v_fmac_f32_e32 v98, v148, v148
	global_store_short v[64:65], v66, off
	v_add_f32_dpp v64, v114, v114 quad_perm:[1,0,3,2] row_mask:0xf bank_mask:0xf bound_ctrl:1
	v_add_f32_dpp v66, v160, v160 quad_perm:[1,0,3,2] row_mask:0xf bank_mask:0xf bound_ctrl:1
	v_add_f32_dpp v68, v161, v161 quad_perm:[1,0,3,2] row_mask:0xf bank_mask:0xf bound_ctrl:1
	v_add_f32_dpp v70, v139, v139 quad_perm:[1,0,3,2] row_mask:0xf bank_mask:0xf bound_ctrl:1
	v_add_f32_dpp v80, v115, v115 quad_perm:[1,0,3,2] row_mask:0xf bank_mask:0xf bound_ctrl:1
	v_add_f32_dpp v82, v141, v141 quad_perm:[1,0,3,2] row_mask:0xf bank_mask:0xf bound_ctrl:1
	v_add_f32_dpp v84, v137, v137 quad_perm:[1,0,3,2] row_mask:0xf bank_mask:0xf bound_ctrl:1
	v_add_f32_dpp v86, v98, v98 quad_perm:[1,0,3,2] row_mask:0xf bank_mask:0xf bound_ctrl:1
	v_add_f32_dpp v64, v64, v64 quad_perm:[2,3,0,1] row_mask:0xf bank_mask:0xf bound_ctrl:1
	v_add_f32_dpp v66, v66, v66 quad_perm:[2,3,0,1] row_mask:0xf bank_mask:0xf bound_ctrl:1
	v_add_f32_dpp v68, v68, v68 quad_perm:[2,3,0,1] row_mask:0xf bank_mask:0xf bound_ctrl:1
	v_add_f32_dpp v70, v70, v70 quad_perm:[2,3,0,1] row_mask:0xf bank_mask:0xf bound_ctrl:1
	v_add_f32_dpp v80, v80, v80 quad_perm:[2,3,0,1] row_mask:0xf bank_mask:0xf bound_ctrl:1
	v_add_f32_dpp v82, v82, v82 quad_perm:[2,3,0,1] row_mask:0xf bank_mask:0xf bound_ctrl:1
	v_add_f32_dpp v84, v84, v84 quad_perm:[2,3,0,1] row_mask:0xf bank_mask:0xf bound_ctrl:1
	v_add_f32_dpp v86, v86, v86 quad_perm:[2,3,0,1] row_mask:0xf bank_mask:0xf bound_ctrl:1
	v_add_f32_dpp v64, v64, v64 row_half_mirror row_mask:0xf bank_mask:0xf bound_ctrl:1
	v_add_f32_dpp v66, v66, v66 row_half_mirror row_mask:0xf bank_mask:0xf bound_ctrl:1
	v_add_f32_dpp v68, v68, v68 row_half_mirror row_mask:0xf bank_mask:0xf bound_ctrl:1
	v_add_f32_dpp v70, v70, v70 row_half_mirror row_mask:0xf bank_mask:0xf bound_ctrl:1
	v_add_f32_dpp v80, v80, v80 row_half_mirror row_mask:0xf bank_mask:0xf bound_ctrl:1
	v_add_f32_dpp v82, v82, v82 row_half_mirror row_mask:0xf bank_mask:0xf bound_ctrl:1
	v_add_f32_dpp v84, v84, v84 row_half_mirror row_mask:0xf bank_mask:0xf bound_ctrl:1
	v_add_f32_dpp v86, v86, v86 row_half_mirror row_mask:0xf bank_mask:0xf bound_ctrl:1
	v_add_f32_dpp v64, v64, v64 row_mirror row_mask:0xf bank_mask:0xf bound_ctrl:1
	v_mov_b32_e32 v65, 0
	v_add_f32_dpp v66, v66, v66 row_mirror row_mask:0xf bank_mask:0xf bound_ctrl:1
	v_mov_b32_e32 v67, 0
	v_add_f32_dpp v68, v68, v68 row_mirror row_mask:0xf bank_mask:0xf bound_ctrl:1
	v_mov_b32_e32 v69, 0
	v_add_f32_dpp v70, v70, v70 row_mirror row_mask:0xf bank_mask:0xf bound_ctrl:1
	v_mov_b32_e32 v71, 0
	v_add_f32_dpp v80, v80, v80 row_mirror row_mask:0xf bank_mask:0xf bound_ctrl:1
	v_mov_b32_e32 v81, 0
	v_add_f32_dpp v82, v82, v82 row_mirror row_mask:0xf bank_mask:0xf bound_ctrl:1
	v_mov_b32_e32 v83, 0
	v_add_f32_dpp v84, v84, v84 row_mirror row_mask:0xf bank_mask:0xf bound_ctrl:1
	v_mov_b32_e32 v85, 0
	v_add_f32_dpp v86, v86, v86 row_mirror row_mask:0xf bank_mask:0xf bound_ctrl:1
	v_mov_b32_e32 v87, 0
	v_mov_b32_dpp v65, v64 row_bcast:15 row_mask:0xa bank_mask:0xf
	v_mov_b32_dpp v67, v66 row_bcast:15 row_mask:0xa bank_mask:0xf
	v_mov_b32_dpp v69, v68 row_bcast:15 row_mask:0xa bank_mask:0xf
	v_mov_b32_dpp v71, v70 row_bcast:15 row_mask:0xa bank_mask:0xf
	v_mov_b32_dpp v81, v80 row_bcast:15 row_mask:0xa bank_mask:0xf
	v_mov_b32_dpp v83, v82 row_bcast:15 row_mask:0xa bank_mask:0xf
	v_mov_b32_dpp v85, v84 row_bcast:15 row_mask:0xa bank_mask:0xf
	v_mov_b32_dpp v87, v86 row_bcast:15 row_mask:0xa bank_mask:0xf
	s_and_saveexec_b64 s[4:5], vcc
	s_cbranch_execz .LBB0_1112
	v_add_f32_e32 v64, v64, v65
	v_add_f32_e32 v86, v86, v87
	v_add_f32_e32 v84, v84, v85
	v_add_f32_e32 v82, v82, v83
	v_add_f32_e32 v80, v80, v81
	v_add_f32_e32 v70, v70, v71
	v_add_f32_e32 v68, v68, v69
	v_add_f32_e32 v66, v66, v67
	global_atomic_add_f32 v[96:97], v64, off
	global_atomic_add_f32 v[96:97], v66, off offset:4
	global_atomic_add_f32 v[96:97], v68, off offset:8
	global_atomic_add_f32 v[96:97], v70, off offset:12
	global_atomic_add_f32 v[96:97], v80, off offset:32
	global_atomic_add_f32 v[96:97], v82, off offset:36
	global_atomic_add_f32 v[96:97], v84, off offset:40
	global_atomic_add_f32 v[96:97], v86, off offset:44

; #define GA_LOAD(pr_) do { _Pragma("unroll") for (int i = 0; i < 4; ++i) ra[i] = *(const u32x4*)(Ab + (i * 32) * lda + (pr_) * 64); } while (0)
; #define GB_LOAD(kt_) do { const bfr* bk_ = Bb + (kt_) * NB * 32; \
;     _Pragma("unroll") for (int i = 0; i < 4; ++i) rb[i] = *(const u32x4*)(bk_ + (i * 64) * 32); } while (0)
; #define G_STORE(kt_) do { bfr* as_ = S0 + ((kt_) & 1) * GSTAGE; bfr* bs_ = as_ + 128 * 40; \
;     if (apar == ((kt_) & 1)) { _Pragma("unroll") for (int i = 0; i < 4; ++i) *(u32x4*)(as_ + asoff + i * 32 * 40) = ra[i]; } \
;     _Pragma("unroll") for (int i = 0; i < 4; ++i) *(u32x4*)(bs_ + bsoff + i * 64 * 40) = rb[i]; } while (0)
; template <int lda>
; DI void gemm_mainloop(const bfr* __restrict__ A, const bfr* __restrict__ Bt, int NB, int K, int m0, int n0, char* smem, f32x16 (&acc)[2][4]) {
;   bfr* S0 = (bfr*)smem;
;   int tid = threadIdx.x;
;   asm volatile("" : "+v"(tid));
;   const int lane = tid & 63, wid = tid >> 6, wr = wid >> 1, wc = wid & 1;
;   const int r = lane & 31, hl = lane >> 5;
; #pragma unroll
;   for (int i = 0; i < 2; ++i)
; #pragma unroll
;     for (int j = 0; j < 4; ++j)
; #pragma unroll
;       for (int q = 0; q < 16; ++q) acc[i][j][q] = 0.f;
;   u32x4 ra[4], rb[4];
;   const int nk = K >> 5;
;   const int arow = tid >> 3, ac8 = tid & 7, apar = ac8 >> 2;
;   const bfr* Ab = A + (m0 + arow) * lda + ac8 * 8;
;   const int asoff = arow * 40 + (ac8 & 3) * 8;
;   const int brow = tid >> 2, bc4 = tid & 3;
;   const bfr* Bb = Bt + (n0 + brow) * 32 + bc4 * 8;
;   const int bsoff = brow * 40 + bc4 * 8;
;     ...
;   GA_LOAD(0);
;   GB_LOAD(0);
;   G_STORE(0);
;   GB_LOAD(1);
;   __syncthreads();
; DI void phase_gemm_bf16out(const Params& p, const bfr* A, const bfr* Wt, bfr* C, int N, const float* ss, char* smem) {
;     ...
;   for (int t0 = blockIdx.x; t0 < 128 * ntn; t0 += gridDim.x) {
;     const int t = ((gridDim.x & 7) == 0) ? xcd_tile(t0, ntn) : t0;
;     int mt = t / ntn, nt = t % ntn;
;     gemm_tile<1024>(A, Wt, N, 1024, mt * 128, nt * 256, smem,
.LBB0_1181:
	s_ashr_i32 s5, s4, 31
	s_lshr_b32 s5, s5, 29
	s_add_i32 s5, s4, s5
	s_and_b32 s18, s5, 0xfffff8
	s_lshl_b32 s5, s5, 4
	s_and_b32 s30, s5, 0xffffff80
	s_sub_i32 s4, s4, s18
	s_lshl_b32 s29, s4, 8
	s_mov_b32 s31, 0
	s_mov_b64 s[18:19], 0
	s_lshl_b32 s98, s30, 11
	s_add_u32 s98, s10, s98
	s_addc_u32 s99, s11, 0
	s_lshl_b32 s100, s29, 6
	s_add_u32 s100, s12, s100
	s_addc_u32 s101, s13, 0
	v_writelane_b32 v187, s64, 0
	v_writelane_b32 v187, s65, 1
	v_writelane_b32 v187, s66, 2
	v_writelane_b32 v187, s67, 3
	v_writelane_b32 v187, s68, 4
	v_writelane_b32 v187, s69, 5
	v_writelane_b32 v187, s70, 6
	v_writelane_b32 v187, s71, 7
	v_writelane_b32 v187, s72, 8
	v_writelane_b32 v187, s73, 9
	v_writelane_b32 v187, s74, 10
	v_writelane_b32 v187, s75, 11
	v_writelane_b32 v187, s76, 12
	v_writelane_b32 v187, s77, 13
	v_writelane_b32 v187, s78, 14
	v_writelane_b32 v187, s79, 15
	v_lshrrev_b32_e32 v188, 6, v196
	v_and_b32_e32 v189, 63, v196
	v_readfirstlane_b32 s73, v188
	v_lshrrev_b32_e32 v190, 2, v189
	v_bfe_u32 v191, v189, 4, 2
	v_and_b32_e32 v188, 3, v189
	v_xor_b32_e32 v188, v188, v191
	v_lshlrev_b32_e32 v188, 4, v188
	v_lshl_add_u32 v176, v190, 11, v188
	v_add_u32_e32 v177, 0x8000, v176
	v_lshl_add_u32 v178, v190, 6, v188
	v_and_b32_e32 v190, 31, v189
	v_lshrrev_b32_e32 v191, 5, v189
	v_bfe_u32 v188, v189, 2, 2
	v_xor_b32_e32 v188, v188, v191
	v_lshlrev_b32_e32 v188, 4, v188
	v_lshl_add_u32 v179, v190, 6, v188
	s_lshr_b32 s74, s73, 1
	s_lshl_b32 s74, s74, 12
	s_and_b32 s75, s73, 1
	s_lshl_b32 s75, s75, 13
	v_add_u32_e32 v181, s75, v179
	v_add_u32_e32 v179, s74, v179
	v_xor_b32_e32 v182, 32, v181
	v_xor_b32_e32 v180, 32, v179
	s_lshl_b32 s74, s73, 16
	s_add_u32 s64, s98, s74
	s_addc_u32 s65, s99, 0
	s_lshl_b32 s74, s73, 12
	s_add_u32 s66, s100, s74
	s_addc_u32 s67, s101, 0
	s_lshl_b32 s68, s73, 11
	s_lshl_b32 s69, s73, 12
	s_mov_b32 s70, 0
	s_mov_b32 s71, 0
	s_mov_b32 s72, 0
	s_waitcnt lgkmcnt(0)
	s_barrier
	s_mul_i32 s74, s70, 0x6000
	s_add_u32 s75, s74, s68
	s_mov_b32 m0, s75
	s_add_u32 s76, s74, 0x2000
	s_cmp_eq_u32 s70, 2
	s_cselect_b32 s76, 0x10000, s76
	global_load_lds_dwordx4 v176, s[64:65]
	s_add_u32 m0, s75, 0x400
	s_add_u32 s76, s76, s69
	global_load_lds_dwordx4 v177, s[64:65]
	s_mov_b32 m0, s76
	s_add_u32 s64, s64, 64
	s_addc_u32 s65, s65, 0
	global_load_lds_dwordx4 v178, s[66:67]
	global_load_lds_dwordx4 v178, s[66:67] offset:1024
	global_load_lds_dwordx4 v178, s[66:67] offset:2048
	global_load_lds_dwordx4 v178, s[66:67] offset:3072
	s_add_u32 s66, s66, 0x20000
	s_addc_u32 s67, s67, 0
	s_add_u32 s70, s70, 1
	s_cmp_eq_u32 s70, 3
	s_cselect_b32 s70, 0, s70
	s_mul_i32 s74, s70, 0x6000
	s_add_u32 s75, s74, s68
	s_mov_b32 m0, s75
	s_add_u32 s76, s74, 0x2000
	s_cmp_eq_u32 s70, 2
	s_cselect_b32 s76, 0x10000, s76
	global_load_lds_dwordx4 v176, s[64:65]
	s_add_u32 m0, s75, 0x400
	s_add_u32 s76, s76, s69
	global_load_lds_dwordx4 v177, s[64:65]
	s_mov_b32 m0, s76
	s_add_u32 s64, s64, 64
	s_addc_u32 s65, s65, 0
	global_load_lds_dwordx4 v178, s[66:67]
	global_load_lds_dwordx4 v178, s[66:67] offset:1024
	global_load_lds_dwordx4 v178, s[66:67] offset:2048
	global_load_lds_dwordx4 v178, s[66:67] offset:3072
	s_add_u32 s66, s66, 0x20000
	s_addc_u32 s67, s67, 0
	s_add_u32 s70, s70, 1
	s_cmp_eq_u32 s70, 3
	s_cselect_b32 s70, 0, s70
	s_cmp_lt_u32 s46, 0x100
	s_cbranch_scc1 .Lp12_nostag
	s_sleep 8
	s_setprio 1

; #define MFMA32(a, b, c) __builtin_amdgcn_mfma_f32_32x32x16_bf16((a), (b), (c), 0, 0, 0)
; #define GA_LOAD(pr_) do { _Pragma("unroll") for (int i = 0; i < 4; ++i) ra[i] = *(const u32x4*)(Ab + (i * 32) * lda + (pr_) * 64); } while (0)
; #define GB_LOAD(kt_) do { const bfr* bk_ = Bb + (kt_) * NB * 32; \
;     _Pragma("unroll") for (int i = 0; i < 4; ++i) rb[i] = *(const u32x4*)(bk_ + (i * 64) * 32); } while (0)
; #define G_STORE(kt_) do { bfr* as_ = S0 + ((kt_) & 1) * GSTAGE; bfr* bs_ = as_ + 128 * 40; \
;     if (apar == ((kt_) & 1)) { _Pragma("unroll") for (int i = 0; i < 4; ++i) *(u32x4*)(as_ + asoff + i * 32 * 40) = ra[i]; } \
;     _Pragma("unroll") for (int i = 0; i < 4; ++i) *(u32x4*)(bs_ + bsoff + i * 64 * 40) = rb[i]; } while (0)
; template <int lda>
; DI void gemm_mainloop(const bfr* __restrict__ A, const bfr* __restrict__ Bt, int NB, int K, int m0, int n0, char* smem, f32x16 (&acc)[2][4]) {
;     ...
;   for (int kt = 0; kt < nk; ++kt) {
;     if (kt + 1 < nk) G_STORE(kt + 1);
;     if (kt + 2 < nk) {
;       GB_LOAD(kt + 2);
;       if ((kt & 1) == 0) GA_LOAD((kt >> 1) + 1);
;     }
;     const bfr* As = S0 + (kt & 1) * GSTAGE;
;     const bfr* Bs = As + 128 * 40;
; #pragma unroll
;     for (int ks = 0; ks < 2; ++ks) {
;       bf16x8 af[2], bfg[4];
; #pragma unroll
;       for (int i = 0; i < 2; ++i) af[i] = *(const bf16x8*)(As + (wr * 64 + i * 32 + r) * 40 + ks * 16 + hl * 8);
; #pragma unroll
;       for (int j = 0; j < 4; ++j) bfg[j] = *(const bf16x8*)(Bs + (wc * 128 + j * 32 + r) * 40 + ks * 16 + hl * 8);
; #pragma unroll
;       for (int i = 0; i < 2; ++i)
; #pragma unroll
;         for (int j = 0; j < 4; ++j) acc[i][j] = MFMA32(af[i], bfg[j], acc[i][j]);
;     }
;     __syncthreads();
.Lp12_loop:
	s_waitcnt vmcnt(6)
	s_barrier
	s_mul_i32 s74, s71, 0x6000
	s_add_u32 s75, s74, 0x2000
	s_cmp_eq_u32 s71, 2
	s_cselect_b32 s75, 0x10000, s75
	v_add_u32_e32 v183, s74, v179
	v_add_u32_e32 v185, s75, v181
	v_add_u32_e32 v184, s74, v180
	v_add_u32_e32 v186, s75, v182
	ds_read_b128 v[128:131], v183
	ds_read_b128 v[144:147], v185
	ds_read_b128 v[148:151], v185 offset:2048
	ds_read_b128 v[152:155], v185 offset:4096
	ds_read_b128 v[156:159], v185 offset:6144
	ds_read_b128 v[132:135], v183 offset:2048
	ds_read_b128 v[136:139], v184
	ds_read_b128 v[160:163], v186
	ds_read_b128 v[164:167], v186 offset:2048
	ds_read_b128 v[168:171], v186 offset:4096
	ds_read_b128 v[172:175], v186 offset:6144
	ds_read_b128 v[140:143], v184 offset:2048
	s_add_u32 s71, s71, 1
	s_cmp_eq_u32 s71, 3
	s_cselect_b32 s71, 0, s71
	s_waitcnt lgkmcnt(10)
	v_mfma_f32_32x32x16_bf16 v[112:127], v[128:131], v[144:147], v[112:127]
	s_mul_i32 s74, s70, 0x6000
	s_add_u32 s75, s74, s68
	s_mov_b32 m0, s75
	s_add_u32 s76, s74, 0x2000
	s_cmp_eq_u32 s70, 2
	s_cselect_b32 s76, 0x10000, s76
	global_load_lds_dwordx4 v176, s[64:65]
	s_waitcnt lgkmcnt(9)
	v_mfma_f32_32x32x16_bf16 v[96:111], v[128:131], v[148:151], v[96:111]
	s_add_u32 m0, s75, 0x400
	s_add_u32 s76, s76, s69
	global_load_lds_dwordx4 v177, s[64:65]
	s_waitcnt lgkmcnt(8)
	v_mfma_f32_32x32x16_bf16 v[80:95], v[128:131], v[152:155], v[80:95]
	s_mov_b32 m0, s76
	s_add_u32 s64, s64, 64
	s_addc_u32 s65, s65, 0
	global_load_lds_dwordx4 v178, s[66:67]
	s_waitcnt lgkmcnt(7)
	v_mfma_f32_32x32x16_bf16 v[64:79], v[128:131], v[156:159], v[64:79]
	global_load_lds_dwordx4 v178, s[66:67] offset:1024
	s_waitcnt lgkmcnt(6)
	v_mfma_f32_32x32x16_bf16 v[48:63], v[132:135], v[144:147], v[48:63]
	global_load_lds_dwordx4 v178, s[66:67] offset:2048
	v_mfma_f32_32x32x16_bf16 v[32:47], v[132:135], v[148:151], v[32:47]
	global_load_lds_dwordx4 v178, s[66:67] offset:3072
	s_add_u32 s66, s66, 0x20000
	s_addc_u32 s67, s67, 0
	v_mfma_f32_32x32x16_bf16 v[16:31], v[132:135], v[152:155], v[16:31]
	s_add_u32 s70, s70, 1
	s_cmp_eq_u32 s70, 3
	s_cselect_b32 s70, 0, s70
	v_mfma_f32_32x32x16_bf16 v[0:15], v[132:135], v[156:159], v[0:15]
	s_waitcnt lgkmcnt(4)
	v_mfma_f32_32x32x16_bf16 v[112:127], v[136:139], v[160:163], v[112:127]
	s_waitcnt lgkmcnt(3)
	v_mfma_f32_32x32x16_bf16 v[96:111], v[136:139], v[164:167], v[96:111]
	s_waitcnt lgkmcnt(2)
	v_mfma_f32_32x32x16_bf16 v[80:95], v[136:139], v[168:171], v[80:95]
	s_waitcnt lgkmcnt(1)
	v_mfma_f32_32x32x16_bf16 v[64:79], v[136:139], v[172:175], v[64:79]
	s_waitcnt lgkmcnt(0)
	v_mfma_f32_32x32x16_bf16 v[48:63], v[140:143], v[160:163], v[48:63]
	v_mfma_f32_32x32x16_bf16 v[32:47], v[140:143], v[164:167], v[32:47]
	v_mfma_f32_32x32x16_bf16 v[16:31], v[140:143], v[168:171], v[16:31]
	v_mfma_f32_32x32x16_bf16 v[0:15], v[140:143], v[172:175], v[0:15]
	s_add_u32 s72, s72, 1
	s_cmp_lt_u32 s72, 30
	s_cbranch_scc1 .Lp12_loop
	s_waitcnt vmcnt(6)
	s_barrier
; #define MFMA32(a, b, c) __builtin_amdgcn_mfma_f32_32x32x16_bf16((a), (b), (c), 0, 0, 0)
; #define GA_LOAD(pr_) do { _Pragma("unroll") for (int i = 0; i < 4; ++i) ra[i] = *(const u32x4*)(Ab + (i * 32) * lda + (pr_) * 64); } while (0)
; #define GB_LOAD(kt_) do { const bfr* bk_ = Bb + (kt_) * NB * 32; \
;     _Pragma("unroll") for (int i = 0; i < 4; ++i) rb[i] = *(const u32x4*)(bk_ + (i * 64) * 32); } while (0)
; #define G_STORE(kt_) do { bfr* as_ = S0 + ((kt_) & 1) * GSTAGE; bfr* bs_ = as_ + 128 * 40; \
;     if (apar == ((kt_) & 1)) { _Pragma("unroll") for (int i = 0; i < 4; ++i) *(u32x4*)(as_ + asoff + i * 32 * 40) = ra[i]; } \
;     _Pragma("unroll") for (int i = 0; i < 4; ++i) *(u32x4*)(bs_ + bsoff + i * 64 * 40) = rb[i]; } while (0)
; template <int lda>
; DI void gemm_mainloop(const bfr* __restrict__ A, const bfr* __restrict__ Bt, int NB, int K, int m0, int n0, char* smem, f32x16 (&acc)[2][4]) {
;     ...
;   for (int kt = 0; kt < nk; ++kt) {
;     if (kt + 1 < nk) G_STORE(kt + 1);
;     if (kt + 2 < nk) {
;       GB_LOAD(kt + 2);
;       if ((kt & 1) == 0) GA_LOAD((kt >> 1) + 1);
;     }
;     const bfr* As = S0 + (kt & 1) * GSTAGE;
;     const bfr* Bs = As + 128 * 40;
; #pragma unroll
;     for (int ks = 0; ks < 2; ++ks) {
;       bf16x8 af[2], bfg[4];
; #pragma unroll
;       for (int i = 0; i < 2; ++i) af[i] = *(const bf16x8*)(As + (wr * 64 + i * 32 + r) * 40 + ks * 16 + hl * 8);
; #pragma unroll
;       for (int j = 0; j < 4; ++j) bfg[j] = *(const bf16x8*)(Bs + (wc * 128 + j * 32 + r) * 40 + ks * 16 + hl * 8);
; #pragma unroll
;       for (int i = 0; i < 2; ++i)
; #pragma unroll
;         for (int j = 0; j < 4; ++j) acc[i][j] = MFMA32(af[i], bfg[j], acc[i][j]);
;     }
;     __syncthreads();
	s_mul_i32 s74, s71, 0x6000
	s_add_u32 s75, s74, 0x2000
	s_cmp_eq_u32 s71, 2
	s_cselect_b32 s75, 0x10000, s75
	v_add_u32_e32 v183, s74, v179
	v_add_u32_e32 v185, s75, v181
	v_add_u32_e32 v184, s74, v180
	v_add_u32_e32 v186, s75, v182
	ds_read_b128 v[128:131], v183
	ds_read_b128 v[144:147], v185
	ds_read_b128 v[148:151], v185 offset:2048
	ds_read_b128 v[152:155], v185 offset:4096
	ds_read_b128 v[156:159], v185 offset:6144
	ds_read_b128 v[132:135], v183 offset:2048
	ds_read_b128 v[136:139], v184
	ds_read_b128 v[160:163], v186
	ds_read_b128 v[164:167], v186 offset:2048
	ds_read_b128 v[168:171], v186 offset:4096
	ds_read_b128 v[172:175], v186 offset:6144
	ds_read_b128 v[140:143], v184 offset:2048
	s_add_u32 s71, s71, 1
	s_cmp_eq_u32 s71, 3
	s_cselect_b32 s71, 0, s71
	s_waitcnt lgkmcnt(10)
	v_mfma_f32_32x32x16_bf16 v[112:127], v[128:131], v[144:147], v[112:127]
	s_waitcnt lgkmcnt(9)
	v_mfma_f32_32x32x16_bf16 v[96:111], v[128:131], v[148:151], v[96:111]
	s_waitcnt lgkmcnt(8)
	v_mfma_f32_32x32x16_bf16 v[80:95], v[128:131], v[152:155], v[80:95]
	s_waitcnt lgkmcnt(7)
	v_mfma_f32_32x32x16_bf16 v[64:79], v[128:131], v[156:159], v[64:79]
	s_waitcnt lgkmcnt(6)
	v_mfma_f32_32x32x16_bf16 v[48:63], v[132:135], v[144:147], v[48:63]
	v_mfma_f32_32x32x16_bf16 v[32:47], v[132:135], v[148:151], v[32:47]
	v_mfma_f32_32x32x16_bf16 v[16:31], v[132:135], v[152:155], v[16:31]
	v_mfma_f32_32x32x16_bf16 v[0:15], v[132:135], v[156:159], v[0:15]
	s_waitcnt lgkmcnt(4)
	v_mfma_f32_32x32x16_bf16 v[112:127], v[136:139], v[160:163], v[112:127]
	s_waitcnt lgkmcnt(3)
	v_mfma_f32_32x32x16_bf16 v[96:111], v[136:139], v[164:167], v[96:111]
	s_waitcnt lgkmcnt(2)
	v_mfma_f32_32x32x16_bf16 v[80:95], v[136:139], v[168:171], v[80:95]
	s_waitcnt lgkmcnt(1)
	v_mfma_f32_32x32x16_bf16 v[64:79], v[136:139], v[172:175], v[64:79]
	s_waitcnt lgkmcnt(0)
	v_mfma_f32_32x32x16_bf16 v[48:63], v[140:143], v[160:163], v[48:63]
	v_mfma_f32_32x32x16_bf16 v[32:47], v[140:143], v[164:167], v[32:47]
	v_mfma_f32_32x32x16_bf16 v[16:31], v[140:143], v[168:171], v[16:31]
	v_mfma_f32_32x32x16_bf16 v[0:15], v[140:143], v[172:175], v[0:15]
	s_waitcnt vmcnt(0)
	s_barrier
	s_mul_i32 s74, s71, 0x6000
	s_add_u32 s75, s74, 0x2000
	s_cmp_eq_u32 s71, 2
	s_cselect_b32 s75, 0x10000, s75
	v_add_u32_e32 v183, s74, v179
	v_add_u32_e32 v185, s75, v181
	v_add_u32_e32 v184, s74, v180
	v_add_u32_e32 v186, s75, v182
	ds_read_b128 v[128:131], v183
	ds_read_b128 v[144:147], v185
	ds_read_b128 v[148:151], v185 offset:2048
	ds_read_b128 v[152:155], v185 offset:4096
	ds_read_b128 v[156:159], v185 offset:6144
	ds_read_b128 v[132:135], v183 offset:2048
	ds_read_b128 v[136:139], v184
	ds_read_b128 v[160:163], v186
	ds_read_b128 v[164:167], v186 offset:2048
	ds_read_b128 v[168:171], v186 offset:4096
	ds_read_b128 v[172:175], v186 offset:6144
	ds_read_b128 v[140:143], v184 offset:2048
	s_add_u32 s71, s71, 1
	s_cmp_eq_u32 s71, 3
	s_cselect_b32 s71, 0, s71
	s_waitcnt lgkmcnt(10)
	v_mfma_f32_32x32x16_bf16 v[112:127], v[128:131], v[144:147], v[112:127]
	s_waitcnt lgkmcnt(9)
	v_mfma_f32_32x32x16_bf16 v[96:111], v[128:131], v[148:151], v[96:111]
	s_waitcnt lgkmcnt(8)
	v_mfma_f32_32x32x16_bf16 v[80:95], v[128:131], v[152:155], v[80:95]
	s_waitcnt lgkmcnt(7)
	v_mfma_f32_32x32x16_bf16 v[64:79], v[128:131], v[156:159], v[64:79]
	s_waitcnt lgkmcnt(6)
	v_mfma_f32_32x32x16_bf16 v[48:63], v[132:135], v[144:147], v[48:63]
	v_mfma_f32_32x32x16_bf16 v[32:47], v[132:135], v[148:151], v[32:47]
	v_mfma_f32_32x32x16_bf16 v[16:31], v[132:135], v[152:155], v[16:31]
	v_mfma_f32_32x32x16_bf16 v[0:15], v[132:135], v[156:159], v[0:15]
	s_waitcnt lgkmcnt(4)
	v_mfma_f32_32x32x16_bf16 v[112:127], v[136:139], v[160:163], v[112:127]
	s_waitcnt lgkmcnt(3)
	v_mfma_f32_32x32x16_bf16 v[96:111], v[136:139], v[164:167], v[96:111]
	s_waitcnt lgkmcnt(2)
	v_mfma_f32_32x32x16_bf16 v[80:95], v[136:139], v[168:171], v[80:95]
	s_waitcnt lgkmcnt(1)
	v_mfma_f32_32x32x16_bf16 v[64:79], v[136:139], v[172:175], v[64:79]
	s_waitcnt lgkmcnt(0)
	v_mfma_f32_32x32x16_bf16 v[48:63], v[140:143], v[160:163], v[48:63]
	v_mfma_f32_32x32x16_bf16 v[32:47], v[140:143], v[164:167], v[32:47]
	v_mfma_f32_32x32x16_bf16 v[16:31], v[140:143], v[168:171], v[16:31]
	v_mfma_f32_32x32x16_bf16 v[0:15], v[140:143], v[172:175], v[0:15]
	s_setprio 0
	s_nop 7
	v_readlane_b32 s64, v187, 0
	v_readlane_b32 s65, v187, 1
	v_readlane_b32 s66, v187, 2
	v_readlane_b32 s67, v187, 3
	v_readlane_b32 s68, v187, 4
	v_readlane_b32 s69, v187, 5
	v_readlane_b32 s70, v187, 6
	v_readlane_b32 s71, v187, 7
	v_readlane_b32 s72, v187, 8
	v_readlane_b32 s73, v187, 9
	v_readlane_b32 s74, v187, 10
	v_readlane_b32 s75, v187, 11
	v_readlane_b32 s76, v187, 12
	v_readlane_b32 s77, v187, 13
	v_readlane_b32 s78, v187, 14
	v_readlane_b32 s79, v187, 15
	s_nop 7
	s_branch .LBB0_1178

; #define MFMA32(a, b, c) __builtin_amdgcn_mfma_f32_32x32x16_bf16((a), (b), (c), 0, 0, 0)
; #define GA_LOAD(pr_) do { _Pragma("unroll") for (int i = 0; i < 4; ++i) ra[i] = *(const u32x4*)(Ab + (i * 32) * lda + (pr_) * 64); } while (0)
; #define GB_LOAD(kt_) do { const bfr* bk_ = Bb + (kt_) * NB * 32; \
;     _Pragma("unroll") for (int i = 0; i < 4; ++i) rb[i] = *(const u32x4*)(bk_ + (i * 64) * 32); } while (0)
; #define G_STORE(kt_) do { bfr* as_ = S0 + ((kt_) & 1) * GSTAGE; bfr* bs_ = as_ + 128 * 40; \
;     if (apar == ((kt_) & 1)) { _Pragma("unroll") for (int i = 0; i < 4; ++i) *(u32x4*)(as_ + asoff + i * 32 * 40) = ra[i]; } \
;     _Pragma("unroll") for (int i = 0; i < 4; ++i) *(u32x4*)(bs_ + bsoff + i * 64 * 40) = rb[i]; } while (0)
; template <int lda>
; DI void gemm_mainloop(const bfr* __restrict__ A, const bfr* __restrict__ Bt, int NB, int K, int m0, int n0, char* smem, f32x16 (&acc)[2][4]) {
;     ...
;   for (int kt = 0; kt < nk; ++kt) {
;     if (kt + 1 < nk) G_STORE(kt + 1);
;     if (kt + 2 < nk) {
;       GB_LOAD(kt + 2);
;       if ((kt & 1) == 0) GA_LOAD((kt >> 1) + 1);
;     }
;     const bfr* As = S0 + (kt & 1) * GSTAGE;
;     const bfr* Bs = As + 128 * 40;
; #pragma unroll
;     for (int ks = 0; ks < 2; ++ks) {
;       bf16x8 af[2], bfg[4];
; #pragma unroll
;       for (int i = 0; i < 2; ++i) af[i] = *(const bf16x8*)(As + (wr * 64 + i * 32 + r) * 40 + ks * 16 + hl * 8);
; #pragma unroll
;       for (int j = 0; j < 4; ++j) bfg[j] = *(const bf16x8*)(Bs + (wc * 128 + j * 32 + r) * 40 + ks * 16 + hl * 8);
; #pragma unroll
;       for (int i = 0; i < 2; ++i)
; #pragma unroll
;         for (int j = 0; j < 4; ++j) acc[i][j] = MFMA32(af[i], bfg[j], acc[i][j]);
;     }
;     __syncthreads();
.Lp15_loop:
	s_waitcnt vmcnt(6)
	s_barrier
	s_mul_i32 s74, s71, 0x6000
	s_add_u32 s75, s74, 0x2000
	s_cmp_eq_u32 s71, 2
	s_cselect_b32 s75, 0x10000, s75
	v_add_u32_e32 v183, s74, v179
	v_add_u32_e32 v185, s75, v181
	v_add_u32_e32 v184, s74, v180
	v_add_u32_e32 v186, s75, v182
	ds_read_b128 v[128:131], v183
	ds_read_b128 v[144:147], v185
	ds_read_b128 v[148:151], v185 offset:2048
	ds_read_b128 v[152:155], v185 offset:4096
	ds_read_b128 v[156:159], v185 offset:6144
	ds_read_b128 v[132:135], v183 offset:2048
	ds_read_b128 v[136:139], v184
	ds_read_b128 v[160:163], v186
	ds_read_b128 v[164:167], v186 offset:2048
	ds_read_b128 v[168:171], v186 offset:4096
	ds_read_b128 v[172:175], v186 offset:6144
	ds_read_b128 v[140:143], v184 offset:2048
	s_add_u32 s71, s71, 1
	s_cmp_eq_u32 s71, 3
	s_cselect_b32 s71, 0, s71
	s_waitcnt lgkmcnt(10)
	v_mfma_f32_32x32x16_bf16 v[112:127], v[128:131], v[144:147], v[112:127]
	s_mul_i32 s74, s70, 0x6000
	s_add_u32 s75, s74, s68
	s_mov_b32 m0, s75
	s_add_u32 s76, s74, 0x2000
	s_cmp_eq_u32 s70, 2
	s_cselect_b32 s76, 0x10000, s76
	global_load_lds_dwordx4 v176, s[64:65]
	s_waitcnt lgkmcnt(9)
	v_mfma_f32_32x32x16_bf16 v[96:111], v[128:131], v[148:151], v[96:111]
	s_add_u32 m0, s75, 0x400
	s_add_u32 s76, s76, s69
	global_load_lds_dwordx4 v177, s[64:65]
	s_waitcnt lgkmcnt(8)
	v_mfma_f32_32x32x16_bf16 v[80:95], v[128:131], v[152:155], v[80:95]
	s_mov_b32 m0, s76
	s_add_u32 s64, s64, 64
	s_addc_u32 s65, s65, 0
	global_load_lds_dwordx4 v178, s[66:67]
	s_waitcnt lgkmcnt(7)
	v_mfma_f32_32x32x16_bf16 v[64:79], v[128:131], v[156:159], v[64:79]
	global_load_lds_dwordx4 v178, s[66:67] offset:1024
	s_waitcnt lgkmcnt(6)
	v_mfma_f32_32x32x16_bf16 v[48:63], v[132:135], v[144:147], v[48:63]
	global_load_lds_dwordx4 v178, s[66:67] offset:2048
	v_mfma_f32_32x32x16_bf16 v[32:47], v[132:135], v[148:151], v[32:47]
	global_load_lds_dwordx4 v178, s[66:67] offset:3072
	s_add_u32 s66, s66, 0x10000
	s_addc_u32 s67, s67, 0
	v_mfma_f32_32x32x16_bf16 v[16:31], v[132:135], v[152:155], v[16:31]
	s_add_u32 s70, s70, 1
	s_cmp_eq_u32 s70, 3
	s_cselect_b32 s70, 0, s70
	v_mfma_f32_32x32x16_bf16 v[0:15], v[132:135], v[156:159], v[0:15]
	s_waitcnt lgkmcnt(4)
	v_mfma_f32_32x32x16_bf16 v[112:127], v[136:139], v[160:163], v[112:127]
	s_waitcnt lgkmcnt(3)
	v_mfma_f32_32x32x16_bf16 v[96:111], v[136:139], v[164:167], v[96:111]
	s_waitcnt lgkmcnt(2)
	v_mfma_f32_32x32x16_bf16 v[80:95], v[136:139], v[168:171], v[80:95]
	s_waitcnt lgkmcnt(1)
	v_mfma_f32_32x32x16_bf16 v[64:79], v[136:139], v[172:175], v[64:79]
	s_waitcnt lgkmcnt(0)
	v_mfma_f32_32x32x16_bf16 v[48:63], v[140:143], v[160:163], v[48:63]
	v_mfma_f32_32x32x16_bf16 v[32:47], v[140:143], v[164:167], v[32:47]
	v_mfma_f32_32x32x16_bf16 v[16:31], v[140:143], v[168:171], v[16:31]
	v_mfma_f32_32x32x16_bf16 v[0:15], v[140:143], v[172:175], v[0:15]
	s_add_u32 s72, s72, 1
	s_cmp_lt_u32 s72, 30
	s_cbranch_scc1 .Lp15_loop
	s_waitcnt vmcnt(6)
	s_barrier
	s_mul_i32 s74, s71, 0x6000
	s_add_u32 s75, s74, 0x2000
	s_cmp_eq_u32 s71, 2
	s_cselect_b32 s75, 0x10000, s75
	v_add_u32_e32 v183, s74, v179
	v_add_u32_e32 v185, s75, v181
	v_add_u32_e32 v184, s74, v180
	v_add_u32_e32 v186, s75, v182
	ds_read_b128 v[128:131], v183
	ds_read_b128 v[144:147], v185
	ds_read_b128 v[148:151], v185 offset:2048
	ds_read_b128 v[152:155], v185 offset:4096
	ds_read_b128 v[156:159], v185 offset:6144
	ds_read_b128 v[132:135], v183 offset:2048
	ds_read_b128 v[136:139], v184
	ds_read_b128 v[160:163], v186
	ds_read_b128 v[164:167], v186 offset:2048
	ds_read_b128 v[168:171], v186 offset:4096
	ds_read_b128 v[172:175], v186 offset:6144
	ds_read_b128 v[140:143], v184 offset:2048
	s_add_u32 s71, s71, 1
	s_cmp_eq_u32 s71, 3
	s_cselect_b32 s71, 0, s71
	s_waitcnt lgkmcnt(10)
	v_mfma_f32_32x32x16_bf16 v[112:127], v[128:131], v[144:147], v[112:127]
	s_waitcnt lgkmcnt(9)
	v_mfma_f32_32x32x16_bf16 v[96:111], v[128:131], v[148:151], v[96:111]
	s_waitcnt lgkmcnt(8)
	v_mfma_f32_32x32x16_bf16 v[80:95], v[128:131], v[152:155], v[80:95]
	s_waitcnt lgkmcnt(7)
	v_mfma_f32_32x32x16_bf16 v[64:79], v[128:131], v[156:159], v[64:79]
	s_waitcnt lgkmcnt(6)
	v_mfma_f32_32x32x16_bf16 v[48:63], v[132:135], v[144:147], v[48:63]
	v_mfma_f32_32x32x16_bf16 v[32:47], v[132:135], v[148:151], v[32:47]
	v_mfma_f32_32x32x16_bf16 v[16:31], v[132:135], v[152:155], v[16:31]
	v_mfma_f32_32x32x16_bf16 v[0:15], v[132:135], v[156:159], v[0:15]
	s_waitcnt lgkmcnt(4)
	v_mfma_f32_32x32x16_bf16 v[112:127], v[136:139], v[160:163], v[112:127]
	s_waitcnt lgkmcnt(3)
	v_mfma_f32_32x32x16_bf16 v[96:111], v[136:139], v[164:167], v[96:111]
	s_waitcnt lgkmcnt(2)
	v_mfma_f32_32x32x16_bf16 v[80:95], v[136:139], v[168:171], v[80:95]
	s_waitcnt lgkmcnt(1)
	v_mfma_f32_32x32x16_bf16 v[64:79], v[136:139], v[172:175], v[64:79]
	s_waitcnt lgkmcnt(0)
	v_mfma_f32_32x32x16_bf16 v[48:63], v[140:143], v[160:163], v[48:63]
	v_mfma_f32_32x32x16_bf16 v[32:47], v[140:143], v[164:167], v[32:47]
	v_mfma_f32_32x32x16_bf16 v[16:31], v[140:143], v[168:171], v[16:31]
	v_mfma_f32_32x32x16_bf16 v[0:15], v[140:143], v[172:175], v[0:15]
	s_waitcnt vmcnt(0)
	s_barrier
; #define MFMA32(a, b, c) __builtin_amdgcn_mfma_f32_32x32x16_bf16((a), (b), (c), 0, 0, 0)
; template <int lda>
; DI void gemm_mainloop(const bfr* __restrict__ A, const bfr* __restrict__ Bt, int NB, int K, int m0, int n0, char* smem, f32x16 (&acc)[2][4]) {
;     ...
;     const bfr* As = S0 + (kt & 1) * GSTAGE;
;     const bfr* Bs = As + 128 * 40;
; #pragma unroll
;     for (int ks = 0; ks < 2; ++ks) {
;       bf16x8 af[2], bfg[4];
; #pragma unroll
;       for (int i = 0; i < 2; ++i) af[i] = *(const bf16x8*)(As + (wr * 64 + i * 32 + r) * 40 + ks * 16 + hl * 8);
; #pragma unroll
;       for (int j = 0; j < 4; ++j) bfg[j] = *(const bf16x8*)(Bs + (wc * 128 + j * 32 + r) * 40 + ks * 16 + hl * 8);
; #pragma unroll
;       for (int i = 0; i < 2; ++i)
; #pragma unroll
;         for (int j = 0; j < 4; ++j) acc[i][j] = MFMA32(af[i], bfg[j], acc[i][j]);
;     }
;     __syncthreads();
; template <bool FIRST, bool HAS_H>
; DI void phase_gemm_resid(const Params& p, const bfr* A, const bfr* Wt, const float* gnext, float* ss, char* smem) {
;     ...
;     int tid2 = threadIdx.x;
;     asm volatile("" : "+v"(tid2));
;     const int lane = tid2 & 63, wid = tid2 >> 6, wr = wid >> 1, wc = wid & 1, r = lane & 31, hl = lane >> 5;
;     const float* xsrc = FIRST ? p.x_prompt : X;
;     const int rbase = m0 + wr * 64 + 4 * hl, cbase = n0 + wc * 128 + r;
; #pragma unroll
;     for (int i = 0; i < 2; ++i) {
; #pragma unroll
;       for (int qh = 0; qh < 2; ++qh) {
;         float rs[8];
; #pragma unroll
;         for (int q = 0; q < 8; ++q) rs[q] = 0.f;
; #pragma unroll
;         for (int jh = 0; jh < 2; ++jh) {
;           float xo[2][8];
; #pragma unroll
;           for (int jj = 0; jj < 2; ++jj)
; #pragma unroll
;             for (int q = 0; q < 8; ++q)
;               xo[jj][q] = xsrc[(rbase + i * 32 + crow(qh * 8 + q, 0)) * 1024 + cbase + (jh * 2 + jj) * 32];
; #pragma unroll
;           for (int q = 0; q < 8; ++q) {
;             const int o = (rbase + i * 32 + crow(qh * 8 + q, 0)) * 1024 + cbase;
; #pragma unroll
;             for (int jj = 0; jj < 2; ++jj) {
;               const int j = jh * 2 + jj;
;               const float xn = xo[jj][q] + acc[i][j][qh * 8 + q];
;               X[o + j * 32] = xn;
;               if (HAS_H) Hn[o + j * 32] = f2bf(xn * gnext[cbase + j * 32]);
;               rs[q] += xn * xn;
;             }
;           }
;         }
	s_mul_i32 s74, s71, 0x6000
	s_add_u32 s75, s74, 0x2000
	s_cmp_eq_u32 s71, 2
	s_cselect_b32 s75, 0x10000, s75
	v_add_u32_e32 v183, s74, v179
	v_add_u32_e32 v185, s75, v181
	v_add_u32_e32 v184, s74, v180
	v_add_u32_e32 v186, s75, v182
	ds_read_b128 v[128:131], v183
	ds_read_b128 v[144:147], v185
	ds_read_b128 v[148:151], v185 offset:2048
	ds_read_b128 v[152:155], v185 offset:4096
	ds_read_b128 v[156:159], v185 offset:6144
	ds_read_b128 v[132:135], v183 offset:2048
	ds_read_b128 v[136:139], v184
	ds_read_b128 v[160:163], v186
	ds_read_b128 v[164:167], v186 offset:2048
	ds_read_b128 v[168:171], v186 offset:4096
	ds_read_b128 v[172:175], v186 offset:6144
	ds_read_b128 v[140:143], v184 offset:2048
	s_add_u32 s71, s71, 1
	s_cmp_eq_u32 s71, 3
	s_cselect_b32 s71, 0, s71
	s_waitcnt lgkmcnt(10)
	v_mfma_f32_32x32x16_bf16 v[112:127], v[128:131], v[144:147], v[112:127]
	s_waitcnt lgkmcnt(9)
	v_mfma_f32_32x32x16_bf16 v[96:111], v[128:131], v[148:151], v[96:111]
	s_waitcnt lgkmcnt(8)
	v_mfma_f32_32x32x16_bf16 v[80:95], v[128:131], v[152:155], v[80:95]
	s_waitcnt lgkmcnt(7)
	v_mfma_f32_32x32x16_bf16 v[64:79], v[128:131], v[156:159], v[64:79]
	s_waitcnt lgkmcnt(6)
	v_mfma_f32_32x32x16_bf16 v[48:63], v[132:135], v[144:147], v[48:63]
	v_mfma_f32_32x32x16_bf16 v[32:47], v[132:135], v[148:151], v[32:47]
	v_mfma_f32_32x32x16_bf16 v[16:31], v[132:135], v[152:155], v[16:31]
	v_mfma_f32_32x32x16_bf16 v[0:15], v[132:135], v[156:159], v[0:15]
	s_waitcnt lgkmcnt(4)
	v_mfma_f32_32x32x16_bf16 v[112:127], v[136:139], v[160:163], v[112:127]
	s_waitcnt lgkmcnt(3)
	v_mfma_f32_32x32x16_bf16 v[96:111], v[136:139], v[164:167], v[96:111]
	s_waitcnt lgkmcnt(2)
	v_mfma_f32_32x32x16_bf16 v[80:95], v[136:139], v[168:171], v[80:95]
	s_waitcnt lgkmcnt(1)
	v_mfma_f32_32x32x16_bf16 v[64:79], v[136:139], v[172:175], v[64:79]
	s_waitcnt lgkmcnt(0)
	v_mfma_f32_32x32x16_bf16 v[48:63], v[140:143], v[160:163], v[48:63]
	v_mfma_f32_32x32x16_bf16 v[32:47], v[140:143], v[164:167], v[32:47]
	v_mfma_f32_32x32x16_bf16 v[16:31], v[140:143], v[168:171], v[16:31]
	v_mfma_f32_32x32x16_bf16 v[0:15], v[140:143], v[172:175], v[0:15]
	s_setprio 0
	s_nop 7
	v_readlane_b32 s64, v187, 0
	v_readlane_b32 s65, v187, 1
	v_readlane_b32 s66, v187, 2
	v_readlane_b32 s67, v187, 3
	v_readlane_b32 s68, v187, 4
	v_readlane_b32 s69, v187, 5
	v_readlane_b32 s70, v187, 6
	v_readlane_b32 s71, v187, 7
	v_readlane_b32 s72, v187, 8
	v_readlane_b32 s73, v187, 9
	v_readlane_b32 s74, v187, 10
	v_readlane_b32 s75, v187, 11
	v_readlane_b32 s76, v187, 12
	v_readlane_b32 s77, v187, 13
	v_readlane_b32 s78, v187, 14
	v_readlane_b32 s79, v187, 15
	s_nop 7
	s_waitcnt vmcnt(1)
	s_nop 0
	s_nop 0
	s_nop 0
	s_waitcnt vmcnt(0)
	s_nop 0
	v_add_u32_e32 v132, v169, v171
	s_nop 0
	v_add_u32_e32 v133, v169, v170
	s_nop 0
	s_nop 0
	s_nop 0
	s_nop 0
	s_nop 0
	s_nop 0
	s_nop 0
	s_nop 0
	s_nop 0
	s_nop 0
	s_nop 0
	v_mov_b32_e32 v192, v196
	s_waitcnt lgkmcnt(0)
	s_nop 0
	s_nop 0
	s_nop 0
	s_nop 0
	s_nop 0
	s_nop 0
	s_nop 0
	s_nop 0
	s_nop 0
	s_nop 0
	s_nop 0
	s_nop 0
	s_nop 0
	s_nop 0
	s_nop 0
	s_nop 0
	s_nop 0
	s_waitcnt lgkmcnt(0)
	s_nop 0
	s_nop 0
	v_ashrrev_i32_e32 v194, 1, v192
	v_and_b32_e32 v194, 0xffffffc0, v194
	v_add_u32_e32 v194, s36, v194
	v_lshrrev_b32_e32 v195, 3, v192
	v_and_b32_e32 v232, 31, v192
	s_nop 0
	v_and_or_b32 v216, v195, 4, v194
	v_lshlrev_b32_e32 v192, 1, v192
	v_and_b32_e32 v192, 0x80, v192
	v_lshlrev_b32_e32 v205, 10, v216
	v_or3_b32 v199, s33, v192, v232
	v_or_b32_e32 v194, v205, v199
	v_ashrrev_i32_e32 v195, 31, v194
	s_nop 0
	v_or_b32_e32 v220, 0x400, v205
	v_or_b32_e32 v218, v220, v199
	v_ashrrev_i32_e32 v219, 31, v218
	v_lshl_add_u64 v[218:219], v[218:219], 2, s[10:11]
	v_or_b32_e32 v204, 32, v199
	global_load_dword v221, v[218:219], off
	v_or_b32_e32 v218, v220, v204
	s_nop 0
	v_ashrrev_i32_e32 v203, 31, v205
	v_mov_b32_e32 v202, v194
	v_lshl_add_u64 v[200:201], v[194:195], 2, s[10:11]
	v_lshl_add_u64 v[202:203], v[202:203], 2, s[10:11]
	global_load_dword v192, v[200:201], off
	global_load_dword v217, v[202:203], off offset:128
	v_ashrrev_i32_e32 v219, 31, v218
	v_lshl_add_u64 v[218:219], v[218:219], 2, s[10:11]
	v_or_b32_e32 v223, 0x800, v205
	global_load_dword v222, v[218:219], off
	v_or_b32_e32 v218, v223, v199
	v_ashrrev_i32_e32 v219, 31, v218
	v_lshl_add_u64 v[218:219], v[218:219], 2, s[10:11]
	s_nop 0
	global_load_dword v224, v[218:219], off
	v_or_b32_e32 v218, v223, v204
	v_ashrrev_i32_e32 v219, 31, v218
	v_lshl_add_u64 v[218:219], v[218:219], 2, s[10:11]
	global_load_dword v225, v[218:219], off
	v_or_b32_e32 v226, 0xc00, v205
	v_or_b32_e32 v227, 0x2000, v205
	s_nop 0
	v_or_b32_e32 v228, 0x2400, v205
	v_or_b32_e32 v229, 0x2800, v205
	v_or_b32_e32 v218, v226, v199
	v_or_b32_e32 v230, 0x2c00, v205
	v_ashrrev_i32_e32 v219, 31, v218
	v_lshl_add_u64 v[218:219], v[218:219], 2, s[10:11]
	v_cmp_eq_u32_e32 vcc, 31, v232
	s_nop 0
	s_nop 0
	s_nop 0
	s_nop 0
	s_nop 0
	s_nop 0
	s_waitcnt vmcnt(0)
; DI bfr f2bf(float a) { return (bfr)(pack2(a, 0.f) & 0xffffu); }
; DI int crow(int reg, int h) { return (reg & 3) + 8 * (reg >> 2) + 4 * h; }
; template <bool FIRST, bool HAS_H>
; DI void phase_gemm_resid(const Params& p, const bfr* A, const bfr* Wt, const float* gnext, float* ss, char* smem) {
;     ...
;     int tid2 = threadIdx.x;
;     asm volatile("" : "+v"(tid2));
;     const int lane = tid2 & 63, wid = tid2 >> 6, wr = wid >> 1, wc = wid & 1, r = lane & 31, hl = lane >> 5;
;     const float* xsrc = FIRST ? p.x_prompt : X;
;     const int rbase = m0 + wr * 64 + 4 * hl, cbase = n0 + wc * 128 + r;
; #pragma unroll
;     for (int i = 0; i < 2; ++i) {
; #pragma unroll
;       for (int qh = 0; qh < 2; ++qh) {
;         float rs[8];
; #pragma unroll
;         for (int q = 0; q < 8; ++q) rs[q] = 0.f;
; #pragma unroll
;         for (int jh = 0; jh < 2; ++jh) {
;           float xo[2][8];
; #pragma unroll
;           for (int jj = 0; jj < 2; ++jj)
; #pragma unroll
;             for (int q = 0; q < 8; ++q)
;               xo[jj][q] = xsrc[(rbase + i * 32 + crow(qh * 8 + q, 0)) * 1024 + cbase + (jh * 2 + jj) * 32];
; #pragma unroll
;           for (int q = 0; q < 8; ++q) {
;             const int o = (rbase + i * 32 + crow(qh * 8 + q, 0)) * 1024 + cbase;
; #pragma unroll
;             for (int jj = 0; jj < 2; ++jj) {
;               const int j = jh * 2 + jj;
;               const float xn = xo[jj][q] + acc[i][j][qh * 8 + q];
;               X[o + j * 32] = xn;
;               if (HAS_H) Hn[o + j * 32] = f2bf(xn * gnext[cbase + j * 32]);
;               rs[q] += xn * xn;
;             }
;           }
;         }
	s_nop 9
	v_add_f32_e32 v98, v98, v225
	s_nop 0
	v_or_b32_e32 v206, v227, v199
	v_or_b32_e32 v208, v228, v199
	v_ashrrev_i32_e32 v207, 31, v206
	v_ashrrev_i32_e32 v209, 31, v208
	v_lshl_add_u64 v[206:207], v[206:207], 2, s[10:11]
	v_lshl_add_u64 v[208:209], v[208:209], 2, s[10:11]
	s_nop 0
	v_or_b32_e32 v210, v229, v199
	v_ashrrev_i32_e32 v211, 31, v210
	v_or_b32_e32 v212, v230, v199
	v_lshl_add_u64 v[210:211], v[210:211], 2, s[10:11]
	v_ashrrev_i32_e32 v213, 31, v212
	v_lshl_add_u64 v[212:213], v[212:213], 2, s[10:11]
	global_load_dword v231, v[218:219], off
	global_load_dword v233, v[206:207], off
	global_load_dword v234, v[208:209], off
	global_load_dword v235, v[210:211], off
	global_load_dword v236, v[212:213], off
	v_or_b32_e32 v206, v226, v204
	v_or_b32_e32 v208, v227, v204
	v_or_b32_e32 v210, v228, v204
	v_ashrrev_i32_e32 v207, 31, v206
	v_ashrrev_i32_e32 v209, 31, v208
	v_ashrrev_i32_e32 v211, 31, v210
	v_or_b32_e32 v212, v229, v204
	v_or_b32_e32 v218, v230, v204
	v_lshl_add_u64 v[206:207], v[206:207], 2, s[10:11]
	v_lshl_add_u64 v[208:209], v[208:209], 2, s[10:11]
	v_lshl_add_u64 v[210:211], v[210:211], 2, s[10:11]
	v_ashrrev_i32_e32 v213, 31, v212
	v_ashrrev_i32_e32 v219, 31, v218
	v_lshl_add_u64 v[212:213], v[212:213], 2, s[10:11]
	v_lshl_add_u64 v[218:219], v[218:219], 2, s[10:11]
	global_load_dword v206, v[206:207], off
	s_nop 0
	global_load_dword v207, v[208:209], off
	s_nop 0
	global_load_dword v208, v[210:211], off
	global_load_dword v209, v[212:213], off
	s_nop 0
	global_load_dword v210, v[218:219], off
	v_add_f32_e32 v211, v112, v192
	v_or_b32_e32 v112, 0x400, v194
	global_store_dword v[200:201], v211, off
	v_lshlrev_b32_e32 v192, 2, v199
	v_add_f32_e32 v213, v96, v217
	s_nop 0
	v_add_f32_e32 v189, v113, v221
	v_ashrrev_i32_e32 v113, 31, v112
	v_or_b32_e32 v96, 0x420, v194
	global_load_dword v212, v192, s[12:13]
	v_lshl_add_u64 v[112:113], v[112:113], 2, s[10:11]
	global_store_dword v[200:201], v213, off offset:128
	global_load_dword v188, v192, s[12:13] offset:128
	s_nop 0
	v_add_f32_e32 v185, v97, v222
	v_ashrrev_i32_e32 v97, 31, v96
	global_store_dword v[112:113], v189, off
	v_lshl_add_u64 v[96:97], v[96:97], 2, s[10:11]
	global_load_dword v184, v192, s[12:13]
	v_ashrrev_i32_e32 v217, 31, v216
	global_store_dword v[96:97], v185, off
	s_nop 0
	v_or_b32_e32 v172, 0x800, v194
	v_ashrrev_i32_e32 v173, 31, v172
	v_add_f32_e32 v176, v114, v224
	v_lshl_add_u64 v[96:97], v[172:173], 2, s[10:11]
	v_or_b32_e32 v174, 0x820, v194
	global_load_dword v186, v192, s[12:13] offset:128
	v_ashrrev_i32_e32 v175, 31, v174
	global_store_dword v[96:97], v176, off
	global_load_dword v177, v192, s[12:13]
	v_lshl_add_u64 v[96:97], v[174:175], 2, s[10:11]
	global_store_dword v[96:97], v98, off
	global_load_dword v178, v192, s[12:13] offset:128
	s_nop 0
	v_lshl_add_u64 v[162:163], v[172:173], 1, s[6:7]
	v_lshl_add_u64 v[96:97], v[216:217], 2, s[14:15]
	s_waitcnt vmcnt(21)
	v_add_f32_e32 v115, v115, v231
	s_nop 0
	s_waitcnt vmcnt(10)
	v_mul_f32_e32 v112, v211, v212
	s_nop 0
	v_cvt_pk_bf16_f32 v114, v112, s0
	v_lshl_add_u64 v[112:113], v[194:195], 1, s[6:7]
	global_store_short v[112:113], v114, off
	s_waitcnt vmcnt(9)
	v_mul_f32_e32 v114, v213, v188
	v_cvt_pk_bf16_f32 v114, v114, s0
	global_store_short v[112:113], v114, off offset:64
	v_mul_f32_e32 v114, v213, v213
	s_nop 0
	v_or_b32_e32 v152, 0xc00, v194
	v_ashrrev_i32_e32 v153, 31, v152
	v_lshl_add_u64 v[154:155], v[152:153], 2, s[10:11]
	global_store_dword v[154:155], v115, off
	v_or_b32_e32 v154, 0xc20, v194
	v_ashrrev_i32_e32 v155, 31, v154
	s_waitcnt vmcnt(9)
	v_mul_f32_e32 v160, v189, v184
	s_nop 0
	v_add_f32_e32 v169, v119, v236
	v_add_f32_e32 v171, v103, v210
	v_cvt_pk_bf16_f32 v160, v160, s0
	s_waitcnt vmcnt(5)
	v_mul_f32_e32 v161, v176, v177
	v_cvt_pk_bf16_f32 v161, v161, s0
	global_store_short v[162:163], v161, off
	s_waitcnt vmcnt(4)
	v_mul_f32_e32 v161, v98, v178
	s_nop 0
	global_load_dword v158, v192, s[12:13]
	v_cvt_pk_bf16_f32 v161, v161, s0
	v_lshl_add_u64 v[162:163], v[174:175], 1, s[6:7]
	global_store_short v[162:163], v161, off
	v_mul_f32_e32 v161, v98, v98
	v_add_f32_e32 v159, v99, v206
	v_lshl_add_u64 v[98:99], v[154:155], 2, s[10:11]
	global_store_dword v[98:99], v159, off
	global_load_dword v162, v192, s[12:13] offset:128
	v_or_b32_e32 v156, 0x2000, v194
	v_ashrrev_i32_e32 v157, 31, v156
	s_nop 0
	v_add_f32_e32 v163, v116, v233
	v_lshl_add_u64 v[98:99], v[156:157], 2, s[10:11]
	global_store_dword v[98:99], v163, off
	v_or_b32_e32 v116, 0x2400, v194
	v_add_f32_e32 v165, v117, v234
	v_ashrrev_i32_e32 v117, 31, v116
	v_add_f32_e32 v167, v102, v209
	s_nop 0
	v_or_b32_e32 v148, 0x2020, v194
	v_ashrrev_i32_e32 v149, 31, v148
	global_load_dword v150, v192, s[12:13]
	v_add_f32_e32 v151, v100, v207
	v_lshl_add_u64 v[98:99], v[148:149], 2, s[10:11]
	global_store_dword v[98:99], v151, off
	global_load_dword v164, v192, s[12:13] offset:128
	s_nop 0
	v_lshl_add_u64 v[98:99], v[116:117], 2, s[10:11]
	v_or_b32_e32 v140, 0x2420, v194
	global_store_dword v[98:99], v165, off
	v_ashrrev_i32_e32 v141, 31, v140
	v_lshl_add_u64 v[98:99], v[140:141], 2, s[10:11]
	global_store_short v[112:113], v160, off offset:2048
	v_mul_f32_e32 v160, v185, v186
	s_nop 0
	global_load_dword v144, v192, s[12:13]
	v_add_f32_e32 v145, v101, v208
	global_store_dword v[98:99], v145, off
	global_load_dword v146, v192, s[12:13] offset:128
	v_add_f32_e32 v147, v118, v235
	v_cvt_pk_bf16_f32 v160, v160, s0
	global_store_short v[112:113], v160, off offset:2112
	s_nop 0
	v_or_b32_e32 v136, 0x2800, v194
	v_ashrrev_i32_e32 v137, 31, v136
	v_lshl_add_u64 v[98:99], v[136:137], 2, s[10:11]
	global_store_dword v[98:99], v147, off
	global_load_dword v166, v192, s[12:13]
	v_lshl_add_u64 v[116:117], v[116:117], 1, s[6:7]
	v_mul_f32_e32 v160, v185, v185
	s_nop 0
	v_or_b32_e32 v128, 0x2820, v194
	v_ashrrev_i32_e32 v129, 31, v128
	v_lshl_add_u64 v[98:99], v[128:129], 2, s[10:11]
	global_store_dword v[98:99], v167, off
	global_load_dword v168, v192, s[12:13] offset:128
	v_or_b32_e32 v98, 0x2c00, v194
	v_ashrrev_i32_e32 v99, 31, v98
	v_lshl_add_u64 v[100:101], v[98:99], 2, s[10:11]
	global_store_dword v[100:101], v169, off
	global_load_dword v170, v192, s[12:13]
	v_or_b32_e32 v100, 0x2c20, v194
	v_ashrrev_i32_e32 v101, 31, v100
	v_lshl_add_u64 v[102:103], v[100:101], 2, s[10:11]
	global_store_dword v[102:103], v171, off
	v_or_b32_e32 v102, 64, v199
	v_or_b32_e32 v118, v220, v102
	v_or_b32_e32 v130, v223, v102
	v_or_b32_e32 v132, v226, v102
	v_or_b32_e32 v134, v227, v102
	v_ashrrev_i32_e32 v119, 31, v118
	v_ashrrev_i32_e32 v131, 31, v130
	v_ashrrev_i32_e32 v133, 31, v132
	v_ashrrev_i32_e32 v135, 31, v134
	v_or_b32_e32 v138, v228, v102
	v_or_b32_e32 v142, v229, v102
	v_lshl_add_u64 v[118:119], v[118:119], 2, s[10:11]
	v_lshl_add_u64 v[130:131], v[130:131], 2, s[10:11]
	v_lshl_add_u64 v[132:133], v[132:133], 2, s[10:11]
	v_lshl_add_u64 v[134:135], v[134:135], 2, s[10:11]
	v_ashrrev_i32_e32 v139, 31, v138
	v_ashrrev_i32_e32 v143, 31, v142
	s_waitcnt vmcnt(20)
; DI bfr f2bf(float a) { return (bfr)(pack2(a, 0.f) & 0xffffu); }
; DI int crow(int reg, int h) { return (reg & 3) + 8 * (reg >> 2) + 4 * h; }
; template <bool FIRST, bool HAS_H>
; DI void phase_gemm_resid(const Params& p, const bfr* A, const bfr* Wt, const float* gnext, float* ss, char* smem) {
;     ...
;     int tid2 = threadIdx.x;
;     asm volatile("" : "+v"(tid2));
;     const int lane = tid2 & 63, wid = tid2 >> 6, wr = wid >> 1, wc = wid & 1, r = lane & 31, hl = lane >> 5;
;     const float* xsrc = FIRST ? p.x_prompt : X;
;     const int rbase = m0 + wr * 64 + 4 * hl, cbase = n0 + wc * 128 + r;
; #pragma unroll
;     for (int i = 0; i < 2; ++i) {
; #pragma unroll
;       for (int qh = 0; qh < 2; ++qh) {
;         float rs[8];
; #pragma unroll
;         for (int q = 0; q < 8; ++q) rs[q] = 0.f;
; #pragma unroll
;         for (int jh = 0; jh < 2; ++jh) {
;           float xo[2][8];
; #pragma unroll
;           for (int jj = 0; jj < 2; ++jj)
; #pragma unroll
;             for (int q = 0; q < 8; ++q)
;               xo[jj][q] = xsrc[(rbase + i * 32 + crow(qh * 8 + q, 0)) * 1024 + cbase + (jh * 2 + jj) * 32];
; #pragma unroll
;           for (int q = 0; q < 8; ++q) {
;             const int o = (rbase + i * 32 + crow(qh * 8 + q, 0)) * 1024 + cbase;
; #pragma unroll
;             for (int jj = 0; jj < 2; ++jj) {
;               const int j = jh * 2 + jj;
;               const float xn = xo[jj][q] + acc[i][j][qh * 8 + q];
;               X[o + j * 32] = xn;
;               if (HAS_H) Hn[o + j * 32] = f2bf(xn * gnext[cbase + j * 32]);
;               rs[q] += xn * xn;
;             }
;           }
;         }
	v_mul_f32_e32 v103, v115, v158
	v_lshl_add_u64 v[138:139], v[138:139], 2, s[10:11]
	v_lshl_add_u64 v[142:143], v[142:143], 2, s[10:11]
	global_load_dword v172, v[202:203], off offset:256
	global_load_dword v173, v[118:119], off
	s_nop 0
	global_load_dword v130, v[130:131], off
	s_nop 0
	global_load_dword v131, v[132:133], off
	s_nop 0
	global_load_dword v132, v[134:135], off
	global_load_dword v133, v[138:139], off
	s_nop 0
	global_load_dword v134, v[142:143], off
	global_load_dword v135, v[202:203], off offset:384
	v_cvt_pk_bf16_f32 v103, v103, s0
	v_lshl_add_u64 v[118:119], v[152:153], 1, s[6:7]
	global_store_short v[118:119], v103, off
	v_or_b32_e32 v103, 0x60, v199
	v_or_b32_e32 v118, v220, v103
	v_ashrrev_i32_e32 v119, 31, v118
	v_lshl_add_u64 v[118:119], v[118:119], 2, s[10:11]
	global_load_dword v138, v[118:119], off
	s_waitcnt vmcnt(27)
	v_mul_f32_e32 v118, v159, v162
	v_cvt_pk_bf16_f32 v139, v118, s0
	v_lshl_add_u64 v[118:119], v[154:155], 1, s[6:7]
	global_store_short v[118:119], v139, off
	v_or_b32_e32 v118, v223, v103
	v_mul_f32_e32 v139, v159, v159
	v_ashrrev_i32_e32 v119, 31, v118
	v_fmac_f32_e32 v139, v115, v115
	s_waitcnt vmcnt(26)
	v_mul_f32_e32 v115, v163, v150
	v_lshl_add_u64 v[118:119], v[118:119], 2, s[10:11]
	v_cvt_pk_bf16_f32 v115, v115, s0
	global_load_dword v142, v[118:119], off
	v_lshl_add_u64 v[118:119], v[156:157], 1, s[6:7]
	global_store_short v[118:119], v115, off
	s_waitcnt vmcnt(26)
	v_mul_f32_e32 v115, v151, v164
	v_cvt_pk_bf16_f32 v115, v115, s0
	v_lshl_add_u64 v[118:119], v[148:149], 1, s[6:7]
	global_store_short v[118:119], v115, off
	v_or_b32_e32 v118, v226, v103
	v_ashrrev_i32_e32 v119, 31, v118
	v_lshl_add_u64 v[118:119], v[118:119], 2, s[10:11]
	global_load_dword v143, v[118:119], off
	s_waitcnt vmcnt(25)
	v_mul_f32_e32 v118, v165, v144
	v_cvt_pk_bf16_f32 v118, v118, s0
	global_store_short v[116:117], v118, off
	s_waitcnt vmcnt(24)
	v_mul_f32_e32 v116, v145, v146
	v_cvt_pk_bf16_f32 v118, v116, s0
	v_lshl_add_u64 v[116:117], v[140:141], 1, s[6:7]
	global_store_short v[116:117], v118, off
	v_or_b32_e32 v116, v227, v103
	v_ashrrev_i32_e32 v117, 31, v116
	v_lshl_add_u64 v[116:117], v[116:117], 2, s[10:11]
	global_load_dword v140, v[116:117], off
	s_waitcnt vmcnt(23)
	v_mul_f32_e32 v116, v147, v166
	v_cvt_pk_bf16_f32 v118, v116, s0
	v_lshl_add_u64 v[116:117], v[136:137], 1, s[6:7]
	global_store_short v[116:117], v118, off
	v_mul_f32_e32 v137, v167, v167
	v_mul_f32_e32 v141, v145, v145
	v_fmac_f32_e32 v137, v147, v147
	global_load_dword v145, v192, s[12:13] offset:128
	s_waitcnt vmcnt(23)
	v_mul_f32_e32 v116, v167, v168
	v_cvt_pk_bf16_f32 v118, v116, s0
	v_or_b32_e32 v116, v228, v103
	v_ashrrev_i32_e32 v117, 31, v116
	v_lshl_add_u64 v[116:117], v[116:117], 2, s[10:11]
	global_load_dword v136, v[116:117], off
	v_lshl_add_u64 v[116:117], v[128:129], 1, s[6:7]
	global_store_short v[116:117], v118, off
	v_or_b32_e32 v118, v229, v103
	s_waitcnt vmcnt(23)
	v_mul_f32_e32 v116, v169, v170
	v_ashrrev_i32_e32 v119, 31, v118
	v_cvt_pk_bf16_f32 v144, v116, s0
	v_or_b32_e32 v116, v230, v102
	v_lshl_add_u64 v[118:119], v[118:119], 2, s[10:11]
	global_load_dword v146, v[118:119], off
	v_ashrrev_i32_e32 v117, 31, v116
	v_or_b32_e32 v118, v230, v103
	v_lshl_add_u64 v[116:117], v[116:117], 2, s[10:11]
	v_ashrrev_i32_e32 v119, 31, v118
	v_lshl_add_u64 v[118:119], v[118:119], 2, s[10:11]
	global_load_dword v147, v[116:117], off
	global_load_dword v148, v[118:119], off
	v_mul_f32_e32 v115, v151, v151
	v_fmac_f32_e32 v115, v163, v163
	s_waitcnt vmcnt(24)
	v_add_f32_e32 v149, v80, v172
	global_store_dword v[200:201], v149, off offset:256
	v_or_b32_e32 v80, 0x440, v194
	global_load_dword v150, v192, s[12:13] offset:256
	s_waitcnt vmcnt(25)
	v_add_f32_e32 v152, v81, v173
	v_ashrrev_i32_e32 v81, 31, v80
	v_lshl_add_u64 v[80:81], v[80:81], 2, s[10:11]
	s_waitcnt vmcnt(19)
	v_add_f32_e32 v135, v64, v135
	v_or_b32_e32 v64, 0x460, v194
	global_store_dword v[200:201], v135, off offset:384
	global_load_dword v151, v192, s[12:13] offset:384
	v_add_f32_e32 v155, v82, v130
	global_store_dword v[80:81], v152, off
	global_load_dword v153, v192, s[12:13] offset:256
	v_or_b32_e32 v82, 0xc40, v194
	s_waitcnt vmcnt(21)
	v_add_f32_e32 v138, v65, v138
	v_ashrrev_i32_e32 v65, 31, v64
	v_lshl_add_u64 v[64:65], v[64:65], 2, s[10:11]
	global_store_dword v[64:65], v138, off
	v_or_b32_e32 v64, 0x840, v194
	v_ashrrev_i32_e32 v65, 31, v64
	v_lshl_add_u64 v[80:81], v[64:65], 2, s[10:11]
	global_load_dword v154, v192, s[12:13] offset:384
	v_add_f32_e32 v158, v83, v131
	global_store_dword v[80:81], v155, off
	v_or_b32_e32 v80, 0x860, v194
	v_ashrrev_i32_e32 v81, 31, v80
	global_load_dword v156, v192, s[12:13] offset:256
	s_waitcnt vmcnt(23)
	v_add_f32_e32 v142, v66, v142
	v_lshl_add_u64 v[116:117], v[80:81], 2, s[10:11]
	v_ashrrev_i32_e32 v83, 31, v82
	v_or_b32_e32 v66, 0xc60, v194
	global_store_dword v[116:117], v142, off
	v_lshl_add_u64 v[116:117], v[82:83], 2, s[10:11]
	global_load_dword v157, v192, s[12:13] offset:384
	v_add_f32_e32 v163, v84, v132
	global_store_dword v[116:117], v158, off
	s_waitcnt vmcnt(23)
	v_add_f32_e32 v143, v67, v143
	v_ashrrev_i32_e32 v67, 31, v66
	v_lshl_add_u64 v[116:117], v[66:67], 2, s[10:11]
	global_load_dword v159, v192, s[12:13] offset:256
	v_or_b32_e32 v84, 0x2440, v194
	global_store_dword v[116:117], v143, off
	v_or_b32_e32 v116, 0x2040, v194
	v_ashrrev_i32_e32 v117, 31, v116
	v_lshl_add_u64 v[118:119], v[116:117], 2, s[10:11]
	global_load_dword v162, v192, s[12:13] offset:384
	v_add_f32_e32 v166, v85, v133
	global_store_dword v[118:119], v163, off
	v_or_b32_e32 v118, 0x2060, v194
	v_ashrrev_i32_e32 v119, 31, v118
	global_load_dword v164, v192, s[12:13] offset:256
	s_waitcnt vmcnt(25)
; DI bfr f2bf(float a) { return (bfr)(pack2(a, 0.f) & 0xffffu); }
; DI int crow(int reg, int h) { return (reg & 3) + 8 * (reg >> 2) + 4 * h; }
; template <bool FIRST, bool HAS_H>
; DI void phase_gemm_resid(const Params& p, const bfr* A, const bfr* Wt, const float* gnext, float* ss, char* smem) {
;     ...
;     int tid2 = threadIdx.x;
;     asm volatile("" : "+v"(tid2));
;     const int lane = tid2 & 63, wid = tid2 >> 6, wr = wid >> 1, wc = wid & 1, r = lane & 31, hl = lane >> 5;
;     const float* xsrc = FIRST ? p.x_prompt : X;
;     const int rbase = m0 + wr * 64 + 4 * hl, cbase = n0 + wc * 128 + r;
; #pragma unroll
;     for (int i = 0; i < 2; ++i) {
; #pragma unroll
;       for (int qh = 0; qh < 2; ++qh) {
;         float rs[8];
; #pragma unroll
;         for (int q = 0; q < 8; ++q) rs[q] = 0.f;
; #pragma unroll
;         for (int jh = 0; jh < 2; ++jh) {
;           float xo[2][8];
; #pragma unroll
;           for (int jj = 0; jj < 2; ++jj)
; #pragma unroll
;             for (int q = 0; q < 8; ++q)
;               xo[jj][q] = xsrc[(rbase + i * 32 + crow(qh * 8 + q, 0)) * 1024 + cbase + (jh * 2 + jj) * 32];
; #pragma unroll
;           for (int q = 0; q < 8; ++q) {
;             const int o = (rbase + i * 32 + crow(qh * 8 + q, 0)) * 1024 + cbase;
; #pragma unroll
;             for (int jj = 0; jj < 2; ++jj) {
;               const int j = jh * 2 + jj;
;               const float xn = xo[jj][q] + acc[i][j][qh * 8 + q];
;               X[o + j * 32] = xn;
;               if (HAS_H) Hn[o + j * 32] = f2bf(xn * gnext[cbase + j * 32]);
;               rs[q] += xn * xn;
;             }
;           }
;         }
	v_add_f32_e32 v140, v68, v140
	v_lshl_add_u64 v[128:129], v[118:119], 2, s[10:11]
	v_ashrrev_i32_e32 v85, 31, v84
	v_or_b32_e32 v68, 0x2460, v194
	global_store_dword v[128:129], v140, off
	v_lshl_add_u64 v[128:129], v[84:85], 2, s[10:11]
	v_fmac_f32_e32 v141, v165, v165
	global_load_dword v165, v192, s[12:13] offset:384
	v_add_f32_e32 v134, v86, v134
	global_store_dword v[128:129], v166, off
	s_waitcnt vmcnt(25)
	v_add_f32_e32 v136, v69, v136
	v_ashrrev_i32_e32 v69, 31, v68
	v_lshl_add_u64 v[128:129], v[68:69], 2, s[10:11]
	global_load_dword v167, v192, s[12:13] offset:256
	v_or_b32_e32 v86, 0x2c40, v194
	global_store_dword v[128:129], v136, off
	v_or_b32_e32 v128, 0x2840, v194
	v_ashrrev_i32_e32 v129, 31, v128
	v_lshl_add_u64 v[130:131], v[128:129], 2, s[10:11]
	global_load_dword v168, v192, s[12:13] offset:384
	s_waitcnt vmcnt(26)
	v_add_f32_e32 v146, v70, v146
	global_store_dword v[130:131], v134, off
	v_or_b32_e32 v130, 0x2860, v194
	v_ashrrev_i32_e32 v131, 31, v130
	global_load_dword v170, v192, s[12:13] offset:256
	v_lshl_add_u64 v[132:133], v[130:131], 2, s[10:11]
	global_store_dword v[132:133], v146, off
	s_waitcnt vmcnt(28)
	v_add_f32_e32 v147, v87, v147
	v_ashrrev_i32_e32 v87, 31, v86
	global_load_dword v172, v192, s[12:13] offset:384
	v_lshl_add_u64 v[132:133], v[86:87], 2, s[10:11]
	v_or_b32_e32 v70, 0x2c60, v194
	global_store_dword v[132:133], v147, off
	s_waitcnt vmcnt(29)
	v_add_f32_e32 v148, v71, v148
	v_ashrrev_i32_e32 v71, 31, v70
	global_load_dword v173, v192, s[12:13] offset:256
	v_lshl_add_u64 v[132:133], v[70:71], 2, s[10:11]
	global_store_dword v[132:133], v148, off
	global_load_dword v132, v192, s[12:13] offset:384
	v_lshl_add_u64 v[98:99], v[98:99], 1, s[6:7]
	global_store_short v[98:99], v144, off
	v_mul_f32_e32 v98, v171, v145
	v_cvt_pk_bf16_f32 v133, v98, s0
	v_lshl_add_u64 v[98:99], v[100:101], 1, s[6:7]
	global_store_short v[98:99], v133, off
	s_waitcnt vmcnt(32)
	v_mul_f32_e32 v99, v149, v150
	v_cvt_pk_bf16_f32 v99, v99, s0
	global_store_short v[112:113], v99, off offset:128
	s_waitcnt vmcnt(31)
	v_mul_f32_e32 v99, v135, v151
	v_cvt_pk_bf16_f32 v99, v99, s0
	global_store_short v[112:113], v99, off offset:192
	s_waitcnt vmcnt(30)
	v_mul_f32_e32 v99, v152, v153
	v_cvt_pk_bf16_f32 v99, v99, s0
	global_store_short v[112:113], v99, off offset:2176
	s_waitcnt vmcnt(29)
	v_mul_f32_e32 v99, v138, v154
	v_cvt_pk_bf16_f32 v99, v99, s0
	global_store_short v[112:113], v99, off offset:2240
	s_waitcnt vmcnt(28)
	v_mul_f32_e32 v99, v155, v156
	v_cvt_pk_bf16_f32 v99, v99, s0
	v_lshl_add_u64 v[64:65], v[64:65], 1, s[6:7]
	global_store_short v[64:65], v99, off
	v_mul_f32_e32 v98, v171, v171
	s_waitcnt vmcnt(27)
	v_mul_f32_e32 v64, v142, v157
	v_cvt_pk_bf16_f32 v99, v64, s0
	v_lshl_add_u64 v[64:65], v[80:81], 1, s[6:7]
	global_store_short v[64:65], v99, off
	v_fmac_f32_e32 v114, v211, v211
	v_fmac_f32_e32 v160, v189, v189
	s_waitcnt vmcnt(26)
	v_mul_f32_e32 v64, v158, v159
	v_cvt_pk_bf16_f32 v80, v64, s0
	v_lshl_add_u64 v[64:65], v[82:83], 1, s[6:7]
	global_store_short v[64:65], v80, off
	v_fmac_f32_e32 v161, v176, v176
	v_fmac_f32_e32 v98, v169, v169
	s_waitcnt vmcnt(25)
	v_mul_f32_e32 v64, v143, v162
	v_cvt_pk_bf16_f32 v80, v64, s0
	v_lshl_add_u64 v[64:65], v[66:67], 1, s[6:7]
	global_store_short v[64:65], v80, off
	v_fmac_f32_e32 v114, v149, v149
	s_waitcnt vmcnt(24)
	v_mul_f32_e32 v64, v163, v164
	v_cvt_pk_bf16_f32 v66, v64, s0
	v_lshl_add_u64 v[64:65], v[116:117], 1, s[6:7]
	global_store_short v[64:65], v66, off
	v_fmac_f32_e32 v160, v152, v152
	v_fmac_f32_e32 v161, v155, v155
	v_fmac_f32_e32 v139, v158, v158
	v_fmac_f32_e32 v115, v163, v163
	s_waitcnt vmcnt(23)
	v_mul_f32_e32 v64, v140, v165
	v_cvt_pk_bf16_f32 v66, v64, s0
	v_lshl_add_u64 v[64:65], v[118:119], 1, s[6:7]
	global_store_short v[64:65], v66, off
	v_fmac_f32_e32 v141, v166, v166
	v_fmac_f32_e32 v137, v134, v134
	s_waitcnt vmcnt(22)
	v_mul_f32_e32 v64, v166, v167
	v_cvt_pk_bf16_f32 v66, v64, s0
	v_lshl_add_u64 v[64:65], v[84:85], 1, s[6:7]
	global_store_short v[64:65], v66, off
	v_fmac_f32_e32 v98, v147, v147
	v_fmac_f32_e32 v114, v135, v135
	s_waitcnt vmcnt(21)
	v_mul_f32_e32 v64, v136, v168
	v_cvt_pk_bf16_f32 v66, v64, s0
	v_lshl_add_u64 v[64:65], v[68:69], 1, s[6:7]
	global_store_short v[64:65], v66, off
	v_fmac_f32_e32 v160, v138, v138
	s_waitcnt vmcnt(20)
	v_mul_f32_e32 v64, v134, v170
	v_cvt_pk_bf16_f32 v66, v64, s0
	v_lshl_add_u64 v[64:65], v[128:129], 1, s[6:7]
	global_store_short v[64:65], v66, off
	v_fmac_f32_e32 v161, v142, v142
	s_waitcnt vmcnt(19)
	v_mul_f32_e32 v64, v146, v172
	v_cvt_pk_bf16_f32 v66, v64, s0
	v_lshl_add_u64 v[64:65], v[130:131], 1, s[6:7]
	global_store_short v[64:65], v66, off
	v_fmac_f32_e32 v139, v143, v143
	v_fmac_f32_e32 v115, v140, v140
	s_waitcnt vmcnt(18)
; DI bfr f2bf(float a) { return (bfr)(pack2(a, 0.f) & 0xffffu); }
; #define DPPF(v, ctrl, rmask) __builtin_bit_cast(float, __builtin_amdgcn_update_dpp(0, __builtin_bit_cast(int, (v)), (ctrl), (rmask), 0xf, false))
; DI int crow(int reg, int h) { return (reg & 3) + 8 * (reg >> 2) + 4 * h; }
; DI float row16_sum(float v) {
;   v += DPPF(v, 0xB1, 0xf);
;   v += DPPF(v, 0x4E, 0xf);
;   v += DPPF(v, 0x141, 0xf);
;   v += DPPF(v, 0x140, 0xf);
;   return v;
; }
; DI float half32_sum_hi(float v) {
;   v = row16_sum(v);
;   v += DPPF(v, 0x142, 0xa);
;   return v;
; template <bool FIRST, bool HAS_H>
; DI void phase_gemm_resid(const Params& p, const bfr* A, const bfr* Wt, const float* gnext, float* ss, char* smem) {
;     ...
;           for (int q = 0; q < 8; ++q) {
;             const int o = (rbase + i * 32 + crow(qh * 8 + q, 0)) * 1024 + cbase;
; #pragma unroll
;             for (int jj = 0; jj < 2; ++jj) {
;               const int j = jh * 2 + jj;
;               const float xn = xo[jj][q] + acc[i][j][qh * 8 + q];
;               X[o + j * 32] = xn;
;               if (HAS_H) Hn[o + j * 32] = f2bf(xn * gnext[cbase + j * 32]);
;               rs[q] += xn * xn;
;             }
;           }
;         }
; #pragma unroll
;         for (int q = 0; q < 8; ++q) rs[q] = half32_sum_hi(rs[q]);
;         if (r == 31) {
; #pragma unroll
;           for (int q = 0; q < 8; ++q) unsafeAtomicAdd(ss + rbase + i * 32 + crow(qh * 8 + q, 0), rs[q]);
	v_mul_f32_e32 v64, v147, v173
	v_cvt_pk_bf16_f32 v66, v64, s0
	v_lshl_add_u64 v[64:65], v[86:87], 1, s[6:7]
	global_store_short v[64:65], v66, off
	s_waitcnt vmcnt(17)
	v_mul_f32_e32 v64, v148, v132
	v_fmac_f32_e32 v141, v136, v136
	v_fmac_f32_e32 v137, v146, v146
	v_cvt_pk_bf16_f32 v66, v64, s0
	v_lshl_add_u64 v[64:65], v[70:71], 1, s[6:7]
	v_fmac_f32_e32 v98, v148, v148
	global_store_short v[64:65], v66, off
	v_add_f32_dpp v64, v114, v114 quad_perm:[1,0,3,2] row_mask:0xf bank_mask:0xf bound_ctrl:1
	v_add_f32_dpp v66, v160, v160 quad_perm:[1,0,3,2] row_mask:0xf bank_mask:0xf bound_ctrl:1
	v_add_f32_dpp v68, v161, v161 quad_perm:[1,0,3,2] row_mask:0xf bank_mask:0xf bound_ctrl:1
	v_add_f32_dpp v70, v139, v139 quad_perm:[1,0,3,2] row_mask:0xf bank_mask:0xf bound_ctrl:1
	v_add_f32_dpp v80, v115, v115 quad_perm:[1,0,3,2] row_mask:0xf bank_mask:0xf bound_ctrl:1
	v_add_f32_dpp v82, v141, v141 quad_perm:[1,0,3,2] row_mask:0xf bank_mask:0xf bound_ctrl:1
	v_add_f32_dpp v84, v137, v137 quad_perm:[1,0,3,2] row_mask:0xf bank_mask:0xf bound_ctrl:1
	v_add_f32_dpp v86, v98, v98 quad_perm:[1,0,3,2] row_mask:0xf bank_mask:0xf bound_ctrl:1
	v_add_f32_dpp v64, v64, v64 quad_perm:[2,3,0,1] row_mask:0xf bank_mask:0xf bound_ctrl:1
	v_add_f32_dpp v66, v66, v66 quad_perm:[2,3,0,1] row_mask:0xf bank_mask:0xf bound_ctrl:1
	v_add_f32_dpp v68, v68, v68 quad_perm:[2,3,0,1] row_mask:0xf bank_mask:0xf bound_ctrl:1
	v_add_f32_dpp v70, v70, v70 quad_perm:[2,3,0,1] row_mask:0xf bank_mask:0xf bound_ctrl:1
	v_add_f32_dpp v80, v80, v80 quad_perm:[2,3,0,1] row_mask:0xf bank_mask:0xf bound_ctrl:1
	v_add_f32_dpp v82, v82, v82 quad_perm:[2,3,0,1] row_mask:0xf bank_mask:0xf bound_ctrl:1
	v_add_f32_dpp v84, v84, v84 quad_perm:[2,3,0,1] row_mask:0xf bank_mask:0xf bound_ctrl:1
	v_add_f32_dpp v86, v86, v86 quad_perm:[2,3,0,1] row_mask:0xf bank_mask:0xf bound_ctrl:1
	v_add_f32_dpp v64, v64, v64 row_half_mirror row_mask:0xf bank_mask:0xf bound_ctrl:1
	v_add_f32_dpp v66, v66, v66 row_half_mirror row_mask:0xf bank_mask:0xf bound_ctrl:1
	v_add_f32_dpp v68, v68, v68 row_half_mirror row_mask:0xf bank_mask:0xf bound_ctrl:1
	v_add_f32_dpp v70, v70, v70 row_half_mirror row_mask:0xf bank_mask:0xf bound_ctrl:1
	v_add_f32_dpp v80, v80, v80 row_half_mirror row_mask:0xf bank_mask:0xf bound_ctrl:1
	v_add_f32_dpp v82, v82, v82 row_half_mirror row_mask:0xf bank_mask:0xf bound_ctrl:1
	v_add_f32_dpp v84, v84, v84 row_half_mirror row_mask:0xf bank_mask:0xf bound_ctrl:1
	v_add_f32_dpp v86, v86, v86 row_half_mirror row_mask:0xf bank_mask:0xf bound_ctrl:1
	v_add_f32_dpp v64, v64, v64 row_mirror row_mask:0xf bank_mask:0xf bound_ctrl:1
	v_mov_b32_e32 v65, 0
	v_add_f32_dpp v66, v66, v66 row_mirror row_mask:0xf bank_mask:0xf bound_ctrl:1
	v_mov_b32_e32 v67, 0
	v_add_f32_dpp v68, v68, v68 row_mirror row_mask:0xf bank_mask:0xf bound_ctrl:1
	v_mov_b32_e32 v69, 0
	v_add_f32_dpp v70, v70, v70 row_mirror row_mask:0xf bank_mask:0xf bound_ctrl:1
	v_mov_b32_e32 v71, 0
	v_add_f32_dpp v80, v80, v80 row_mirror row_mask:0xf bank_mask:0xf bound_ctrl:1
	v_mov_b32_e32 v81, 0
	v_add_f32_dpp v82, v82, v82 row_mirror row_mask:0xf bank_mask:0xf bound_ctrl:1
	v_mov_b32_e32 v83, 0
	v_add_f32_dpp v84, v84, v84 row_mirror row_mask:0xf bank_mask:0xf bound_ctrl:1
	v_mov_b32_e32 v85, 0
	v_add_f32_dpp v86, v86, v86 row_mirror row_mask:0xf bank_mask:0xf bound_ctrl:1
	v_mov_b32_e32 v87, 0
	v_mov_b32_dpp v65, v64 row_bcast:15 row_mask:0xa bank_mask:0xf
	v_mov_b32_dpp v67, v66 row_bcast:15 row_mask:0xa bank_mask:0xf
	v_mov_b32_dpp v69, v68 row_bcast:15 row_mask:0xa bank_mask:0xf
	v_mov_b32_dpp v71, v70 row_bcast:15 row_mask:0xa bank_mask:0xf
	v_mov_b32_dpp v81, v80 row_bcast:15 row_mask:0xa bank_mask:0xf
	v_mov_b32_dpp v83, v82 row_bcast:15 row_mask:0xa bank_mask:0xf
	v_mov_b32_dpp v85, v84 row_bcast:15 row_mask:0xa bank_mask:0xf
	v_mov_b32_dpp v87, v86 row_bcast:15 row_mask:0xa bank_mask:0xf
	s_and_saveexec_b64 s[4:5], vcc
	s_cbranch_execz .LBB0_1479
	v_add_f32_e32 v64, v64, v65
	v_add_f32_e32 v86, v86, v87
	v_add_f32_e32 v84, v84, v85
	v_add_f32_e32 v82, v82, v83
	v_add_f32_e32 v80, v80, v81
	v_add_f32_e32 v70, v70, v71
	v_add_f32_e32 v68, v68, v69
	v_add_f32_e32 v66, v66, v67
	global_atomic_add_f32 v[96:97], v64, off
	global_atomic_add_f32 v[96:97], v66, off offset:4
	global_atomic_add_f32 v[96:97], v68, off offset:8
	global_atomic_add_f32 v[96:97], v70, off offset:12
	global_atomic_add_f32 v[96:97], v80, off offset:32
	global_atomic_add_f32 v[96:97], v82, off offset:36
	global_atomic_add_f32 v[96:97], v84, off offset:40
	global_atomic_add_f32 v[96:97], v86, off offset:44

; #define GA_LOAD(pr_) do { _Pragma("unroll") for (int i = 0; i < 4; ++i) ra[i] = *(const u32x4*)(Ab + (i * 32) * lda + (pr_) * 64); } while (0)
; #define GB_LOAD(kt_) do { const bfr* bk_ = Bb + (kt_) * NB * 32; \
;     _Pragma("unroll") for (int i = 0; i < 4; ++i) rb[i] = *(const u32x4*)(bk_ + (i * 64) * 32); } while (0)
; #define G_STORE(kt_) do { bfr* as_ = S0 + ((kt_) & 1) * GSTAGE; bfr* bs_ = as_ + 128 * 40; \
;     if (apar == ((kt_) & 1)) { _Pragma("unroll") for (int i = 0; i < 4; ++i) *(u32x4*)(as_ + asoff + i * 32 * 40) = ra[i]; } \
;     _Pragma("unroll") for (int i = 0; i < 4; ++i) *(u32x4*)(bs_ + bsoff + i * 64 * 40) = rb[i]; } while (0)
; template <int lda>
; DI void gemm_mainloop(const bfr* __restrict__ A, const bfr* __restrict__ Bt, int NB, int K, int m0, int n0, char* smem, f32x16 (&acc)[2][4]) {
;   bfr* S0 = (bfr*)smem;
;   int tid = threadIdx.x;
;   asm volatile("" : "+v"(tid));
;   const int lane = tid & 63, wid = tid >> 6, wr = wid >> 1, wc = wid & 1;
;   const int r = lane & 31, hl = lane >> 5;
; #pragma unroll
;   for (int i = 0; i < 2; ++i)
; #pragma unroll
;     for (int j = 0; j < 4; ++j)
; #pragma unroll
;       for (int q = 0; q < 16; ++q) acc[i][j][q] = 0.f;
;   u32x4 ra[4], rb[4];
;   const int nk = K >> 5;
;   const int arow = tid >> 3, ac8 = tid & 7, apar = ac8 >> 2;
;   const bfr* Ab = A + (m0 + arow) * lda + ac8 * 8;
;   const int asoff = arow * 40 + (ac8 & 3) * 8;
;   const int brow = tid >> 2, bc4 = tid & 3;
;   const bfr* Bb = Bt + (n0 + brow) * 32 + bc4 * 8;
;   const int bsoff = brow * 40 + bc4 * 8;
;     ...
;   GA_LOAD(0);
;   GB_LOAD(0);
;   G_STORE(0);
;   GB_LOAD(1);
;   __syncthreads();
; DI void phase_gemm_bf16out(const Params& p, const bfr* A, const bfr* Wt, bfr* C, int N, const float* ss, char* smem) {
;     ...
;   for (int t0 = blockIdx.x; t0 < 128 * ntn; t0 += gridDim.x) {
;     const int t = ((gridDim.x & 7) == 0) ? xcd_tile(t0, ntn) : t0;
;     int mt = t / ntn, nt = t % ntn;
;     gemm_tile<1024>(A, Wt, N, 1024, mt * 128, nt * 256, smem,
.LBB0_1548:
	s_ashr_i32 s5, s4, 31
	s_lshr_b32 s5, s5, 30
	s_add_i32 s5, s4, s5
	s_and_b32 s20, s5, 0xfffffc
	s_lshl_b32 s5, s5, 5
	s_and_b32 s33, s5, 0xffffff80
	s_sub_i32 s4, s4, s20
	s_lshl_b32 s31, s4, 8
	s_mov_b32 s36, 0
	s_mov_b64 s[20:21], 0
	s_lshl_b32 s98, s33, 11
	s_add_u32 s98, s10, s98
	s_addc_u32 s99, s11, 0
	s_lshl_b32 s100, s31, 6
	s_add_u32 s100, s14, s100
	s_addc_u32 s101, s15, 0
	v_writelane_b32 v187, s64, 0
	v_writelane_b32 v187, s65, 1
	v_writelane_b32 v187, s66, 2
	v_writelane_b32 v187, s67, 3
	v_writelane_b32 v187, s68, 4
	v_writelane_b32 v187, s69, 5
	v_writelane_b32 v187, s70, 6
	v_writelane_b32 v187, s71, 7
	v_writelane_b32 v187, s72, 8
	v_writelane_b32 v187, s73, 9
	v_writelane_b32 v187, s74, 10
	v_writelane_b32 v187, s75, 11
	v_writelane_b32 v187, s76, 12
	v_writelane_b32 v187, s77, 13
	v_writelane_b32 v187, s78, 14
	v_writelane_b32 v187, s79, 15
	v_lshrrev_b32_e32 v188, 6, v196
	v_and_b32_e32 v189, 63, v196
	v_readfirstlane_b32 s73, v188
	v_lshrrev_b32_e32 v190, 2, v189
	v_bfe_u32 v191, v189, 4, 2
	v_and_b32_e32 v188, 3, v189
	v_xor_b32_e32 v188, v188, v191
	v_lshlrev_b32_e32 v188, 4, v188
	v_lshl_add_u32 v176, v190, 11, v188
	v_add_u32_e32 v177, 0x8000, v176
	v_lshl_add_u32 v178, v190, 6, v188
	v_and_b32_e32 v190, 31, v189
	v_lshrrev_b32_e32 v191, 5, v189
	v_bfe_u32 v188, v189, 2, 2
	v_xor_b32_e32 v188, v188, v191
	v_lshlrev_b32_e32 v188, 4, v188
	v_lshl_add_u32 v179, v190, 6, v188
	s_lshr_b32 s74, s73, 1
	s_lshl_b32 s74, s74, 12
	s_and_b32 s75, s73, 1
	s_lshl_b32 s75, s75, 13
	v_add_u32_e32 v181, s75, v179
	v_add_u32_e32 v179, s74, v179
	v_xor_b32_e32 v182, 32, v181
	v_xor_b32_e32 v180, 32, v179
	s_lshl_b32 s74, s73, 16
	s_add_u32 s64, s98, s74
	s_addc_u32 s65, s99, 0
	s_lshl_b32 s74, s73, 12
	s_add_u32 s66, s100, s74
	s_addc_u32 s67, s101, 0
	s_lshl_b32 s68, s73, 11
	s_lshl_b32 s69, s73, 12
	s_mov_b32 s70, 0
	s_mov_b32 s71, 0
	s_mov_b32 s72, 0
	s_waitcnt lgkmcnt(0)
	s_barrier
	s_mul_i32 s74, s70, 0x6000
	s_add_u32 s75, s74, s68
	s_mov_b32 m0, s75
	s_add_u32 s76, s74, 0x2000
	s_cmp_eq_u32 s70, 2
	s_cselect_b32 s76, 0x10000, s76
	global_load_lds_dwordx4 v176, s[64:65]
	s_add_u32 m0, s75, 0x400
	s_add_u32 s76, s76, s69
	global_load_lds_dwordx4 v177, s[64:65]
	s_mov_b32 m0, s76
	s_add_u32 s64, s64, 64
	s_addc_u32 s65, s65, 0
	global_load_lds_dwordx4 v178, s[66:67]
	global_load_lds_dwordx4 v178, s[66:67] offset:1024
	global_load_lds_dwordx4 v178, s[66:67] offset:2048
	global_load_lds_dwordx4 v178, s[66:67] offset:3072
	s_add_u32 s66, s66, 0x10000
	s_addc_u32 s67, s67, 0
	s_add_u32 s70, s70, 1
	s_cmp_eq_u32 s70, 3
	s_cselect_b32 s70, 0, s70
	s_mul_i32 s74, s70, 0x6000
	s_add_u32 s75, s74, s68
	s_mov_b32 m0, s75
	s_add_u32 s76, s74, 0x2000
	s_cmp_eq_u32 s70, 2
	s_cselect_b32 s76, 0x10000, s76
	global_load_lds_dwordx4 v176, s[64:65]
	s_add_u32 m0, s75, 0x400
	s_add_u32 s76, s76, s69
	global_load_lds_dwordx4 v177, s[64:65]
	s_mov_b32 m0, s76
	s_add_u32 s64, s64, 64
	s_addc_u32 s65, s65, 0
	global_load_lds_dwordx4 v178, s[66:67]
	global_load_lds_dwordx4 v178, s[66:67] offset:1024
	global_load_lds_dwordx4 v178, s[66:67] offset:2048
	global_load_lds_dwordx4 v178, s[66:67] offset:3072
	s_add_u32 s66, s66, 0x10000
	s_addc_u32 s67, s67, 0
	s_add_u32 s70, s70, 1
	s_cmp_eq_u32 s70, 3
	s_cselect_b32 s70, 0, s70
	s_cmp_lt_u32 s46, 0x100
	s_cbranch_scc1 .Lp17_nostag
	s_sleep 8
	s_setprio 1

; #define GA_LOAD(pr_) do { _Pragma("unroll") for (int i = 0; i < 4; ++i) ra[i] = *(const u32x4*)(Ab + (i * 32) * lda + (pr_) * 64); } while (0)
; #define GB_LOAD(kt_) do { const bfr* bk_ = Bb + (kt_) * NB * 32; \
;     _Pragma("unroll") for (int i = 0; i < 4; ++i) rb[i] = *(const u32x4*)(bk_ + (i * 64) * 32); } while (0)
; #define G_STORE(kt_) do { bfr* as_ = S0 + ((kt_) & 1) * GSTAGE; bfr* bs_ = as_ + 128 * 40; \
;     if (apar == ((kt_) & 1)) { _Pragma("unroll") for (int i = 0; i < 4; ++i) *(u32x4*)(as_ + asoff + i * 32 * 40) = ra[i]; } \
;     _Pragma("unroll") for (int i = 0; i < 4; ++i) *(u32x4*)(bs_ + bsoff + i * 64 * 40) = rb[i]; } while (0)
; template <int lda>
; DI void gemm_mainloop(const bfr* __restrict__ A, const bfr* __restrict__ Bt, int NB, int K, int m0, int n0, char* smem, f32x16 (&acc)[2][4]) {
;   bfr* S0 = (bfr*)smem;
;   int tid = threadIdx.x;
;   asm volatile("" : "+v"(tid));
;   const int lane = tid & 63, wid = tid >> 6, wr = wid >> 1, wc = wid & 1;
;   const int r = lane & 31, hl = lane >> 5;
; #pragma unroll
;   for (int i = 0; i < 2; ++i)
; #pragma unroll
;     for (int j = 0; j < 4; ++j)
; #pragma unroll
;       for (int q = 0; q < 16; ++q) acc[i][j][q] = 0.f;
;   u32x4 ra[4], rb[4];
;   const int nk = K >> 5;
;   const int arow = tid >> 3, ac8 = tid & 7, apar = ac8 >> 2;
;   const bfr* Ab = A + (m0 + arow) * lda + ac8 * 8;
;   const int asoff = arow * 40 + (ac8 & 3) * 8;
;   const int brow = tid >> 2, bc4 = tid & 3;
;   const bfr* Bb = Bt + (n0 + brow) * 32 + bc4 * 8;
;   const int bsoff = brow * 40 + bc4 * 8;
;     ...
;   GA_LOAD(0);
;   GB_LOAD(0);
;   G_STORE(0);
;   GB_LOAD(1);
;   __syncthreads();
; template <bool FIRST, bool HAS_H>
; DI void phase_gemm_resid(const Params& p, const bfr* A, const bfr* Wt, const float* gnext, float* ss, char* smem) {
;     ...
;   for (int t0 = blockIdx.x; t0 < 128 * 4; t0 += gridDim.x) {
;     const int t = ((gridDim.x & 7) == 0) ? xcd_tile(t0, 4) : t0;
;     const int mt = t >> 2, nt = t & 3, m0 = mt * 128, n0 = nt * 256;
;     f32x16 acc[2][4];
;     gemm_mainloop<1024>(A, Wt, 1024, 1024, m0, n0, smem, acc);
.LBB0_1721:
	s_lshl_b32 s5, s4, 5
	s_and_b32 s59, s5, 0xffffff80
	s_lshl_b32 s4, s4, 8
	s_and_b32 s58, s4, 0x300
	s_mov_b32 s60, 0
	s_mov_b64 s[16:17], 0
	s_lshl_b32 s98, s59, 11
	s_add_u32 s98, s6, s98
	s_addc_u32 s99, s7, 0
	s_lshl_b32 s100, s58, 6
	s_add_u32 s100, s2, s100
	s_addc_u32 s101, s3, 0
	v_writelane_b32 v188, s64, 0
	v_writelane_b32 v188, s65, 1
	v_writelane_b32 v188, s66, 2
	v_writelane_b32 v188, s67, 3
	v_writelane_b32 v188, s68, 4
	v_writelane_b32 v188, s69, 5
	v_writelane_b32 v188, s70, 6
	v_writelane_b32 v188, s71, 7
	v_writelane_b32 v188, s72, 8
	v_writelane_b32 v188, s73, 9
	v_writelane_b32 v188, s74, 10
	v_writelane_b32 v188, s75, 11
	v_writelane_b32 v188, s76, 12
	v_writelane_b32 v188, s77, 13
	v_writelane_b32 v188, s78, 14
	v_writelane_b32 v188, s79, 15
	v_lshrrev_b32_e32 v189, 6, v196
	v_and_b32_e32 v190, 63, v196
	v_readfirstlane_b32 s73, v189
	v_lshrrev_b32_e32 v191, 2, v190
	v_bfe_u32 v192, v190, 4, 2
	v_and_b32_e32 v189, 3, v190
	v_xor_b32_e32 v189, v189, v192
	v_lshlrev_b32_e32 v189, 4, v189
	v_lshl_add_u32 v176, v191, 11, v189
	v_add_u32_e32 v177, 0x8000, v176
	v_lshl_add_u32 v178, v191, 6, v189
	v_and_b32_e32 v191, 31, v190
	v_lshrrev_b32_e32 v192, 5, v190
	v_bfe_u32 v189, v190, 2, 2
	v_xor_b32_e32 v189, v189, v192
	v_lshlrev_b32_e32 v189, 4, v189
	v_lshl_add_u32 v179, v191, 6, v189
	s_lshr_b32 s74, s73, 1
	s_lshl_b32 s74, s74, 12
	s_and_b32 s75, s73, 1
	s_lshl_b32 s75, s75, 13
	v_add_u32_e32 v182, s75, v179
	v_add_u32_e32 v179, s74, v179
	v_xor_b32_e32 v183, 32, v182
	v_xor_b32_e32 v180, 32, v179
	s_lshl_b32 s74, s73, 16
	s_add_u32 s64, s98, s74
	s_addc_u32 s65, s99, 0
	s_lshl_b32 s74, s73, 12
	s_add_u32 s66, s100, s74
	s_addc_u32 s67, s101, 0
	s_lshl_b32 s68, s73, 11
	s_lshl_b32 s69, s73, 12
	s_mov_b32 s70, 0
	s_mov_b32 s71, 0
	s_mov_b32 s72, 0
	s_waitcnt lgkmcnt(0)
	s_barrier
	s_mul_i32 s74, s70, 0x6000
	s_add_u32 s75, s74, s68
	s_mov_b32 m0, s75
	s_add_u32 s76, s74, 0x2000
	s_cmp_eq_u32 s70, 2
	s_cselect_b32 s76, 0x10000, s76
	global_load_lds_dwordx4 v176, s[64:65]
	s_add_u32 m0, s75, 0x400
	s_add_u32 s76, s76, s69
	global_load_lds_dwordx4 v177, s[64:65]
	s_mov_b32 m0, s76
	s_add_u32 s64, s64, 64
	s_addc_u32 s65, s65, 0
	global_load_lds_dwordx4 v178, s[66:67]
	global_load_lds_dwordx4 v178, s[66:67] offset:1024
	global_load_lds_dwordx4 v178, s[66:67] offset:2048
	global_load_lds_dwordx4 v178, s[66:67] offset:3072
	s_add_u32 s66, s66, 0x10000
	s_addc_u32 s67, s67, 0
	s_add_u32 s70, s70, 1
	s_cmp_eq_u32 s70, 3
	s_cselect_b32 s70, 0, s70
	s_mul_i32 s74, s70, 0x6000
	s_add_u32 s75, s74, s68
	s_mov_b32 m0, s75
	s_add_u32 s76, s74, 0x2000
	s_cmp_eq_u32 s70, 2
	s_cselect_b32 s76, 0x10000, s76
	global_load_lds_dwordx4 v176, s[64:65]
	s_add_u32 m0, s75, 0x400
	s_add_u32 s76, s76, s69
	global_load_lds_dwordx4 v177, s[64:65]
	s_mov_b32 m0, s76
	s_add_u32 s64, s64, 64
	s_addc_u32 s65, s65, 0
	global_load_lds_dwordx4 v178, s[66:67]
	global_load_lds_dwordx4 v178, s[66:67] offset:1024
	global_load_lds_dwordx4 v178, s[66:67] offset:2048
	global_load_lds_dwordx4 v178, s[66:67] offset:3072
	s_add_u32 s66, s66, 0x10000
	s_addc_u32 s67, s67, 0
	s_add_u32 s70, s70, 1
	s_cmp_eq_u32 s70, 3
	s_cselect_b32 s70, 0, s70
	s_cmp_lt_u32 s46, 0x100
	s_cbranch_scc1 .Lp19_nostag
	s_sleep 8
	s_setprio 1

; #define MFMA32(a, b, c) __builtin_amdgcn_mfma_f32_32x32x16_bf16((a), (b), (c), 0, 0, 0)
; #define GA_LOAD(pr_) do { _Pragma("unroll") for (int i = 0; i < 4; ++i) ra[i] = *(const u32x4*)(Ab + (i * 32) * lda + (pr_) * 64); } while (0)
; #define GB_LOAD(kt_) do { const bfr* bk_ = Bb + (kt_) * NB * 32; \
;     _Pragma("unroll") for (int i = 0; i < 4; ++i) rb[i] = *(const u32x4*)(bk_ + (i * 64) * 32); } while (0)
; #define G_STORE(kt_) do { bfr* as_ = S0 + ((kt_) & 1) * GSTAGE; bfr* bs_ = as_ + 128 * 40; \
;     if (apar == ((kt_) & 1)) { _Pragma("unroll") for (int i = 0; i < 4; ++i) *(u32x4*)(as_ + asoff + i * 32 * 40) = ra[i]; } \
;     _Pragma("unroll") for (int i = 0; i < 4; ++i) *(u32x4*)(bs_ + bsoff + i * 64 * 40) = rb[i]; } while (0)
; template <int lda>
; DI void gemm_mainloop(const bfr* __restrict__ A, const bfr* __restrict__ Bt, int NB, int K, int m0, int n0, char* smem, f32x16 (&acc)[2][4]) {
;     ...
;   for (int kt = 0; kt < nk; ++kt) {
;     if (kt + 1 < nk) G_STORE(kt + 1);
;     if (kt + 2 < nk) {
;       GB_LOAD(kt + 2);
;       if ((kt & 1) == 0) GA_LOAD((kt >> 1) + 1);
;     }
;     const bfr* As = S0 + (kt & 1) * GSTAGE;
;     const bfr* Bs = As + 128 * 40;
; #pragma unroll
;     for (int ks = 0; ks < 2; ++ks) {
;       bf16x8 af[2], bfg[4];
; #pragma unroll
;       for (int i = 0; i < 2; ++i) af[i] = *(const bf16x8*)(As + (wr * 64 + i * 32 + r) * 40 + ks * 16 + hl * 8);
; #pragma unroll
;       for (int j = 0; j < 4; ++j) bfg[j] = *(const bf16x8*)(Bs + (wc * 128 + j * 32 + r) * 40 + ks * 16 + hl * 8);
; #pragma unroll
;       for (int i = 0; i < 2; ++i)
; #pragma unroll
;         for (int j = 0; j < 4; ++j) acc[i][j] = MFMA32(af[i], bfg[j], acc[i][j]);
;     }
;     __syncthreads();
;   }
.Lp19_loop:
	s_waitcnt vmcnt(6)
	s_barrier
	s_mul_i32 s74, s71, 0x6000
	s_add_u32 s75, s74, 0x2000
	s_cmp_eq_u32 s71, 2
	s_cselect_b32 s75, 0x10000, s75
	v_add_u32_e32 v184, s74, v179
	v_add_u32_e32 v186, s75, v182
	v_add_u32_e32 v185, s74, v180
	v_add_u32_e32 v187, s75, v183
	ds_read_b128 v[128:131], v184
	ds_read_b128 v[144:147], v186
	ds_read_b128 v[148:151], v186 offset:2048
	ds_read_b128 v[152:155], v186 offset:4096
	ds_read_b128 v[156:159], v186 offset:6144
	ds_read_b128 v[132:135], v184 offset:2048
	ds_read_b128 v[136:139], v185
	ds_read_b128 v[160:163], v187
	ds_read_b128 v[164:167], v187 offset:2048
	ds_read_b128 v[168:171], v187 offset:4096
	ds_read_b128 v[172:175], v187 offset:6144
	ds_read_b128 v[140:143], v185 offset:2048
	s_add_u32 s71, s71, 1
	s_cmp_eq_u32 s71, 3
	s_cselect_b32 s71, 0, s71
	s_waitcnt lgkmcnt(10)
	v_mfma_f32_32x32x16_bf16 v[112:127], v[128:131], v[144:147], v[112:127]
	s_mul_i32 s74, s70, 0x6000
	s_add_u32 s75, s74, s68
	s_mov_b32 m0, s75
	s_add_u32 s76, s74, 0x2000
	s_cmp_eq_u32 s70, 2
	s_cselect_b32 s76, 0x10000, s76
	global_load_lds_dwordx4 v176, s[64:65]
	s_waitcnt lgkmcnt(9)
	v_mfma_f32_32x32x16_bf16 v[96:111], v[128:131], v[148:151], v[96:111]
	s_add_u32 m0, s75, 0x400
	s_add_u32 s76, s76, s69
	global_load_lds_dwordx4 v177, s[64:65]
	s_waitcnt lgkmcnt(8)
	v_mfma_f32_32x32x16_bf16 v[80:95], v[128:131], v[152:155], v[80:95]
	s_mov_b32 m0, s76
	s_add_u32 s64, s64, 64
	s_addc_u32 s65, s65, 0
	global_load_lds_dwordx4 v178, s[66:67]
	s_waitcnt lgkmcnt(7)
	v_mfma_f32_32x32x16_bf16 v[64:79], v[128:131], v[156:159], v[64:79]
	global_load_lds_dwordx4 v178, s[66:67] offset:1024
	s_waitcnt lgkmcnt(6)
	v_mfma_f32_32x32x16_bf16 v[48:63], v[132:135], v[144:147], v[48:63]
	global_load_lds_dwordx4 v178, s[66:67] offset:2048
	v_mfma_f32_32x32x16_bf16 v[32:47], v[132:135], v[148:151], v[32:47]
	global_load_lds_dwordx4 v178, s[66:67] offset:3072
	s_add_u32 s66, s66, 0x10000
	s_addc_u32 s67, s67, 0
	v_mfma_f32_32x32x16_bf16 v[16:31], v[132:135], v[152:155], v[16:31]
	s_add_u32 s70, s70, 1
	s_cmp_eq_u32 s70, 3
	s_cselect_b32 s70, 0, s70
	v_mfma_f32_32x32x16_bf16 v[0:15], v[132:135], v[156:159], v[0:15]
	s_waitcnt lgkmcnt(4)
	v_mfma_f32_32x32x16_bf16 v[112:127], v[136:139], v[160:163], v[112:127]
	s_waitcnt lgkmcnt(3)
	v_mfma_f32_32x32x16_bf16 v[96:111], v[136:139], v[164:167], v[96:111]
	s_waitcnt lgkmcnt(2)
	v_mfma_f32_32x32x16_bf16 v[80:95], v[136:139], v[168:171], v[80:95]
	s_waitcnt lgkmcnt(1)
	v_mfma_f32_32x32x16_bf16 v[64:79], v[136:139], v[172:175], v[64:79]
	s_waitcnt lgkmcnt(0)
	v_mfma_f32_32x32x16_bf16 v[48:63], v[140:143], v[160:163], v[48:63]
	v_mfma_f32_32x32x16_bf16 v[32:47], v[140:143], v[164:167], v[32:47]
	v_mfma_f32_32x32x16_bf16 v[16:31], v[140:143], v[168:171], v[16:31]
	v_mfma_f32_32x32x16_bf16 v[0:15], v[140:143], v[172:175], v[0:15]
	s_add_u32 s72, s72, 1
	s_cmp_lt_u32 s72, 30
	s_cbranch_scc1 .Lp19_loop
	s_waitcnt vmcnt(6)
	s_barrier
	s_mul_i32 s74, s71, 0x6000
	s_add_u32 s75, s74, 0x2000
	s_cmp_eq_u32 s71, 2
	s_cselect_b32 s75, 0x10000, s75
	v_add_u32_e32 v184, s74, v179
	v_add_u32_e32 v186, s75, v182
	v_add_u32_e32 v185, s74, v180
	v_add_u32_e32 v187, s75, v183
	ds_read_b128 v[128:131], v184
	ds_read_b128 v[144:147], v186
	ds_read_b128 v[148:151], v186 offset:2048
	ds_read_b128 v[152:155], v186 offset:4096
	ds_read_b128 v[156:159], v186 offset:6144
	ds_read_b128 v[132:135], v184 offset:2048
	ds_read_b128 v[136:139], v185
	ds_read_b128 v[160:163], v187
	ds_read_b128 v[164:167], v187 offset:2048
	ds_read_b128 v[168:171], v187 offset:4096
	ds_read_b128 v[172:175], v187 offset:6144
	ds_read_b128 v[140:143], v185 offset:2048
	s_add_u32 s71, s71, 1
	s_cmp_eq_u32 s71, 3
	s_cselect_b32 s71, 0, s71
	s_waitcnt lgkmcnt(10)
	v_mfma_f32_32x32x16_bf16 v[112:127], v[128:131], v[144:147], v[112:127]
	s_waitcnt lgkmcnt(9)
	v_mfma_f32_32x32x16_bf16 v[96:111], v[128:131], v[148:151], v[96:111]
	s_waitcnt lgkmcnt(8)
	v_mfma_f32_32x32x16_bf16 v[80:95], v[128:131], v[152:155], v[80:95]
	s_waitcnt lgkmcnt(7)
	v_mfma_f32_32x32x16_bf16 v[64:79], v[128:131], v[156:159], v[64:79]
	s_waitcnt lgkmcnt(6)
	v_mfma_f32_32x32x16_bf16 v[48:63], v[132:135], v[144:147], v[48:63]
	v_mfma_f32_32x32x16_bf16 v[32:47], v[132:135], v[148:151], v[32:47]
	v_mfma_f32_32x32x16_bf16 v[16:31], v[132:135], v[152:155], v[16:31]
	v_mfma_f32_32x32x16_bf16 v[0:15], v[132:135], v[156:159], v[0:15]
	s_waitcnt lgkmcnt(4)
	v_mfma_f32_32x32x16_bf16 v[112:127], v[136:139], v[160:163], v[112:127]
	s_waitcnt lgkmcnt(3)
	v_mfma_f32_32x32x16_bf16 v[96:111], v[136:139], v[164:167], v[96:111]
	s_waitcnt lgkmcnt(2)
	v_mfma_f32_32x32x16_bf16 v[80:95], v[136:139], v[168:171], v[80:95]
	s_waitcnt lgkmcnt(1)
	v_mfma_f32_32x32x16_bf16 v[64:79], v[136:139], v[172:175], v[64:79]
	s_waitcnt lgkmcnt(0)
	v_mfma_f32_32x32x16_bf16 v[48:63], v[140:143], v[160:163], v[48:63]
	v_mfma_f32_32x32x16_bf16 v[32:47], v[140:143], v[164:167], v[32:47]
	v_mfma_f32_32x32x16_bf16 v[16:31], v[140:143], v[168:171], v[16:31]
	v_mfma_f32_32x32x16_bf16 v[0:15], v[140:143], v[172:175], v[0:15]
	s_waitcnt vmcnt(0)
	s_barrier
; #define MFMA32(a, b, c) __builtin_amdgcn_mfma_f32_32x32x16_bf16((a), (b), (c), 0, 0, 0)
; DI int crow(int reg, int h) { return (reg & 3) + 8 * (reg >> 2) + 4 * h; }
; template <int lda>
; DI void gemm_mainloop(const bfr* __restrict__ A, const bfr* __restrict__ Bt, int NB, int K, int m0, int n0, char* smem, f32x16 (&acc)[2][4]) {
;     ...
;     const bfr* As = S0 + (kt & 1) * GSTAGE;
;     const bfr* Bs = As + 128 * 40;
; #pragma unroll
;     for (int ks = 0; ks < 2; ++ks) {
;       bf16x8 af[2], bfg[4];
; #pragma unroll
;       for (int i = 0; i < 2; ++i) af[i] = *(const bf16x8*)(As + (wr * 64 + i * 32 + r) * 40 + ks * 16 + hl * 8);
; #pragma unroll
;       for (int j = 0; j < 4; ++j) bfg[j] = *(const bf16x8*)(Bs + (wc * 128 + j * 32 + r) * 40 + ks * 16 + hl * 8);
; #pragma unroll
;       for (int i = 0; i < 2; ++i)
; #pragma unroll
;         for (int j = 0; j < 4; ++j) acc[i][j] = MFMA32(af[i], bfg[j], acc[i][j]);
; template <bool FIRST, bool HAS_H>
; DI void phase_gemm_resid(const Params& p, const bfr* A, const bfr* Wt, const float* gnext, float* ss, char* smem) {
;     ...
;     int tid2 = threadIdx.x;
;     asm volatile("" : "+v"(tid2));
;     const int lane = tid2 & 63, wid = tid2 >> 6, wr = wid >> 1, wc = wid & 1, r = lane & 31, hl = lane >> 5;
;     const float* xsrc = FIRST ? p.x_prompt : X;
;     const int rbase = m0 + wr * 64 + 4 * hl, cbase = n0 + wc * 128 + r;
; #pragma unroll
;     for (int i = 0; i < 2; ++i) {
; #pragma unroll
;       for (int qh = 0; qh < 2; ++qh) {
;         float rs[8];
; #pragma unroll
;         for (int q = 0; q < 8; ++q) rs[q] = 0.f;
; #pragma unroll
;         for (int jh = 0; jh < 2; ++jh) {
;           float xo[2][8];
; #pragma unroll
;           for (int jj = 0; jj < 2; ++jj)
; #pragma unroll
;             for (int q = 0; q < 8; ++q)
;               xo[jj][q] = xsrc[(rbase + i * 32 + crow(qh * 8 + q, 0)) * 1024 + cbase + (jh * 2 + jj) * 32];
	s_mul_i32 s74, s71, 0x6000
	s_add_u32 s75, s74, 0x2000
	s_cmp_eq_u32 s71, 2
	s_cselect_b32 s75, 0x10000, s75
	v_add_u32_e32 v184, s74, v179
	v_add_u32_e32 v186, s75, v182
	v_add_u32_e32 v185, s74, v180
	v_add_u32_e32 v187, s75, v183
	ds_read_b128 v[128:131], v184
	ds_read_b128 v[144:147], v186
	ds_read_b128 v[148:151], v186 offset:2048
	ds_read_b128 v[152:155], v186 offset:4096
	ds_read_b128 v[156:159], v186 offset:6144
	ds_read_b128 v[132:135], v184 offset:2048
	ds_read_b128 v[136:139], v185
	ds_read_b128 v[160:163], v187
	ds_read_b128 v[164:167], v187 offset:2048
	ds_read_b128 v[168:171], v187 offset:4096
	ds_read_b128 v[172:175], v187 offset:6144
	ds_read_b128 v[140:143], v185 offset:2048
	s_add_u32 s71, s71, 1
	s_cmp_eq_u32 s71, 3
	s_cselect_b32 s71, 0, s71
	s_waitcnt lgkmcnt(10)
	v_mfma_f32_32x32x16_bf16 v[112:127], v[128:131], v[144:147], v[112:127]
	s_waitcnt lgkmcnt(9)
	v_mfma_f32_32x32x16_bf16 v[96:111], v[128:131], v[148:151], v[96:111]
	s_waitcnt lgkmcnt(8)
	v_mfma_f32_32x32x16_bf16 v[80:95], v[128:131], v[152:155], v[80:95]
	s_waitcnt lgkmcnt(7)
	v_mfma_f32_32x32x16_bf16 v[64:79], v[128:131], v[156:159], v[64:79]
	s_waitcnt lgkmcnt(6)
	v_mfma_f32_32x32x16_bf16 v[48:63], v[132:135], v[144:147], v[48:63]
	v_mfma_f32_32x32x16_bf16 v[32:47], v[132:135], v[148:151], v[32:47]
	v_mfma_f32_32x32x16_bf16 v[16:31], v[132:135], v[152:155], v[16:31]
	v_mfma_f32_32x32x16_bf16 v[0:15], v[132:135], v[156:159], v[0:15]
	s_waitcnt lgkmcnt(4)
	v_mfma_f32_32x32x16_bf16 v[112:127], v[136:139], v[160:163], v[112:127]
	s_waitcnt lgkmcnt(3)
	v_mfma_f32_32x32x16_bf16 v[96:111], v[136:139], v[164:167], v[96:111]
	s_waitcnt lgkmcnt(2)
	v_mfma_f32_32x32x16_bf16 v[80:95], v[136:139], v[168:171], v[80:95]
	s_waitcnt lgkmcnt(1)
	v_mfma_f32_32x32x16_bf16 v[64:79], v[136:139], v[172:175], v[64:79]
	s_waitcnt lgkmcnt(0)
	v_mfma_f32_32x32x16_bf16 v[48:63], v[140:143], v[160:163], v[48:63]
	v_mfma_f32_32x32x16_bf16 v[32:47], v[140:143], v[164:167], v[32:47]
	v_mfma_f32_32x32x16_bf16 v[16:31], v[140:143], v[168:171], v[16:31]
	v_mfma_f32_32x32x16_bf16 v[0:15], v[140:143], v[172:175], v[0:15]
	s_setprio 0
	s_nop 7
	v_readlane_b32 s64, v188, 0
	v_readlane_b32 s65, v188, 1
	v_readlane_b32 s66, v188, 2
	v_readlane_b32 s67, v188, 3
	v_readlane_b32 s68, v188, 4
	v_readlane_b32 s69, v188, 5
	v_readlane_b32 s70, v188, 6
	v_readlane_b32 s71, v188, 7
	v_readlane_b32 s72, v188, 8
	v_readlane_b32 s73, v188, 9
	v_readlane_b32 s74, v188, 10
	v_readlane_b32 s75, v188, 11
	v_readlane_b32 s76, v188, 12
	v_readlane_b32 s77, v188, 13
	v_readlane_b32 s78, v188, 14
	v_readlane_b32 s79, v188, 15
	s_nop 7
	s_waitcnt vmcnt(1)
	s_nop 0
	s_nop 0
	s_nop 0
	s_waitcnt vmcnt(0)
	s_nop 0
	v_add_u32_e32 v136, v169, v171
	s_nop 0
	v_add_u32_e32 v180, v169, v170
	s_nop 0
	s_nop 0
	s_nop 0
	s_nop 0
	s_nop 0
	s_nop 0
	s_nop 0
	s_nop 0
	s_nop 0
	s_nop 0
	s_nop 0
	s_waitcnt lgkmcnt(0)
	s_nop 0
	s_nop 0
	s_nop 0
	s_nop 0
	s_nop 0
	s_nop 0
	s_nop 0
	s_nop 0
	s_nop 0
	s_nop 0
	s_nop 0
	s_nop 0
	s_nop 0
	s_nop 0
	s_nop 0
	s_nop 0
	s_nop 0
	s_nop 0
	v_mov_b32_e32 v180, v196
	s_waitcnt lgkmcnt(0)
	s_nop 0
	s_nop 0
	v_ashrrev_i32_e32 v182, 1, v180
	v_and_b32_e32 v182, 0xffffffc0, v182
	v_add_u32_e32 v182, s59, v182
	v_lshrrev_b32_e32 v183, 3, v180
	v_and_b32_e32 v185, 31, v180
	v_and_or_b32 v184, v183, 4, v182
	v_lshlrev_b32_e32 v180, 1, v180
	v_and_b32_e32 v180, 0x80, v180
	v_lshlrev_b32_e32 v186, 10, v184
	v_or3_b32 v180, s58, v180, v185
	v_or_b32_e32 v197, 0x400, v186
	v_or_b32_e32 v199, 0x800, v186
	s_nop 0
	v_or_b32_e32 v204, v186, v180
	v_or_b32_e32 v206, v197, v180
	v_ashrrev_i32_e32 v205, 31, v204
	v_ashrrev_i32_e32 v207, 31, v206
	v_or_b32_e32 v187, 32, v180
	v_lshl_add_u64 v[182:183], v[204:205], 2, s[8:9]
	v_lshl_add_u64 v[206:207], v[206:207], 2, s[8:9]
	s_nop 0
	v_or_b32_e32 v212, v199, v180
	v_ashrrev_i32_e32 v213, 31, v212
	v_lshl_add_u64 v[212:213], v[212:213], 2, s[8:9]
	v_or_b32_e32 v224, 0xc00, v186
	v_or_b32_e32 v225, 0x2000, v186
	v_or_b32_e32 v214, v197, v187
	global_load_dword v216, v[182:183], off
	global_load_dword v217, v[206:207], off
	global_load_dword v218, v[212:213], off
	s_nop 0
	v_ashrrev_i32_e32 v205, 31, v186
	v_or_b32_e32 v206, v224, v180
	v_or_b32_e32 v212, v225, v180
	v_ashrrev_i32_e32 v215, 31, v214
	v_lshl_add_u64 v[204:205], v[204:205], 2, s[8:9]
	v_ashrrev_i32_e32 v207, 31, v206
	v_ashrrev_i32_e32 v213, 31, v212
	s_nop 0
	v_lshl_add_u64 v[214:215], v[214:215], 2, s[8:9]
	global_load_dword v219, v[204:205], off offset:128
	v_lshl_add_u64 v[206:207], v[206:207], 2, s[8:9]
	global_load_dword v214, v[214:215], off
	s_nop 0
	s_nop 0
	v_or_b32_e32 v188, v199, v187
	v_ashrrev_i32_e32 v189, 31, v188
	v_lshl_add_u64 v[188:189], v[188:189], 2, s[8:9]
	global_load_dword v215, v[188:189], off
	v_lshl_add_u64 v[188:189], v[212:213], 2, s[8:9]
	global_load_dword v206, v[206:207], off
	s_nop 0
	global_load_dword v207, v[188:189], off
	v_or_b32_e32 v188, v224, v187
	v_or_b32_e32 v190, v225, v187
	v_ashrrev_i32_e32 v189, 31, v188
	v_ashrrev_i32_e32 v191, 31, v190
	s_nop 0
	v_or_b32_e32 v192, 0x2400, v186
	v_lshl_add_u64 v[188:189], v[188:189], 2, s[8:9]
	v_lshl_add_u64 v[190:191], v[190:191], 2, s[8:9]
	global_load_dword v193, v[188:189], off
	v_or_b32_e32 v195, 0x2800, v186
	s_nop 0
	global_load_dword v200, v[190:191], off
	v_or_b32_e32 v188, v192, v180
	v_or_b32_e32 v190, v192, v187
	v_ashrrev_i32_e32 v189, 31, v188
	v_ashrrev_i32_e32 v191, 31, v190
	v_lshl_add_u64 v[188:189], v[188:189], 2, s[8:9]
	v_lshl_add_u64 v[190:191], v[190:191], 2, s[8:9]
	global_load_dword v194, v[188:189], off
	v_or_b32_e32 v201, 0x2c00, v186
	global_load_dword v190, v[190:191], off
	v_or_b32_e32 v188, v195, v180
	v_ashrrev_i32_e32 v189, 31, v188
	v_lshl_add_u64 v[188:189], v[188:189], 2, s[8:9]
	global_load_dword v191, v[188:189], off
	v_or_b32_e32 v188, v201, v180
	v_ashrrev_i32_e32 v189, 31, v188
	v_lshl_add_u64 v[188:189], v[188:189], 2, s[8:9]
	global_load_dword v202, v[188:189], off
	v_or_b32_e32 v188, v195, v187
	v_ashrrev_i32_e32 v189, 31, v188
	v_lshl_add_u64 v[188:189], v[188:189], 2, s[8:9]
	global_load_dword v203, v[188:189], off
	v_or_b32_e32 v188, v201, v187
	v_ashrrev_i32_e32 v189, 31, v188
	v_lshl_add_u64 v[188:189], v[188:189], 2, s[8:9]
	global_load_dword v212, v[188:189], off
	s_nop 0
	s_nop 0
	s_nop 0
	s_waitcnt vmcnt(15)
; DI bfr f2bf(float a) { return (bfr)(pack2(a, 0.f) & 0xffffu); }
; DI int crow(int reg, int h) { return (reg & 3) + 8 * (reg >> 2) + 4 * h; }
; template <bool FIRST, bool HAS_H>
; DI void phase_gemm_resid(const Params& p, const bfr* A, const bfr* Wt, const float* gnext, float* ss, char* smem) {
;     ...
;         for (int jh = 0; jh < 2; ++jh) {
;           float xo[2][8];
; #pragma unroll
;           for (int jj = 0; jj < 2; ++jj)
; #pragma unroll
;             for (int q = 0; q < 8; ++q)
;               xo[jj][q] = xsrc[(rbase + i * 32 + crow(qh * 8 + q, 0)) * 1024 + cbase + (jh * 2 + jj) * 32];
; #pragma unroll
;           for (int q = 0; q < 8; ++q) {
;             const int o = (rbase + i * 32 + crow(qh * 8 + q, 0)) * 1024 + cbase;
; #pragma unroll
;             for (int jj = 0; jj < 2; ++jj) {
;               const int j = jh * 2 + jj;
;               const float xn = xo[jj][q] + acc[i][j][qh * 8 + q];
;               X[o + j * 32] = xn;
;               if (HAS_H) Hn[o + j * 32] = f2bf(xn * gnext[cbase + j * 32]);
;               rs[q] += xn * xn;
;             }
;           }
;         }
; #pragma unroll
;         for (int q = 0; q < 8; ++q) rs[q] = half32_sum_hi(rs[q]);
	s_nop 9
	v_add_f32_e32 v213, v112, v216
	v_add_co_u32_e32 v112, vcc, s23, v182
	s_waitcnt vmcnt(14)
	v_add_f32_e32 v217, v113, v217
	v_addc_co_u32_e32 v113, vcc, 0, v183, vcc
	v_add_co_u32_e32 v188, vcc, s24, v182
	s_nop 0
	s_nop 0
	v_addc_co_u32_e32 v189, vcc, 0, v183, vcc
	global_store_dword v[182:183], v213, off
	global_store_dword v[188:189], v217, off offset:-4096
	s_waitcnt vmcnt(11)
	v_add_f32_e32 v206, v115, v206
	s_nop 0
	v_add_f32_e32 v209, v114, v218
	v_add_co_u32_e32 v114, vcc, s25, v182
	s_nop 2
	v_add_f32_e32 v210, v98, v215
	v_addc_co_u32_e32 v115, vcc, 0, v183, vcc
	v_or_b32_e32 v98, 64, v180
	s_nop 0
	v_add_co_u32_e32 v172, vcc, s33, v182
	v_add_f32_e32 v216, v96, v219
	s_nop 0
	v_addc_co_u32_e32 v173, vcc, 0, v183, vcc
	v_add_co_u32_e32 v174, vcc, s36, v182
	s_nop 0
	s_nop 0
	v_addc_co_u32_e32 v175, vcc, 0, v183, vcc
	s_waitcnt vmcnt(10)
	v_add_f32_e32 v207, v116, v207
	v_or_b32_e32 v96, v197, v98
	v_add_f32_e32 v208, v97, v214
	s_waitcnt vmcnt(9)
	v_add_f32_e32 v193, v99, v193
	v_ashrrev_i32_e32 v97, 31, v96
	s_nop 0
	global_store_dword v[182:183], v216, off offset:128
	global_store_dword v[112:113], v208, off offset:128
	global_store_dword v[188:189], v209, off
	global_store_dword v[188:189], v210, off offset:128
	global_store_dword v[114:115], v206, off
	global_store_dword v[114:115], v193, off offset:128
	global_store_dword v[174:175], v207, off offset:-4096
	s_nop 0
	s_waitcnt vmcnt(15)
	v_add_f32_e32 v164, v100, v200
	v_add_co_u32_e32 v100, vcc, s37, v182
	s_waitcnt vmcnt(13)
	v_add_f32_e32 v166, v101, v190
	v_addc_co_u32_e32 v101, vcc, 0, v183, vcc
	s_waitcnt vmcnt(12)
	v_add_f32_e32 v167, v118, v191
	s_nop 0
	v_add_co_u32_e32 v116, vcc, s38, v182
	s_waitcnt vmcnt(10)
	v_add_f32_e32 v168, v102, v203
	v_or_b32_e32 v102, v199, v98
	v_or_b32_e32 v118, v224, v98
	v_add_f32_e32 v165, v117, v194
	v_addc_co_u32_e32 v117, vcc, 0, v183, vcc
	s_nop 0
	v_add_f32_e32 v160, v119, v202
	s_waitcnt vmcnt(9)
	v_add_f32_e32 v161, v103, v212
	v_ashrrev_i32_e32 v103, 31, v102
	v_ashrrev_i32_e32 v119, 31, v118
	global_store_dword v[172:173], v164, off offset:128
	global_store_dword v[174:175], v165, off
	global_store_dword v[174:175], v166, off offset:128
	s_nop 0
	v_or_b32_e32 v152, v225, v98
	v_or_b32_e32 v154, v192, v98
	v_ashrrev_i32_e32 v153, 31, v152
	v_ashrrev_i32_e32 v155, 31, v154
	v_or_b32_e32 v156, v195, v98
	global_store_dword v[116:117], v167, off offset:-4096
	global_store_dword v[100:101], v168, off offset:128
	global_store_dword v[116:117], v160, off
	global_store_dword v[116:117], v161, off offset:128
	v_lshl_add_u64 v[96:97], v[96:97], 2, s[8:9]
	v_lshl_add_u64 v[102:103], v[102:103], 2, s[8:9]
	v_lshl_add_u64 v[118:119], v[118:119], 2, s[8:9]
	v_lshl_add_u64 v[152:153], v[152:153], 2, s[8:9]
	v_lshl_add_u64 v[154:155], v[154:155], 2, s[8:9]
	v_ashrrev_i32_e32 v157, 31, v156
	v_or_b32_e32 v99, 0x60, v180
	v_lshl_add_u64 v[156:157], v[156:157], 2, s[8:9]
	global_load_dword v158, v[204:205], off offset:256
	global_load_dword v159, v[96:97], off
	global_load_dword v162, v[102:103], off
	s_nop 0
	global_load_dword v118, v[118:119], off
	s_nop 0
	global_load_dword v119, v[152:153], off
	s_nop 0
	global_load_dword v152, v[154:155], off
	global_load_dword v153, v[156:157], off
	s_nop 0
	global_load_dword v154, v[204:205], off offset:384
	v_or_b32_e32 v96, v197, v99
	v_or_b32_e32 v102, v192, v99
	v_ashrrev_i32_e32 v97, 31, v96
	v_ashrrev_i32_e32 v103, 31, v102
	v_lshl_add_u64 v[96:97], v[96:97], 2, s[8:9]
	v_lshl_add_u64 v[102:103], v[102:103], 2, s[8:9]
	s_nop 0
	v_cmp_eq_u32_e32 vcc, 31, v185
	v_ashrrev_i32_e32 v185, 31, v184
	s_nop 0
	global_load_dword v148, v[96:97], off
	s_waitcnt vmcnt(8)
	s_nop 6
	v_add_f32_e32 v80, v80, v158
	s_nop 0
	global_load_dword v142, v[102:103], off
	v_or_b32_e32 v96, v199, v99
	v_ashrrev_i32_e32 v97, 31, v96
	v_lshl_add_u64 v[96:97], v[96:97], 2, s[8:9]
	global_load_dword v149, v[96:97], off
	v_or_b32_e32 v96, v224, v99
	v_ashrrev_i32_e32 v97, 31, v96
	v_lshl_add_u64 v[96:97], v[96:97], 2, s[8:9]
	global_load_dword v140, v[96:97], off
	v_or_b32_e32 v96, v225, v99
	v_ashrrev_i32_e32 v97, 31, v96
	v_lshl_add_u64 v[96:97], v[96:97], 2, s[8:9]
	global_load_dword v141, v[96:97], off
	v_or_b32_e32 v96, v201, v98
	v_or_b32_e32 v102, v195, v99
	v_ashrrev_i32_e32 v97, 31, v96
	v_ashrrev_i32_e32 v103, 31, v102
	v_lshl_add_u64 v[96:97], v[96:97], 2, s[8:9]
	v_lshl_add_u64 v[102:103], v[102:103], 2, s[8:9]
	global_load_dword v102, v[102:103], off
	s_nop 0
	global_load_dword v103, v[96:97], off
	v_or_b32_e32 v96, v201, v99
	v_ashrrev_i32_e32 v97, 31, v96
	v_lshl_add_u64 v[96:97], v[96:97], 2, s[8:9]
	s_nop 0
	global_load_dword v136, v[96:97], off
	s_waitcnt vmcnt(8)
	v_add_f32_e32 v64, v64, v154
	global_store_dword v[182:183], v64, off offset:384
	global_store_dword v[182:183], v80, off offset:256
	v_lshl_add_u64 v[96:97], v[184:185], 2, s[10:11]
	s_nop 0
	s_nop 0
	v_mul_f32_e32 v128, v216, v216
	v_fmac_f32_e32 v128, v213, v213
	v_mul_f32_e32 v129, v208, v208
	v_fmac_f32_e32 v128, v80, v80
	v_fmac_f32_e32 v129, v217, v217
	v_fmac_f32_e32 v128, v64, v64
	v_add_f32_e32 v64, v81, v159
	v_mul_f32_e32 v130, v210, v210
	global_store_dword v[112:113], v64, off offset:256
	v_fmac_f32_e32 v129, v64, v64
	s_waitcnt vmcnt(10)
	v_add_f32_e32 v64, v65, v148
	v_fmac_f32_e32 v130, v209, v209
	global_store_dword v[112:113], v64, off offset:384
	v_fmac_f32_e32 v129, v64, v64
	v_add_f32_e32 v64, v82, v162
	v_mul_f32_e32 v131, v193, v193
	global_store_dword v[188:189], v64, off offset:256
	v_fmac_f32_e32 v130, v64, v64
	v_fmac_f32_e32 v131, v206, v206
	v_mul_f32_e32 v132, v164, v164
	v_fmac_f32_e32 v132, v207, v207
	v_mul_f32_e32 v133, v166, v166
	v_fmac_f32_e32 v133, v165, v165
	v_mul_f32_e32 v134, v168, v168
	v_fmac_f32_e32 v134, v167, v167
	v_mul_f32_e32 v135, v161, v161
	v_fmac_f32_e32 v135, v160, v160
	v_mov_b32_e32 v65, 0
	v_mov_b32_e32 v81, 0
	s_waitcnt vmcnt(10)
; DI bfr f2bf(float a) { return (bfr)(pack2(a, 0.f) & 0xffffu); }
; #define DPPF(v, ctrl, rmask) __builtin_bit_cast(float, __builtin_amdgcn_update_dpp(0, __builtin_bit_cast(int, (v)), (ctrl), (rmask), 0xf, false))
; DI int crow(int reg, int h) { return (reg & 3) + 8 * (reg >> 2) + 4 * h; }
; DI float row16_sum(float v) {
;   v += DPPF(v, 0xB1, 0xf);
;   v += DPPF(v, 0x4E, 0xf);
;   v += DPPF(v, 0x141, 0xf);
;   v += DPPF(v, 0x140, 0xf);
;   return v;
; }
; DI float half32_sum_hi(float v) {
;   v = row16_sum(v);
;   v += DPPF(v, 0x142, 0xa);
;   return v;
; }
; template <bool FIRST, bool HAS_H>
; DI void phase_gemm_resid(const Params& p, const bfr* A, const bfr* Wt, const float* gnext, float* ss, char* smem) {
;     ...
;           for (int q = 0; q < 8; ++q) {
;             const int o = (rbase + i * 32 + crow(qh * 8 + q, 0)) * 1024 + cbase;
; #pragma unroll
;             for (int jj = 0; jj < 2; ++jj) {
;               const int j = jh * 2 + jj;
;               const float xn = xo[jj][q] + acc[i][j][qh * 8 + q];
;               X[o + j * 32] = xn;
;               if (HAS_H) Hn[o + j * 32] = f2bf(xn * gnext[cbase + j * 32]);
;               rs[q] += xn * xn;
;             }
;           }
;         }
; #pragma unroll
;         for (int q = 0; q < 8; ++q) rs[q] = half32_sum_hi(rs[q]);
;         if (r == 31) {
; #pragma unroll
;           for (int q = 0; q < 8; ++q) unsafeAtomicAdd(ss + rbase + i * 32 + crow(qh * 8 + q, 0), rs[q]);
;         }
	v_add_f32_e32 v64, v66, v149
	global_store_dword v[188:189], v64, off offset:384
	v_fmac_f32_e32 v130, v64, v64
	v_add_f32_e32 v64, v83, v118
	global_store_dword v[114:115], v64, off offset:256
	v_fmac_f32_e32 v131, v64, v64
	s_waitcnt vmcnt(11)
	v_add_f32_e32 v64, v67, v140
	global_store_dword v[114:115], v64, off offset:384
	v_fmac_f32_e32 v131, v64, v64
	v_add_f32_e32 v64, v84, v119
	global_store_dword v[172:173], v64, off offset:256
	v_fmac_f32_e32 v132, v64, v64
	s_waitcnt vmcnt(12)
	v_add_f32_e32 v64, v68, v141
	global_store_dword v[172:173], v64, off offset:384
	v_fmac_f32_e32 v132, v64, v64
	v_add_f32_e32 v64, v85, v152
	global_store_dword v[174:175], v64, off offset:256
	v_fmac_f32_e32 v133, v64, v64
	v_add_f32_e32 v64, v69, v142
	global_store_dword v[174:175], v64, off offset:384
	v_fmac_f32_e32 v133, v64, v64
	v_add_f32_e32 v64, v86, v153
	global_store_dword v[100:101], v64, off offset:256
	v_fmac_f32_e32 v134, v64, v64
	s_waitcnt vmcnt(15)
	v_add_f32_e32 v64, v70, v102
	global_store_dword v[100:101], v64, off offset:384
	v_fmac_f32_e32 v134, v64, v64
	s_waitcnt vmcnt(15)
	v_add_f32_e32 v64, v87, v103
	global_store_dword v[116:117], v64, off offset:256
	v_fmac_f32_e32 v135, v64, v64
	s_waitcnt vmcnt(15)
	v_add_f32_e32 v64, v71, v136
	v_fmac_f32_e32 v135, v64, v64
	global_store_dword v[116:117], v64, off offset:384
	v_add_f32_dpp v64, v128, v128 quad_perm:[1,0,3,2] row_mask:0xf bank_mask:0xf bound_ctrl:1
	v_add_f32_dpp v66, v129, v129 quad_perm:[1,0,3,2] row_mask:0xf bank_mask:0xf bound_ctrl:1
	v_add_f32_dpp v68, v130, v130 quad_perm:[1,0,3,2] row_mask:0xf bank_mask:0xf bound_ctrl:1
	v_add_f32_dpp v70, v131, v131 quad_perm:[1,0,3,2] row_mask:0xf bank_mask:0xf bound_ctrl:1
	v_add_f32_dpp v80, v132, v132 quad_perm:[1,0,3,2] row_mask:0xf bank_mask:0xf bound_ctrl:1
	v_add_f32_dpp v82, v133, v133 quad_perm:[1,0,3,2] row_mask:0xf bank_mask:0xf bound_ctrl:1
	v_add_f32_dpp v84, v134, v134 quad_perm:[1,0,3,2] row_mask:0xf bank_mask:0xf bound_ctrl:1
	v_add_f32_dpp v86, v135, v135 quad_perm:[1,0,3,2] row_mask:0xf bank_mask:0xf bound_ctrl:1
	v_add_f32_dpp v64, v64, v64 quad_perm:[2,3,0,1] row_mask:0xf bank_mask:0xf bound_ctrl:1
	v_add_f32_dpp v66, v66, v66 quad_perm:[2,3,0,1] row_mask:0xf bank_mask:0xf bound_ctrl:1
	v_add_f32_dpp v68, v68, v68 quad_perm:[2,3,0,1] row_mask:0xf bank_mask:0xf bound_ctrl:1
	v_add_f32_dpp v70, v70, v70 quad_perm:[2,3,0,1] row_mask:0xf bank_mask:0xf bound_ctrl:1
	v_add_f32_dpp v80, v80, v80 quad_perm:[2,3,0,1] row_mask:0xf bank_mask:0xf bound_ctrl:1
	v_add_f32_dpp v82, v82, v82 quad_perm:[2,3,0,1] row_mask:0xf bank_mask:0xf bound_ctrl:1
	v_add_f32_dpp v84, v84, v84 quad_perm:[2,3,0,1] row_mask:0xf bank_mask:0xf bound_ctrl:1
	v_add_f32_dpp v86, v86, v86 quad_perm:[2,3,0,1] row_mask:0xf bank_mask:0xf bound_ctrl:1
	v_add_f32_dpp v64, v64, v64 row_half_mirror row_mask:0xf bank_mask:0xf bound_ctrl:1
	v_add_f32_dpp v66, v66, v66 row_half_mirror row_mask:0xf bank_mask:0xf bound_ctrl:1
	v_add_f32_dpp v68, v68, v68 row_half_mirror row_mask:0xf bank_mask:0xf bound_ctrl:1
	v_add_f32_dpp v70, v70, v70 row_half_mirror row_mask:0xf bank_mask:0xf bound_ctrl:1
	v_add_f32_dpp v80, v80, v80 row_half_mirror row_mask:0xf bank_mask:0xf bound_ctrl:1
	v_add_f32_dpp v82, v82, v82 row_half_mirror row_mask:0xf bank_mask:0xf bound_ctrl:1
	v_add_f32_dpp v84, v84, v84 row_half_mirror row_mask:0xf bank_mask:0xf bound_ctrl:1
	v_add_f32_dpp v86, v86, v86 row_half_mirror row_mask:0xf bank_mask:0xf bound_ctrl:1
	v_add_f32_dpp v64, v64, v64 row_mirror row_mask:0xf bank_mask:0xf bound_ctrl:1
	v_add_f32_dpp v66, v66, v66 row_mirror row_mask:0xf bank_mask:0xf bound_ctrl:1
	v_mov_b32_e32 v67, 0
	v_add_f32_dpp v68, v68, v68 row_mirror row_mask:0xf bank_mask:0xf bound_ctrl:1
	v_mov_b32_e32 v69, 0
	v_add_f32_dpp v70, v70, v70 row_mirror row_mask:0xf bank_mask:0xf bound_ctrl:1
	v_mov_b32_e32 v71, 0
	v_add_f32_dpp v80, v80, v80 row_mirror row_mask:0xf bank_mask:0xf bound_ctrl:1
	v_add_f32_dpp v82, v82, v82 row_mirror row_mask:0xf bank_mask:0xf bound_ctrl:1
	v_mov_b32_e32 v83, 0
	v_add_f32_dpp v84, v84, v84 row_mirror row_mask:0xf bank_mask:0xf bound_ctrl:1
	v_mov_b32_e32 v85, 0
	v_add_f32_dpp v86, v86, v86 row_mirror row_mask:0xf bank_mask:0xf bound_ctrl:1
	v_mov_b32_e32 v87, 0
	v_mov_b32_dpp v65, v64 row_bcast:15 row_mask:0xa bank_mask:0xf
	v_mov_b32_dpp v67, v66 row_bcast:15 row_mask:0xa bank_mask:0xf
	v_mov_b32_dpp v69, v68 row_bcast:15 row_mask:0xa bank_mask:0xf
	v_mov_b32_dpp v71, v70 row_bcast:15 row_mask:0xa bank_mask:0xf
	v_mov_b32_dpp v81, v80 row_bcast:15 row_mask:0xa bank_mask:0xf
	v_mov_b32_dpp v83, v82 row_bcast:15 row_mask:0xa bank_mask:0xf
	v_mov_b32_dpp v85, v84 row_bcast:15 row_mask:0xa bank_mask:0xf
	v_mov_b32_dpp v87, v86 row_bcast:15 row_mask:0xa bank_mask:0xf
	s_and_saveexec_b64 s[4:5], vcc
	s_cbranch_execz .LBB0_1734
	v_add_f32_e32 v64, v64, v65
	v_add_f32_e32 v86, v86, v87
	v_add_f32_e32 v84, v84, v85
	v_add_f32_e32 v82, v82, v83
	v_add_f32_e32 v80, v80, v81
	v_add_f32_e32 v70, v70, v71
	v_add_f32_e32 v68, v68, v69
	v_add_f32_e32 v66, v66, v67
	global_atomic_add_f32 v[96:97], v64, off
	global_atomic_add_f32 v[96:97], v66, off offset:4
	global_atomic_add_f32 v[96:97], v68, off offset:8
	global_atomic_add_f32 v[96:97], v70, off offset:12
	global_atomic_add_f32 v[96:97], v80, off offset:32
	global_atomic_add_f32 v[96:97], v82, off offset:36
	global_atomic_add_f32 v[96:97], v84, off offset:40
	global_atomic_add_f32 v[96:97], v86, off offset:44
